# first K-loop iteration peeled (zero accumulator inputs, no zero-init) re-applied on top of v44
# speedup vs baseline: 1.0090x; 1.0035x over previous
; #define LDA8(dst, b, h) _Pragma("unroll") for (int m = 0; m < 4; ++m) _Pragma("unroll") for (int k = 0; k < 2; ++k) \
;     dst[m][k] = *(const bf16x8*)((const char*)SA8(b, h) + lds_byte8(wr * 64 + m * 16 + fr, k * 32 + fq * 8))
; #define LDB8(dst, b, h) _Pragma("unroll") for (int n = 0; n < 2; ++n) _Pragma("unroll") for (int k = 0; k < 2; ++k) \
;     dst[n][k] = *(const bf16x8*)((const char*)SB8(b, h) + lds_byte8(wc * 32 + n * 16 + fr, k * 32 + fq * 8))
; #define WAIT_V8(n) asm volatile("s_waitcnt vmcnt(" #n ")" ::: "memory")
; #define WAIT_L8(n) asm volatile("s_waitcnt lgkmcnt(" #n ")" ::: "memory")
; #define BAR8 __builtin_amdgcn_s_barrier()
; #define SCHED8 __builtin_amdgcn_sched_barrier(0)
;     ...
;   const int brow = m0, bcol = n0;
;   const int wid = t >> 6, lane = t & 63, wr = wid >> 2, wc = wid & 3, fr = lane & 15, fq = lane >> 4;
;   f32x4 acc[2][2][4][2];
;   {
;     float zinit = 0.f;
;     asm volatile("" : "+v"(zinit));
; #pragma unroll
;     for (int a = 0; a < 2; ++a)
; #pragma unroll
;       for (int b = 0; b < 2; ++b)
; #pragma unroll
;         for (int m = 0; m < 4; ++m)
; #pragma unroll
;           for (int n = 0; n < 2; ++n)
; #pragma unroll
;             for (int j = 0; j < 4; ++j) acc[a][b][m][n][j] = zinit;
;   }
;   bf16x8 At[4][2], B0[2][2], B1[2][2];
;   const int nt = K / 64;
;   if (!pre) {
;     STAGE8(SB8(0, 0), Bt, K, bcol, 0); STAGE8(SA8(0, 0), A, lda, brow, 0);
;     STAGE8(SB8(0, 1), Bt, K, bcol + 128, 0); STAGE8(SA8(0, 1), A, lda, brow + 128, 0);
;   }
;   if (wr == 1) BAR8;
;   WAIT_V8(4); BAR8;
;   STAGE8(SB8(1, 0), Bt, K, bcol, 1); STAGE8(SA8(1, 0), A, lda, brow, 1); STAGE8(SB8(1, 1), Bt, K, bcol + 128, 1);
;   WAIT_V8(6); BAR8;
;   for (int tt = 0; tt < nt - 2; tt += 2) {
;     LDB8(B0, 0, 0); SCHED8; LDA8(At, 0, 0); STAGE8(SA8(1, 1), A, lda, brow + 128, tt + 1);
;     WAIT_L8(8); BAR8; WAIT_L8(0); MMA8(0, 0, At, B0); BAR8; SCHED8;
.LBB0_191:
	s_or_b64 exec, exec, s[14:15]
	s_mov_b64 s[60:61], 0x80
	v_lshl_add_u64 v[10:11], v[10:11], 0, s[60:61]
	s_or_b32 m0, s100, 0x18000
	s_waitcnt vmcnt(4)
	s_barrier
	global_load_lds_dwordx4 v[10:11], off
	v_lshl_add_u64 v[10:11], v[12:13], 0, s[60:61]
	s_or_b32 m0, s100, 0x1a000
	global_load_lds_dwordx4 v[10:11], off
	v_lshl_add_u64 v[10:11], v[14:15], 0, s[60:61]
	s_or_b32 m0, s100, 0x8000
	global_load_lds_dwordx4 v[10:11], off
	v_lshl_add_u64 v[10:11], v[16:17], 0, s[60:61]
	s_or_b32 m0, s100, 0xa000
	global_load_lds_dwordx4 v[10:11], off
	v_lshl_add_u64 v[10:11], v[18:19], 0, s[60:61]
	s_or_b32 m0, s100, 0x1c000
	s_nop 0
	global_load_lds_dwordx4 v[10:11], off
	v_lshl_add_u64 v[10:11], v[20:21], 0, s[60:61]
	s_or_b32 m0, s100, 0x1e000
	v_and_b32_e32 v147, 15, v3
	global_load_lds_dwordx4 v[10:11], off
	v_bfe_u32 v148, v3, 4, 2
	v_lshlrev_b32_e32 v10, 4, v148
	v_lshlrev_b32_e32 v11, 6, v147
	v_lshlrev_b32_e32 v14, 2, v3
	v_or_b32_e32 v13, v10, v11
	v_and_b32_e32 v14, 32, v14
	s_mov_b32 s14, 0x10000
	v_bitop3_b32 v16, v13, s14, v14 bitop3:0xde
	s_mov_b32 s14, 0x14000
	v_bitop3_b32 v15, v10, v14, v11 bitop3:0x36
	v_bitop3_b32 v17, v13, s14, v14 bitop3:0xde
	s_mov_b32 s14, 0x18000
	v_lshlrev_b32_e32 v11, 6, v3
	v_bitop3_b32 v18, v13, s14, v14 bitop3:0xde
	s_mov_b32 s14, 0x1c000
	v_and_b32_e32 v11, 0x3c0, v11
	v_bitop3_b32 v13, v13, s14, v14 bitop3:0xde
	v_bitop3_b32 v14, v11, v14, v10 bitop3:0x36
	v_lshl_add_u64 v[10:11], s[30:31], 0, v[136:137]
	v_lshl_add_u64 v[10:11], v[10:11], 0, v[8:9]
	v_lshl_add_u64 v[138:139], s[12:13], 0, v[10:11]
	v_lshl_add_u64 v[10:11], s[30:31], 0, v[132:133]
	v_lshl_add_u64 v[10:11], v[10:11], 0, v[6:7]
	v_lshl_add_u64 v[140:141], s[12:13], 0, v[10:11]
	v_lshl_add_u64 v[10:11], s[56:57], 0, v[132:133]
	v_lshl_add_u64 v[6:7], v[10:11], 0, v[6:7]
	v_bfe_u32 v146, v3, 6, 2
	s_waitcnt vmcnt(6)
	v_lshlrev_b32_e32 v149, 6, v5
	v_lshlrev_b32_e32 v5, 13, v5
	v_lshl_add_u64 v[142:143], s[46:47], 0, v[6:7]
	v_lshl_add_u64 v[6:7], s[56:57], 0, v[136:137]
	v_lshlrev_b32_e32 v12, 12, v146
	v_or_b32_e32 v19, 0x800, v5
	v_or_b32_e32 v20, 0x1000, v5
	v_or_b32_e32 v21, 0x1800, v5
	v_lshl_add_u64 v[6:7], v[6:7], 0, v[8:9]
	v_lshl_add_u64 v[144:145], s[46:47], 0, v[6:7]
	s_mov_b32 s14, -2
	s_mov_b64 s[12:13], 0
	v_add_u32_e32 v173, v16, v12
	v_add_u32_e32 v156, v15, v5
	v_add_u32_e32 v154, v14, v19
	v_add_u32_e32 v153, v14, v20
	v_add_u32_e32 v152, v14, v21
	v_add_u32_e32 v169, v17, v12
	v_add_u32_e32 v159, v18, v12
	v_add_u32_e32 v158, v13, v12
	s_mov_b64 s[60:61], 0xc000100
	s_mov_b64 s[62:63], 0xc040100
	s_mov_b64 s[64:65], 0xc000180
	s_mov_b64 s[66:67], 0xc040180
	s_barrier
	ds_read_b128 v[174:177], v173
	ds_read_b128 v[178:181], v173 offset:1024
	ds_read_b128 v[182:185], v173 offset:2048
	ds_read_b128 v[186:189], v173 offset:3072
	v_lshl_add_u64 v[222:223], v[140:141], 0, s[12:13]
	v_lshl_add_u64 v[226:227], v[222:223], 0, s[34:35]
	s_or_b32 m0, s100, 0xc000
	ds_read_b128 v[190:193], v156
	ds_read_b128 v[194:197], v156 offset:1024
	ds_read_b128 v[198:201], v154
	ds_read_b128 v[202:205], v154 offset:1024
	ds_read_b128 v[206:209], v153
	ds_read_b128 v[210:213], v153 offset:1024
	ds_read_b128 v[214:217], v152
	ds_read_b128 v[218:221], v152 offset:1024
	global_load_lds_dwordx4 v[226:227], off
	v_lshl_add_u64 v[226:227], v[138:139], 0, s[12:13]
	v_lshl_add_u64 v[228:229], v[226:227], 0, s[34:35]
	s_or_b32 m0, s100, 0xe000
	s_nop 0
	global_load_lds_dwordx4 v[228:229], off
	s_waitcnt lgkmcnt(8)
	s_barrier
	s_waitcnt lgkmcnt(0)
	v_mfma_f32_16x16x32_f16 v[128:131], v[190:193], v[174:177], 0
	v_mfma_f32_16x16x32_f16 v[124:127], v[190:193], v[182:185], 0
	v_mfma_f32_16x16x32_f16 v[120:123], v[198:201], v[174:177], 0
	v_mfma_f32_16x16x32_f16 v[116:119], v[198:201], v[182:185], 0
	v_mfma_f32_16x16x32_f16 v[112:115], v[206:209], v[174:177], 0
	v_mfma_f32_16x16x32_f16 v[108:111], v[206:209], v[182:185], 0
	v_mfma_f32_16x16x32_f16 v[104:107], v[214:217], v[174:177], 0
	v_mfma_f32_16x16x32_f16 v[100:103], v[214:217], v[182:185], 0
	v_mfma_f32_16x16x32_f16 v[128:131], v[194:197], v[178:181], v[128:131]
	v_mfma_f32_16x16x32_f16 v[124:127], v[194:197], v[186:189], v[124:127]
	v_mfma_f32_16x16x32_f16 v[120:123], v[202:205], v[178:181], v[120:123]
	v_mfma_f32_16x16x32_f16 v[116:119], v[202:205], v[186:189], v[116:119]
	v_mfma_f32_16x16x32_f16 v[112:115], v[210:213], v[178:181], v[112:115]
	v_mfma_f32_16x16x32_f16 v[108:111], v[210:213], v[186:189], v[108:111]
	v_mfma_f32_16x16x32_f16 v[104:107], v[218:221], v[178:181], v[104:107]
	v_mfma_f32_16x16x32_f16 v[100:103], v[218:221], v[186:189], v[100:103]
	s_barrier
	v_lshl_add_u64 v[228:229], v[142:143], 0, s[12:13]
	v_lshl_add_u64 v[236:237], v[228:229], 0, s[60:61]
	s_or_b32 m0, s100, 0x10000
	ds_read_b128 v[238:241], v169
	ds_read_b128 v[242:245], v169 offset:1024
	ds_read_b128 v[246:249], v169 offset:2048
	ds_read_b128 v[230:233], v169 offset:3072
	global_load_lds_dwordx4 v[236:237], off
	v_lshl_add_u64 v[236:237], v[144:145], 0, s[12:13]
	v_lshl_add_u64 v[250:251], v[236:237], 0, s[60:61]
	s_or_b32 m0, s100, 0x12000
	s_nop 0
	global_load_lds_dwordx4 v[250:251], off
	s_barrier
; #define LDA8(dst, b, h) _Pragma("unroll") for (int m = 0; m < 4; ++m) _Pragma("unroll") for (int k = 0; k < 2; ++k) \
;     dst[m][k] = *(const bf16x8*)((const char*)SA8(b, h) + lds_byte8(wr * 64 + m * 16 + fr, k * 32 + fq * 8))
; #define LDB8(dst, b, h) _Pragma("unroll") for (int n = 0; n < 2; ++n) _Pragma("unroll") for (int k = 0; k < 2; ++k) \
;     dst[n][k] = *(const bf16x8*)((const char*)SB8(b, h) + lds_byte8(wc * 32 + n * 16 + fr, k * 32 + fq * 8))
; #define WAIT_V8(n) asm volatile("s_waitcnt vmcnt(" #n ")" ::: "memory")
; #define WAIT_L8(n) asm volatile("s_waitcnt lgkmcnt(" #n ")" ::: "memory")
; #define BAR8 __builtin_amdgcn_s_barrier()
; #define SCHED8 __builtin_amdgcn_sched_barrier(0)
;     ...
;     WAIT_L8(8); BAR8; WAIT_L8(0); MMA8(0, 0, At, B0); BAR8; SCHED8;
;     LDB8(B1, 0, 1); STAGE8(SB8(0, 0), Bt, K, bcol, tt + 2);
;     BAR8; WAIT_L8(0); MMA8(0, 1, At, B1); BAR8;
;     LDA8(At, 0, 1); STAGE8(SA8(0, 0), A, lda, brow, tt + 2);
;     BAR8; WAIT_L8(0); MMA8(1, 0, At, B0); BAR8; SCHED8;
;     STAGE8(SB8(0, 1), Bt, K, bcol + 128, tt + 2);
;     WAIT_V8(6); BAR8; MMA8(1, 1, At, B1); BAR8;
;     LDB8(B0, 1, 0); SCHED8; LDA8(At, 1, 0); STAGE8(SA8(0, 1), A, lda, brow + 128, tt + 2);
;     WAIT_L8(8); BAR8; WAIT_L8(0); MMA8(0, 0, At, B0); BAR8; SCHED8;
	s_waitcnt lgkmcnt(0)
	v_mfma_f32_16x16x32_f16 v[96:99], v[190:193], v[238:241], 0
	v_mfma_f32_16x16x32_f16 v[92:95], v[190:193], v[246:249], 0
	v_mfma_f32_16x16x32_f16 v[88:91], v[198:201], v[238:241], 0
	v_mfma_f32_16x16x32_f16 v[84:87], v[198:201], v[246:249], 0
	v_mfma_f32_16x16x32_f16 v[80:83], v[206:209], v[238:241], 0
	v_mfma_f32_16x16x32_f16 v[76:79], v[206:209], v[246:249], 0
	v_mfma_f32_16x16x32_f16 v[72:75], v[214:217], v[238:241], 0
	v_mfma_f32_16x16x32_f16 v[68:71], v[214:217], v[246:249], 0
	v_mfma_f32_16x16x32_f16 v[96:99], v[194:197], v[242:245], v[96:99]
	v_mfma_f32_16x16x32_f16 v[92:95], v[194:197], v[230:233], v[92:95]
	v_mfma_f32_16x16x32_f16 v[88:91], v[202:205], v[242:245], v[88:91]
	v_mfma_f32_16x16x32_f16 v[84:87], v[202:205], v[230:233], v[84:87]
	v_mfma_f32_16x16x32_f16 v[80:83], v[210:213], v[242:245], v[80:83]
	v_mfma_f32_16x16x32_f16 v[76:79], v[210:213], v[230:233], v[76:79]
	v_mfma_f32_16x16x32_f16 v[72:75], v[218:221], v[242:245], v[72:75]
	v_mfma_f32_16x16x32_f16 v[68:71], v[218:221], v[230:233], v[68:71]
	v_lshl_add_u64 v[250:251], v[222:223], 0, s[10:11]
	s_mov_b32 m0, s100
	s_barrier
	ds_read_b128 v[190:193], v156 offset:16384
	ds_read_b128 v[194:197], v156 offset:17408
	ds_read_b128 v[198:201], v154 offset:16384
	ds_read_b128 v[202:205], v154 offset:17408
	ds_read_b128 v[206:209], v153 offset:16384
	ds_read_b128 v[210:213], v153 offset:17408
	ds_read_b128 v[214:217], v152 offset:16384
	ds_read_b128 v[218:221], v152 offset:17408
	global_load_lds_dwordx4 v[250:251], off
	v_lshl_add_u64 v[250:251], v[226:227], 0, s[10:11]
	s_or_b32 m0, s100, 0x2000
	s_nop 0
	global_load_lds_dwordx4 v[250:251], off
	s_barrier
	s_waitcnt lgkmcnt(0)
	v_mfma_f32_16x16x32_f16 v[64:67], v[190:193], v[174:177], 0
	v_mfma_f32_16x16x32_f16 v[60:63], v[190:193], v[182:185], 0
	v_mfma_f32_16x16x32_f16 v[56:59], v[198:201], v[174:177], 0
	v_mfma_f32_16x16x32_f16 v[52:55], v[198:201], v[182:185], 0
	v_mfma_f32_16x16x32_f16 v[48:51], v[206:209], v[174:177], 0
	v_mfma_f32_16x16x32_f16 v[44:47], v[206:209], v[182:185], 0
	v_mfma_f32_16x16x32_f16 v[40:43], v[214:217], v[174:177], 0
	v_mfma_f32_16x16x32_f16 v[36:39], v[214:217], v[182:185], 0
	v_mfma_f32_16x16x32_f16 v[64:67], v[194:197], v[178:181], v[64:67]
	v_mfma_f32_16x16x32_f16 v[60:63], v[194:197], v[186:189], v[60:63]
	v_mfma_f32_16x16x32_f16 v[56:59], v[202:205], v[178:181], v[56:59]
	v_mfma_f32_16x16x32_f16 v[52:55], v[202:205], v[186:189], v[52:55]
	v_mfma_f32_16x16x32_f16 v[48:51], v[210:213], v[178:181], v[48:51]
	v_mfma_f32_16x16x32_f16 v[44:47], v[210:213], v[186:189], v[44:47]
	v_mfma_f32_16x16x32_f16 v[40:43], v[218:221], v[178:181], v[40:43]
	v_mfma_f32_16x16x32_f16 v[36:39], v[218:221], v[186:189], v[36:39]
	s_barrier
	v_lshl_add_u64 v[174:175], v[228:229], 0, s[62:63]
	s_or_b32 m0, s100, 0x14000
	s_nop 0
	global_load_lds_dwordx4 v[174:175], off
	v_lshl_add_u64 v[174:175], v[236:237], 0, s[62:63]
	s_or_b32 m0, s100, 0x16000
	s_nop 0
	global_load_lds_dwordx4 v[174:175], off
	s_waitcnt vmcnt(6)
	s_barrier
	v_mfma_f32_16x16x32_f16 v[32:35], v[190:193], v[238:241], 0
	v_mfma_f32_16x16x32_f16 v[28:31], v[190:193], v[246:249], 0
	v_mfma_f32_16x16x32_f16 v[24:27], v[198:201], v[238:241], 0
	v_mfma_f32_16x16x32_f16 v[20:23], v[198:201], v[246:249], 0
	v_mfma_f32_16x16x32_f16 v[16:19], v[206:209], v[238:241], 0
	v_mfma_f32_16x16x32_f16 v[12:15], v[206:209], v[246:249], 0
	v_mfma_f32_16x16x32_f16 v[8:11], v[214:217], v[238:241], 0
	v_mfma_f32_16x16x32_f16 v[4:7], v[214:217], v[246:249], 0
	v_mfma_f32_16x16x32_f16 v[32:35], v[194:197], v[242:245], v[32:35]
	v_mfma_f32_16x16x32_f16 v[28:31], v[194:197], v[230:233], v[28:31]
	v_mfma_f32_16x16x32_f16 v[24:27], v[202:205], v[242:245], v[24:27]
	v_mfma_f32_16x16x32_f16 v[20:23], v[202:205], v[230:233], v[20:23]
	v_mfma_f32_16x16x32_f16 v[16:19], v[210:213], v[242:245], v[16:19]
	v_mfma_f32_16x16x32_f16 v[12:15], v[210:213], v[230:233], v[12:15]
	v_mfma_f32_16x16x32_f16 v[8:11], v[218:221], v[242:245], v[8:11]
	v_mfma_f32_16x16x32_f16 v[4:7], v[218:221], v[230:233], v[4:7]
	s_barrier
	ds_read_b128 v[174:177], v159
	ds_read_b128 v[178:181], v159 offset:1024
	ds_read_b128 v[182:185], v159 offset:2048
	ds_read_b128 v[186:189], v159 offset:3072
	v_lshl_add_u64 v[230:231], v[222:223], 0, s[18:19]
	s_or_b32 m0, s100, 0x4000
	ds_read_b128 v[190:193], v156 offset:32768
	ds_read_b128 v[194:197], v156 offset:33792
	ds_read_b128 v[198:201], v154 offset:32768
	ds_read_b128 v[202:205], v154 offset:33792
	ds_read_b128 v[206:209], v153 offset:32768
	ds_read_b128 v[210:213], v153 offset:33792
	ds_read_b128 v[214:217], v152 offset:32768
	ds_read_b128 v[218:221], v152 offset:33792
	global_load_lds_dwordx4 v[230:231], off
	v_lshl_add_u64 v[230:231], v[226:227], 0, s[18:19]
	s_or_b32 m0, s100, 0x6000
	s_nop 0
	global_load_lds_dwordx4 v[230:231], off
	s_waitcnt lgkmcnt(8)
	s_barrier
; #define LDA8(dst, b, h) _Pragma("unroll") for (int m = 0; m < 4; ++m) _Pragma("unroll") for (int k = 0; k < 2; ++k) \
;     dst[m][k] = *(const bf16x8*)((const char*)SA8(b, h) + lds_byte8(wr * 64 + m * 16 + fr, k * 32 + fq * 8))
; #define LDB8(dst, b, h) _Pragma("unroll") for (int n = 0; n < 2; ++n) _Pragma("unroll") for (int k = 0; k < 2; ++k) \
;     dst[n][k] = *(const bf16x8*)((const char*)SB8(b, h) + lds_byte8(wc * 32 + n * 16 + fr, k * 32 + fq * 8))
; #define WAIT_V8(n) asm volatile("s_waitcnt vmcnt(" #n ")" ::: "memory")
; #define WAIT_L8(n) asm volatile("s_waitcnt lgkmcnt(" #n ")" ::: "memory")
; #define BAR8 __builtin_amdgcn_s_barrier()
; #define SCHED8 __builtin_amdgcn_sched_barrier(0)
;     ...
;     WAIT_L8(8); BAR8; WAIT_L8(0); MMA8(0, 0, At, B0); BAR8; SCHED8;
;     LDB8(B1, 1, 1); STAGE8(SB8(1, 0), Bt, K, bcol, tt + 3);
;     BAR8; WAIT_L8(0); MMA8(0, 1, At, B1); BAR8;
;     LDA8(At, 1, 1); STAGE8(SA8(1, 0), A, lda, brow, tt + 3);
;     BAR8; WAIT_L8(0); MMA8(1, 0, At, B0); BAR8; SCHED8;
;     STAGE8(SB8(1, 1), Bt, K, bcol + 128, tt + 3);
;     WAIT_V8(6); BAR8; MMA8(1, 1, At, B1); BAR8;
	s_waitcnt lgkmcnt(0)
	v_mfma_f32_16x16x32_f16 v[128:131], v[190:193], v[174:177], v[128:131]
	v_mfma_f32_16x16x32_f16 v[124:127], v[190:193], v[182:185], v[124:127]
	v_mfma_f32_16x16x32_f16 v[120:123], v[198:201], v[174:177], v[120:123]
	v_mfma_f32_16x16x32_f16 v[116:119], v[198:201], v[182:185], v[116:119]
	v_mfma_f32_16x16x32_f16 v[112:115], v[206:209], v[174:177], v[112:115]
	v_mfma_f32_16x16x32_f16 v[108:111], v[206:209], v[182:185], v[108:111]
	v_mfma_f32_16x16x32_f16 v[104:107], v[214:217], v[174:177], v[104:107]
	v_mfma_f32_16x16x32_f16 v[100:103], v[214:217], v[182:185], v[100:103]
	v_mfma_f32_16x16x32_f16 v[128:131], v[194:197], v[178:181], v[128:131]
	v_mfma_f32_16x16x32_f16 v[124:127], v[194:197], v[186:189], v[124:127]
	v_mfma_f32_16x16x32_f16 v[120:123], v[202:205], v[178:181], v[120:123]
	v_mfma_f32_16x16x32_f16 v[116:119], v[202:205], v[186:189], v[116:119]
	v_mfma_f32_16x16x32_f16 v[112:115], v[210:213], v[178:181], v[112:115]
	v_mfma_f32_16x16x32_f16 v[108:111], v[210:213], v[186:189], v[108:111]
	v_mfma_f32_16x16x32_f16 v[104:107], v[218:221], v[178:181], v[104:107]
	v_mfma_f32_16x16x32_f16 v[100:103], v[218:221], v[186:189], v[100:103]
	s_barrier
	v_lshl_add_u64 v[250:251], v[228:229], 0, s[64:65]
	s_or_b32 m0, s100, 0x18000
	ds_read_b128 v[230:233], v158
	ds_read_b128 v[238:241], v158 offset:1024
	ds_read_b128 v[242:245], v158 offset:2048
	ds_read_b128 v[246:249], v158 offset:3072
	global_load_lds_dwordx4 v[250:251], off
	v_lshl_add_u64 v[250:251], v[236:237], 0, s[64:65]
	s_or_b32 m0, s100, 0x1a000
	s_nop 0
	global_load_lds_dwordx4 v[250:251], off
	s_barrier
	s_waitcnt lgkmcnt(0)
	v_mfma_f32_16x16x32_f16 v[96:99], v[190:193], v[230:233], v[96:99]
	v_mfma_f32_16x16x32_f16 v[92:95], v[190:193], v[242:245], v[92:95]
	v_mfma_f32_16x16x32_f16 v[88:91], v[198:201], v[230:233], v[88:91]
	v_mfma_f32_16x16x32_f16 v[84:87], v[198:201], v[242:245], v[84:87]
	v_mfma_f32_16x16x32_f16 v[80:83], v[206:209], v[230:233], v[80:83]
	v_mfma_f32_16x16x32_f16 v[76:79], v[206:209], v[242:245], v[76:79]
	v_mfma_f32_16x16x32_f16 v[72:75], v[214:217], v[230:233], v[72:75]
	v_mfma_f32_16x16x32_f16 v[68:71], v[214:217], v[242:245], v[68:71]
	v_mfma_f32_16x16x32_f16 v[96:99], v[194:197], v[238:241], v[96:99]
	v_mfma_f32_16x16x32_f16 v[92:95], v[194:197], v[246:249], v[92:95]
	v_mfma_f32_16x16x32_f16 v[88:91], v[202:205], v[238:241], v[88:91]
	v_mfma_f32_16x16x32_f16 v[84:87], v[202:205], v[246:249], v[84:87]
	v_mfma_f32_16x16x32_f16 v[80:83], v[210:213], v[238:241], v[80:83]
	v_mfma_f32_16x16x32_f16 v[76:79], v[210:213], v[246:249], v[76:79]
	v_mfma_f32_16x16x32_f16 v[72:75], v[218:221], v[238:241], v[72:75]
	v_mfma_f32_16x16x32_f16 v[68:71], v[218:221], v[246:249], v[68:71]
	v_lshl_add_u64 v[222:223], v[222:223], 0, s[22:23]
	s_or_b32 m0, s100, 0x8000
	s_barrier
	ds_read_b128 v[190:193], v156 offset:49152
	ds_read_b128 v[194:197], v156 offset:50176
	ds_read_b128 v[198:201], v154 offset:49152
	ds_read_b128 v[202:205], v154 offset:50176
	ds_read_b128 v[206:209], v153 offset:49152
	ds_read_b128 v[210:213], v153 offset:50176
	ds_read_b128 v[214:217], v152 offset:49152
	ds_read_b128 v[218:221], v152 offset:50176
	global_load_lds_dwordx4 v[222:223], off
	v_lshl_add_u64 v[222:223], v[226:227], 0, s[22:23]
	s_or_b32 m0, s100, 0xa000
	s_nop 0
	global_load_lds_dwordx4 v[222:223], off
	s_barrier
	s_waitcnt lgkmcnt(0)
	v_mfma_f32_16x16x32_f16 v[64:67], v[190:193], v[174:177], v[64:67]
	v_mfma_f32_16x16x32_f16 v[60:63], v[190:193], v[182:185], v[60:63]
	v_mfma_f32_16x16x32_f16 v[56:59], v[198:201], v[174:177], v[56:59]
	v_mfma_f32_16x16x32_f16 v[52:55], v[198:201], v[182:185], v[52:55]
	v_mfma_f32_16x16x32_f16 v[48:51], v[206:209], v[174:177], v[48:51]
	v_mfma_f32_16x16x32_f16 v[44:47], v[206:209], v[182:185], v[44:47]
	v_mfma_f32_16x16x32_f16 v[40:43], v[214:217], v[174:177], v[40:43]
	v_mfma_f32_16x16x32_f16 v[36:39], v[214:217], v[182:185], v[36:39]
	v_mfma_f32_16x16x32_f16 v[64:67], v[194:197], v[178:181], v[64:67]
	v_mfma_f32_16x16x32_f16 v[60:63], v[194:197], v[186:189], v[60:63]
	v_mfma_f32_16x16x32_f16 v[56:59], v[202:205], v[178:181], v[56:59]
	v_mfma_f32_16x16x32_f16 v[52:55], v[202:205], v[186:189], v[52:55]
	v_mfma_f32_16x16x32_f16 v[48:51], v[210:213], v[178:181], v[48:51]
	v_mfma_f32_16x16x32_f16 v[44:47], v[210:213], v[186:189], v[44:47]
	v_mfma_f32_16x16x32_f16 v[40:43], v[218:221], v[178:181], v[40:43]
	v_mfma_f32_16x16x32_f16 v[36:39], v[218:221], v[186:189], v[36:39]
	s_barrier
	v_lshl_add_u64 v[174:175], v[228:229], 0, s[66:67]
	s_or_b32 m0, s100, 0x1c000
	s_nop 0
	global_load_lds_dwordx4 v[174:175], off
	v_lshl_add_u64 v[174:175], v[236:237], 0, s[66:67]
	s_or_b32 m0, s100, 0x1e000
	s_nop 0
	global_load_lds_dwordx4 v[174:175], off
	s_waitcnt vmcnt(6)
	s_barrier
	v_mfma_f32_16x16x32_f16 v[32:35], v[190:193], v[230:233], v[32:35]
	v_mfma_f32_16x16x32_f16 v[28:31], v[190:193], v[242:245], v[28:31]
	v_mfma_f32_16x16x32_f16 v[24:27], v[198:201], v[230:233], v[24:27]
	v_mfma_f32_16x16x32_f16 v[20:23], v[198:201], v[242:245], v[20:23]
	v_mfma_f32_16x16x32_f16 v[16:19], v[206:209], v[230:233], v[16:19]
	v_mfma_f32_16x16x32_f16 v[12:15], v[206:209], v[242:245], v[12:15]
	v_mfma_f32_16x16x32_f16 v[8:11], v[214:217], v[230:233], v[8:11]
	v_mfma_f32_16x16x32_f16 v[4:7], v[214:217], v[242:245], v[4:7]
	v_mfma_f32_16x16x32_f16 v[32:35], v[194:197], v[238:241], v[32:35]
	v_mfma_f32_16x16x32_f16 v[28:31], v[194:197], v[246:249], v[28:31]
	v_mfma_f32_16x16x32_f16 v[24:27], v[202:205], v[238:241], v[24:27]
	v_mfma_f32_16x16x32_f16 v[20:23], v[202:205], v[246:249], v[20:23]
	v_mfma_f32_16x16x32_f16 v[16:19], v[210:213], v[238:241], v[16:19]
	v_mfma_f32_16x16x32_f16 v[12:15], v[210:213], v[246:249], v[12:15]
	v_mfma_f32_16x16x32_f16 v[8:11], v[218:221], v[238:241], v[8:11]
	v_mfma_f32_16x16x32_f16 v[4:7], v[218:221], v[246:249], v[4:7]
	s_add_i32 s14, s14, 2
	s_add_u32 s12, s12, 0x100
	s_addc_u32 s13, s13, 0
	s_cmp_lt_u32 s14, 12
	s_barrier
	s_cbranch_scc0 .Lpk_exit_0

; #define LDA8(dst, b, h) _Pragma("unroll") for (int m = 0; m < 4; ++m) _Pragma("unroll") for (int k = 0; k < 2; ++k) \
;     dst[m][k] = *(const bf16x8*)((const char*)SA8(b, h) + lds_byte8(wr * 64 + m * 16 + fr, k * 32 + fq * 8))
; #define LDB8(dst, b, h) _Pragma("unroll") for (int n = 0; n < 2; ++n) _Pragma("unroll") for (int k = 0; k < 2; ++k) \
;     dst[n][k] = *(const bf16x8*)((const char*)SB8(b, h) + lds_byte8(wc * 32 + n * 16 + fr, k * 32 + fq * 8))
; #define WAIT_V8(n) asm volatile("s_waitcnt vmcnt(" #n ")" ::: "memory")
; #define WAIT_L8(n) asm volatile("s_waitcnt lgkmcnt(" #n ")" ::: "memory")
; #define BAR8 __builtin_amdgcn_s_barrier()
;     ...
;   { LDB8(B0, 0, 0); LDA8(At, 0, 0); STAGE8(SA8(1, 1), A, lda, brow + 128, nt - 1);
;     BAR8; WAIT_L8(0); MMA8(0, 0, At, B0); BAR8;
;     LDB8(B1, 0, 1); BAR8; WAIT_L8(0); MMA8(0, 1, At, B1); BAR8;
;     LDA8(At, 0, 1); WAIT_V8(4); BAR8; WAIT_L8(0); MMA8(1, 0, At, B0); MMA8(1, 1, At, B1); BAR8; }
;   { LDB8(B0, 1, 0); LDA8(At, 1, 0); WAIT_V8(2); BAR8; WAIT_L8(0); MMA8(0, 0, At, B0); BAR8;
.Lpk_exit_0:
	s_add_u32 s4, s4, 0x40780
	s_addc_u32 s5, s5, 0
	v_lshl_add_u64 v[132:133], s[4:5], 0, v[132:133]
	v_lshl_add_u64 v[0:1], v[0:1], 1, v[132:133]
	s_or_b32 m0, s100, 0xc000
	ds_read_b128 v[138:141], v173
	ds_read_b128 v[142:145], v173 offset:1024
	ds_read_b128 v[160:163], v173 offset:2048
	ds_read_b128 v[164:167], v173 offset:3072
	ds_read_b128 v[174:177], v156
	ds_read_b128 v[178:181], v156 offset:1024
	ds_read_b128 v[182:185], v154
	ds_read_b128 v[186:189], v154 offset:1024
	ds_read_b128 v[190:193], v153
	ds_read_b128 v[194:197], v153 offset:1024
	ds_read_b128 v[198:201], v152
	ds_read_b128 v[202:205], v152 offset:1024
	global_load_lds_dwordx4 v[0:1], off
	v_lshl_add_u64 v[0:1], s[4:5], 0, v[136:137]
	v_lshl_add_u64 v[0:1], v[134:135], 1, v[0:1]
	s_or_b32 m0, s100, 0xe000
	s_nop 0
	global_load_lds_dwordx4 v[0:1], off
	s_barrier
	s_waitcnt lgkmcnt(0)
	v_mfma_f32_16x16x32_f16 v[128:131], v[174:177], v[138:141], v[128:131]
	v_mfma_f32_16x16x32_f16 v[124:127], v[174:177], v[160:163], v[124:127]
	v_mfma_f32_16x16x32_f16 v[120:123], v[182:185], v[138:141], v[120:123]
	v_mfma_f32_16x16x32_f16 v[112:115], v[190:193], v[138:141], v[112:115]
	v_mfma_f32_16x16x32_f16 v[128:131], v[178:181], v[142:145], v[128:131]
	v_mfma_f32_16x16x32_f16 v[124:127], v[178:181], v[164:167], v[124:127]
	v_mfma_f32_16x16x32_f16 v[120:123], v[186:189], v[142:145], v[120:123]
	v_mfma_f32_16x16x32_f16 v[116:119], v[182:185], v[160:163], v[116:119]
	v_mfma_f32_16x16x32_f16 v[112:115], v[194:197], v[142:145], v[112:115]
	v_mfma_f32_16x16x32_f16 v[108:111], v[190:193], v[160:163], v[108:111]
	v_mfma_f32_16x16x32_f16 v[104:107], v[198:201], v[138:141], v[104:107]
	v_mfma_f32_16x16x32_f16 v[100:103], v[198:201], v[160:163], v[100:103]
	v_mfma_f32_16x16x32_f16 v[132:135], v[186:189], v[164:167], v[116:119]
	v_mfma_f32_16x16x32_f16 v[170:173], v[194:197], v[164:167], v[108:111]
	v_mfma_f32_16x16x32_f16 v[206:209], v[202:205], v[142:145], v[104:107]
	v_mfma_f32_16x16x32_f16 v[210:213], v[202:205], v[164:167], v[100:103]
	s_barrier
	s_nop 1
	ds_read_b128 v[100:103], v169
	ds_read_b128 v[104:107], v169 offset:1024
	ds_read_b128 v[108:111], v169 offset:2048
	ds_read_b128 v[116:119], v169 offset:3072
	s_barrier
	s_waitcnt lgkmcnt(0)
	v_mfma_f32_16x16x32_f16 v[80:83], v[190:193], v[100:103], v[80:83]
	v_mfma_f32_16x16x32_f16 v[76:79], v[190:193], v[108:111], v[76:79]
	v_mfma_f32_16x16x32_f16 v[72:75], v[198:201], v[100:103], v[72:75]
	v_mfma_f32_16x16x32_f16 v[68:71], v[198:201], v[108:111], v[68:71]
	v_mfma_f32_16x16x32_f16 v[96:99], v[174:177], v[100:103], v[96:99]
	v_mfma_f32_16x16x32_f16 v[92:95], v[174:177], v[108:111], v[92:95]
	v_mfma_f32_16x16x32_f16 v[88:91], v[182:185], v[100:103], v[88:91]
	v_mfma_f32_16x16x32_f16 v[84:87], v[182:185], v[108:111], v[84:87]
	v_mfma_f32_16x16x32_f16 v[80:83], v[194:197], v[104:107], v[80:83]
	v_mfma_f32_16x16x32_f16 v[76:79], v[194:197], v[116:119], v[76:79]
	v_mfma_f32_16x16x32_f16 v[72:75], v[202:205], v[104:107], v[72:75]
	v_mfma_f32_16x16x32_f16 v[68:71], v[202:205], v[116:119], v[68:71]
	v_mfma_f32_16x16x32_f16 v[214:217], v[178:181], v[104:107], v[96:99]
	v_mfma_f32_16x16x32_f16 v[174:177], v[178:181], v[116:119], v[92:95]
	v_mfma_f32_16x16x32_f16 v[178:181], v[186:189], v[104:107], v[88:91]
	v_mfma_f32_16x16x32_f16 v[182:185], v[186:189], v[116:119], v[84:87]
	s_barrier
	s_nop 0
	ds_read_b128 v[84:87], v156 offset:16384
	ds_read_b128 v[88:91], v156 offset:17408
	ds_read_b128 v[92:95], v154 offset:16384
	ds_read_b128 v[96:99], v154 offset:17408
	ds_read_b128 v[186:189], v153 offset:16384
	ds_read_b128 v[190:193], v153 offset:17408
	ds_read_b128 v[194:197], v152 offset:16384
	ds_read_b128 v[198:201], v152 offset:17408
	s_waitcnt vmcnt(4)
	s_barrier
	s_waitcnt lgkmcnt(0)
	v_mfma_f32_16x16x32_f16 v[64:67], v[84:87], v[138:141], v[64:67]
	v_mfma_f32_16x16x32_f16 v[60:63], v[84:87], v[160:163], v[60:63]
	v_mfma_f32_16x16x32_f16 v[56:59], v[92:95], v[138:141], v[56:59]
	v_mfma_f32_16x16x32_f16 v[52:55], v[92:95], v[160:163], v[52:55]
	v_mfma_f32_16x16x32_f16 v[48:51], v[186:189], v[138:141], v[48:51]
	v_mfma_f32_16x16x32_f16 v[44:47], v[186:189], v[160:163], v[44:47]
	v_mfma_f32_16x16x32_f16 v[64:67], v[88:91], v[142:145], v[64:67]
	v_mfma_f32_16x16x32_f16 v[60:63], v[88:91], v[164:167], v[60:63]
	v_mfma_f32_16x16x32_f16 v[56:59], v[96:99], v[142:145], v[56:59]
	v_mfma_f32_16x16x32_f16 v[52:55], v[96:99], v[164:167], v[52:55]
	v_mfma_f32_16x16x32_f16 v[48:51], v[190:193], v[142:145], v[48:51]
	v_mfma_f32_16x16x32_f16 v[44:47], v[190:193], v[164:167], v[44:47]
	v_mfma_f32_16x16x32_f16 v[40:43], v[194:197], v[138:141], v[40:43]
	v_mfma_f32_16x16x32_f16 v[36:39], v[194:197], v[160:163], v[36:39]
	v_mfma_f32_16x16x32_f16 v[136:139], v[198:201], v[142:145], v[40:43]
	v_mfma_f32_16x16x32_f16 v[140:143], v[198:201], v[164:167], v[36:39]
	v_mfma_f32_16x16x32_f16 v[32:35], v[84:87], v[100:103], v[32:35]
	v_mfma_f32_16x16x32_f16 v[28:31], v[84:87], v[108:111], v[28:31]
	v_mfma_f32_16x16x32_f16 v[24:27], v[92:95], v[100:103], v[24:27]
	v_mfma_f32_16x16x32_f16 v[20:23], v[92:95], v[108:111], v[20:23]
	v_mfma_f32_16x16x32_f16 v[16:19], v[186:189], v[100:103], v[16:19]
	v_mfma_f32_16x16x32_f16 v[12:15], v[186:189], v[108:111], v[12:15]
	v_mfma_f32_16x16x32_f16 v[8:11], v[194:197], v[100:103], v[8:11]
	v_mfma_f32_16x16x32_f16 v[4:7], v[194:197], v[108:111], v[4:7]
	v_mfma_f32_16x16x32_f16 v[160:163], v[88:91], v[104:107], v[32:35]
	v_mfma_f32_16x16x32_f16 v[164:167], v[88:91], v[116:119], v[28:31]
	v_mfma_f32_16x16x32_f16 v[202:205], v[96:99], v[104:107], v[24:27]
	v_mfma_f32_16x16x32_f16 v[218:221], v[96:99], v[116:119], v[20:23]
	v_mfma_f32_16x16x32_f16 v[230:233], v[190:193], v[104:107], v[16:19]
	v_mfma_f32_16x16x32_f16 v[186:189], v[190:193], v[116:119], v[12:15]
	v_mfma_f32_16x16x32_f16 v[190:193], v[198:201], v[104:107], v[8:11]
	v_mfma_f32_16x16x32_f16 v[194:197], v[198:201], v[116:119], v[4:7]
	s_barrier
; #define LDA8(dst, b, h) _Pragma("unroll") for (int m = 0; m < 4; ++m) _Pragma("unroll") for (int k = 0; k < 2; ++k) \
;     dst[m][k] = *(const bf16x8*)((const char*)SA8(b, h) + lds_byte8(wr * 64 + m * 16 + fr, k * 32 + fq * 8))
; #define LDB8(dst, b, h) _Pragma("unroll") for (int n = 0; n < 2; ++n) _Pragma("unroll") for (int k = 0; k < 2; ++k) \
;     dst[n][k] = *(const bf16x8*)((const char*)SB8(b, h) + lds_byte8(wc * 32 + n * 16 + fr, k * 32 + fq * 8))
; #define WAIT_V8(n) asm volatile("s_waitcnt vmcnt(" #n ")" ::: "memory")
; #define WAIT_L8(n) asm volatile("s_waitcnt lgkmcnt(" #n ")" ::: "memory")
; #define BAR8 __builtin_amdgcn_s_barrier()
;     ...
;   { LDB8(B0, 1, 0); LDA8(At, 1, 0); WAIT_V8(2); BAR8; WAIT_L8(0); MMA8(0, 0, At, B0); BAR8;
;     LDB8(B1, 1, 1); WAIT_V8(0); BAR8; WAIT_L8(0); MMA8(0, 1, At, B1); BAR8;
;     LDA8(At, 1, 1); BAR8; WAIT_L8(0); MMA8(1, 0, At, B0); MMA8(1, 1, At, B1); BAR8; }
;   if (wr == 0) BAR8;
;   __syncthreads();
;     ...
;   if (t < 256) {
	s_nop 0
	ds_read_b128 v[4:7], v159
	ds_read_b128 v[8:11], v159 offset:1024
	ds_read_b128 v[198:201], v159 offset:2048
	ds_read_b128 v[238:241], v159 offset:3072
	ds_read_b128 v[16:19], v156 offset:32768
	ds_read_b128 v[20:23], v156 offset:33792
	ds_read_b128 v[24:27], v154 offset:32768
	ds_read_b128 v[32:35], v154 offset:33792
	ds_read_b128 v[36:39], v153 offset:32768
	ds_read_b128 v[40:43], v153 offset:33792
	ds_read_b128 v[242:245], v152 offset:32768
	ds_read_b128 v[246:249], v152 offset:33792
	s_waitcnt vmcnt(2)
	s_barrier
	s_waitcnt lgkmcnt(0)
	v_mfma_f32_16x16x32_f16 v[12:15], v[16:19], v[4:7], v[128:131]
	v_mfma_f32_16x16x32_f16 v[104:107], v[20:23], v[8:11], v[12:15]
	v_mfma_f32_16x16x32_f16 v[12:15], v[16:19], v[198:201], v[124:127]
	v_mfma_f32_16x16x32_f16 v[116:119], v[20:23], v[238:241], v[12:15]
	v_mfma_f32_16x16x32_f16 v[12:15], v[24:27], v[4:7], v[120:123]
	v_mfma_f32_16x16x32_f16 v[100:103], v[32:35], v[8:11], v[12:15]
	v_mfma_f32_16x16x32_f16 v[12:15], v[24:27], v[198:201], v[132:135]
	v_mfma_f32_16x16x32_f16 v[108:111], v[32:35], v[238:241], v[12:15]
	v_mfma_f32_16x16x32_f16 v[12:15], v[36:39], v[4:7], v[112:115]
	v_mfma_f32_16x16x32_f16 v[92:95], v[40:43], v[8:11], v[12:15]
	v_mfma_f32_16x16x32_f16 v[12:15], v[36:39], v[198:201], v[170:173]
	v_mfma_f32_16x16x32_f16 v[96:99], v[40:43], v[238:241], v[12:15]
	v_mfma_f32_16x16x32_f16 v[12:15], v[242:245], v[4:7], v[206:209]
	v_mfma_f32_16x16x32_f16 v[84:87], v[246:249], v[8:11], v[12:15]
	v_mfma_f32_16x16x32_f16 v[12:15], v[242:245], v[198:201], v[210:213]
	v_mfma_f32_16x16x32_f16 v[88:91], v[246:249], v[238:241], v[12:15]
	s_barrier
	ds_read_b128 v[132:135], v158
	ds_read_b128 v[168:171], v158 offset:1024
	ds_read_b128 v[206:209], v158 offset:2048
	ds_read_b128 v[210:213], v158 offset:3072
	s_waitcnt vmcnt(0)
	s_barrier
	s_waitcnt lgkmcnt(0)
	v_mfma_f32_16x16x32_f16 v[12:15], v[16:19], v[132:135], v[214:217]
	v_mfma_f32_16x16x32_f16 v[16:19], v[16:19], v[206:209], v[174:177]
	v_mfma_f32_16x16x32_f16 v[12:15], v[20:23], v[168:171], v[12:15]
	v_mfma_f32_16x16x32_f16 v[28:31], v[20:23], v[210:213], v[16:19]
	v_mfma_f32_16x16x32_f16 v[16:19], v[24:27], v[132:135], v[178:181]
	v_mfma_f32_16x16x32_f16 v[20:23], v[24:27], v[206:209], v[182:185]
	v_mfma_f32_16x16x32_f16 v[16:19], v[32:35], v[168:171], v[16:19]
	v_mfma_f32_16x16x32_f16 v[32:35], v[32:35], v[210:213], v[20:23]
	v_mfma_f32_16x16x32_f16 v[20:23], v[36:39], v[132:135], v[80:83]
	v_mfma_f32_16x16x32_f16 v[24:27], v[36:39], v[206:209], v[76:79]
	v_mfma_f32_16x16x32_f16 v[20:23], v[40:43], v[168:171], v[20:23]
	v_mfma_f32_16x16x32_f16 v[36:39], v[40:43], v[210:213], v[24:27]
	v_mfma_f32_16x16x32_f16 v[24:27], v[242:245], v[132:135], v[72:75]
	v_mfma_f32_16x16x32_f16 v[40:43], v[242:245], v[206:209], v[68:71]
	v_mfma_f32_16x16x32_f16 v[24:27], v[246:249], v[168:171], v[24:27]
	v_mfma_f32_16x16x32_f16 v[40:43], v[246:249], v[210:213], v[40:43]
	s_barrier
	ds_read_b128 v[68:71], v156 offset:49152
	ds_read_b128 v[72:75], v156 offset:50176
	ds_read_b128 v[156:159], v154 offset:49152
	ds_read_b128 v[172:175], v154 offset:50176
	ds_read_b128 v[176:179], v153 offset:49152
	ds_read_b128 v[180:183], v153 offset:50176
	ds_read_b128 v[214:217], v152 offset:49152
	ds_read_b128 v[150:153], v152 offset:50176
	s_barrier
	s_waitcnt lgkmcnt(0)
	v_mfma_f32_16x16x32_f16 v[64:67], v[68:71], v[4:7], v[64:67]
	v_mfma_f32_16x16x32_f16 v[56:59], v[156:159], v[4:7], v[56:59]
	v_mfma_f32_16x16x32_f16 v[48:51], v[176:179], v[4:7], v[48:51]
	v_mfma_f32_16x16x32_f16 v[4:7], v[214:217], v[4:7], v[136:139]
	v_mfma_f32_16x16x32_f16 v[128:131], v[72:75], v[8:11], v[64:67]
	v_mfma_f32_16x16x32_f16 v[60:63], v[68:71], v[198:201], v[60:63]
	v_mfma_f32_16x16x32_f16 v[120:123], v[172:175], v[8:11], v[56:59]
	v_mfma_f32_16x16x32_f16 v[52:55], v[156:159], v[198:201], v[52:55]
	v_mfma_f32_16x16x32_f16 v[80:83], v[180:183], v[8:11], v[48:51]
	v_mfma_f32_16x16x32_f16 v[44:47], v[176:179], v[198:201], v[44:47]
	v_mfma_f32_16x16x32_f16 v[8:11], v[150:153], v[8:11], v[4:7]
	v_mfma_f32_16x16x32_f16 v[4:7], v[214:217], v[198:201], v[140:143]
	v_mfma_f32_16x16x32_f16 v[124:127], v[72:75], v[238:241], v[60:63]
	v_mfma_f32_16x16x32_f16 v[112:115], v[172:175], v[238:241], v[52:55]
	v_mfma_f32_16x16x32_f16 v[76:79], v[180:183], v[238:241], v[44:47]
	v_mfma_f32_16x16x32_f16 v[4:7], v[150:153], v[238:241], v[4:7]
	v_mfma_f32_16x16x32_f16 v[44:47], v[68:71], v[132:135], v[160:163]
	v_mfma_f32_16x16x32_f16 v[48:51], v[68:71], v[206:209], v[164:167]
	v_mfma_f32_16x16x32_f16 v[52:55], v[156:159], v[206:209], v[218:221]
	v_mfma_f32_16x16x32_f16 v[56:59], v[176:179], v[206:209], v[186:189]
	v_mfma_f32_16x16x32_f16 v[44:47], v[72:75], v[168:171], v[44:47]
	v_mfma_f32_16x16x32_f16 v[60:63], v[72:75], v[210:213], v[48:51]
	v_mfma_f32_16x16x32_f16 v[48:51], v[156:159], v[132:135], v[202:205]
	v_mfma_f32_16x16x32_f16 v[64:67], v[172:175], v[210:213], v[52:55]
	v_mfma_f32_16x16x32_f16 v[52:55], v[176:179], v[132:135], v[230:233]
	v_mfma_f32_16x16x32_f16 v[68:71], v[180:183], v[210:213], v[56:59]
	v_mfma_f32_16x16x32_f16 v[56:59], v[214:217], v[132:135], v[190:193]
	v_mfma_f32_16x16x32_f16 v[72:75], v[214:217], v[206:209], v[194:197]
	v_mfma_f32_16x16x32_f16 v[48:51], v[172:175], v[168:171], v[48:51]
	v_mfma_f32_16x16x32_f16 v[52:55], v[180:183], v[168:171], v[52:55]
	v_mfma_f32_16x16x32_f16 v[56:59], v[150:153], v[168:171], v[56:59]
	v_mfma_f32_16x16x32_f16 v[72:75], v[150:153], v[210:213], v[72:75]
	s_movk_i32 s4, 0x100
	v_cmp_gt_u32_e32 vcc, s4, v3
	s_barrier
	s_and_saveexec_b64 s[4:5], vcc
	s_cbranch_execz .LBB0_195
	s_barrier

; #define LDA8(dst, b, h) _Pragma("unroll") for (int m = 0; m < 4; ++m) _Pragma("unroll") for (int k = 0; k < 2; ++k) \
;     dst[m][k] = *(const bf16x8*)((const char*)SA8(b, h) + lds_byte8(wr * 64 + m * 16 + fr, k * 32 + fq * 8))
; #define LDB8(dst, b, h) _Pragma("unroll") for (int n = 0; n < 2; ++n) _Pragma("unroll") for (int k = 0; k < 2; ++k) \
;     dst[n][k] = *(const bf16x8*)((const char*)SB8(b, h) + lds_byte8(wc * 32 + n * 16 + fr, k * 32 + fq * 8))
; #define WAIT_V8(n) asm volatile("s_waitcnt vmcnt(" #n ")" ::: "memory")
; #define WAIT_L8(n) asm volatile("s_waitcnt lgkmcnt(" #n ")" ::: "memory")
; #define BAR8 __builtin_amdgcn_s_barrier()
; #define SCHED8 __builtin_amdgcn_sched_barrier(0)
;     ...
;   const int brow = m0, bcol = n0;
;   const int wid = t >> 6, lane = t & 63, wr = wid >> 2, wc = wid & 3, fr = lane & 15, fq = lane >> 4;
;   f32x4 acc[2][2][4][2];
;   {
;     float zinit = 0.f;
;     asm volatile("" : "+v"(zinit));
; #pragma unroll
;     for (int a = 0; a < 2; ++a)
; #pragma unroll
;       for (int b = 0; b < 2; ++b)
; #pragma unroll
;         for (int m = 0; m < 4; ++m)
; #pragma unroll
;           for (int n = 0; n < 2; ++n)
; #pragma unroll
;             for (int j = 0; j < 4; ++j) acc[a][b][m][n][j] = zinit;
;   }
;   bf16x8 At[4][2], B0[2][2], B1[2][2];
;   const int nt = K / 64;
;   if (!pre) {
;     STAGE8(SB8(0, 0), Bt, K, bcol, 0); STAGE8(SA8(0, 0), A, lda, brow, 0);
;     STAGE8(SB8(0, 1), Bt, K, bcol + 128, 0); STAGE8(SA8(0, 1), A, lda, brow + 128, 0);
;   }
;   if (wr == 1) BAR8;
;   WAIT_V8(4); BAR8;
;   STAGE8(SB8(1, 0), Bt, K, bcol, 1); STAGE8(SA8(1, 0), A, lda, brow, 1); STAGE8(SB8(1, 1), Bt, K, bcol + 128, 1);
;   WAIT_V8(6); BAR8;
;   for (int tt = 0; tt < nt - 2; tt += 2) {
;     LDB8(B0, 0, 0); SCHED8; LDA8(At, 0, 0); STAGE8(SA8(1, 1), A, lda, brow + 128, tt + 1);
;     WAIT_L8(8); BAR8; WAIT_L8(0); MMA8(0, 0, At, B0); BAR8; SCHED8;
.LBB0_241:
	s_or_b64 exec, exec, s[20:21]
	s_mov_b64 s[20:21], 0x80
	v_lshl_add_u64 v[10:11], v[10:11], 0, s[20:21]
	s_or_b32 m0, s100, 0x18000
	s_waitcnt vmcnt(4)
	s_barrier
	global_load_lds_dwordx4 v[10:11], off
	v_lshl_add_u64 v[10:11], v[12:13], 0, s[20:21]
	s_or_b32 m0, s100, 0x1a000
	global_load_lds_dwordx4 v[10:11], off
	v_lshl_add_u64 v[10:11], v[14:15], 0, s[20:21]
	s_or_b32 m0, s100, 0x8000
	global_load_lds_dwordx4 v[10:11], off
	v_lshl_add_u64 v[10:11], v[16:17], 0, s[20:21]
	s_or_b32 m0, s100, 0xa000
	global_load_lds_dwordx4 v[10:11], off
	v_lshl_add_u64 v[10:11], v[18:19], 0, s[20:21]
	s_or_b32 m0, s100, 0x1c000
	s_nop 0
	global_load_lds_dwordx4 v[10:11], off
	v_lshl_add_u64 v[10:11], v[20:21], 0, s[20:21]
	s_or_b32 m0, s100, 0x1e000
	v_and_b32_e32 v147, 15, v3
	global_load_lds_dwordx4 v[10:11], off
	v_bfe_u32 v148, v3, 4, 2
	v_lshlrev_b32_e32 v10, 4, v148
	v_lshlrev_b32_e32 v11, 6, v147
	v_lshlrev_b32_e32 v14, 2, v3
	v_or_b32_e32 v13, v10, v11
	v_and_b32_e32 v14, 32, v14
	s_mov_b32 s1, 0x10000
	v_bitop3_b32 v16, v13, s1, v14 bitop3:0xde
	s_mov_b32 s1, 0x14000
	v_bitop3_b32 v15, v10, v14, v11 bitop3:0x36
	v_bitop3_b32 v17, v13, s1, v14 bitop3:0xde
	s_mov_b32 s1, 0x18000
	v_lshlrev_b32_e32 v11, 6, v3
	v_bitop3_b32 v18, v13, s1, v14 bitop3:0xde
	s_mov_b32 s1, 0x1c000
	v_and_b32_e32 v11, 0x3c0, v11
	v_bitop3_b32 v13, v13, s1, v14 bitop3:0xde
	v_bitop3_b32 v14, v11, v14, v10 bitop3:0x36
	v_lshl_add_u64 v[10:11], s[30:31], 0, v[136:137]
	v_lshl_add_u64 v[10:11], v[10:11], 0, v[8:9]
	v_lshl_add_u64 v[138:139], s[14:15], 0, v[10:11]
	v_lshl_add_u64 v[10:11], s[30:31], 0, v[132:133]
	v_lshl_add_u64 v[10:11], v[10:11], 0, v[6:7]
	v_lshl_add_u64 v[140:141], s[14:15], 0, v[10:11]
	v_lshl_add_u64 v[10:11], s[56:57], 0, v[132:133]
	v_lshl_add_u64 v[6:7], v[10:11], 0, v[6:7]
	v_bfe_u32 v146, v3, 6, 2
	s_waitcnt vmcnt(6)
	v_lshlrev_b32_e32 v149, 6, v5
	v_lshlrev_b32_e32 v5, 13, v5
	v_lshl_add_u64 v[142:143], s[46:47], 0, v[6:7]
	v_lshl_add_u64 v[6:7], s[56:57], 0, v[136:137]
	v_lshlrev_b32_e32 v12, 12, v146
	v_or_b32_e32 v19, 0x800, v5
	v_or_b32_e32 v20, 0x1000, v5
	v_or_b32_e32 v21, 0x1800, v5
	v_lshl_add_u64 v[6:7], v[6:7], 0, v[8:9]
	v_lshl_add_u64 v[144:145], s[46:47], 0, v[6:7]
	s_mov_b32 s1, -2
	s_mov_b64 s[14:15], 0
	v_add_u32_e32 v171, v16, v12
	v_add_u32_e32 v156, v15, v5
	v_add_u32_e32 v154, v14, v19
	v_add_u32_e32 v153, v14, v20
	v_add_u32_e32 v152, v14, v21
	v_add_u32_e32 v168, v17, v12
	v_add_u32_e32 v159, v18, v12
	v_add_u32_e32 v157, v13, v12
	s_mov_b64 s[30:31], 0xc000100
	s_mov_b64 s[56:57], 0xc040100
	s_mov_b64 s[58:59], 0xc000180
	s_mov_b64 s[60:61], 0xc040180
	s_barrier
	ds_read_b128 v[174:177], v171
	ds_read_b128 v[178:181], v171 offset:1024
	ds_read_b128 v[182:185], v171 offset:2048
	ds_read_b128 v[186:189], v171 offset:3072
	v_lshl_add_u64 v[222:223], v[140:141], 0, s[14:15]
	v_lshl_add_u64 v[226:227], v[222:223], 0, s[34:35]
	s_or_b32 m0, s100, 0xc000
	ds_read_b128 v[190:193], v156
	ds_read_b128 v[194:197], v156 offset:1024
	ds_read_b128 v[198:201], v154
	ds_read_b128 v[202:205], v154 offset:1024
	ds_read_b128 v[206:209], v153
	ds_read_b128 v[210:213], v153 offset:1024
	ds_read_b128 v[214:217], v152
	ds_read_b128 v[218:221], v152 offset:1024
	global_load_lds_dwordx4 v[226:227], off
	v_lshl_add_u64 v[226:227], v[138:139], 0, s[14:15]
	v_lshl_add_u64 v[228:229], v[226:227], 0, s[34:35]
	s_or_b32 m0, s100, 0xe000
	s_nop 0
	global_load_lds_dwordx4 v[228:229], off
	s_waitcnt lgkmcnt(8)
	s_barrier
	s_waitcnt lgkmcnt(0)
	v_mfma_f32_16x16x32_f16 v[128:131], v[190:193], v[174:177], 0
	v_mfma_f32_16x16x32_f16 v[124:127], v[190:193], v[182:185], 0
	v_mfma_f32_16x16x32_f16 v[120:123], v[198:201], v[174:177], 0
	v_mfma_f32_16x16x32_f16 v[116:119], v[198:201], v[182:185], 0
	v_mfma_f32_16x16x32_f16 v[112:115], v[206:209], v[174:177], 0
	v_mfma_f32_16x16x32_f16 v[108:111], v[206:209], v[182:185], 0
	v_mfma_f32_16x16x32_f16 v[104:107], v[214:217], v[174:177], 0
	v_mfma_f32_16x16x32_f16 v[100:103], v[214:217], v[182:185], 0
	v_mfma_f32_16x16x32_f16 v[128:131], v[194:197], v[178:181], v[128:131]
	v_mfma_f32_16x16x32_f16 v[124:127], v[194:197], v[186:189], v[124:127]
	v_mfma_f32_16x16x32_f16 v[120:123], v[202:205], v[178:181], v[120:123]
	v_mfma_f32_16x16x32_f16 v[116:119], v[202:205], v[186:189], v[116:119]
	v_mfma_f32_16x16x32_f16 v[112:115], v[210:213], v[178:181], v[112:115]
	v_mfma_f32_16x16x32_f16 v[108:111], v[210:213], v[186:189], v[108:111]
	v_mfma_f32_16x16x32_f16 v[104:107], v[218:221], v[178:181], v[104:107]
	v_mfma_f32_16x16x32_f16 v[100:103], v[218:221], v[186:189], v[100:103]
	s_barrier
	v_lshl_add_u64 v[228:229], v[142:143], 0, s[14:15]
	v_lshl_add_u64 v[236:237], v[228:229], 0, s[30:31]
	s_or_b32 m0, s100, 0x10000
	ds_read_b128 v[230:233], v168
	ds_read_b128 v[238:241], v168 offset:1024
	ds_read_b128 v[242:245], v168 offset:2048
	ds_read_b128 v[246:249], v168 offset:3072
	global_load_lds_dwordx4 v[236:237], off
	v_lshl_add_u64 v[236:237], v[144:145], 0, s[14:15]
	v_lshl_add_u64 v[250:251], v[236:237], 0, s[30:31]
	s_or_b32 m0, s100, 0x12000
	s_nop 0
	global_load_lds_dwordx4 v[250:251], off
	s_barrier
; #define LDA8(dst, b, h) _Pragma("unroll") for (int m = 0; m < 4; ++m) _Pragma("unroll") for (int k = 0; k < 2; ++k) \
;     dst[m][k] = *(const bf16x8*)((const char*)SA8(b, h) + lds_byte8(wr * 64 + m * 16 + fr, k * 32 + fq * 8))
; #define LDB8(dst, b, h) _Pragma("unroll") for (int n = 0; n < 2; ++n) _Pragma("unroll") for (int k = 0; k < 2; ++k) \
;     dst[n][k] = *(const bf16x8*)((const char*)SB8(b, h) + lds_byte8(wc * 32 + n * 16 + fr, k * 32 + fq * 8))
; #define WAIT_V8(n) asm volatile("s_waitcnt vmcnt(" #n ")" ::: "memory")
; #define WAIT_L8(n) asm volatile("s_waitcnt lgkmcnt(" #n ")" ::: "memory")
; #define BAR8 __builtin_amdgcn_s_barrier()
; #define SCHED8 __builtin_amdgcn_sched_barrier(0)
;     ...
;     WAIT_L8(8); BAR8; WAIT_L8(0); MMA8(0, 0, At, B0); BAR8; SCHED8;
;     LDB8(B1, 0, 1); STAGE8(SB8(0, 0), Bt, K, bcol, tt + 2);
;     BAR8; WAIT_L8(0); MMA8(0, 1, At, B1); BAR8;
;     LDA8(At, 0, 1); STAGE8(SA8(0, 0), A, lda, brow, tt + 2);
;     BAR8; WAIT_L8(0); MMA8(1, 0, At, B0); BAR8; SCHED8;
;     STAGE8(SB8(0, 1), Bt, K, bcol + 128, tt + 2);
;     WAIT_V8(6); BAR8; MMA8(1, 1, At, B1); BAR8;
;     LDB8(B0, 1, 0); SCHED8; LDA8(At, 1, 0); STAGE8(SA8(0, 1), A, lda, brow + 128, tt + 2);
;     WAIT_L8(8); BAR8; WAIT_L8(0); MMA8(0, 0, At, B0); BAR8; SCHED8;
	s_waitcnt lgkmcnt(0)
	v_mfma_f32_16x16x32_f16 v[96:99], v[190:193], v[230:233], 0
	v_mfma_f32_16x16x32_f16 v[92:95], v[190:193], v[242:245], 0
	v_mfma_f32_16x16x32_f16 v[88:91], v[198:201], v[230:233], 0
	v_mfma_f32_16x16x32_f16 v[84:87], v[198:201], v[242:245], 0
	v_mfma_f32_16x16x32_f16 v[80:83], v[206:209], v[230:233], 0
	v_mfma_f32_16x16x32_f16 v[76:79], v[206:209], v[242:245], 0
	v_mfma_f32_16x16x32_f16 v[72:75], v[214:217], v[230:233], 0
	v_mfma_f32_16x16x32_f16 v[68:71], v[214:217], v[242:245], 0
	v_mfma_f32_16x16x32_f16 v[96:99], v[194:197], v[238:241], v[96:99]
	v_mfma_f32_16x16x32_f16 v[92:95], v[194:197], v[246:249], v[92:95]
	v_mfma_f32_16x16x32_f16 v[88:91], v[202:205], v[238:241], v[88:91]
	v_mfma_f32_16x16x32_f16 v[84:87], v[202:205], v[246:249], v[84:87]
	v_mfma_f32_16x16x32_f16 v[80:83], v[210:213], v[238:241], v[80:83]
	v_mfma_f32_16x16x32_f16 v[76:79], v[210:213], v[246:249], v[76:79]
	v_mfma_f32_16x16x32_f16 v[72:75], v[218:221], v[238:241], v[72:75]
	v_mfma_f32_16x16x32_f16 v[68:71], v[218:221], v[246:249], v[68:71]
	v_lshl_add_u64 v[250:251], v[222:223], 0, s[10:11]
	s_mov_b32 m0, s100
	s_barrier
	ds_read_b128 v[190:193], v156 offset:16384
	ds_read_b128 v[194:197], v156 offset:17408
	ds_read_b128 v[198:201], v154 offset:16384
	ds_read_b128 v[202:205], v154 offset:17408
	ds_read_b128 v[206:209], v153 offset:16384
	ds_read_b128 v[210:213], v153 offset:17408
	ds_read_b128 v[214:217], v152 offset:16384
	ds_read_b128 v[218:221], v152 offset:17408
	global_load_lds_dwordx4 v[250:251], off
	v_lshl_add_u64 v[250:251], v[226:227], 0, s[10:11]
	s_or_b32 m0, s100, 0x2000
	s_nop 0
	global_load_lds_dwordx4 v[250:251], off
	s_barrier
	s_waitcnt lgkmcnt(0)
	v_mfma_f32_16x16x32_f16 v[64:67], v[190:193], v[174:177], 0
	v_mfma_f32_16x16x32_f16 v[60:63], v[190:193], v[182:185], 0
	v_mfma_f32_16x16x32_f16 v[56:59], v[198:201], v[174:177], 0
	v_mfma_f32_16x16x32_f16 v[52:55], v[198:201], v[182:185], 0
	v_mfma_f32_16x16x32_f16 v[48:51], v[206:209], v[174:177], 0
	v_mfma_f32_16x16x32_f16 v[44:47], v[206:209], v[182:185], 0
	v_mfma_f32_16x16x32_f16 v[40:43], v[214:217], v[174:177], 0
	v_mfma_f32_16x16x32_f16 v[36:39], v[214:217], v[182:185], 0
	v_mfma_f32_16x16x32_f16 v[64:67], v[194:197], v[178:181], v[64:67]
	v_mfma_f32_16x16x32_f16 v[60:63], v[194:197], v[186:189], v[60:63]
	v_mfma_f32_16x16x32_f16 v[56:59], v[202:205], v[178:181], v[56:59]
	v_mfma_f32_16x16x32_f16 v[52:55], v[202:205], v[186:189], v[52:55]
	v_mfma_f32_16x16x32_f16 v[48:51], v[210:213], v[178:181], v[48:51]
	v_mfma_f32_16x16x32_f16 v[44:47], v[210:213], v[186:189], v[44:47]
	v_mfma_f32_16x16x32_f16 v[40:43], v[218:221], v[178:181], v[40:43]
	v_mfma_f32_16x16x32_f16 v[36:39], v[218:221], v[186:189], v[36:39]
	s_barrier
	v_lshl_add_u64 v[174:175], v[228:229], 0, s[56:57]
	s_or_b32 m0, s100, 0x14000
	s_nop 0
	global_load_lds_dwordx4 v[174:175], off
	v_lshl_add_u64 v[174:175], v[236:237], 0, s[56:57]
	s_or_b32 m0, s100, 0x16000
	s_nop 0
	global_load_lds_dwordx4 v[174:175], off
	s_waitcnt vmcnt(6)
	s_barrier
	v_mfma_f32_16x16x32_f16 v[32:35], v[190:193], v[230:233], 0
	v_mfma_f32_16x16x32_f16 v[28:31], v[190:193], v[242:245], 0
	v_mfma_f32_16x16x32_f16 v[24:27], v[198:201], v[230:233], 0
	v_mfma_f32_16x16x32_f16 v[20:23], v[198:201], v[242:245], 0
	v_mfma_f32_16x16x32_f16 v[16:19], v[206:209], v[230:233], 0
	v_mfma_f32_16x16x32_f16 v[12:15], v[206:209], v[242:245], 0
	v_mfma_f32_16x16x32_f16 v[8:11], v[214:217], v[230:233], 0
	v_mfma_f32_16x16x32_f16 v[4:7], v[214:217], v[242:245], 0
	v_mfma_f32_16x16x32_f16 v[32:35], v[194:197], v[238:241], v[32:35]
	v_mfma_f32_16x16x32_f16 v[28:31], v[194:197], v[246:249], v[28:31]
	v_mfma_f32_16x16x32_f16 v[24:27], v[202:205], v[238:241], v[24:27]
	v_mfma_f32_16x16x32_f16 v[20:23], v[202:205], v[246:249], v[20:23]
	v_mfma_f32_16x16x32_f16 v[16:19], v[210:213], v[238:241], v[16:19]
	v_mfma_f32_16x16x32_f16 v[12:15], v[210:213], v[246:249], v[12:15]
	v_mfma_f32_16x16x32_f16 v[8:11], v[218:221], v[238:241], v[8:11]
	v_mfma_f32_16x16x32_f16 v[4:7], v[218:221], v[246:249], v[4:7]
	s_barrier
	ds_read_b128 v[174:177], v159
	ds_read_b128 v[178:181], v159 offset:1024
	ds_read_b128 v[182:185], v159 offset:2048
	ds_read_b128 v[186:189], v159 offset:3072
	v_lshl_add_u64 v[230:231], v[222:223], 0, s[18:19]
	s_or_b32 m0, s100, 0x4000
	ds_read_b128 v[190:193], v156 offset:32768
	ds_read_b128 v[194:197], v156 offset:33792
	ds_read_b128 v[198:201], v154 offset:32768
	ds_read_b128 v[202:205], v154 offset:33792
	ds_read_b128 v[206:209], v153 offset:32768
	ds_read_b128 v[210:213], v153 offset:33792
	ds_read_b128 v[214:217], v152 offset:32768
	ds_read_b128 v[218:221], v152 offset:33792
	global_load_lds_dwordx4 v[230:231], off
	v_lshl_add_u64 v[230:231], v[226:227], 0, s[18:19]
	s_or_b32 m0, s100, 0x6000
	s_nop 0
	global_load_lds_dwordx4 v[230:231], off
	s_waitcnt lgkmcnt(8)
	s_barrier
; #define LDA8(dst, b, h) _Pragma("unroll") for (int m = 0; m < 4; ++m) _Pragma("unroll") for (int k = 0; k < 2; ++k) \
;     dst[m][k] = *(const bf16x8*)((const char*)SA8(b, h) + lds_byte8(wr * 64 + m * 16 + fr, k * 32 + fq * 8))
; #define LDB8(dst, b, h) _Pragma("unroll") for (int n = 0; n < 2; ++n) _Pragma("unroll") for (int k = 0; k < 2; ++k) \
;     dst[n][k] = *(const bf16x8*)((const char*)SB8(b, h) + lds_byte8(wc * 32 + n * 16 + fr, k * 32 + fq * 8))
; #define WAIT_V8(n) asm volatile("s_waitcnt vmcnt(" #n ")" ::: "memory")
; #define WAIT_L8(n) asm volatile("s_waitcnt lgkmcnt(" #n ")" ::: "memory")
; #define BAR8 __builtin_amdgcn_s_barrier()
; #define SCHED8 __builtin_amdgcn_sched_barrier(0)
;     ...
;     WAIT_L8(8); BAR8; WAIT_L8(0); MMA8(0, 0, At, B0); BAR8; SCHED8;
;     LDB8(B1, 1, 1); STAGE8(SB8(1, 0), Bt, K, bcol, tt + 3);
;     BAR8; WAIT_L8(0); MMA8(0, 1, At, B1); BAR8;
;     LDA8(At, 1, 1); STAGE8(SA8(1, 0), A, lda, brow, tt + 3);
;     BAR8; WAIT_L8(0); MMA8(1, 0, At, B0); BAR8; SCHED8;
;     STAGE8(SB8(1, 1), Bt, K, bcol + 128, tt + 3);
;     WAIT_V8(6); BAR8; MMA8(1, 1, At, B1); BAR8;
	s_waitcnt lgkmcnt(0)
	v_mfma_f32_16x16x32_f16 v[128:131], v[190:193], v[174:177], v[128:131]
	v_mfma_f32_16x16x32_f16 v[124:127], v[190:193], v[182:185], v[124:127]
	v_mfma_f32_16x16x32_f16 v[120:123], v[198:201], v[174:177], v[120:123]
	v_mfma_f32_16x16x32_f16 v[116:119], v[198:201], v[182:185], v[116:119]
	v_mfma_f32_16x16x32_f16 v[112:115], v[206:209], v[174:177], v[112:115]
	v_mfma_f32_16x16x32_f16 v[108:111], v[206:209], v[182:185], v[108:111]
	v_mfma_f32_16x16x32_f16 v[104:107], v[214:217], v[174:177], v[104:107]
	v_mfma_f32_16x16x32_f16 v[100:103], v[214:217], v[182:185], v[100:103]
	v_mfma_f32_16x16x32_f16 v[128:131], v[194:197], v[178:181], v[128:131]
	v_mfma_f32_16x16x32_f16 v[124:127], v[194:197], v[186:189], v[124:127]
	v_mfma_f32_16x16x32_f16 v[120:123], v[202:205], v[178:181], v[120:123]
	v_mfma_f32_16x16x32_f16 v[116:119], v[202:205], v[186:189], v[116:119]
	v_mfma_f32_16x16x32_f16 v[112:115], v[210:213], v[178:181], v[112:115]
	v_mfma_f32_16x16x32_f16 v[108:111], v[210:213], v[186:189], v[108:111]
	v_mfma_f32_16x16x32_f16 v[104:107], v[218:221], v[178:181], v[104:107]
	v_mfma_f32_16x16x32_f16 v[100:103], v[218:221], v[186:189], v[100:103]
	s_barrier
	v_lshl_add_u64 v[250:251], v[228:229], 0, s[58:59]
	s_or_b32 m0, s100, 0x18000
	ds_read_b128 v[230:233], v157
	ds_read_b128 v[238:241], v157 offset:1024
	ds_read_b128 v[242:245], v157 offset:2048
	ds_read_b128 v[246:249], v157 offset:3072
	global_load_lds_dwordx4 v[250:251], off
	v_lshl_add_u64 v[250:251], v[236:237], 0, s[58:59]
	s_or_b32 m0, s100, 0x1a000
	s_nop 0
	global_load_lds_dwordx4 v[250:251], off
	s_barrier
	s_waitcnt lgkmcnt(0)
	v_mfma_f32_16x16x32_f16 v[96:99], v[190:193], v[230:233], v[96:99]
	v_mfma_f32_16x16x32_f16 v[92:95], v[190:193], v[242:245], v[92:95]
	v_mfma_f32_16x16x32_f16 v[88:91], v[198:201], v[230:233], v[88:91]
	v_mfma_f32_16x16x32_f16 v[84:87], v[198:201], v[242:245], v[84:87]
	v_mfma_f32_16x16x32_f16 v[80:83], v[206:209], v[230:233], v[80:83]
	v_mfma_f32_16x16x32_f16 v[76:79], v[206:209], v[242:245], v[76:79]
	v_mfma_f32_16x16x32_f16 v[72:75], v[214:217], v[230:233], v[72:75]
	v_mfma_f32_16x16x32_f16 v[68:71], v[214:217], v[242:245], v[68:71]
	v_mfma_f32_16x16x32_f16 v[96:99], v[194:197], v[238:241], v[96:99]
	v_mfma_f32_16x16x32_f16 v[92:95], v[194:197], v[246:249], v[92:95]
	v_mfma_f32_16x16x32_f16 v[88:91], v[202:205], v[238:241], v[88:91]
	v_mfma_f32_16x16x32_f16 v[84:87], v[202:205], v[246:249], v[84:87]
	v_mfma_f32_16x16x32_f16 v[80:83], v[210:213], v[238:241], v[80:83]
	v_mfma_f32_16x16x32_f16 v[76:79], v[210:213], v[246:249], v[76:79]
	v_mfma_f32_16x16x32_f16 v[72:75], v[218:221], v[238:241], v[72:75]
	v_mfma_f32_16x16x32_f16 v[68:71], v[218:221], v[246:249], v[68:71]
	v_lshl_add_u64 v[222:223], v[222:223], 0, s[22:23]
	s_or_b32 m0, s100, 0x8000
	s_barrier
	ds_read_b128 v[190:193], v156 offset:49152
	ds_read_b128 v[194:197], v156 offset:50176
	ds_read_b128 v[198:201], v154 offset:49152
	ds_read_b128 v[202:205], v154 offset:50176
	ds_read_b128 v[206:209], v153 offset:49152
	ds_read_b128 v[210:213], v153 offset:50176
	ds_read_b128 v[214:217], v152 offset:49152
	ds_read_b128 v[218:221], v152 offset:50176
	global_load_lds_dwordx4 v[222:223], off
	v_lshl_add_u64 v[222:223], v[226:227], 0, s[22:23]
	s_or_b32 m0, s100, 0xa000
	s_nop 0
	global_load_lds_dwordx4 v[222:223], off
	s_barrier
	s_waitcnt lgkmcnt(0)
	v_mfma_f32_16x16x32_f16 v[64:67], v[190:193], v[174:177], v[64:67]
	v_mfma_f32_16x16x32_f16 v[60:63], v[190:193], v[182:185], v[60:63]
	v_mfma_f32_16x16x32_f16 v[56:59], v[198:201], v[174:177], v[56:59]
	v_mfma_f32_16x16x32_f16 v[52:55], v[198:201], v[182:185], v[52:55]
	v_mfma_f32_16x16x32_f16 v[48:51], v[206:209], v[174:177], v[48:51]
	v_mfma_f32_16x16x32_f16 v[44:47], v[206:209], v[182:185], v[44:47]
	v_mfma_f32_16x16x32_f16 v[40:43], v[214:217], v[174:177], v[40:43]
	v_mfma_f32_16x16x32_f16 v[36:39], v[214:217], v[182:185], v[36:39]
	v_mfma_f32_16x16x32_f16 v[64:67], v[194:197], v[178:181], v[64:67]
	v_mfma_f32_16x16x32_f16 v[60:63], v[194:197], v[186:189], v[60:63]
	v_mfma_f32_16x16x32_f16 v[56:59], v[202:205], v[178:181], v[56:59]
	v_mfma_f32_16x16x32_f16 v[52:55], v[202:205], v[186:189], v[52:55]
	v_mfma_f32_16x16x32_f16 v[48:51], v[210:213], v[178:181], v[48:51]
	v_mfma_f32_16x16x32_f16 v[44:47], v[210:213], v[186:189], v[44:47]
	v_mfma_f32_16x16x32_f16 v[40:43], v[218:221], v[178:181], v[40:43]
	v_mfma_f32_16x16x32_f16 v[36:39], v[218:221], v[186:189], v[36:39]
	s_barrier
	v_lshl_add_u64 v[174:175], v[228:229], 0, s[60:61]
	s_or_b32 m0, s100, 0x1c000
	s_nop 0
	global_load_lds_dwordx4 v[174:175], off
	v_lshl_add_u64 v[174:175], v[236:237], 0, s[60:61]
	s_or_b32 m0, s100, 0x1e000
	s_nop 0
	global_load_lds_dwordx4 v[174:175], off
	s_waitcnt vmcnt(6)
	s_barrier
	v_mfma_f32_16x16x32_f16 v[32:35], v[190:193], v[230:233], v[32:35]
	v_mfma_f32_16x16x32_f16 v[28:31], v[190:193], v[242:245], v[28:31]
	v_mfma_f32_16x16x32_f16 v[24:27], v[198:201], v[230:233], v[24:27]
	v_mfma_f32_16x16x32_f16 v[20:23], v[198:201], v[242:245], v[20:23]
	v_mfma_f32_16x16x32_f16 v[16:19], v[206:209], v[230:233], v[16:19]
	v_mfma_f32_16x16x32_f16 v[12:15], v[206:209], v[242:245], v[12:15]
	v_mfma_f32_16x16x32_f16 v[8:11], v[214:217], v[230:233], v[8:11]
	v_mfma_f32_16x16x32_f16 v[4:7], v[214:217], v[242:245], v[4:7]
	v_mfma_f32_16x16x32_f16 v[32:35], v[194:197], v[238:241], v[32:35]
	v_mfma_f32_16x16x32_f16 v[28:31], v[194:197], v[246:249], v[28:31]
	v_mfma_f32_16x16x32_f16 v[24:27], v[202:205], v[238:241], v[24:27]
	v_mfma_f32_16x16x32_f16 v[20:23], v[202:205], v[246:249], v[20:23]
	v_mfma_f32_16x16x32_f16 v[16:19], v[210:213], v[238:241], v[16:19]
	v_mfma_f32_16x16x32_f16 v[12:15], v[210:213], v[246:249], v[12:15]
	v_mfma_f32_16x16x32_f16 v[8:11], v[218:221], v[238:241], v[8:11]
	v_mfma_f32_16x16x32_f16 v[4:7], v[218:221], v[246:249], v[4:7]
	s_add_i32 s1, s1, 2
	s_add_u32 s14, s14, 0x100
	s_addc_u32 s15, s15, 0
	s_cmp_lt_u32 s1, 12
	s_barrier
	s_cbranch_scc0 .Lpk_exit_1

; #define LDA8(dst, b, h) _Pragma("unroll") for (int m = 0; m < 4; ++m) _Pragma("unroll") for (int k = 0; k < 2; ++k) \
;     dst[m][k] = *(const bf16x8*)((const char*)SA8(b, h) + lds_byte8(wr * 64 + m * 16 + fr, k * 32 + fq * 8))
; #define LDB8(dst, b, h) _Pragma("unroll") for (int n = 0; n < 2; ++n) _Pragma("unroll") for (int k = 0; k < 2; ++k) \
;     dst[n][k] = *(const bf16x8*)((const char*)SB8(b, h) + lds_byte8(wc * 32 + n * 16 + fr, k * 32 + fq * 8))
; #define WAIT_V8(n) asm volatile("s_waitcnt vmcnt(" #n ")" ::: "memory")
; #define WAIT_L8(n) asm volatile("s_waitcnt lgkmcnt(" #n ")" ::: "memory")
; #define BAR8 __builtin_amdgcn_s_barrier()
;     ...
;   { LDB8(B0, 0, 0); LDA8(At, 0, 0); STAGE8(SA8(1, 1), A, lda, brow + 128, nt - 1);
;     BAR8; WAIT_L8(0); MMA8(0, 0, At, B0); BAR8;
;     LDB8(B1, 0, 1); BAR8; WAIT_L8(0); MMA8(0, 1, At, B1); BAR8;
;     LDA8(At, 0, 1); WAIT_V8(4); BAR8; WAIT_L8(0); MMA8(1, 0, At, B0); MMA8(1, 1, At, B1); BAR8; }
;   { LDB8(B0, 1, 0); LDA8(At, 1, 0); WAIT_V8(2); BAR8; WAIT_L8(0); MMA8(0, 0, At, B0); BAR8;
.Lpk_exit_1:
	s_add_u32 s12, s12, 0x40780
	s_addc_u32 s13, s13, 0
	v_lshl_add_u64 v[132:133], s[12:13], 0, v[132:133]
	v_lshl_add_u64 v[0:1], v[0:1], 1, v[132:133]
	s_or_b32 m0, s100, 0xc000
	ds_read_b128 v[138:141], v171
	ds_read_b128 v[142:145], v171 offset:1024
	ds_read_b128 v[160:163], v171 offset:2048
	ds_read_b128 v[164:167], v171 offset:3072
	ds_read_b128 v[174:177], v156
	ds_read_b128 v[178:181], v156 offset:1024
	ds_read_b128 v[182:185], v154
	ds_read_b128 v[186:189], v154 offset:1024
	ds_read_b128 v[190:193], v153
	ds_read_b128 v[194:197], v153 offset:1024
	ds_read_b128 v[198:201], v152
	ds_read_b128 v[202:205], v152 offset:1024
	global_load_lds_dwordx4 v[0:1], off
	v_lshl_add_u64 v[0:1], s[12:13], 0, v[136:137]
	v_lshl_add_u64 v[0:1], v[134:135], 1, v[0:1]
	s_or_b32 m0, s100, 0xe000
	s_nop 0
	global_load_lds_dwordx4 v[0:1], off
	s_barrier
	s_waitcnt lgkmcnt(0)
	v_mfma_f32_16x16x32_f16 v[128:131], v[174:177], v[138:141], v[128:131]
	v_mfma_f32_16x16x32_f16 v[124:127], v[174:177], v[160:163], v[124:127]
	v_mfma_f32_16x16x32_f16 v[120:123], v[182:185], v[138:141], v[120:123]
	v_mfma_f32_16x16x32_f16 v[112:115], v[190:193], v[138:141], v[112:115]
	v_mfma_f32_16x16x32_f16 v[128:131], v[178:181], v[142:145], v[128:131]
	v_mfma_f32_16x16x32_f16 v[124:127], v[178:181], v[164:167], v[124:127]
	v_mfma_f32_16x16x32_f16 v[120:123], v[186:189], v[142:145], v[120:123]
	v_mfma_f32_16x16x32_f16 v[116:119], v[182:185], v[160:163], v[116:119]
	v_mfma_f32_16x16x32_f16 v[112:115], v[194:197], v[142:145], v[112:115]
	v_mfma_f32_16x16x32_f16 v[108:111], v[190:193], v[160:163], v[108:111]
	v_mfma_f32_16x16x32_f16 v[104:107], v[198:201], v[138:141], v[104:107]
	v_mfma_f32_16x16x32_f16 v[100:103], v[198:201], v[160:163], v[100:103]
	v_mfma_f32_16x16x32_f16 v[132:135], v[186:189], v[164:167], v[116:119]
	v_mfma_f32_16x16x32_f16 v[170:173], v[194:197], v[164:167], v[108:111]
	v_mfma_f32_16x16x32_f16 v[206:209], v[202:205], v[142:145], v[104:107]
	v_mfma_f32_16x16x32_f16 v[210:213], v[202:205], v[164:167], v[100:103]
	s_barrier
	s_nop 1
	ds_read_b128 v[100:103], v168
	ds_read_b128 v[104:107], v168 offset:1024
	ds_read_b128 v[108:111], v168 offset:2048
	ds_read_b128 v[116:119], v168 offset:3072
	s_barrier
	s_waitcnt lgkmcnt(0)
	v_mfma_f32_16x16x32_f16 v[80:83], v[190:193], v[100:103], v[80:83]
	v_mfma_f32_16x16x32_f16 v[76:79], v[190:193], v[108:111], v[76:79]
	v_mfma_f32_16x16x32_f16 v[72:75], v[198:201], v[100:103], v[72:75]
	v_mfma_f32_16x16x32_f16 v[68:71], v[198:201], v[108:111], v[68:71]
	v_mfma_f32_16x16x32_f16 v[96:99], v[174:177], v[100:103], v[96:99]
	v_mfma_f32_16x16x32_f16 v[92:95], v[174:177], v[108:111], v[92:95]
	v_mfma_f32_16x16x32_f16 v[88:91], v[182:185], v[100:103], v[88:91]
	v_mfma_f32_16x16x32_f16 v[84:87], v[182:185], v[108:111], v[84:87]
	v_mfma_f32_16x16x32_f16 v[80:83], v[194:197], v[104:107], v[80:83]
	v_mfma_f32_16x16x32_f16 v[76:79], v[194:197], v[116:119], v[76:79]
	v_mfma_f32_16x16x32_f16 v[72:75], v[202:205], v[104:107], v[72:75]
	v_mfma_f32_16x16x32_f16 v[68:71], v[202:205], v[116:119], v[68:71]
	v_mfma_f32_16x16x32_f16 v[214:217], v[178:181], v[104:107], v[96:99]
	v_mfma_f32_16x16x32_f16 v[174:177], v[178:181], v[116:119], v[92:95]
	v_mfma_f32_16x16x32_f16 v[178:181], v[186:189], v[104:107], v[88:91]
	v_mfma_f32_16x16x32_f16 v[182:185], v[186:189], v[116:119], v[84:87]
	s_barrier
	s_nop 0
	ds_read_b128 v[84:87], v156 offset:16384
	ds_read_b128 v[88:91], v156 offset:17408
	ds_read_b128 v[92:95], v154 offset:16384
	ds_read_b128 v[96:99], v154 offset:17408
	ds_read_b128 v[186:189], v153 offset:16384
	ds_read_b128 v[190:193], v153 offset:17408
	ds_read_b128 v[194:197], v152 offset:16384
	ds_read_b128 v[198:201], v152 offset:17408
	s_waitcnt vmcnt(4)
	s_barrier
	s_waitcnt lgkmcnt(0)
	v_mfma_f32_16x16x32_f16 v[64:67], v[84:87], v[138:141], v[64:67]
	v_mfma_f32_16x16x32_f16 v[60:63], v[84:87], v[160:163], v[60:63]
	v_mfma_f32_16x16x32_f16 v[56:59], v[92:95], v[138:141], v[56:59]
	v_mfma_f32_16x16x32_f16 v[52:55], v[92:95], v[160:163], v[52:55]
	v_mfma_f32_16x16x32_f16 v[48:51], v[186:189], v[138:141], v[48:51]
	v_mfma_f32_16x16x32_f16 v[44:47], v[186:189], v[160:163], v[44:47]
	v_mfma_f32_16x16x32_f16 v[40:43], v[194:197], v[138:141], v[40:43]
	v_mfma_f32_16x16x32_f16 v[36:39], v[194:197], v[160:163], v[36:39]
	v_mfma_f32_16x16x32_f16 v[64:67], v[88:91], v[142:145], v[64:67]
	v_mfma_f32_16x16x32_f16 v[60:63], v[88:91], v[164:167], v[60:63]
	v_mfma_f32_16x16x32_f16 v[56:59], v[96:99], v[142:145], v[56:59]
	v_mfma_f32_16x16x32_f16 v[52:55], v[96:99], v[164:167], v[52:55]
	v_mfma_f32_16x16x32_f16 v[48:51], v[190:193], v[142:145], v[48:51]
	v_mfma_f32_16x16x32_f16 v[44:47], v[190:193], v[164:167], v[44:47]
	v_mfma_f32_16x16x32_f16 v[40:43], v[198:201], v[142:145], v[40:43]
	v_mfma_f32_16x16x32_f16 v[36:39], v[198:201], v[164:167], v[36:39]
	v_mfma_f32_16x16x32_f16 v[32:35], v[84:87], v[100:103], v[32:35]
	v_mfma_f32_16x16x32_f16 v[28:31], v[84:87], v[108:111], v[28:31]
	v_mfma_f32_16x16x32_f16 v[24:27], v[92:95], v[100:103], v[24:27]
	v_mfma_f32_16x16x32_f16 v[20:23], v[92:95], v[108:111], v[20:23]
	v_mfma_f32_16x16x32_f16 v[16:19], v[186:189], v[100:103], v[16:19]
	v_mfma_f32_16x16x32_f16 v[12:15], v[186:189], v[108:111], v[12:15]
	v_mfma_f32_16x16x32_f16 v[8:11], v[194:197], v[100:103], v[8:11]
	v_mfma_f32_16x16x32_f16 v[4:7], v[194:197], v[108:111], v[4:7]
	v_mfma_f32_16x16x32_f16 v[136:139], v[88:91], v[104:107], v[32:35]
	v_mfma_f32_16x16x32_f16 v[140:143], v[88:91], v[116:119], v[28:31]
	v_mfma_f32_16x16x32_f16 v[160:163], v[96:99], v[104:107], v[24:27]
	v_mfma_f32_16x16x32_f16 v[164:167], v[96:99], v[116:119], v[20:23]
	v_mfma_f32_16x16x32_f16 v[202:205], v[190:193], v[104:107], v[16:19]
	v_mfma_f32_16x16x32_f16 v[186:189], v[190:193], v[116:119], v[12:15]
	v_mfma_f32_16x16x32_f16 v[190:193], v[198:201], v[104:107], v[8:11]
	v_mfma_f32_16x16x32_f16 v[194:197], v[198:201], v[116:119], v[4:7]
	s_barrier
; #define LDA8(dst, b, h) _Pragma("unroll") for (int m = 0; m < 4; ++m) _Pragma("unroll") for (int k = 0; k < 2; ++k) \
;     dst[m][k] = *(const bf16x8*)((const char*)SA8(b, h) + lds_byte8(wr * 64 + m * 16 + fr, k * 32 + fq * 8))
; #define LDB8(dst, b, h) _Pragma("unroll") for (int n = 0; n < 2; ++n) _Pragma("unroll") for (int k = 0; k < 2; ++k) \
;     dst[n][k] = *(const bf16x8*)((const char*)SB8(b, h) + lds_byte8(wc * 32 + n * 16 + fr, k * 32 + fq * 8))
; #define WAIT_V8(n) asm volatile("s_waitcnt vmcnt(" #n ")" ::: "memory")
; #define WAIT_L8(n) asm volatile("s_waitcnt lgkmcnt(" #n ")" ::: "memory")
; #define BAR8 __builtin_amdgcn_s_barrier()
;     ...
;   { LDB8(B0, 1, 0); LDA8(At, 1, 0); WAIT_V8(2); BAR8; WAIT_L8(0); MMA8(0, 0, At, B0); BAR8;
;     LDB8(B1, 1, 1); WAIT_V8(0); BAR8; WAIT_L8(0); MMA8(0, 1, At, B1); BAR8;
;     LDA8(At, 1, 1); BAR8; WAIT_L8(0); MMA8(1, 0, At, B0); MMA8(1, 1, At, B1); BAR8; }
;   if (wr == 0) BAR8;
;   __syncthreads();
;     ...
;   if (t < 256) {
	ds_read_b128 v[198:201], v159
	ds_read_b128 v[218:221], v159 offset:1024
	ds_read_b128 v[230:233], v159 offset:2048
	ds_read_b128 v[238:241], v159 offset:3072
	ds_read_b128 v[8:11], v156 offset:32768
	ds_read_b128 v[12:15], v156 offset:33792
	ds_read_b128 v[16:19], v154 offset:32768
	ds_read_b128 v[24:27], v154 offset:33792
	ds_read_b128 v[28:31], v153 offset:32768
	ds_read_b128 v[32:35], v153 offset:33792
	ds_read_b128 v[242:245], v152 offset:32768
	ds_read_b128 v[246:249], v152 offset:33792
	s_waitcnt vmcnt(2)
	s_barrier
	s_waitcnt lgkmcnt(0)
	v_mfma_f32_16x16x32_f16 v[4:7], v[8:11], v[198:201], v[128:131]
	v_mfma_f32_16x16x32_f16 v[104:107], v[12:15], v[218:221], v[4:7]
	v_mfma_f32_16x16x32_f16 v[4:7], v[8:11], v[230:233], v[124:127]
	v_mfma_f32_16x16x32_f16 v[116:119], v[12:15], v[238:241], v[4:7]
	v_mfma_f32_16x16x32_f16 v[4:7], v[16:19], v[198:201], v[120:123]
	v_mfma_f32_16x16x32_f16 v[100:103], v[24:27], v[218:221], v[4:7]
	v_mfma_f32_16x16x32_f16 v[4:7], v[16:19], v[230:233], v[132:135]
	v_mfma_f32_16x16x32_f16 v[108:111], v[24:27], v[238:241], v[4:7]
	v_mfma_f32_16x16x32_f16 v[4:7], v[28:31], v[198:201], v[112:115]
	v_mfma_f32_16x16x32_f16 v[92:95], v[32:35], v[218:221], v[4:7]
	v_mfma_f32_16x16x32_f16 v[4:7], v[28:31], v[230:233], v[170:173]
	v_mfma_f32_16x16x32_f16 v[96:99], v[32:35], v[238:241], v[4:7]
	v_mfma_f32_16x16x32_f16 v[4:7], v[242:245], v[198:201], v[206:209]
	v_mfma_f32_16x16x32_f16 v[84:87], v[246:249], v[218:221], v[4:7]
	v_mfma_f32_16x16x32_f16 v[4:7], v[242:245], v[230:233], v[210:213]
	v_mfma_f32_16x16x32_f16 v[88:91], v[246:249], v[238:241], v[4:7]
	s_barrier
	ds_read_b128 v[132:135], v157
	ds_read_b128 v[168:171], v157 offset:1024
	ds_read_b128 v[206:209], v157 offset:2048
	ds_read_b128 v[210:213], v157 offset:3072
	s_waitcnt vmcnt(0)
	s_barrier
	s_waitcnt lgkmcnt(0)
	v_mfma_f32_16x16x32_f16 v[4:7], v[8:11], v[132:135], v[214:217]
	v_mfma_f32_16x16x32_f16 v[8:11], v[8:11], v[206:209], v[174:177]
	v_mfma_f32_16x16x32_f16 v[4:7], v[12:15], v[168:171], v[4:7]
	v_mfma_f32_16x16x32_f16 v[20:23], v[12:15], v[210:213], v[8:11]
	v_mfma_f32_16x16x32_f16 v[8:11], v[16:19], v[132:135], v[178:181]
	v_mfma_f32_16x16x32_f16 v[12:15], v[16:19], v[206:209], v[182:185]
	v_mfma_f32_16x16x32_f16 v[8:11], v[24:27], v[168:171], v[8:11]
	v_mfma_f32_16x16x32_f16 v[24:27], v[24:27], v[210:213], v[12:15]
	v_mfma_f32_16x16x32_f16 v[12:15], v[28:31], v[132:135], v[80:83]
	v_mfma_f32_16x16x32_f16 v[16:19], v[28:31], v[206:209], v[76:79]
	v_mfma_f32_16x16x32_f16 v[12:15], v[32:35], v[168:171], v[12:15]
	v_mfma_f32_16x16x32_f16 v[28:31], v[32:35], v[210:213], v[16:19]
	v_mfma_f32_16x16x32_f16 v[16:19], v[242:245], v[132:135], v[72:75]
	v_mfma_f32_16x16x32_f16 v[32:35], v[242:245], v[206:209], v[68:71]
	v_mfma_f32_16x16x32_f16 v[16:19], v[246:249], v[168:171], v[16:19]
	v_mfma_f32_16x16x32_f16 v[32:35], v[246:249], v[210:213], v[32:35]
	s_barrier
	ds_read_b128 v[172:175], v156 offset:49152
	ds_read_b128 v[156:159], v156 offset:50176
	ds_read_b128 v[176:179], v154 offset:49152
	ds_read_b128 v[180:183], v154 offset:50176
	ds_read_b128 v[214:217], v153 offset:49152
	ds_read_b128 v[242:245], v153 offset:50176
	ds_read_b128 v[246:249], v152 offset:49152
	ds_read_b128 v[150:153], v152 offset:50176
	s_barrier
	s_waitcnt lgkmcnt(0)
	v_mfma_f32_16x16x32_f16 v[64:67], v[172:175], v[198:201], v[64:67]
	v_mfma_f32_16x16x32_f16 v[60:63], v[172:175], v[230:233], v[60:63]
	v_mfma_f32_16x16x32_f16 v[56:59], v[176:179], v[198:201], v[56:59]
	v_mfma_f32_16x16x32_f16 v[52:55], v[176:179], v[230:233], v[52:55]
	v_mfma_f32_16x16x32_f16 v[48:51], v[214:217], v[198:201], v[48:51]
	v_mfma_f32_16x16x32_f16 v[44:47], v[214:217], v[230:233], v[44:47]
	v_mfma_f32_16x16x32_f16 v[40:43], v[246:249], v[198:201], v[40:43]
	v_mfma_f32_16x16x32_f16 v[36:39], v[246:249], v[230:233], v[36:39]
	v_mfma_f32_16x16x32_f16 v[128:131], v[156:159], v[218:221], v[64:67]
	v_mfma_f32_16x16x32_f16 v[124:127], v[156:159], v[238:241], v[60:63]
	v_mfma_f32_16x16x32_f16 v[120:123], v[180:183], v[218:221], v[56:59]
	v_mfma_f32_16x16x32_f16 v[112:115], v[180:183], v[238:241], v[52:55]
	v_mfma_f32_16x16x32_f16 v[80:83], v[242:245], v[218:221], v[48:51]
	v_mfma_f32_16x16x32_f16 v[76:79], v[242:245], v[238:241], v[44:47]
	v_mfma_f32_16x16x32_f16 v[72:75], v[150:153], v[218:221], v[40:43]
	v_mfma_f32_16x16x32_f16 v[68:71], v[150:153], v[238:241], v[36:39]
	v_mfma_f32_16x16x32_f16 v[40:43], v[172:175], v[206:209], v[140:143]
	v_mfma_f32_16x16x32_f16 v[44:47], v[176:179], v[206:209], v[164:167]
	v_mfma_f32_16x16x32_f16 v[48:51], v[214:217], v[206:209], v[186:189]
	v_mfma_f32_16x16x32_f16 v[36:39], v[172:175], v[132:135], v[136:139]
	v_mfma_f32_16x16x32_f16 v[52:55], v[156:159], v[210:213], v[40:43]
	v_mfma_f32_16x16x32_f16 v[40:43], v[176:179], v[132:135], v[160:163]
	v_mfma_f32_16x16x32_f16 v[56:59], v[180:183], v[210:213], v[44:47]
	v_mfma_f32_16x16x32_f16 v[44:47], v[214:217], v[132:135], v[202:205]
	v_mfma_f32_16x16x32_f16 v[60:63], v[242:245], v[210:213], v[48:51]
	v_mfma_f32_16x16x32_f16 v[48:51], v[246:249], v[132:135], v[190:193]
	v_mfma_f32_16x16x32_f16 v[64:67], v[246:249], v[206:209], v[194:197]
	v_mfma_f32_16x16x32_f16 v[36:39], v[156:159], v[168:171], v[36:39]
	v_mfma_f32_16x16x32_f16 v[40:43], v[180:183], v[168:171], v[40:43]
	v_mfma_f32_16x16x32_f16 v[44:47], v[242:245], v[168:171], v[44:47]
	v_mfma_f32_16x16x32_f16 v[48:51], v[150:153], v[168:171], v[48:51]
	v_mfma_f32_16x16x32_f16 v[64:67], v[150:153], v[210:213], v[64:67]
	s_movk_i32 s1, 0x100
	v_cmp_gt_u32_e32 vcc, s1, v3
	s_barrier
	s_and_saveexec_b64 s[12:13], vcc
	s_cbranch_execz .LBB0_245
	s_barrier

; #define LDA8(dst, b, h) _Pragma("unroll") for (int m = 0; m < 4; ++m) _Pragma("unroll") for (int k = 0; k < 2; ++k) \
;     dst[m][k] = *(const bf16x8*)((const char*)SA8(b, h) + lds_byte8(wr * 64 + m * 16 + fr, k * 32 + fq * 8))
; #define LDB8(dst, b, h) _Pragma("unroll") for (int n = 0; n < 2; ++n) _Pragma("unroll") for (int k = 0; k < 2; ++k) \
;     dst[n][k] = *(const bf16x8*)((const char*)SB8(b, h) + lds_byte8(wc * 32 + n * 16 + fr, k * 32 + fq * 8))
; #define WAIT_V8(n) asm volatile("s_waitcnt vmcnt(" #n ")" ::: "memory")
; #define WAIT_L8(n) asm volatile("s_waitcnt lgkmcnt(" #n ")" ::: "memory")
; #define BAR8 __builtin_amdgcn_s_barrier()
; #define SCHED8 __builtin_amdgcn_sched_barrier(0)
;     ...
;   const int brow = m0, bcol = n0;
;   const int wid = t >> 6, lane = t & 63, wr = wid >> 2, wc = wid & 3, fr = lane & 15, fq = lane >> 4;
;   f32x4 acc[2][2][4][2];
;   {
;     float zinit = 0.f;
;     asm volatile("" : "+v"(zinit));
; #pragma unroll
;     for (int a = 0; a < 2; ++a)
; #pragma unroll
;       for (int b = 0; b < 2; ++b)
; #pragma unroll
;         for (int m = 0; m < 4; ++m)
; #pragma unroll
;           for (int n = 0; n < 2; ++n)
; #pragma unroll
;             for (int j = 0; j < 4; ++j) acc[a][b][m][n][j] = zinit;
;   }
;   bf16x8 At[4][2], B0[2][2], B1[2][2];
;   const int nt = K / 64;
;   if (!pre) {
;     STAGE8(SB8(0, 0), Bt, K, bcol, 0); STAGE8(SA8(0, 0), A, lda, brow, 0);
;     STAGE8(SB8(0, 1), Bt, K, bcol + 128, 0); STAGE8(SA8(0, 1), A, lda, brow + 128, 0);
;   }
;   if (wr == 1) BAR8;
;   WAIT_V8(4); BAR8;
;   STAGE8(SB8(1, 0), Bt, K, bcol, 1); STAGE8(SA8(1, 0), A, lda, brow, 1); STAGE8(SB8(1, 1), Bt, K, bcol + 128, 1);
;   WAIT_V8(6); BAR8;
;   for (int tt = 0; tt < nt - 2; tt += 2) {
;     LDB8(B0, 0, 0); SCHED8; LDA8(At, 0, 0); STAGE8(SA8(1, 1), A, lda, brow + 128, tt + 1);
;     WAIT_L8(8); BAR8; WAIT_L8(0); MMA8(0, 0, At, B0); BAR8; SCHED8;
.LBB0_907:
	s_or_b64 exec, exec, s[12:13]
	s_lshl_b32 s29, s20, 11
	s_waitcnt vmcnt(0)
	s_and_b32 s36, s29, 0x1f80000
	s_mov_b64 s[38:39], 0x80
	v_lshl_add_u64 v[14:15], v[14:15], 0, s[38:39]
	s_or_b32 m0, s100, 0x18000
	s_waitcnt vmcnt(4)
	s_barrier
	global_load_lds_dwordx4 v[14:15], off
	v_lshl_add_u64 v[14:15], v[18:19], 0, s[38:39]
	s_or_b32 m0, s100, 0x1a000
	global_load_lds_dwordx4 v[14:15], off
	v_lshl_add_u64 v[14:15], v[20:21], 0, s[38:39]
	s_or_b32 m0, s100, 0x8000
	global_load_lds_dwordx4 v[14:15], off
	v_lshl_add_u64 v[14:15], v[22:23], 0, s[38:39]
	s_or_b32 m0, s100, 0xa000
	global_load_lds_dwordx4 v[14:15], off
	v_lshl_add_u64 v[14:15], v[26:27], 0, s[38:39]
	s_or_b32 m0, s100, 0x1c000
	s_nop 0
	global_load_lds_dwordx4 v[14:15], off
	v_lshl_add_u64 v[14:15], v[28:29], 0, s[38:39]
	s_or_b32 m0, s100, 0x1e000
	v_and_b32_e32 v147, 15, v3
	global_load_lds_dwordx4 v[14:15], off
	v_bfe_u32 v148, v3, 4, 2
	v_lshlrev_b32_e32 v14, 4, v148
	v_lshlrev_b32_e32 v15, 6, v147
	v_lshlrev_b32_e32 v18, 2, v3
	v_lshlrev_b64 v[136:137], 10, v[16:17]
	v_or_b32_e32 v17, v14, v15
	v_and_b32_e32 v18, 32, v18
	s_mov_b32 s29, 0x10000
	s_and_b32 s12, s21, 0xffffff00
	v_bitop3_b32 v20, v17, s29, v18 bitop3:0xde
	s_mov_b32 s29, 0x14000
	s_ashr_i32 s13, s12, 31
	v_readlane_b32 s40, v254, 35
	v_bitop3_b32 v19, v14, v18, v15 bitop3:0x36
	v_bitop3_b32 v21, v17, s29, v18 bitop3:0xde
	s_mov_b32 s29, 0x18000
	v_lshlrev_b32_e32 v15, 6, v3
	s_lshl_b64 s[12:13], s[12:13], 11
	s_mov_b32 s37, s40
	v_bitop3_b32 v22, v17, s29, v18 bitop3:0xde
	s_mov_b32 s29, 0x1c000
	v_and_b32_e32 v15, 0x3c0, v15
	v_bitop3_b32 v17, v17, s29, v18 bitop3:0xde
	v_bitop3_b32 v18, v15, v18, v14 bitop3:0x36
	v_lshl_add_u64 v[14:15], s[12:13], 0, v[6:7]
	v_lshl_add_u64 v[6:7], s[36:37], 0, v[6:7]
	v_lshl_add_u64 v[14:15], v[14:15], 0, v[8:9]
	v_lshl_add_u64 v[6:7], v[6:7], 0, v[8:9]
	v_bfe_u32 v146, v3, 6, 2
	s_waitcnt vmcnt(6)
	v_lshlrev_b32_e32 v149, 6, v5
	v_lshlrev_b32_e32 v5, 13, v5
	v_lshl_add_u64 v[138:139], s[4:5], 0, v[14:15]
	v_lshl_add_u64 v[14:15], s[12:13], 0, v[10:11]
	v_lshl_add_u64 v[142:143], s[2:3], 0, v[6:7]
	v_lshl_add_u64 v[6:7], s[36:37], 0, v[10:11]
	v_lshlrev_b64 v[134:135], 10, v[24:25]
	v_readlane_b32 s41, v254, 36
	v_readlane_b32 s42, v254, 37
	v_readlane_b32 s43, v254, 38
	v_lshlrev_b32_e32 v16, 12, v146
	v_or_b32_e32 v23, 0x800, v5
	v_or_b32_e32 v24, 0x1000, v5
	v_or_b32_e32 v25, 0x1800, v5
	v_lshl_add_u64 v[14:15], v[14:15], 0, v[12:13]
	v_lshl_add_u64 v[6:7], v[6:7], 0, v[12:13]
	v_lshl_add_u64 v[140:141], s[4:5], 0, v[14:15]
	v_lshl_add_u64 v[144:145], s[2:3], 0, v[6:7]
	s_mov_b32 s29, -2
	s_mov_b64 s[12:13], 0
	v_add_u32_e32 v171, v20, v16
	v_add_u32_e32 v156, v19, v5
	v_add_u32_e32 v155, v18, v23
	v_add_u32_e32 v154, v18, v24
	v_add_u32_e32 v153, v18, v25
	v_add_u32_e32 v167, v21, v16
	v_add_u32_e32 v160, v22, v16
	v_add_u32_e32 v158, v17, v16
	s_mov_b64 s[36:37], 0x6040080
	s_mov_b64 s[38:39], 0xc4a0100
	s_mov_b64 s[40:41], 0x6000100
	s_mov_b64 s[42:43], 0xc4e0100
	s_mov_b64 s[44:45], 0x6040100
	s_mov_b64 s[46:47], 0xc4a0180
	s_mov_b64 s[48:49], 0x6000180
	s_mov_b64 s[50:51], 0xc4e0180
	s_barrier
	ds_read_b128 v[174:177], v171
	ds_read_b128 v[178:181], v171 offset:1024
	ds_read_b128 v[182:185], v171 offset:2048
	ds_read_b128 v[186:189], v171 offset:3072
	v_lshl_add_u64 v[222:223], v[142:143], 0, s[12:13]
	v_lshl_add_u64 v[226:227], v[222:223], 0, s[36:37]
	s_or_b32 m0, s100, 0xc000
	ds_read_b128 v[190:193], v156
	ds_read_b128 v[194:197], v156 offset:1024
	ds_read_b128 v[198:201], v155
	ds_read_b128 v[202:205], v155 offset:1024
	ds_read_b128 v[206:209], v154
	ds_read_b128 v[210:213], v154 offset:1024
	ds_read_b128 v[214:217], v153
	ds_read_b128 v[218:221], v153 offset:1024
	global_load_lds_dwordx4 v[226:227], off
	v_lshl_add_u64 v[226:227], v[144:145], 0, s[12:13]
	v_lshl_add_u64 v[228:229], v[226:227], 0, s[36:37]
	s_or_b32 m0, s100, 0xe000
	s_nop 0
	global_load_lds_dwordx4 v[228:229], off
	s_waitcnt lgkmcnt(8)
	s_barrier
	s_waitcnt lgkmcnt(0)
	v_mfma_f32_16x16x32_bf16 v[128:131], v[190:193], v[174:177], 0
	v_mfma_f32_16x16x32_bf16 v[124:127], v[190:193], v[182:185], 0
	v_mfma_f32_16x16x32_bf16 v[120:123], v[198:201], v[174:177], 0
	v_mfma_f32_16x16x32_bf16 v[116:119], v[198:201], v[182:185], 0
	v_mfma_f32_16x16x32_bf16 v[112:115], v[206:209], v[174:177], 0
	v_mfma_f32_16x16x32_bf16 v[108:111], v[206:209], v[182:185], 0
	v_mfma_f32_16x16x32_bf16 v[104:107], v[214:217], v[174:177], 0
	v_mfma_f32_16x16x32_bf16 v[100:103], v[214:217], v[182:185], 0
	v_mfma_f32_16x16x32_bf16 v[128:131], v[194:197], v[178:181], v[128:131]
	v_mfma_f32_16x16x32_bf16 v[124:127], v[194:197], v[186:189], v[124:127]
	v_mfma_f32_16x16x32_bf16 v[120:123], v[202:205], v[178:181], v[120:123]
	v_mfma_f32_16x16x32_bf16 v[116:119], v[202:205], v[186:189], v[116:119]
	v_mfma_f32_16x16x32_bf16 v[112:115], v[210:213], v[178:181], v[112:115]
	v_mfma_f32_16x16x32_bf16 v[108:111], v[210:213], v[186:189], v[108:111]
	v_mfma_f32_16x16x32_bf16 v[104:107], v[218:221], v[178:181], v[104:107]
	v_mfma_f32_16x16x32_bf16 v[100:103], v[218:221], v[186:189], v[100:103]
	s_barrier
	v_lshl_add_u64 v[228:229], v[138:139], 0, s[12:13]
	v_lshl_add_u64 v[236:237], v[228:229], 0, s[38:39]
	s_or_b32 m0, s100, 0x10000
	ds_read_b128 v[230:233], v167
	ds_read_b128 v[238:241], v167 offset:1024
	ds_read_b128 v[242:245], v167 offset:2048
	ds_read_b128 v[246:249], v167 offset:3072
	global_load_lds_dwordx4 v[236:237], off
	v_lshl_add_u64 v[236:237], v[140:141], 0, s[12:13]
	v_lshl_add_u64 v[250:251], v[236:237], 0, s[38:39]
	s_or_b32 m0, s100, 0x12000
	s_nop 0
	global_load_lds_dwordx4 v[250:251], off
	s_barrier
; #define LDA8(dst, b, h) _Pragma("unroll") for (int m = 0; m < 4; ++m) _Pragma("unroll") for (int k = 0; k < 2; ++k) \
;     dst[m][k] = *(const bf16x8*)((const char*)SA8(b, h) + lds_byte8(wr * 64 + m * 16 + fr, k * 32 + fq * 8))
; #define LDB8(dst, b, h) _Pragma("unroll") for (int n = 0; n < 2; ++n) _Pragma("unroll") for (int k = 0; k < 2; ++k) \
;     dst[n][k] = *(const bf16x8*)((const char*)SB8(b, h) + lds_byte8(wc * 32 + n * 16 + fr, k * 32 + fq * 8))
; #define WAIT_V8(n) asm volatile("s_waitcnt vmcnt(" #n ")" ::: "memory")
; #define WAIT_L8(n) asm volatile("s_waitcnt lgkmcnt(" #n ")" ::: "memory")
; #define BAR8 __builtin_amdgcn_s_barrier()
; #define SCHED8 __builtin_amdgcn_sched_barrier(0)
;     ...
;     WAIT_L8(8); BAR8; WAIT_L8(0); MMA8(0, 0, At, B0); BAR8; SCHED8;
;     LDB8(B1, 0, 1); STAGE8(SB8(0, 0), Bt, K, bcol, tt + 2);
;     BAR8; WAIT_L8(0); MMA8(0, 1, At, B1); BAR8;
;     LDA8(At, 0, 1); STAGE8(SA8(0, 0), A, lda, brow, tt + 2);
;     BAR8; WAIT_L8(0); MMA8(1, 0, At, B0); BAR8; SCHED8;
;     STAGE8(SB8(0, 1), Bt, K, bcol + 128, tt + 2);
;     WAIT_V8(6); BAR8; MMA8(1, 1, At, B1); BAR8;
;     LDB8(B0, 1, 0); SCHED8; LDA8(At, 1, 0); STAGE8(SA8(0, 1), A, lda, brow + 128, tt + 2);
;     WAIT_L8(8); BAR8; WAIT_L8(0); MMA8(0, 0, At, B0); BAR8; SCHED8;
	s_waitcnt lgkmcnt(0)
	v_mfma_f32_16x16x32_bf16 v[96:99], v[190:193], v[230:233], 0
	v_mfma_f32_16x16x32_bf16 v[92:95], v[190:193], v[242:245], 0
	v_mfma_f32_16x16x32_bf16 v[88:91], v[198:201], v[230:233], 0
	v_mfma_f32_16x16x32_bf16 v[84:87], v[198:201], v[242:245], 0
	v_mfma_f32_16x16x32_bf16 v[80:83], v[206:209], v[230:233], 0
	v_mfma_f32_16x16x32_bf16 v[76:79], v[206:209], v[242:245], 0
	v_mfma_f32_16x16x32_bf16 v[72:75], v[214:217], v[230:233], 0
	v_mfma_f32_16x16x32_bf16 v[68:71], v[214:217], v[242:245], 0
	v_mfma_f32_16x16x32_bf16 v[96:99], v[194:197], v[238:241], v[96:99]
	v_mfma_f32_16x16x32_bf16 v[92:95], v[194:197], v[246:249], v[92:95]
	v_mfma_f32_16x16x32_bf16 v[88:91], v[202:205], v[238:241], v[88:91]
	v_mfma_f32_16x16x32_bf16 v[84:87], v[202:205], v[246:249], v[84:87]
	v_mfma_f32_16x16x32_bf16 v[80:83], v[210:213], v[238:241], v[80:83]
	v_mfma_f32_16x16x32_bf16 v[76:79], v[210:213], v[246:249], v[76:79]
	v_mfma_f32_16x16x32_bf16 v[72:75], v[218:221], v[238:241], v[72:75]
	v_mfma_f32_16x16x32_bf16 v[68:71], v[218:221], v[246:249], v[68:71]
	v_lshl_add_u64 v[250:251], v[222:223], 0, s[40:41]
	s_mov_b32 m0, s100
	s_barrier
	ds_read_b128 v[190:193], v156 offset:16384
	ds_read_b128 v[194:197], v156 offset:17408
	ds_read_b128 v[198:201], v155 offset:16384
	ds_read_b128 v[202:205], v155 offset:17408
	ds_read_b128 v[206:209], v154 offset:16384
	ds_read_b128 v[210:213], v154 offset:17408
	ds_read_b128 v[214:217], v153 offset:16384
	ds_read_b128 v[218:221], v153 offset:17408
	global_load_lds_dwordx4 v[250:251], off
	v_lshl_add_u64 v[250:251], v[226:227], 0, s[40:41]
	s_or_b32 m0, s100, 0x2000
	s_nop 0
	global_load_lds_dwordx4 v[250:251], off
	s_barrier
	s_waitcnt lgkmcnt(0)
	v_mfma_f32_16x16x32_bf16 v[64:67], v[190:193], v[174:177], 0
	v_mfma_f32_16x16x32_bf16 v[60:63], v[190:193], v[182:185], 0
	v_mfma_f32_16x16x32_bf16 v[56:59], v[198:201], v[174:177], 0
	v_mfma_f32_16x16x32_bf16 v[52:55], v[198:201], v[182:185], 0
	v_mfma_f32_16x16x32_bf16 v[48:51], v[206:209], v[174:177], 0
	v_mfma_f32_16x16x32_bf16 v[44:47], v[206:209], v[182:185], 0
	v_mfma_f32_16x16x32_bf16 v[40:43], v[214:217], v[174:177], 0
	v_mfma_f32_16x16x32_bf16 v[36:39], v[214:217], v[182:185], 0
	v_mfma_f32_16x16x32_bf16 v[64:67], v[194:197], v[178:181], v[64:67]
	v_mfma_f32_16x16x32_bf16 v[60:63], v[194:197], v[186:189], v[60:63]
	v_mfma_f32_16x16x32_bf16 v[56:59], v[202:205], v[178:181], v[56:59]
	v_mfma_f32_16x16x32_bf16 v[52:55], v[202:205], v[186:189], v[52:55]
	v_mfma_f32_16x16x32_bf16 v[48:51], v[210:213], v[178:181], v[48:51]
	v_mfma_f32_16x16x32_bf16 v[44:47], v[210:213], v[186:189], v[44:47]
	v_mfma_f32_16x16x32_bf16 v[40:43], v[218:221], v[178:181], v[40:43]
	v_mfma_f32_16x16x32_bf16 v[36:39], v[218:221], v[186:189], v[36:39]
	s_barrier
	v_lshl_add_u64 v[174:175], v[228:229], 0, s[42:43]
	s_or_b32 m0, s100, 0x14000
	s_nop 0
	global_load_lds_dwordx4 v[174:175], off
	v_lshl_add_u64 v[174:175], v[236:237], 0, s[42:43]
	s_or_b32 m0, s100, 0x16000
	s_nop 0
	global_load_lds_dwordx4 v[174:175], off
	s_waitcnt vmcnt(6)
	s_barrier
	v_mfma_f32_16x16x32_bf16 v[32:35], v[190:193], v[230:233], 0
	v_mfma_f32_16x16x32_bf16 v[28:31], v[190:193], v[242:245], 0
	v_mfma_f32_16x16x32_bf16 v[24:27], v[198:201], v[230:233], 0
	v_mfma_f32_16x16x32_bf16 v[20:23], v[198:201], v[242:245], 0
	v_mfma_f32_16x16x32_bf16 v[16:19], v[206:209], v[230:233], 0
	v_mfma_f32_16x16x32_bf16 v[12:15], v[206:209], v[242:245], 0
	v_mfma_f32_16x16x32_bf16 v[8:11], v[214:217], v[230:233], 0
	v_mfma_f32_16x16x32_bf16 v[4:7], v[214:217], v[242:245], 0
	v_mfma_f32_16x16x32_bf16 v[32:35], v[194:197], v[238:241], v[32:35]
	v_mfma_f32_16x16x32_bf16 v[28:31], v[194:197], v[246:249], v[28:31]
	v_mfma_f32_16x16x32_bf16 v[24:27], v[202:205], v[238:241], v[24:27]
	v_mfma_f32_16x16x32_bf16 v[20:23], v[202:205], v[246:249], v[20:23]
	v_mfma_f32_16x16x32_bf16 v[16:19], v[210:213], v[238:241], v[16:19]
	v_mfma_f32_16x16x32_bf16 v[12:15], v[210:213], v[246:249], v[12:15]
	v_mfma_f32_16x16x32_bf16 v[8:11], v[218:221], v[238:241], v[8:11]
	v_mfma_f32_16x16x32_bf16 v[4:7], v[218:221], v[246:249], v[4:7]
	s_barrier
	ds_read_b128 v[174:177], v160
	ds_read_b128 v[178:181], v160 offset:1024
	ds_read_b128 v[182:185], v160 offset:2048
	ds_read_b128 v[186:189], v160 offset:3072
	v_lshl_add_u64 v[230:231], v[222:223], 0, s[44:45]
	s_or_b32 m0, s100, 0x4000
	ds_read_b128 v[190:193], v156 offset:32768
	ds_read_b128 v[194:197], v156 offset:33792
	ds_read_b128 v[198:201], v155 offset:32768
	ds_read_b128 v[202:205], v155 offset:33792
	ds_read_b128 v[206:209], v154 offset:32768
	ds_read_b128 v[210:213], v154 offset:33792
	ds_read_b128 v[214:217], v153 offset:32768
	ds_read_b128 v[218:221], v153 offset:33792
	global_load_lds_dwordx4 v[230:231], off
	v_lshl_add_u64 v[230:231], v[226:227], 0, s[44:45]
	s_or_b32 m0, s100, 0x6000
	s_nop 0
	global_load_lds_dwordx4 v[230:231], off
	s_waitcnt lgkmcnt(8)
	s_barrier
; #define LDA8(dst, b, h) _Pragma("unroll") for (int m = 0; m < 4; ++m) _Pragma("unroll") for (int k = 0; k < 2; ++k) \
;     dst[m][k] = *(const bf16x8*)((const char*)SA8(b, h) + lds_byte8(wr * 64 + m * 16 + fr, k * 32 + fq * 8))
; #define LDB8(dst, b, h) _Pragma("unroll") for (int n = 0; n < 2; ++n) _Pragma("unroll") for (int k = 0; k < 2; ++k) \
;     dst[n][k] = *(const bf16x8*)((const char*)SB8(b, h) + lds_byte8(wc * 32 + n * 16 + fr, k * 32 + fq * 8))
; #define WAIT_V8(n) asm volatile("s_waitcnt vmcnt(" #n ")" ::: "memory")
; #define WAIT_L8(n) asm volatile("s_waitcnt lgkmcnt(" #n ")" ::: "memory")
; #define BAR8 __builtin_amdgcn_s_barrier()
; #define SCHED8 __builtin_amdgcn_sched_barrier(0)
;     ...
;     WAIT_L8(8); BAR8; WAIT_L8(0); MMA8(0, 0, At, B0); BAR8; SCHED8;
;     LDB8(B1, 1, 1); STAGE8(SB8(1, 0), Bt, K, bcol, tt + 3);
;     BAR8; WAIT_L8(0); MMA8(0, 1, At, B1); BAR8;
;     LDA8(At, 1, 1); STAGE8(SA8(1, 0), A, lda, brow, tt + 3);
;     BAR8; WAIT_L8(0); MMA8(1, 0, At, B0); BAR8; SCHED8;
;     STAGE8(SB8(1, 1), Bt, K, bcol + 128, tt + 3);
;     WAIT_V8(6); BAR8; MMA8(1, 1, At, B1); BAR8;
	s_waitcnt lgkmcnt(0)
	v_mfma_f32_16x16x32_bf16 v[128:131], v[190:193], v[174:177], v[128:131]
	v_mfma_f32_16x16x32_bf16 v[124:127], v[190:193], v[182:185], v[124:127]
	v_mfma_f32_16x16x32_bf16 v[120:123], v[198:201], v[174:177], v[120:123]
	v_mfma_f32_16x16x32_bf16 v[116:119], v[198:201], v[182:185], v[116:119]
	v_mfma_f32_16x16x32_bf16 v[112:115], v[206:209], v[174:177], v[112:115]
	v_mfma_f32_16x16x32_bf16 v[108:111], v[206:209], v[182:185], v[108:111]
	v_mfma_f32_16x16x32_bf16 v[104:107], v[214:217], v[174:177], v[104:107]
	v_mfma_f32_16x16x32_bf16 v[100:103], v[214:217], v[182:185], v[100:103]
	v_mfma_f32_16x16x32_bf16 v[128:131], v[194:197], v[178:181], v[128:131]
	v_mfma_f32_16x16x32_bf16 v[124:127], v[194:197], v[186:189], v[124:127]
	v_mfma_f32_16x16x32_bf16 v[120:123], v[202:205], v[178:181], v[120:123]
	v_mfma_f32_16x16x32_bf16 v[116:119], v[202:205], v[186:189], v[116:119]
	v_mfma_f32_16x16x32_bf16 v[112:115], v[210:213], v[178:181], v[112:115]
	v_mfma_f32_16x16x32_bf16 v[108:111], v[210:213], v[186:189], v[108:111]
	v_mfma_f32_16x16x32_bf16 v[104:107], v[218:221], v[178:181], v[104:107]
	v_mfma_f32_16x16x32_bf16 v[100:103], v[218:221], v[186:189], v[100:103]
	s_barrier
	v_lshl_add_u64 v[250:251], v[228:229], 0, s[46:47]
	s_or_b32 m0, s100, 0x18000
	ds_read_b128 v[230:233], v158
	ds_read_b128 v[238:241], v158 offset:1024
	ds_read_b128 v[242:245], v158 offset:2048
	ds_read_b128 v[246:249], v158 offset:3072
	global_load_lds_dwordx4 v[250:251], off
	v_lshl_add_u64 v[250:251], v[236:237], 0, s[46:47]
	s_or_b32 m0, s100, 0x1a000
	s_nop 0
	global_load_lds_dwordx4 v[250:251], off
	s_barrier
	s_waitcnt lgkmcnt(0)
	v_mfma_f32_16x16x32_bf16 v[96:99], v[190:193], v[230:233], v[96:99]
	v_mfma_f32_16x16x32_bf16 v[92:95], v[190:193], v[242:245], v[92:95]
	v_mfma_f32_16x16x32_bf16 v[88:91], v[198:201], v[230:233], v[88:91]
	v_mfma_f32_16x16x32_bf16 v[84:87], v[198:201], v[242:245], v[84:87]
	v_mfma_f32_16x16x32_bf16 v[80:83], v[206:209], v[230:233], v[80:83]
	v_mfma_f32_16x16x32_bf16 v[76:79], v[206:209], v[242:245], v[76:79]
	v_mfma_f32_16x16x32_bf16 v[72:75], v[214:217], v[230:233], v[72:75]
	v_mfma_f32_16x16x32_bf16 v[68:71], v[214:217], v[242:245], v[68:71]
	v_mfma_f32_16x16x32_bf16 v[96:99], v[194:197], v[238:241], v[96:99]
	v_mfma_f32_16x16x32_bf16 v[92:95], v[194:197], v[246:249], v[92:95]
	v_mfma_f32_16x16x32_bf16 v[88:91], v[202:205], v[238:241], v[88:91]
	v_mfma_f32_16x16x32_bf16 v[84:87], v[202:205], v[246:249], v[84:87]
	v_mfma_f32_16x16x32_bf16 v[80:83], v[210:213], v[238:241], v[80:83]
	v_mfma_f32_16x16x32_bf16 v[76:79], v[210:213], v[246:249], v[76:79]
	v_mfma_f32_16x16x32_bf16 v[72:75], v[218:221], v[238:241], v[72:75]
	v_mfma_f32_16x16x32_bf16 v[68:71], v[218:221], v[246:249], v[68:71]
	v_lshl_add_u64 v[222:223], v[222:223], 0, s[48:49]
	s_or_b32 m0, s100, 0x8000
	s_barrier
	ds_read_b128 v[190:193], v156 offset:49152
	ds_read_b128 v[194:197], v156 offset:50176
	ds_read_b128 v[198:201], v155 offset:49152
	ds_read_b128 v[202:205], v155 offset:50176
	ds_read_b128 v[206:209], v154 offset:49152
	ds_read_b128 v[210:213], v154 offset:50176
	ds_read_b128 v[214:217], v153 offset:49152
	ds_read_b128 v[218:221], v153 offset:50176
	global_load_lds_dwordx4 v[222:223], off
	v_lshl_add_u64 v[222:223], v[226:227], 0, s[48:49]
	s_or_b32 m0, s100, 0xa000
	s_nop 0
	global_load_lds_dwordx4 v[222:223], off
	s_barrier
	s_waitcnt lgkmcnt(0)
	v_mfma_f32_16x16x32_bf16 v[64:67], v[190:193], v[174:177], v[64:67]
	v_mfma_f32_16x16x32_bf16 v[60:63], v[190:193], v[182:185], v[60:63]
	v_mfma_f32_16x16x32_bf16 v[56:59], v[198:201], v[174:177], v[56:59]
	v_mfma_f32_16x16x32_bf16 v[52:55], v[198:201], v[182:185], v[52:55]
	v_mfma_f32_16x16x32_bf16 v[48:51], v[206:209], v[174:177], v[48:51]
	v_mfma_f32_16x16x32_bf16 v[44:47], v[206:209], v[182:185], v[44:47]
	v_mfma_f32_16x16x32_bf16 v[40:43], v[214:217], v[174:177], v[40:43]
	v_mfma_f32_16x16x32_bf16 v[36:39], v[214:217], v[182:185], v[36:39]
	v_mfma_f32_16x16x32_bf16 v[64:67], v[194:197], v[178:181], v[64:67]
	v_mfma_f32_16x16x32_bf16 v[60:63], v[194:197], v[186:189], v[60:63]
	v_mfma_f32_16x16x32_bf16 v[56:59], v[202:205], v[178:181], v[56:59]
	v_mfma_f32_16x16x32_bf16 v[52:55], v[202:205], v[186:189], v[52:55]
	v_mfma_f32_16x16x32_bf16 v[48:51], v[210:213], v[178:181], v[48:51]
	v_mfma_f32_16x16x32_bf16 v[44:47], v[210:213], v[186:189], v[44:47]
	v_mfma_f32_16x16x32_bf16 v[40:43], v[218:221], v[178:181], v[40:43]
	v_mfma_f32_16x16x32_bf16 v[36:39], v[218:221], v[186:189], v[36:39]
	s_barrier
	v_lshl_add_u64 v[174:175], v[228:229], 0, s[50:51]
	s_or_b32 m0, s100, 0x1c000
	s_nop 0
	global_load_lds_dwordx4 v[174:175], off
	v_lshl_add_u64 v[174:175], v[236:237], 0, s[50:51]
	s_or_b32 m0, s100, 0x1e000
	s_nop 0
	global_load_lds_dwordx4 v[174:175], off
	s_waitcnt vmcnt(6)
	s_barrier
	v_mfma_f32_16x16x32_bf16 v[32:35], v[190:193], v[230:233], v[32:35]
	v_mfma_f32_16x16x32_bf16 v[28:31], v[190:193], v[242:245], v[28:31]
	v_mfma_f32_16x16x32_bf16 v[24:27], v[198:201], v[230:233], v[24:27]
	v_mfma_f32_16x16x32_bf16 v[20:23], v[198:201], v[242:245], v[20:23]
	v_mfma_f32_16x16x32_bf16 v[16:19], v[206:209], v[230:233], v[16:19]
	v_mfma_f32_16x16x32_bf16 v[12:15], v[206:209], v[242:245], v[12:15]
	v_mfma_f32_16x16x32_bf16 v[8:11], v[214:217], v[230:233], v[8:11]
	v_mfma_f32_16x16x32_bf16 v[4:7], v[214:217], v[242:245], v[4:7]
	v_mfma_f32_16x16x32_bf16 v[32:35], v[194:197], v[238:241], v[32:35]
	v_mfma_f32_16x16x32_bf16 v[28:31], v[194:197], v[246:249], v[28:31]
	v_mfma_f32_16x16x32_bf16 v[24:27], v[202:205], v[238:241], v[24:27]
	v_mfma_f32_16x16x32_bf16 v[20:23], v[202:205], v[246:249], v[20:23]
	v_mfma_f32_16x16x32_bf16 v[16:19], v[210:213], v[238:241], v[16:19]
	v_mfma_f32_16x16x32_bf16 v[12:15], v[210:213], v[246:249], v[12:15]
	v_mfma_f32_16x16x32_bf16 v[8:11], v[218:221], v[238:241], v[8:11]
	v_mfma_f32_16x16x32_bf16 v[4:7], v[218:221], v[246:249], v[4:7]
	s_add_i32 s29, s29, 2
	s_add_u32 s12, s12, 0x100
	s_addc_u32 s13, s13, 0
	s_cmp_lt_u32 s29, 12
	s_barrier
	s_cbranch_scc0 .Lpk_exit_2

; #define LDA8(dst, b, h) _Pragma("unroll") for (int m = 0; m < 4; ++m) _Pragma("unroll") for (int k = 0; k < 2; ++k) \
;     dst[m][k] = *(const bf16x8*)((const char*)SA8(b, h) + lds_byte8(wr * 64 + m * 16 + fr, k * 32 + fq * 8))
; #define LDB8(dst, b, h) _Pragma("unroll") for (int n = 0; n < 2; ++n) _Pragma("unroll") for (int k = 0; k < 2; ++k) \
;     dst[n][k] = *(const bf16x8*)((const char*)SB8(b, h) + lds_byte8(wc * 32 + n * 16 + fr, k * 32 + fq * 8))
; #define WAIT_V8(n) asm volatile("s_waitcnt vmcnt(" #n ")" ::: "memory")
; #define WAIT_L8(n) asm volatile("s_waitcnt lgkmcnt(" #n ")" ::: "memory")
; #define BAR8 __builtin_amdgcn_s_barrier()
;     ...
;   { LDB8(B0, 0, 0); LDA8(At, 0, 0); STAGE8(SA8(1, 1), A, lda, brow + 128, nt - 1);
;     BAR8; WAIT_L8(0); MMA8(0, 0, At, B0); BAR8;
;     LDB8(B1, 0, 1); BAR8; WAIT_L8(0); MMA8(0, 1, At, B1); BAR8;
;     LDA8(At, 0, 1); WAIT_V8(4); BAR8; WAIT_L8(0); MMA8(1, 0, At, B0); MMA8(1, 1, At, B1); BAR8; }
.Lpk_exit_2:
	s_add_u32 s2, s2, s27
	s_addc_u32 s3, s3, 0
	s_add_u32 s2, s2, 0x6000780
	s_addc_u32 s3, s3, 0
	v_lshl_add_u64 v[136:137], v[136:137], 1, s[2:3]
	v_lshl_add_u64 v[0:1], v[0:1], 1, v[136:137]
	s_or_b32 m0, s100, 0xc000
	ds_read_b128 v[138:141], v171
	ds_read_b128 v[142:145], v171 offset:1024
	ds_read_b128 v[162:165], v171 offset:2048
	ds_read_b128 v[168:171], v171 offset:3072
	ds_read_b128 v[174:177], v156
	ds_read_b128 v[178:181], v156 offset:1024
	ds_read_b128 v[182:185], v155
	ds_read_b128 v[186:189], v155 offset:1024
	ds_read_b128 v[190:193], v154
	ds_read_b128 v[194:197], v154 offset:1024
	ds_read_b128 v[198:201], v153
	ds_read_b128 v[202:205], v153 offset:1024
	global_load_lds_dwordx4 v[0:1], off
	v_lshl_add_u64 v[0:1], v[134:135], 1, s[2:3]
	v_lshl_add_u64 v[0:1], v[132:133], 1, v[0:1]
	s_or_b32 m0, s100, 0xe000
	s_nop 0
	global_load_lds_dwordx4 v[0:1], off
	s_barrier
	s_waitcnt lgkmcnt(0)
	v_mfma_f32_16x16x32_bf16 v[128:131], v[174:177], v[138:141], v[128:131]
	v_mfma_f32_16x16x32_bf16 v[124:127], v[174:177], v[162:165], v[124:127]
	v_mfma_f32_16x16x32_bf16 v[120:123], v[182:185], v[138:141], v[120:123]
	v_mfma_f32_16x16x32_bf16 v[112:115], v[190:193], v[138:141], v[112:115]
	v_mfma_f32_16x16x32_bf16 v[128:131], v[178:181], v[142:145], v[128:131]
	v_mfma_f32_16x16x32_bf16 v[124:127], v[178:181], v[168:171], v[124:127]
	v_mfma_f32_16x16x32_bf16 v[120:123], v[186:189], v[142:145], v[120:123]
	v_mfma_f32_16x16x32_bf16 v[116:119], v[182:185], v[162:165], v[116:119]
	v_mfma_f32_16x16x32_bf16 v[112:115], v[194:197], v[142:145], v[112:115]
	v_mfma_f32_16x16x32_bf16 v[108:111], v[190:193], v[162:165], v[108:111]
	v_mfma_f32_16x16x32_bf16 v[104:107], v[198:201], v[138:141], v[104:107]
	v_mfma_f32_16x16x32_bf16 v[100:103], v[198:201], v[162:165], v[100:103]
	v_mfma_f32_16x16x32_bf16 v[132:135], v[186:189], v[168:171], v[116:119]
	v_mfma_f32_16x16x32_bf16 v[206:209], v[194:197], v[168:171], v[108:111]
	v_mfma_f32_16x16x32_bf16 v[210:213], v[202:205], v[142:145], v[104:107]
	v_mfma_f32_16x16x32_bf16 v[214:217], v[202:205], v[168:171], v[100:103]
	s_barrier
	s_nop 1
	ds_read_b128 v[100:103], v167
	ds_read_b128 v[104:107], v167 offset:1024
	ds_read_b128 v[108:111], v167 offset:2048
	ds_read_b128 v[116:119], v167 offset:3072
	s_barrier
	s_waitcnt lgkmcnt(0)
	v_mfma_f32_16x16x32_bf16 v[80:83], v[190:193], v[100:103], v[80:83]
	v_mfma_f32_16x16x32_bf16 v[76:79], v[190:193], v[108:111], v[76:79]
	v_mfma_f32_16x16x32_bf16 v[72:75], v[198:201], v[100:103], v[72:75]
	v_mfma_f32_16x16x32_bf16 v[68:71], v[198:201], v[108:111], v[68:71]
	v_mfma_f32_16x16x32_bf16 v[96:99], v[174:177], v[100:103], v[96:99]
	v_mfma_f32_16x16x32_bf16 v[92:95], v[174:177], v[108:111], v[92:95]
	v_mfma_f32_16x16x32_bf16 v[88:91], v[182:185], v[100:103], v[88:91]
	v_mfma_f32_16x16x32_bf16 v[84:87], v[182:185], v[108:111], v[84:87]
	v_mfma_f32_16x16x32_bf16 v[80:83], v[194:197], v[104:107], v[80:83]
	v_mfma_f32_16x16x32_bf16 v[76:79], v[194:197], v[116:119], v[76:79]
	v_mfma_f32_16x16x32_bf16 v[72:75], v[202:205], v[104:107], v[72:75]
	v_mfma_f32_16x16x32_bf16 v[68:71], v[202:205], v[116:119], v[68:71]
	v_mfma_f32_16x16x32_bf16 v[218:221], v[178:181], v[104:107], v[96:99]
	v_mfma_f32_16x16x32_bf16 v[172:175], v[178:181], v[116:119], v[92:95]
	v_mfma_f32_16x16x32_bf16 v[176:179], v[186:189], v[104:107], v[88:91]
	v_mfma_f32_16x16x32_bf16 v[180:183], v[186:189], v[116:119], v[84:87]
	s_barrier
	s_nop 0
	ds_read_b128 v[84:87], v156 offset:16384
	ds_read_b128 v[88:91], v156 offset:17408
	ds_read_b128 v[92:95], v155 offset:16384
	ds_read_b128 v[96:99], v155 offset:17408
	ds_read_b128 v[184:187], v154 offset:16384
	ds_read_b128 v[188:191], v154 offset:17408
	ds_read_b128 v[192:195], v153 offset:16384
	ds_read_b128 v[196:199], v153 offset:17408
	s_waitcnt vmcnt(4)
	s_barrier
	s_waitcnt lgkmcnt(0)
	v_mfma_f32_16x16x32_bf16 v[64:67], v[84:87], v[138:141], v[64:67]
	v_mfma_f32_16x16x32_bf16 v[60:63], v[84:87], v[162:165], v[60:63]
	v_mfma_f32_16x16x32_bf16 v[56:59], v[92:95], v[138:141], v[56:59]
	v_mfma_f32_16x16x32_bf16 v[52:55], v[92:95], v[162:165], v[52:55]
	v_mfma_f32_16x16x32_bf16 v[48:51], v[184:187], v[138:141], v[48:51]
	v_mfma_f32_16x16x32_bf16 v[44:47], v[184:187], v[162:165], v[44:47]
	v_mfma_f32_16x16x32_bf16 v[40:43], v[192:195], v[138:141], v[40:43]
	v_mfma_f32_16x16x32_bf16 v[36:39], v[192:195], v[162:165], v[36:39]
	v_mfma_f32_16x16x32_bf16 v[64:67], v[88:91], v[142:145], v[64:67]
	v_mfma_f32_16x16x32_bf16 v[60:63], v[88:91], v[168:171], v[60:63]
	v_mfma_f32_16x16x32_bf16 v[56:59], v[96:99], v[142:145], v[56:59]
	v_mfma_f32_16x16x32_bf16 v[52:55], v[96:99], v[168:171], v[52:55]
	v_mfma_f32_16x16x32_bf16 v[48:51], v[188:191], v[142:145], v[48:51]
	v_mfma_f32_16x16x32_bf16 v[44:47], v[188:191], v[168:171], v[44:47]
	v_mfma_f32_16x16x32_bf16 v[40:43], v[196:199], v[142:145], v[40:43]
	v_mfma_f32_16x16x32_bf16 v[36:39], v[196:199], v[168:171], v[36:39]
	v_mfma_f32_16x16x32_bf16 v[32:35], v[84:87], v[100:103], v[32:35]
	v_mfma_f32_16x16x32_bf16 v[28:31], v[84:87], v[108:111], v[28:31]
	v_mfma_f32_16x16x32_bf16 v[24:27], v[92:95], v[100:103], v[24:27]
	v_mfma_f32_16x16x32_bf16 v[20:23], v[92:95], v[108:111], v[20:23]
	v_mfma_f32_16x16x32_bf16 v[16:19], v[184:187], v[100:103], v[16:19]
	v_mfma_f32_16x16x32_bf16 v[12:15], v[184:187], v[108:111], v[12:15]
	v_mfma_f32_16x16x32_bf16 v[8:11], v[192:195], v[100:103], v[8:11]
	v_mfma_f32_16x16x32_bf16 v[4:7], v[192:195], v[108:111], v[4:7]
	v_mfma_f32_16x16x32_bf16 v[136:139], v[88:91], v[104:107], v[32:35]
	v_mfma_f32_16x16x32_bf16 v[140:143], v[88:91], v[116:119], v[28:31]
	v_mfma_f32_16x16x32_bf16 v[162:165], v[96:99], v[104:107], v[24:27]
	v_mfma_f32_16x16x32_bf16 v[166:169], v[96:99], v[116:119], v[20:23]
	v_mfma_f32_16x16x32_bf16 v[200:203], v[188:191], v[104:107], v[16:19]
	v_mfma_f32_16x16x32_bf16 v[184:187], v[188:191], v[116:119], v[12:15]
	v_mfma_f32_16x16x32_bf16 v[188:191], v[196:199], v[104:107], v[8:11]
	v_mfma_f32_16x16x32_bf16 v[192:195], v[196:199], v[116:119], v[4:7]
	s_barrier
; #define LDA8(dst, b, h) _Pragma("unroll") for (int m = 0; m < 4; ++m) _Pragma("unroll") for (int k = 0; k < 2; ++k) \
;     dst[m][k] = *(const bf16x8*)((const char*)SA8(b, h) + lds_byte8(wr * 64 + m * 16 + fr, k * 32 + fq * 8))
; #define LDB8(dst, b, h) _Pragma("unroll") for (int n = 0; n < 2; ++n) _Pragma("unroll") for (int k = 0; k < 2; ++k) \
;     dst[n][k] = *(const bf16x8*)((const char*)SB8(b, h) + lds_byte8(wc * 32 + n * 16 + fr, k * 32 + fq * 8))
; #define WAIT_V8(n) asm volatile("s_waitcnt vmcnt(" #n ")" ::: "memory")
; #define WAIT_L8(n) asm volatile("s_waitcnt lgkmcnt(" #n ")" ::: "memory")
; #define BAR8 __builtin_amdgcn_s_barrier()
;     ...
;   { LDB8(B0, 1, 0); LDA8(At, 1, 0); WAIT_V8(2); BAR8; WAIT_L8(0); MMA8(0, 0, At, B0); BAR8;
;     LDB8(B1, 1, 1); WAIT_V8(0); BAR8; WAIT_L8(0); MMA8(0, 1, At, B1); BAR8;
;     LDA8(At, 1, 1); BAR8; WAIT_L8(0); MMA8(1, 0, At, B0); MMA8(1, 1, At, B1); BAR8; }
;   if (wr == 0) BAR8;
;   __syncthreads();
;     ...
;   if (t < 256) {
	ds_read_b128 v[196:199], v160
	ds_read_b128 v[230:233], v160 offset:1024
	ds_read_b128 v[238:241], v160 offset:2048
	ds_read_b128 v[242:245], v160 offset:3072
	ds_read_b128 v[8:11], v156 offset:32768
	ds_read_b128 v[12:15], v156 offset:33792
	ds_read_b128 v[16:19], v155 offset:32768
	ds_read_b128 v[24:27], v155 offset:33792
	ds_read_b128 v[28:31], v154 offset:32768
	ds_read_b128 v[32:35], v154 offset:33792
	ds_read_b128 v[246:249], v153 offset:32768
	ds_read_b128 v[226:229], v153 offset:33792
	s_waitcnt vmcnt(2)
	s_barrier
	s_waitcnt lgkmcnt(0)
	v_mfma_f32_16x16x32_bf16 v[4:7], v[8:11], v[196:199], v[128:131]
	v_mfma_f32_16x16x32_bf16 v[104:107], v[12:15], v[230:233], v[4:7]
	v_mfma_f32_16x16x32_bf16 v[4:7], v[8:11], v[238:241], v[124:127]
	v_mfma_f32_16x16x32_bf16 v[116:119], v[12:15], v[242:245], v[4:7]
	v_mfma_f32_16x16x32_bf16 v[4:7], v[16:19], v[196:199], v[120:123]
	v_mfma_f32_16x16x32_bf16 v[100:103], v[24:27], v[230:233], v[4:7]
	v_mfma_f32_16x16x32_bf16 v[4:7], v[16:19], v[238:241], v[132:135]
	v_mfma_f32_16x16x32_bf16 v[108:111], v[24:27], v[242:245], v[4:7]
	v_mfma_f32_16x16x32_bf16 v[4:7], v[28:31], v[196:199], v[112:115]
	v_mfma_f32_16x16x32_bf16 v[92:95], v[32:35], v[230:233], v[4:7]
	v_mfma_f32_16x16x32_bf16 v[4:7], v[28:31], v[238:241], v[206:209]
	v_mfma_f32_16x16x32_bf16 v[96:99], v[32:35], v[242:245], v[4:7]
	v_mfma_f32_16x16x32_bf16 v[4:7], v[246:249], v[196:199], v[210:213]
	v_mfma_f32_16x16x32_bf16 v[84:87], v[226:229], v[230:233], v[4:7]
	v_mfma_f32_16x16x32_bf16 v[4:7], v[246:249], v[238:241], v[214:217]
	v_mfma_f32_16x16x32_bf16 v[88:91], v[226:229], v[242:245], v[4:7]
	s_barrier
	ds_read_b128 v[132:135], v158
	ds_read_b128 v[204:207], v158 offset:1024
	ds_read_b128 v[208:211], v158 offset:2048
	ds_read_b128 v[158:161], v158 offset:3072
	s_waitcnt vmcnt(0)
	s_barrier
	s_waitcnt lgkmcnt(0)
	v_mfma_f32_16x16x32_bf16 v[4:7], v[8:11], v[132:135], v[218:221]
	v_mfma_f32_16x16x32_bf16 v[8:11], v[8:11], v[208:211], v[172:175]
	v_mfma_f32_16x16x32_bf16 v[4:7], v[12:15], v[204:207], v[4:7]
	v_mfma_f32_16x16x32_bf16 v[20:23], v[12:15], v[158:161], v[8:11]
	v_mfma_f32_16x16x32_bf16 v[8:11], v[16:19], v[132:135], v[176:179]
	v_mfma_f32_16x16x32_bf16 v[12:15], v[16:19], v[208:211], v[180:183]
	v_mfma_f32_16x16x32_bf16 v[8:11], v[24:27], v[204:207], v[8:11]
	v_mfma_f32_16x16x32_bf16 v[24:27], v[24:27], v[158:161], v[12:15]
	v_mfma_f32_16x16x32_bf16 v[12:15], v[28:31], v[132:135], v[80:83]
	v_mfma_f32_16x16x32_bf16 v[16:19], v[28:31], v[208:211], v[76:79]
	v_mfma_f32_16x16x32_bf16 v[12:15], v[32:35], v[204:207], v[12:15]
	v_mfma_f32_16x16x32_bf16 v[28:31], v[32:35], v[158:161], v[16:19]
	v_mfma_f32_16x16x32_bf16 v[16:19], v[246:249], v[132:135], v[72:75]
	v_mfma_f32_16x16x32_bf16 v[32:35], v[246:249], v[208:211], v[68:71]
	v_mfma_f32_16x16x32_bf16 v[16:19], v[226:229], v[204:207], v[16:19]
	v_mfma_f32_16x16x32_bf16 v[32:35], v[226:229], v[158:161], v[32:35]
	s_barrier
	ds_read_b128 v[170:173], v156 offset:49152
	ds_read_b128 v[174:177], v156 offset:50176
	ds_read_b128 v[178:181], v155 offset:49152
	ds_read_b128 v[212:215], v155 offset:50176
	ds_read_b128 v[216:219], v154 offset:49152
	ds_read_b128 v[154:157], v154 offset:50176
	ds_read_b128 v[220:223], v153 offset:49152
	ds_read_b128 v[150:153], v153 offset:50176
	s_barrier
	s_waitcnt lgkmcnt(0)
	v_mfma_f32_16x16x32_bf16 v[64:67], v[170:173], v[196:199], v[64:67]
	v_mfma_f32_16x16x32_bf16 v[60:63], v[170:173], v[238:241], v[60:63]
	v_mfma_f32_16x16x32_bf16 v[56:59], v[178:181], v[196:199], v[56:59]
	v_mfma_f32_16x16x32_bf16 v[52:55], v[178:181], v[238:241], v[52:55]
	v_mfma_f32_16x16x32_bf16 v[48:51], v[216:219], v[196:199], v[48:51]
	v_mfma_f32_16x16x32_bf16 v[44:47], v[216:219], v[238:241], v[44:47]
	v_mfma_f32_16x16x32_bf16 v[40:43], v[220:223], v[196:199], v[40:43]
	v_mfma_f32_16x16x32_bf16 v[36:39], v[220:223], v[238:241], v[36:39]
	v_mfma_f32_16x16x32_bf16 v[128:131], v[174:177], v[230:233], v[64:67]
	v_mfma_f32_16x16x32_bf16 v[124:127], v[174:177], v[242:245], v[60:63]
	v_mfma_f32_16x16x32_bf16 v[120:123], v[212:215], v[230:233], v[56:59]
	v_mfma_f32_16x16x32_bf16 v[112:115], v[212:215], v[242:245], v[52:55]
	v_mfma_f32_16x16x32_bf16 v[80:83], v[154:157], v[230:233], v[48:51]
	v_mfma_f32_16x16x32_bf16 v[76:79], v[154:157], v[242:245], v[44:47]
	v_mfma_f32_16x16x32_bf16 v[72:75], v[150:153], v[230:233], v[40:43]
	v_mfma_f32_16x16x32_bf16 v[68:71], v[150:153], v[242:245], v[36:39]
	v_mfma_f32_16x16x32_bf16 v[40:43], v[170:173], v[208:211], v[140:143]
	v_mfma_f32_16x16x32_bf16 v[44:47], v[178:181], v[208:211], v[166:169]
	v_mfma_f32_16x16x32_bf16 v[48:51], v[216:219], v[208:211], v[184:187]
	v_mfma_f32_16x16x32_bf16 v[36:39], v[170:173], v[132:135], v[136:139]
	v_mfma_f32_16x16x32_bf16 v[52:55], v[174:177], v[158:161], v[40:43]
	v_mfma_f32_16x16x32_bf16 v[40:43], v[178:181], v[132:135], v[162:165]
	v_mfma_f32_16x16x32_bf16 v[56:59], v[212:215], v[158:161], v[44:47]
	v_mfma_f32_16x16x32_bf16 v[44:47], v[216:219], v[132:135], v[200:203]
	v_mfma_f32_16x16x32_bf16 v[60:63], v[154:157], v[158:161], v[48:51]
	v_mfma_f32_16x16x32_bf16 v[48:51], v[220:223], v[132:135], v[188:191]
	v_mfma_f32_16x16x32_bf16 v[64:67], v[220:223], v[208:211], v[192:195]
	v_mfma_f32_16x16x32_bf16 v[36:39], v[174:177], v[204:207], v[36:39]
	v_mfma_f32_16x16x32_bf16 v[40:43], v[212:215], v[204:207], v[40:43]
	v_mfma_f32_16x16x32_bf16 v[44:47], v[154:157], v[204:207], v[44:47]
	v_mfma_f32_16x16x32_bf16 v[48:51], v[150:153], v[204:207], v[48:51]
	v_mfma_f32_16x16x32_bf16 v[64:67], v[150:153], v[158:161], v[64:67]
	s_movk_i32 s2, 0x100
	v_cmp_gt_u32_e32 vcc, s2, v3
	s_barrier
	s_and_saveexec_b64 s[2:3], vcc
	s_cbranch_execz .LBB0_911
	s_barrier

; #define LDA8(dst, b, h) _Pragma("unroll") for (int m = 0; m < 4; ++m) _Pragma("unroll") for (int k = 0; k < 2; ++k) \
;     dst[m][k] = *(const bf16x8*)((const char*)SA8(b, h) + lds_byte8(wr * 64 + m * 16 + fr, k * 32 + fq * 8))
; #define LDB8(dst, b, h) _Pragma("unroll") for (int n = 0; n < 2; ++n) _Pragma("unroll") for (int k = 0; k < 2; ++k) \
;     dst[n][k] = *(const bf16x8*)((const char*)SB8(b, h) + lds_byte8(wc * 32 + n * 16 + fr, k * 32 + fq * 8))
; #define WAIT_V8(n) asm volatile("s_waitcnt vmcnt(" #n ")" ::: "memory")
; #define WAIT_L8(n) asm volatile("s_waitcnt lgkmcnt(" #n ")" ::: "memory")
; #define BAR8 __builtin_amdgcn_s_barrier()
; #define SCHED8 __builtin_amdgcn_sched_barrier(0)
;     ...
;   const int brow = m0, bcol = n0;
;   const int wid = t >> 6, lane = t & 63, wr = wid >> 2, wc = wid & 3, fr = lane & 15, fq = lane >> 4;
;   f32x4 acc[2][2][4][2];
;   {
;     float zinit = 0.f;
;     asm volatile("" : "+v"(zinit));
; #pragma unroll
;     for (int a = 0; a < 2; ++a)
; #pragma unroll
;       for (int b = 0; b < 2; ++b)
; #pragma unroll
;         for (int m = 0; m < 4; ++m)
; #pragma unroll
;           for (int n = 0; n < 2; ++n)
; #pragma unroll
;             for (int j = 0; j < 4; ++j) acc[a][b][m][n][j] = zinit;
;   }
;   bf16x8 At[4][2], B0[2][2], B1[2][2];
;   const int nt = K / 64;
;   if (!pre) {
;     STAGE8(SB8(0, 0), Bt, K, bcol, 0); STAGE8(SA8(0, 0), A, lda, brow, 0);
;     STAGE8(SB8(0, 1), Bt, K, bcol + 128, 0); STAGE8(SA8(0, 1), A, lda, brow + 128, 0);
;   }
;   if (wr == 1) BAR8;
;   WAIT_V8(4); BAR8;
;   STAGE8(SB8(1, 0), Bt, K, bcol, 1); STAGE8(SA8(1, 0), A, lda, brow, 1); STAGE8(SB8(1, 1), Bt, K, bcol + 128, 1);
;   WAIT_V8(6); BAR8;
;   for (int tt = 0; tt < nt - 2; tt += 2) {
;     LDB8(B0, 0, 0); SCHED8; LDA8(At, 0, 0); STAGE8(SA8(1, 1), A, lda, brow + 128, tt + 1);
;     WAIT_L8(8); BAR8; WAIT_L8(0); MMA8(0, 0, At, B0); BAR8; SCHED8;
;     LDB8(B1, 0, 1); STAGE8(SB8(0, 0), Bt, K, bcol, tt + 2);
.LBB0_1004:
	s_or_b64 exec, exec, s[20:21]
	v_readlane_b32 s40, v254, 35
	s_lshl_b32 s20, s36, 10
	v_readlane_b32 s42, v254, 37
	v_readlane_b32 s43, v254, 38
	s_waitcnt vmcnt(0)
	s_and_b32 s20, s20, 0xfffc0000
	s_mov_b32 s21, s40
	s_mov_b64 s[42:43], 0x80
	s_and_b32 s1, s27, 7
	s_add_i32 s20, s20, 0xffc00000
	v_lshl_add_u64 v[10:11], v[10:11], 0, s[42:43]
	s_or_b32 m0, s100, 0x18000
	s_lshl_b32 s1, s1, 19
	s_lshl_b64 s[20:21], s[20:21], 1
	s_waitcnt vmcnt(4)
	s_barrier
	global_load_lds_dwordx4 v[10:11], off
	v_lshl_add_u64 v[10:11], v[12:13], 0, s[42:43]
	s_or_b32 m0, s100, 0x1a000
	global_load_lds_dwordx4 v[10:11], off
	v_lshl_add_u64 v[10:11], v[16:17], 0, s[42:43]
	s_or_b32 m0, s100, 0x8000
	s_add_u32 s14, s14, 0x40080
	global_load_lds_dwordx4 v[10:11], off
	v_lshl_add_u64 v[10:11], v[14:15], 0, s[42:43]
	s_addc_u32 s15, s15, 0
	s_or_b32 m0, s100, 0xa000
	global_load_lds_dwordx4 v[10:11], off
	v_lshl_add_u64 v[10:11], s[14:15], 0, v[132:133]
	v_lshl_add_u64 v[10:11], v[10:11], 0, v[6:7]
	s_or_b32 m0, s100, 0x1c000
	global_load_lds_dwordx4 v[10:11], off
	v_lshl_add_u64 v[10:11], s[14:15], 0, v[136:137]
	v_lshl_add_u64 v[10:11], v[10:11], 0, v[8:9]
	s_or_b32 m0, s100, 0x1e000
	v_and_b32_e32 v147, 15, v3
	global_load_lds_dwordx4 v[10:11], off
	v_bfe_u32 v148, v3, 4, 2
	v_lshlrev_b32_e32 v11, 4, v148
	v_lshlrev_b32_e32 v12, 6, v147
	v_lshlrev_b32_e32 v14, 2, v3
	v_or_b32_e32 v13, v11, v12
	v_and_b32_e32 v14, 32, v14
	s_mov_b32 s14, 0x10000
	v_bitop3_b32 v15, v13, s14, v14 bitop3:0xde
	s_mov_b32 s14, 0x14000
	s_add_u32 s12, s12, s1
	v_bitop3_b32 v16, v13, s14, v14 bitop3:0xde
	s_mov_b32 s14, 0x18000
	v_lshlrev_b32_e32 v18, 6, v3
	s_addc_u32 s13, s13, 0
	v_lshl_add_u64 v[8:9], v[136:137], 0, v[8:9]
	v_lshl_add_u64 v[6:7], v[132:133], 0, v[6:7]
	v_bfe_u32 v146, v3, 6, 2
	s_waitcnt vmcnt(6)
	v_lshlrev_b32_e32 v149, 6, v5
	v_bitop3_b32 v17, v13, s14, v14 bitop3:0xde
	s_mov_b32 s14, 0x1c000
	v_lshlrev_b32_e32 v5, 13, v5
	v_and_b32_e32 v18, 0x3c0, v18
	v_lshl_add_u64 v[138:139], s[12:13], 0, v[8:9]
	v_lshl_add_u64 v[140:141], s[12:13], 0, v[6:7]
	s_add_u32 s12, s4, s20
	v_readlane_b32 s41, v254, 36
	v_lshlrev_b32_e32 v10, 12, v146
	v_bitop3_b32 v12, v11, v14, v12 bitop3:0x36
	v_bitop3_b32 v13, v13, s14, v14 bitop3:0xde
	v_bitop3_b32 v11, v18, v14, v11 bitop3:0x36
	v_or_b32_e32 v14, 0x800, v5
	v_or_b32_e32 v18, 0x1000, v5
	v_or_b32_e32 v19, 0x1800, v5
	s_addc_u32 s13, s5, s21
	v_lshl_add_u64 v[142:143], s[12:13], 0, v[6:7]
	v_lshl_add_u64 v[144:145], s[12:13], 0, v[8:9]
	s_mov_b32 s1, -2
	s_mov_b64 s[12:13], 0
	v_add_u32_e32 v171, v15, v10
	v_add_u32_e32 v156, v12, v5
	v_add_u32_e32 v155, v11, v14
	v_add_u32_e32 v154, v11, v18
	v_add_u32_e32 v153, v11, v19
	v_add_u32_e32 v168, v16, v10
	v_add_u32_e32 v161, v17, v10
	v_add_u32_e32 v158, v13, v10
	s_mov_b64 s[20:21], 0xb840080
	s_mov_b64 s[40:41], 0xc7a0100
	s_mov_b64 s[42:43], 0xb800100
	s_mov_b64 s[44:45], 0xc7e0100
	s_mov_b64 s[46:47], 0xb840100
	s_mov_b64 s[48:49], 0xc7a0180
	s_mov_b64 s[50:51], 0xb800180
	s_mov_b64 s[52:53], 0xc7e0180
	s_barrier
	ds_read_b128 v[174:177], v171
	ds_read_b128 v[178:181], v171 offset:1024
	ds_read_b128 v[182:185], v171 offset:2048
	ds_read_b128 v[186:189], v171 offset:3072
	v_lshl_add_u64 v[222:223], v[140:141], 0, s[12:13]
	v_lshl_add_u64 v[226:227], v[222:223], 0, s[20:21]
	s_or_b32 m0, s100, 0xc000
	v_lshl_add_u64 v[236:237], v[138:139], 0, s[12:13]
	ds_read_b128 v[190:193], v156
	ds_read_b128 v[194:197], v156 offset:1024
	ds_read_b128 v[198:201], v155
	ds_read_b128 v[202:205], v155 offset:1024
	ds_read_b128 v[206:209], v154
	ds_read_b128 v[210:213], v154 offset:1024
	ds_read_b128 v[214:217], v153
	ds_read_b128 v[218:221], v153 offset:1024
	global_load_lds_dwordx4 v[226:227], off
	v_lshl_add_u64 v[226:227], v[236:237], 0, s[20:21]
	s_or_b32 m0, s100, 0xe000
	s_nop 0
	global_load_lds_dwordx4 v[226:227], off
	s_waitcnt lgkmcnt(8)
	s_barrier
	s_waitcnt lgkmcnt(0)
	v_mfma_f32_16x16x32_bf16 v[128:131], v[190:193], v[174:177], 0
	v_mfma_f32_16x16x32_bf16 v[124:127], v[190:193], v[182:185], 0
	v_mfma_f32_16x16x32_bf16 v[120:123], v[198:201], v[174:177], 0
	v_mfma_f32_16x16x32_bf16 v[116:119], v[198:201], v[182:185], 0
	v_mfma_f32_16x16x32_bf16 v[112:115], v[206:209], v[174:177], 0
	v_mfma_f32_16x16x32_bf16 v[108:111], v[206:209], v[182:185], 0
	v_mfma_f32_16x16x32_bf16 v[104:107], v[214:217], v[174:177], 0
	v_mfma_f32_16x16x32_bf16 v[100:103], v[214:217], v[182:185], 0
	v_mfma_f32_16x16x32_bf16 v[128:131], v[194:197], v[178:181], v[128:131]
	v_mfma_f32_16x16x32_bf16 v[124:127], v[194:197], v[186:189], v[124:127]
	v_mfma_f32_16x16x32_bf16 v[120:123], v[202:205], v[178:181], v[120:123]
	v_mfma_f32_16x16x32_bf16 v[116:119], v[202:205], v[186:189], v[116:119]
	v_mfma_f32_16x16x32_bf16 v[112:115], v[210:213], v[178:181], v[112:115]
	v_mfma_f32_16x16x32_bf16 v[108:111], v[210:213], v[186:189], v[108:111]
	v_mfma_f32_16x16x32_bf16 v[104:107], v[218:221], v[178:181], v[104:107]
	v_mfma_f32_16x16x32_bf16 v[100:103], v[218:221], v[186:189], v[100:103]
	s_barrier
	v_lshl_add_u64 v[246:247], v[142:143], 0, s[12:13]
	v_lshl_add_u64 v[248:249], v[246:247], 0, s[40:41]
	s_or_b32 m0, s100, 0x10000
	ds_read_b128 v[226:229], v168
	ds_read_b128 v[230:233], v168 offset:1024
	ds_read_b128 v[238:241], v168 offset:2048
	ds_read_b128 v[242:245], v168 offset:3072
	global_load_lds_dwordx4 v[248:249], off
	v_lshl_add_u64 v[248:249], v[144:145], 0, s[12:13]
	v_lshl_add_u64 v[250:251], v[248:249], 0, s[40:41]
	s_or_b32 m0, s100, 0x12000
	s_nop 0
	global_load_lds_dwordx4 v[250:251], off
	s_barrier
; #define LDA8(dst, b, h) _Pragma("unroll") for (int m = 0; m < 4; ++m) _Pragma("unroll") for (int k = 0; k < 2; ++k) \
;     dst[m][k] = *(const bf16x8*)((const char*)SA8(b, h) + lds_byte8(wr * 64 + m * 16 + fr, k * 32 + fq * 8))
; #define LDB8(dst, b, h) _Pragma("unroll") for (int n = 0; n < 2; ++n) _Pragma("unroll") for (int k = 0; k < 2; ++k) \
;     dst[n][k] = *(const bf16x8*)((const char*)SB8(b, h) + lds_byte8(wc * 32 + n * 16 + fr, k * 32 + fq * 8))
; #define WAIT_V8(n) asm volatile("s_waitcnt vmcnt(" #n ")" ::: "memory")
; #define WAIT_L8(n) asm volatile("s_waitcnt lgkmcnt(" #n ")" ::: "memory")
; #define BAR8 __builtin_amdgcn_s_barrier()
; #define SCHED8 __builtin_amdgcn_sched_barrier(0)
;     ...
;     WAIT_L8(8); BAR8; WAIT_L8(0); MMA8(0, 0, At, B0); BAR8; SCHED8;
;     LDB8(B1, 0, 1); STAGE8(SB8(0, 0), Bt, K, bcol, tt + 2);
;     BAR8; WAIT_L8(0); MMA8(0, 1, At, B1); BAR8;
;     LDA8(At, 0, 1); STAGE8(SA8(0, 0), A, lda, brow, tt + 2);
;     BAR8; WAIT_L8(0); MMA8(1, 0, At, B0); BAR8; SCHED8;
;     STAGE8(SB8(0, 1), Bt, K, bcol + 128, tt + 2);
;     WAIT_V8(6); BAR8; MMA8(1, 1, At, B1); BAR8;
;     LDB8(B0, 1, 0); SCHED8; LDA8(At, 1, 0); STAGE8(SA8(0, 1), A, lda, brow + 128, tt + 2);
;     WAIT_L8(8); BAR8; WAIT_L8(0); MMA8(0, 0, At, B0); BAR8; SCHED8;
	s_waitcnt lgkmcnt(0)
	v_mfma_f32_16x16x32_bf16 v[96:99], v[190:193], v[226:229], 0
	v_mfma_f32_16x16x32_bf16 v[92:95], v[190:193], v[238:241], 0
	v_mfma_f32_16x16x32_bf16 v[88:91], v[198:201], v[226:229], 0
	v_mfma_f32_16x16x32_bf16 v[84:87], v[198:201], v[238:241], 0
	v_mfma_f32_16x16x32_bf16 v[80:83], v[206:209], v[226:229], 0
	v_mfma_f32_16x16x32_bf16 v[76:79], v[206:209], v[238:241], 0
	v_mfma_f32_16x16x32_bf16 v[72:75], v[214:217], v[226:229], 0
	v_mfma_f32_16x16x32_bf16 v[68:71], v[214:217], v[238:241], 0
	v_mfma_f32_16x16x32_bf16 v[96:99], v[194:197], v[230:233], v[96:99]
	v_mfma_f32_16x16x32_bf16 v[92:95], v[194:197], v[242:245], v[92:95]
	v_mfma_f32_16x16x32_bf16 v[88:91], v[202:205], v[230:233], v[88:91]
	v_mfma_f32_16x16x32_bf16 v[84:87], v[202:205], v[242:245], v[84:87]
	v_mfma_f32_16x16x32_bf16 v[80:83], v[210:213], v[230:233], v[80:83]
	v_mfma_f32_16x16x32_bf16 v[76:79], v[210:213], v[242:245], v[76:79]
	v_mfma_f32_16x16x32_bf16 v[72:75], v[218:221], v[230:233], v[72:75]
	v_mfma_f32_16x16x32_bf16 v[68:71], v[218:221], v[242:245], v[68:71]
	v_lshl_add_u64 v[250:251], v[222:223], 0, s[42:43]
	s_mov_b32 m0, s100
	s_barrier
	ds_read_b128 v[190:193], v156 offset:16384
	ds_read_b128 v[194:197], v156 offset:17408
	ds_read_b128 v[198:201], v155 offset:16384
	ds_read_b128 v[202:205], v155 offset:17408
	ds_read_b128 v[206:209], v154 offset:16384
	ds_read_b128 v[210:213], v154 offset:17408
	ds_read_b128 v[214:217], v153 offset:16384
	ds_read_b128 v[218:221], v153 offset:17408
	global_load_lds_dwordx4 v[250:251], off
	v_lshl_add_u64 v[250:251], v[236:237], 0, s[42:43]
	s_or_b32 m0, s100, 0x2000
	s_nop 0
	global_load_lds_dwordx4 v[250:251], off
	s_barrier
	s_waitcnt lgkmcnt(0)
	v_mfma_f32_16x16x32_bf16 v[64:67], v[190:193], v[174:177], 0
	v_mfma_f32_16x16x32_bf16 v[60:63], v[190:193], v[182:185], 0
	v_mfma_f32_16x16x32_bf16 v[56:59], v[198:201], v[174:177], 0
	v_mfma_f32_16x16x32_bf16 v[52:55], v[198:201], v[182:185], 0
	v_mfma_f32_16x16x32_bf16 v[48:51], v[206:209], v[174:177], 0
	v_mfma_f32_16x16x32_bf16 v[44:47], v[206:209], v[182:185], 0
	v_mfma_f32_16x16x32_bf16 v[40:43], v[214:217], v[174:177], 0
	v_mfma_f32_16x16x32_bf16 v[36:39], v[214:217], v[182:185], 0
	v_mfma_f32_16x16x32_bf16 v[64:67], v[194:197], v[178:181], v[64:67]
	v_mfma_f32_16x16x32_bf16 v[60:63], v[194:197], v[186:189], v[60:63]
	v_mfma_f32_16x16x32_bf16 v[56:59], v[202:205], v[178:181], v[56:59]
	v_mfma_f32_16x16x32_bf16 v[52:55], v[202:205], v[186:189], v[52:55]
	v_mfma_f32_16x16x32_bf16 v[48:51], v[210:213], v[178:181], v[48:51]
	v_mfma_f32_16x16x32_bf16 v[44:47], v[210:213], v[186:189], v[44:47]
	v_mfma_f32_16x16x32_bf16 v[40:43], v[218:221], v[178:181], v[40:43]
	v_mfma_f32_16x16x32_bf16 v[36:39], v[218:221], v[186:189], v[36:39]
	s_barrier
	v_lshl_add_u64 v[174:175], v[246:247], 0, s[44:45]
	s_or_b32 m0, s100, 0x14000
	s_nop 0
	global_load_lds_dwordx4 v[174:175], off
	v_lshl_add_u64 v[174:175], v[248:249], 0, s[44:45]
	s_or_b32 m0, s100, 0x16000
	s_nop 0
	global_load_lds_dwordx4 v[174:175], off
	s_waitcnt vmcnt(6)
	s_barrier
	v_mfma_f32_16x16x32_bf16 v[32:35], v[190:193], v[226:229], 0
	v_mfma_f32_16x16x32_bf16 v[28:31], v[190:193], v[238:241], 0
	v_mfma_f32_16x16x32_bf16 v[24:27], v[198:201], v[226:229], 0
	v_mfma_f32_16x16x32_bf16 v[20:23], v[198:201], v[238:241], 0
	v_mfma_f32_16x16x32_bf16 v[16:19], v[206:209], v[226:229], 0
	v_mfma_f32_16x16x32_bf16 v[12:15], v[206:209], v[238:241], 0
	v_mfma_f32_16x16x32_bf16 v[8:11], v[214:217], v[226:229], 0
	v_mfma_f32_16x16x32_bf16 v[4:7], v[214:217], v[238:241], 0
	v_mfma_f32_16x16x32_bf16 v[32:35], v[194:197], v[230:233], v[32:35]
	v_mfma_f32_16x16x32_bf16 v[28:31], v[194:197], v[242:245], v[28:31]
	v_mfma_f32_16x16x32_bf16 v[24:27], v[202:205], v[230:233], v[24:27]
	v_mfma_f32_16x16x32_bf16 v[20:23], v[202:205], v[242:245], v[20:23]
	v_mfma_f32_16x16x32_bf16 v[16:19], v[210:213], v[230:233], v[16:19]
	v_mfma_f32_16x16x32_bf16 v[12:15], v[210:213], v[242:245], v[12:15]
	v_mfma_f32_16x16x32_bf16 v[8:11], v[218:221], v[230:233], v[8:11]
	v_mfma_f32_16x16x32_bf16 v[4:7], v[218:221], v[242:245], v[4:7]
	s_barrier
	ds_read_b128 v[174:177], v161
	ds_read_b128 v[178:181], v161 offset:1024
	ds_read_b128 v[182:185], v161 offset:2048
	ds_read_b128 v[186:189], v161 offset:3072
	v_lshl_add_u64 v[226:227], v[222:223], 0, s[46:47]
	s_or_b32 m0, s100, 0x4000
	ds_read_b128 v[190:193], v156 offset:32768
	ds_read_b128 v[194:197], v156 offset:33792
	ds_read_b128 v[198:201], v155 offset:32768
	ds_read_b128 v[202:205], v155 offset:33792
	ds_read_b128 v[206:209], v154 offset:32768
	ds_read_b128 v[210:213], v154 offset:33792
	ds_read_b128 v[214:217], v153 offset:32768
	ds_read_b128 v[218:221], v153 offset:33792
	global_load_lds_dwordx4 v[226:227], off
	v_lshl_add_u64 v[226:227], v[236:237], 0, s[46:47]
	s_or_b32 m0, s100, 0x6000
	s_nop 0
	global_load_lds_dwordx4 v[226:227], off
	s_waitcnt lgkmcnt(8)
	s_barrier
; #define LDA8(dst, b, h) _Pragma("unroll") for (int m = 0; m < 4; ++m) _Pragma("unroll") for (int k = 0; k < 2; ++k) \
;     dst[m][k] = *(const bf16x8*)((const char*)SA8(b, h) + lds_byte8(wr * 64 + m * 16 + fr, k * 32 + fq * 8))
; #define LDB8(dst, b, h) _Pragma("unroll") for (int n = 0; n < 2; ++n) _Pragma("unroll") for (int k = 0; k < 2; ++k) \
;     dst[n][k] = *(const bf16x8*)((const char*)SB8(b, h) + lds_byte8(wc * 32 + n * 16 + fr, k * 32 + fq * 8))
; #define WAIT_V8(n) asm volatile("s_waitcnt vmcnt(" #n ")" ::: "memory")
; #define WAIT_L8(n) asm volatile("s_waitcnt lgkmcnt(" #n ")" ::: "memory")
; #define BAR8 __builtin_amdgcn_s_barrier()
; #define SCHED8 __builtin_amdgcn_sched_barrier(0)
;     ...
;   for (int tt = 0; tt < nt - 2; tt += 2) {
;     LDB8(B0, 0, 0); SCHED8; LDA8(At, 0, 0); STAGE8(SA8(1, 1), A, lda, brow + 128, tt + 1);
;     WAIT_L8(8); BAR8; WAIT_L8(0); MMA8(0, 0, At, B0); BAR8; SCHED8;
;     LDB8(B1, 0, 1); STAGE8(SB8(0, 0), Bt, K, bcol, tt + 2);
;     BAR8; WAIT_L8(0); MMA8(0, 1, At, B1); BAR8;
;     LDA8(At, 0, 1); STAGE8(SA8(0, 0), A, lda, brow, tt + 2);
;     BAR8; WAIT_L8(0); MMA8(1, 0, At, B0); BAR8; SCHED8;
;     STAGE8(SB8(0, 1), Bt, K, bcol + 128, tt + 2);
;     WAIT_V8(6); BAR8; MMA8(1, 1, At, B1); BAR8;
;     LDB8(B0, 1, 0); SCHED8; LDA8(At, 1, 0); STAGE8(SA8(0, 1), A, lda, brow + 128, tt + 2);
;     WAIT_L8(8); BAR8; WAIT_L8(0); MMA8(0, 0, At, B0); BAR8; SCHED8;
;     LDB8(B1, 1, 1); STAGE8(SB8(1, 0), Bt, K, bcol, tt + 3);
;     BAR8; WAIT_L8(0); MMA8(0, 1, At, B1); BAR8;
;     LDA8(At, 1, 1); STAGE8(SA8(1, 0), A, lda, brow, tt + 3);
;     BAR8; WAIT_L8(0); MMA8(1, 0, At, B0); BAR8; SCHED8;
;     STAGE8(SB8(1, 1), Bt, K, bcol + 128, tt + 3);
;     WAIT_V8(6); BAR8; MMA8(1, 1, At, B1); BAR8;
	s_waitcnt lgkmcnt(0)
	v_mfma_f32_16x16x32_bf16 v[128:131], v[190:193], v[174:177], v[128:131]
	v_mfma_f32_16x16x32_bf16 v[124:127], v[190:193], v[182:185], v[124:127]
	v_mfma_f32_16x16x32_bf16 v[120:123], v[198:201], v[174:177], v[120:123]
	v_mfma_f32_16x16x32_bf16 v[116:119], v[198:201], v[182:185], v[116:119]
	v_mfma_f32_16x16x32_bf16 v[112:115], v[206:209], v[174:177], v[112:115]
	v_mfma_f32_16x16x32_bf16 v[108:111], v[206:209], v[182:185], v[108:111]
	v_mfma_f32_16x16x32_bf16 v[104:107], v[214:217], v[174:177], v[104:107]
	v_mfma_f32_16x16x32_bf16 v[100:103], v[214:217], v[182:185], v[100:103]
	v_mfma_f32_16x16x32_bf16 v[128:131], v[194:197], v[178:181], v[128:131]
	v_mfma_f32_16x16x32_bf16 v[124:127], v[194:197], v[186:189], v[124:127]
	v_mfma_f32_16x16x32_bf16 v[120:123], v[202:205], v[178:181], v[120:123]
	v_mfma_f32_16x16x32_bf16 v[116:119], v[202:205], v[186:189], v[116:119]
	v_mfma_f32_16x16x32_bf16 v[112:115], v[210:213], v[178:181], v[112:115]
	v_mfma_f32_16x16x32_bf16 v[108:111], v[210:213], v[186:189], v[108:111]
	v_mfma_f32_16x16x32_bf16 v[104:107], v[218:221], v[178:181], v[104:107]
	v_mfma_f32_16x16x32_bf16 v[100:103], v[218:221], v[186:189], v[100:103]
	s_barrier
	v_lshl_add_u64 v[250:251], v[246:247], 0, s[48:49]
	s_or_b32 m0, s100, 0x18000
	ds_read_b128 v[226:229], v158
	ds_read_b128 v[230:233], v158 offset:1024
	ds_read_b128 v[238:241], v158 offset:2048
	ds_read_b128 v[242:245], v158 offset:3072
	global_load_lds_dwordx4 v[250:251], off
	v_lshl_add_u64 v[250:251], v[248:249], 0, s[48:49]
	s_or_b32 m0, s100, 0x1a000
	s_nop 0
	global_load_lds_dwordx4 v[250:251], off
	s_barrier
	s_waitcnt lgkmcnt(0)
	v_mfma_f32_16x16x32_bf16 v[96:99], v[190:193], v[226:229], v[96:99]
	v_mfma_f32_16x16x32_bf16 v[92:95], v[190:193], v[238:241], v[92:95]
	v_mfma_f32_16x16x32_bf16 v[88:91], v[198:201], v[226:229], v[88:91]
	v_mfma_f32_16x16x32_bf16 v[84:87], v[198:201], v[238:241], v[84:87]
	v_mfma_f32_16x16x32_bf16 v[80:83], v[206:209], v[226:229], v[80:83]
	v_mfma_f32_16x16x32_bf16 v[76:79], v[206:209], v[238:241], v[76:79]
	v_mfma_f32_16x16x32_bf16 v[72:75], v[214:217], v[226:229], v[72:75]
	v_mfma_f32_16x16x32_bf16 v[68:71], v[214:217], v[238:241], v[68:71]
	v_mfma_f32_16x16x32_bf16 v[96:99], v[194:197], v[230:233], v[96:99]
	v_mfma_f32_16x16x32_bf16 v[92:95], v[194:197], v[242:245], v[92:95]
	v_mfma_f32_16x16x32_bf16 v[88:91], v[202:205], v[230:233], v[88:91]
	v_mfma_f32_16x16x32_bf16 v[84:87], v[202:205], v[242:245], v[84:87]
	v_mfma_f32_16x16x32_bf16 v[80:83], v[210:213], v[230:233], v[80:83]
	v_mfma_f32_16x16x32_bf16 v[76:79], v[210:213], v[242:245], v[76:79]
	v_mfma_f32_16x16x32_bf16 v[72:75], v[218:221], v[230:233], v[72:75]
	v_mfma_f32_16x16x32_bf16 v[68:71], v[218:221], v[242:245], v[68:71]
	v_lshl_add_u64 v[222:223], v[222:223], 0, s[50:51]
	s_or_b32 m0, s100, 0x8000
	s_barrier
	ds_read_b128 v[190:193], v156 offset:49152
	ds_read_b128 v[194:197], v156 offset:50176
	ds_read_b128 v[198:201], v155 offset:49152
	ds_read_b128 v[202:205], v155 offset:50176
	ds_read_b128 v[206:209], v154 offset:49152
	ds_read_b128 v[210:213], v154 offset:50176
	ds_read_b128 v[214:217], v153 offset:49152
	ds_read_b128 v[218:221], v153 offset:50176
	global_load_lds_dwordx4 v[222:223], off
	v_lshl_add_u64 v[222:223], v[236:237], 0, s[50:51]
	s_or_b32 m0, s100, 0xa000
	s_nop 0
	global_load_lds_dwordx4 v[222:223], off
	s_barrier
	s_waitcnt lgkmcnt(0)
	v_mfma_f32_16x16x32_bf16 v[64:67], v[190:193], v[174:177], v[64:67]
	v_mfma_f32_16x16x32_bf16 v[60:63], v[190:193], v[182:185], v[60:63]
	v_mfma_f32_16x16x32_bf16 v[56:59], v[198:201], v[174:177], v[56:59]
	v_mfma_f32_16x16x32_bf16 v[52:55], v[198:201], v[182:185], v[52:55]
	v_mfma_f32_16x16x32_bf16 v[48:51], v[206:209], v[174:177], v[48:51]
	v_mfma_f32_16x16x32_bf16 v[44:47], v[206:209], v[182:185], v[44:47]
	v_mfma_f32_16x16x32_bf16 v[40:43], v[214:217], v[174:177], v[40:43]
	v_mfma_f32_16x16x32_bf16 v[36:39], v[214:217], v[182:185], v[36:39]
	v_mfma_f32_16x16x32_bf16 v[64:67], v[194:197], v[178:181], v[64:67]
	v_mfma_f32_16x16x32_bf16 v[60:63], v[194:197], v[186:189], v[60:63]
	v_mfma_f32_16x16x32_bf16 v[56:59], v[202:205], v[178:181], v[56:59]
	v_mfma_f32_16x16x32_bf16 v[52:55], v[202:205], v[186:189], v[52:55]
	v_mfma_f32_16x16x32_bf16 v[48:51], v[210:213], v[178:181], v[48:51]
	v_mfma_f32_16x16x32_bf16 v[44:47], v[210:213], v[186:189], v[44:47]
	v_mfma_f32_16x16x32_bf16 v[40:43], v[218:221], v[178:181], v[40:43]
	v_mfma_f32_16x16x32_bf16 v[36:39], v[218:221], v[186:189], v[36:39]
	s_barrier
	v_lshl_add_u64 v[174:175], v[246:247], 0, s[52:53]
	s_or_b32 m0, s100, 0x1c000
	s_nop 0
	global_load_lds_dwordx4 v[174:175], off
	v_lshl_add_u64 v[174:175], v[248:249], 0, s[52:53]
	s_or_b32 m0, s100, 0x1e000
	s_nop 0
	global_load_lds_dwordx4 v[174:175], off
	s_waitcnt vmcnt(6)
	s_barrier
	v_mfma_f32_16x16x32_bf16 v[32:35], v[190:193], v[226:229], v[32:35]
	v_mfma_f32_16x16x32_bf16 v[28:31], v[190:193], v[238:241], v[28:31]
	v_mfma_f32_16x16x32_bf16 v[24:27], v[198:201], v[226:229], v[24:27]
	v_mfma_f32_16x16x32_bf16 v[20:23], v[198:201], v[238:241], v[20:23]
	v_mfma_f32_16x16x32_bf16 v[16:19], v[206:209], v[226:229], v[16:19]
	v_mfma_f32_16x16x32_bf16 v[12:15], v[206:209], v[238:241], v[12:15]
	v_mfma_f32_16x16x32_bf16 v[8:11], v[214:217], v[226:229], v[8:11]
	v_mfma_f32_16x16x32_bf16 v[4:7], v[214:217], v[238:241], v[4:7]
	v_mfma_f32_16x16x32_bf16 v[32:35], v[194:197], v[230:233], v[32:35]
	v_mfma_f32_16x16x32_bf16 v[28:31], v[194:197], v[242:245], v[28:31]
	v_mfma_f32_16x16x32_bf16 v[24:27], v[202:205], v[230:233], v[24:27]
	v_mfma_f32_16x16x32_bf16 v[20:23], v[202:205], v[242:245], v[20:23]
	v_mfma_f32_16x16x32_bf16 v[16:19], v[210:213], v[230:233], v[16:19]
	v_mfma_f32_16x16x32_bf16 v[12:15], v[210:213], v[242:245], v[12:15]
	v_mfma_f32_16x16x32_bf16 v[8:11], v[218:221], v[230:233], v[8:11]
	v_mfma_f32_16x16x32_bf16 v[4:7], v[218:221], v[242:245], v[4:7]
	s_add_i32 s1, s1, 2
	s_add_u32 s12, s12, 0x100
	s_addc_u32 s13, s13, 0
	s_cmp_lt_u32 s1, 12
	s_barrier
	s_cbranch_scc0 .Lpk_exit_3

; #define LDA8(dst, b, h) _Pragma("unroll") for (int m = 0; m < 4; ++m) _Pragma("unroll") for (int k = 0; k < 2; ++k) \
;     dst[m][k] = *(const bf16x8*)((const char*)SA8(b, h) + lds_byte8(wr * 64 + m * 16 + fr, k * 32 + fq * 8))
; #define LDB8(dst, b, h) _Pragma("unroll") for (int n = 0; n < 2; ++n) _Pragma("unroll") for (int k = 0; k < 2; ++k) \
;     dst[n][k] = *(const bf16x8*)((const char*)SB8(b, h) + lds_byte8(wc * 32 + n * 16 + fr, k * 32 + fq * 8))
; #define WAIT_V8(n) asm volatile("s_waitcnt vmcnt(" #n ")" ::: "memory")
; #define WAIT_L8(n) asm volatile("s_waitcnt lgkmcnt(" #n ")" ::: "memory")
; #define BAR8 __builtin_amdgcn_s_barrier()
;     ...
;   { LDB8(B0, 0, 0); LDA8(At, 0, 0); STAGE8(SA8(1, 1), A, lda, brow + 128, nt - 1);
;     BAR8; WAIT_L8(0); MMA8(0, 0, At, B0); BAR8;
;     LDB8(B1, 0, 1); BAR8; WAIT_L8(0); MMA8(0, 1, At, B1); BAR8;
;     LDA8(At, 0, 1); WAIT_V8(4); BAR8; WAIT_L8(0); MMA8(1, 0, At, B0); MMA8(1, 1, At, B1); BAR8; }
.Lpk_exit_3:
	s_add_u32 s8, s8, 0x40780
	s_addc_u32 s9, s9, 0
	v_lshl_add_u64 v[132:133], s[8:9], 0, v[132:133]
	v_lshl_add_u64 v[0:1], v[0:1], 1, v[132:133]
	s_or_b32 m0, s100, 0xc000
	ds_read_b128 v[138:141], v171
	ds_read_b128 v[142:145], v171 offset:1024
	ds_read_b128 v[162:165], v171 offset:2048
	ds_read_b128 v[174:177], v171 offset:3072
	ds_read_b128 v[178:181], v156
	ds_read_b128 v[182:185], v156 offset:1024
	ds_read_b128 v[186:189], v155
	ds_read_b128 v[190:193], v155 offset:1024
	ds_read_b128 v[194:197], v154
	ds_read_b128 v[198:201], v154 offset:1024
	ds_read_b128 v[202:205], v153
	ds_read_b128 v[206:209], v153 offset:1024
	global_load_lds_dwordx4 v[0:1], off
	v_lshl_add_u64 v[0:1], s[8:9], 0, v[136:137]
	v_lshl_add_u64 v[0:1], v[134:135], 1, v[0:1]
	s_or_b32 m0, s100, 0xe000
	s_nop 0
	global_load_lds_dwordx4 v[0:1], off
	s_barrier
	s_waitcnt lgkmcnt(0)
	v_mfma_f32_16x16x32_bf16 v[128:131], v[178:181], v[138:141], v[128:131]
	v_mfma_f32_16x16x32_bf16 v[124:127], v[178:181], v[162:165], v[124:127]
	v_mfma_f32_16x16x32_bf16 v[120:123], v[186:189], v[138:141], v[120:123]
	v_mfma_f32_16x16x32_bf16 v[112:115], v[194:197], v[138:141], v[112:115]
	v_mfma_f32_16x16x32_bf16 v[128:131], v[182:185], v[142:145], v[128:131]
	v_mfma_f32_16x16x32_bf16 v[124:127], v[182:185], v[174:177], v[124:127]
	v_mfma_f32_16x16x32_bf16 v[120:123], v[190:193], v[142:145], v[120:123]
	v_mfma_f32_16x16x32_bf16 v[116:119], v[186:189], v[162:165], v[116:119]
	v_mfma_f32_16x16x32_bf16 v[112:115], v[198:201], v[142:145], v[112:115]
	v_mfma_f32_16x16x32_bf16 v[108:111], v[194:197], v[162:165], v[108:111]
	v_mfma_f32_16x16x32_bf16 v[104:107], v[202:205], v[138:141], v[104:107]
	v_mfma_f32_16x16x32_bf16 v[100:103], v[202:205], v[162:165], v[100:103]
	v_mfma_f32_16x16x32_bf16 v[132:135], v[190:193], v[174:177], v[116:119]
	v_mfma_f32_16x16x32_bf16 v[170:173], v[198:201], v[174:177], v[108:111]
	v_mfma_f32_16x16x32_bf16 v[210:213], v[206:209], v[142:145], v[104:107]
	v_mfma_f32_16x16x32_bf16 v[214:217], v[206:209], v[174:177], v[100:103]
	s_barrier
	s_nop 1
	ds_read_b128 v[100:103], v168
	ds_read_b128 v[104:107], v168 offset:1024
	ds_read_b128 v[108:111], v168 offset:2048
	ds_read_b128 v[116:119], v168 offset:3072
	s_barrier
	s_waitcnt lgkmcnt(0)
	v_mfma_f32_16x16x32_bf16 v[80:83], v[194:197], v[100:103], v[80:83]
	v_mfma_f32_16x16x32_bf16 v[76:79], v[194:197], v[108:111], v[76:79]
	v_mfma_f32_16x16x32_bf16 v[72:75], v[202:205], v[100:103], v[72:75]
	v_mfma_f32_16x16x32_bf16 v[68:71], v[202:205], v[108:111], v[68:71]
	v_mfma_f32_16x16x32_bf16 v[96:99], v[178:181], v[100:103], v[96:99]
	v_mfma_f32_16x16x32_bf16 v[92:95], v[178:181], v[108:111], v[92:95]
	v_mfma_f32_16x16x32_bf16 v[88:91], v[186:189], v[100:103], v[88:91]
	v_mfma_f32_16x16x32_bf16 v[84:87], v[186:189], v[108:111], v[84:87]
	v_mfma_f32_16x16x32_bf16 v[80:83], v[198:201], v[104:107], v[80:83]
	v_mfma_f32_16x16x32_bf16 v[76:79], v[198:201], v[116:119], v[76:79]
	v_mfma_f32_16x16x32_bf16 v[72:75], v[206:209], v[104:107], v[72:75]
	v_mfma_f32_16x16x32_bf16 v[68:71], v[206:209], v[116:119], v[68:71]
	v_mfma_f32_16x16x32_bf16 v[166:169], v[182:185], v[104:107], v[96:99]
	v_mfma_f32_16x16x32_bf16 v[178:181], v[182:185], v[116:119], v[92:95]
	v_mfma_f32_16x16x32_bf16 v[182:185], v[190:193], v[104:107], v[88:91]
	v_mfma_f32_16x16x32_bf16 v[186:189], v[190:193], v[116:119], v[84:87]
	s_barrier
	s_nop 0
	ds_read_b128 v[84:87], v156 offset:16384
	ds_read_b128 v[88:91], v156 offset:17408
	ds_read_b128 v[92:95], v155 offset:16384
	ds_read_b128 v[96:99], v155 offset:17408
	ds_read_b128 v[190:193], v154 offset:16384
	ds_read_b128 v[194:197], v154 offset:17408
	ds_read_b128 v[198:201], v153 offset:16384
	ds_read_b128 v[202:205], v153 offset:17408
	s_waitcnt vmcnt(4)
	s_barrier
	s_waitcnt lgkmcnt(0)
	v_mfma_f32_16x16x32_bf16 v[64:67], v[84:87], v[138:141], v[64:67]
	v_mfma_f32_16x16x32_bf16 v[60:63], v[84:87], v[162:165], v[60:63]
	v_mfma_f32_16x16x32_bf16 v[56:59], v[92:95], v[138:141], v[56:59]
	v_mfma_f32_16x16x32_bf16 v[52:55], v[92:95], v[162:165], v[52:55]
	v_mfma_f32_16x16x32_bf16 v[48:51], v[190:193], v[138:141], v[48:51]
	v_mfma_f32_16x16x32_bf16 v[44:47], v[190:193], v[162:165], v[44:47]
	v_mfma_f32_16x16x32_bf16 v[40:43], v[198:201], v[138:141], v[40:43]
	v_mfma_f32_16x16x32_bf16 v[36:39], v[198:201], v[162:165], v[36:39]
	v_mfma_f32_16x16x32_bf16 v[64:67], v[88:91], v[142:145], v[64:67]
	v_mfma_f32_16x16x32_bf16 v[60:63], v[88:91], v[174:177], v[60:63]
	v_mfma_f32_16x16x32_bf16 v[56:59], v[96:99], v[142:145], v[56:59]
	v_mfma_f32_16x16x32_bf16 v[52:55], v[96:99], v[174:177], v[52:55]
	v_mfma_f32_16x16x32_bf16 v[48:51], v[194:197], v[142:145], v[48:51]
	v_mfma_f32_16x16x32_bf16 v[44:47], v[194:197], v[174:177], v[44:47]
	v_mfma_f32_16x16x32_bf16 v[40:43], v[202:205], v[142:145], v[40:43]
	v_mfma_f32_16x16x32_bf16 v[36:39], v[202:205], v[174:177], v[36:39]
	v_mfma_f32_16x16x32_bf16 v[32:35], v[84:87], v[100:103], v[32:35]
	v_mfma_f32_16x16x32_bf16 v[28:31], v[84:87], v[108:111], v[28:31]
	v_mfma_f32_16x16x32_bf16 v[24:27], v[92:95], v[100:103], v[24:27]
	v_mfma_f32_16x16x32_bf16 v[20:23], v[92:95], v[108:111], v[20:23]
	v_mfma_f32_16x16x32_bf16 v[16:19], v[190:193], v[100:103], v[16:19]
	v_mfma_f32_16x16x32_bf16 v[12:15], v[190:193], v[108:111], v[12:15]
	v_mfma_f32_16x16x32_bf16 v[8:11], v[198:201], v[100:103], v[8:11]
	v_mfma_f32_16x16x32_bf16 v[4:7], v[198:201], v[108:111], v[4:7]
	v_mfma_f32_16x16x32_bf16 v[136:139], v[88:91], v[104:107], v[32:35]
	v_mfma_f32_16x16x32_bf16 v[140:143], v[88:91], v[116:119], v[28:31]
	v_mfma_f32_16x16x32_bf16 v[162:165], v[96:99], v[104:107], v[24:27]
	v_mfma_f32_16x16x32_bf16 v[174:177], v[96:99], v[116:119], v[20:23]
	v_mfma_f32_16x16x32_bf16 v[206:209], v[194:197], v[104:107], v[16:19]
	v_mfma_f32_16x16x32_bf16 v[190:193], v[194:197], v[116:119], v[12:15]
	v_mfma_f32_16x16x32_bf16 v[194:197], v[202:205], v[104:107], v[8:11]
	v_mfma_f32_16x16x32_bf16 v[198:201], v[202:205], v[116:119], v[4:7]
	s_barrier
; #define LDA8(dst, b, h) _Pragma("unroll") for (int m = 0; m < 4; ++m) _Pragma("unroll") for (int k = 0; k < 2; ++k) \
;     dst[m][k] = *(const bf16x8*)((const char*)SA8(b, h) + lds_byte8(wr * 64 + m * 16 + fr, k * 32 + fq * 8))
; #define LDB8(dst, b, h) _Pragma("unroll") for (int n = 0; n < 2; ++n) _Pragma("unroll") for (int k = 0; k < 2; ++k) \
;     dst[n][k] = *(const bf16x8*)((const char*)SB8(b, h) + lds_byte8(wc * 32 + n * 16 + fr, k * 32 + fq * 8))
; #define WAIT_V8(n) asm volatile("s_waitcnt vmcnt(" #n ")" ::: "memory")
; #define WAIT_L8(n) asm volatile("s_waitcnt lgkmcnt(" #n ")" ::: "memory")
; #define BAR8 __builtin_amdgcn_s_barrier()
;     ...
;   { LDB8(B0, 1, 0); LDA8(At, 1, 0); WAIT_V8(2); BAR8; WAIT_L8(0); MMA8(0, 0, At, B0); BAR8;
;     LDB8(B1, 1, 1); WAIT_V8(0); BAR8; WAIT_L8(0); MMA8(0, 1, At, B1); BAR8;
;     LDA8(At, 1, 1); BAR8; WAIT_L8(0); MMA8(1, 0, At, B0); MMA8(1, 1, At, B1); BAR8; }
;   if (wr == 0) BAR8;
;   __syncthreads();
;     ...
;   if (t < 256) {
	ds_read_b128 v[202:205], v161
	ds_read_b128 v[218:221], v161 offset:1024
	ds_read_b128 v[226:229], v161 offset:2048
	ds_read_b128 v[230:233], v161 offset:3072
	ds_read_b128 v[8:11], v156 offset:32768
	ds_read_b128 v[12:15], v156 offset:33792
	ds_read_b128 v[16:19], v155 offset:32768
	ds_read_b128 v[24:27], v155 offset:33792
	ds_read_b128 v[28:31], v154 offset:32768
	ds_read_b128 v[32:35], v154 offset:33792
	ds_read_b128 v[238:241], v153 offset:32768
	ds_read_b128 v[242:245], v153 offset:33792
	s_waitcnt vmcnt(2)
	s_barrier
	s_waitcnt lgkmcnt(0)
	v_mfma_f32_16x16x32_bf16 v[4:7], v[8:11], v[202:205], v[128:131]
	v_mfma_f32_16x16x32_bf16 v[104:107], v[12:15], v[218:221], v[4:7]
	v_mfma_f32_16x16x32_bf16 v[4:7], v[8:11], v[226:229], v[124:127]
	v_mfma_f32_16x16x32_bf16 v[116:119], v[12:15], v[230:233], v[4:7]
	v_mfma_f32_16x16x32_bf16 v[4:7], v[16:19], v[202:205], v[120:123]
	v_mfma_f32_16x16x32_bf16 v[100:103], v[24:27], v[218:221], v[4:7]
	v_mfma_f32_16x16x32_bf16 v[4:7], v[16:19], v[226:229], v[132:135]
	v_mfma_f32_16x16x32_bf16 v[108:111], v[24:27], v[230:233], v[4:7]
	v_mfma_f32_16x16x32_bf16 v[4:7], v[28:31], v[202:205], v[112:115]
	v_mfma_f32_16x16x32_bf16 v[92:95], v[32:35], v[218:221], v[4:7]
	v_mfma_f32_16x16x32_bf16 v[4:7], v[28:31], v[226:229], v[170:173]
	v_mfma_f32_16x16x32_bf16 v[96:99], v[32:35], v[230:233], v[4:7]
	v_mfma_f32_16x16x32_bf16 v[4:7], v[238:241], v[202:205], v[210:213]
	v_mfma_f32_16x16x32_bf16 v[84:87], v[242:245], v[218:221], v[4:7]
	v_mfma_f32_16x16x32_bf16 v[4:7], v[238:241], v[226:229], v[214:217]
	v_mfma_f32_16x16x32_bf16 v[88:91], v[242:245], v[230:233], v[4:7]
	s_barrier
	ds_read_b128 v[132:135], v158
	ds_read_b128 v[170:173], v158 offset:1024
	ds_read_b128 v[210:213], v158 offset:2048
	ds_read_b128 v[158:161], v158 offset:3072
	s_waitcnt vmcnt(0)
	s_barrier
	s_waitcnt lgkmcnt(0)
	v_mfma_f32_16x16x32_bf16 v[4:7], v[8:11], v[132:135], v[166:169]
	v_mfma_f32_16x16x32_bf16 v[8:11], v[8:11], v[210:213], v[178:181]
	v_mfma_f32_16x16x32_bf16 v[4:7], v[12:15], v[170:173], v[4:7]
	v_mfma_f32_16x16x32_bf16 v[20:23], v[12:15], v[158:161], v[8:11]
	v_mfma_f32_16x16x32_bf16 v[8:11], v[16:19], v[132:135], v[182:185]
	v_mfma_f32_16x16x32_bf16 v[12:15], v[16:19], v[210:213], v[186:189]
	v_mfma_f32_16x16x32_bf16 v[8:11], v[24:27], v[170:173], v[8:11]
	v_mfma_f32_16x16x32_bf16 v[24:27], v[24:27], v[158:161], v[12:15]
	v_mfma_f32_16x16x32_bf16 v[12:15], v[28:31], v[132:135], v[80:83]
	v_mfma_f32_16x16x32_bf16 v[16:19], v[28:31], v[210:213], v[76:79]
	v_mfma_f32_16x16x32_bf16 v[12:15], v[32:35], v[170:173], v[12:15]
	v_mfma_f32_16x16x32_bf16 v[28:31], v[32:35], v[158:161], v[16:19]
	v_mfma_f32_16x16x32_bf16 v[16:19], v[238:241], v[132:135], v[72:75]
	v_mfma_f32_16x16x32_bf16 v[32:35], v[238:241], v[210:213], v[68:71]
	v_mfma_f32_16x16x32_bf16 v[16:19], v[242:245], v[170:173], v[16:19]
	v_mfma_f32_16x16x32_bf16 v[32:35], v[242:245], v[158:161], v[32:35]
	s_barrier
	ds_read_b128 v[166:169], v156 offset:49152
	ds_read_b128 v[178:181], v156 offset:50176
	ds_read_b128 v[182:185], v155 offset:49152
	ds_read_b128 v[186:189], v155 offset:50176
	ds_read_b128 v[214:217], v154 offset:49152
	ds_read_b128 v[154:157], v154 offset:50176
	ds_read_b128 v[238:241], v153 offset:49152
	ds_read_b128 v[150:153], v153 offset:50176
	s_barrier
	s_waitcnt lgkmcnt(0)
	v_mfma_f32_16x16x32_bf16 v[64:67], v[166:169], v[202:205], v[64:67]
	v_mfma_f32_16x16x32_bf16 v[60:63], v[166:169], v[226:229], v[60:63]
	v_mfma_f32_16x16x32_bf16 v[56:59], v[182:185], v[202:205], v[56:59]
	v_mfma_f32_16x16x32_bf16 v[52:55], v[182:185], v[226:229], v[52:55]
	v_mfma_f32_16x16x32_bf16 v[48:51], v[214:217], v[202:205], v[48:51]
	v_mfma_f32_16x16x32_bf16 v[44:47], v[214:217], v[226:229], v[44:47]
	v_mfma_f32_16x16x32_bf16 v[40:43], v[238:241], v[202:205], v[40:43]
	v_mfma_f32_16x16x32_bf16 v[36:39], v[238:241], v[226:229], v[36:39]
	v_mfma_f32_16x16x32_bf16 v[128:131], v[178:181], v[218:221], v[64:67]
	v_mfma_f32_16x16x32_bf16 v[124:127], v[178:181], v[230:233], v[60:63]
	v_mfma_f32_16x16x32_bf16 v[120:123], v[186:189], v[218:221], v[56:59]
	v_mfma_f32_16x16x32_bf16 v[112:115], v[186:189], v[230:233], v[52:55]
	v_mfma_f32_16x16x32_bf16 v[80:83], v[154:157], v[218:221], v[48:51]
	v_mfma_f32_16x16x32_bf16 v[76:79], v[154:157], v[230:233], v[44:47]
	v_mfma_f32_16x16x32_bf16 v[72:75], v[150:153], v[218:221], v[40:43]
	v_mfma_f32_16x16x32_bf16 v[68:71], v[150:153], v[230:233], v[36:39]
	v_mfma_f32_16x16x32_bf16 v[36:39], v[166:169], v[132:135], v[136:139]
	v_mfma_f32_16x16x32_bf16 v[64:67], v[178:181], v[170:173], v[36:39]
	v_mfma_f32_16x16x32_bf16 v[36:39], v[166:169], v[210:213], v[140:143]
	v_mfma_f32_16x16x32_bf16 v[60:63], v[178:181], v[158:161], v[36:39]
	v_mfma_f32_16x16x32_bf16 v[36:39], v[182:185], v[132:135], v[162:165]
	v_mfma_f32_16x16x32_bf16 v[56:59], v[186:189], v[170:173], v[36:39]
	v_mfma_f32_16x16x32_bf16 v[36:39], v[182:185], v[210:213], v[174:177]
	v_mfma_f32_16x16x32_bf16 v[52:55], v[186:189], v[158:161], v[36:39]
	v_mfma_f32_16x16x32_bf16 v[36:39], v[214:217], v[132:135], v[206:209]
	v_mfma_f32_16x16x32_bf16 v[48:51], v[154:157], v[170:173], v[36:39]
	v_mfma_f32_16x16x32_bf16 v[36:39], v[214:217], v[210:213], v[190:193]
	v_mfma_f32_16x16x32_bf16 v[44:47], v[154:157], v[158:161], v[36:39]
	v_mfma_f32_16x16x32_bf16 v[36:39], v[238:241], v[132:135], v[194:197]
	v_mfma_f32_16x16x32_bf16 v[40:43], v[150:153], v[170:173], v[36:39]
	v_mfma_f32_16x16x32_bf16 v[36:39], v[238:241], v[210:213], v[198:201]
	v_mfma_f32_16x16x32_bf16 v[36:39], v[150:153], v[158:161], v[36:39]
	s_movk_i32 s1, 0x100
	v_cmp_gt_u32_e32 vcc, s1, v3
	s_barrier
	s_and_saveexec_b64 s[8:9], vcc
	s_cbranch_execz .LBB0_1008
	s_barrier

; #define LDA8(dst, b, h) _Pragma("unroll") for (int m = 0; m < 4; ++m) _Pragma("unroll") for (int k = 0; k < 2; ++k) \
;     dst[m][k] = *(const bf16x8*)((const char*)SA8(b, h) + lds_byte8(wr * 64 + m * 16 + fr, k * 32 + fq * 8))
; #define LDB8(dst, b, h) _Pragma("unroll") for (int n = 0; n < 2; ++n) _Pragma("unroll") for (int k = 0; k < 2; ++k) \
;     dst[n][k] = *(const bf16x8*)((const char*)SB8(b, h) + lds_byte8(wc * 32 + n * 16 + fr, k * 32 + fq * 8))
; #define WAIT_V8(n) asm volatile("s_waitcnt vmcnt(" #n ")" ::: "memory")
; #define WAIT_L8(n) asm volatile("s_waitcnt lgkmcnt(" #n ")" ::: "memory")
; #define BAR8 __builtin_amdgcn_s_barrier()
; #define SCHED8 __builtin_amdgcn_sched_barrier(0)
;     ...
;   const int brow = m0, bcol = n0;
;   const int wid = t >> 6, lane = t & 63, wr = wid >> 2, wc = wid & 3, fr = lane & 15, fq = lane >> 4;
;   f32x4 acc[2][2][4][2];
;   {
;     float zinit = 0.f;
;     asm volatile("" : "+v"(zinit));
; #pragma unroll
;     for (int a = 0; a < 2; ++a)
; #pragma unroll
;       for (int b = 0; b < 2; ++b)
; #pragma unroll
;         for (int m = 0; m < 4; ++m)
; #pragma unroll
;           for (int n = 0; n < 2; ++n)
; #pragma unroll
;             for (int j = 0; j < 4; ++j) acc[a][b][m][n][j] = zinit;
;   }
;   bf16x8 At[4][2], B0[2][2], B1[2][2];
;   const int nt = K / 64;
;   if (!pre) {
;     STAGE8(SB8(0, 0), Bt, K, bcol, 0); STAGE8(SA8(0, 0), A, lda, brow, 0);
;     STAGE8(SB8(0, 1), Bt, K, bcol + 128, 0); STAGE8(SA8(0, 1), A, lda, brow + 128, 0);
;   }
;   if (wr == 1) BAR8;
;   WAIT_V8(4); BAR8;
;   STAGE8(SB8(1, 0), Bt, K, bcol, 1); STAGE8(SA8(1, 0), A, lda, brow, 1); STAGE8(SB8(1, 1), Bt, K, bcol + 128, 1);
;   WAIT_V8(6); BAR8;
;   for (int tt = 0; tt < nt - 2; tt += 2) {
;     LDB8(B0, 0, 0); SCHED8; LDA8(At, 0, 0); STAGE8(SA8(1, 1), A, lda, brow + 128, tt + 1);
;     WAIT_L8(8); BAR8; WAIT_L8(0); MMA8(0, 0, At, B0); BAR8; SCHED8;
;     LDB8(B1, 0, 1); STAGE8(SB8(0, 0), Bt, K, bcol, tt + 2);
.LBB0_1014:
	s_or_b64 exec, exec, s[14:15]
	v_readlane_b32 s40, v254, 35
	v_readlane_b32 s42, v254, 37
	v_readlane_b32 s43, v254, 38
	s_waitcnt vmcnt(0)
	s_mov_b64 s[42:43], 0x80
	v_lshl_add_u64 v[10:11], v[10:11], 0, s[42:43]
	s_or_b32 m0, s100, 0x18000
	s_waitcnt vmcnt(4)
	s_barrier
	global_load_lds_dwordx4 v[10:11], off
	v_lshl_add_u64 v[10:11], v[12:13], 0, s[42:43]
	s_or_b32 m0, s100, 0x1a000
	global_load_lds_dwordx4 v[10:11], off
	v_lshl_add_u64 v[10:11], v[14:15], 0, s[42:43]
	s_or_b32 m0, s100, 0x8000
	global_load_lds_dwordx4 v[10:11], off
	v_lshl_add_u64 v[10:11], v[16:17], 0, s[42:43]
	s_or_b32 m0, s100, 0xa000
	global_load_lds_dwordx4 v[10:11], off
	v_lshl_add_u64 v[10:11], v[18:19], 0, s[42:43]
	s_or_b32 m0, s100, 0x1c000
	s_nop 0
	global_load_lds_dwordx4 v[10:11], off
	v_lshl_add_u64 v[10:11], v[20:21], 0, s[42:43]
	s_or_b32 m0, s100, 0x1e000
	v_and_b32_e32 v147, 15, v3
	global_load_lds_dwordx4 v[10:11], off
	v_bfe_u32 v148, v3, 4, 2
	v_lshlrev_b32_e32 v10, 4, v148
	v_lshlrev_b32_e32 v11, 6, v147
	v_lshlrev_b32_e32 v14, 2, v3
	v_or_b32_e32 v13, v10, v11
	v_and_b32_e32 v14, 32, v14
	s_mov_b32 s21, 0x10000
	v_bitop3_b32 v16, v13, s21, v14 bitop3:0xde
	s_mov_b32 s21, 0x14000
	s_and_b32 s14, s27, 63
	v_bitop3_b32 v15, v10, v14, v11 bitop3:0x36
	v_bitop3_b32 v17, v13, s21, v14 bitop3:0xde
	s_mov_b32 s21, 0x18000
	v_lshlrev_b32_e32 v11, 6, v3
	s_lshl_b32 s14, s14, 19
	s_mov_b32 s15, s40
	v_bitop3_b32 v18, v13, s21, v14 bitop3:0xde
	s_mov_b32 s21, 0x1c000
	v_and_b32_e32 v11, 0x3c0, v11
	v_bitop3_b32 v13, v13, s21, v14 bitop3:0xde
	v_bitop3_b32 v14, v11, v14, v10 bitop3:0x36
	v_lshl_add_u64 v[10:11], s[14:15], 0, v[136:137]
	v_readlane_b32 s41, v254, 36
	s_and_b32 s40, s33, 0xffffff00
	v_lshl_add_u64 v[10:11], v[10:11], 0, v[8:9]
	s_ashr_i32 s41, s40, 31
	v_lshl_add_u64 v[138:139], s[12:13], 0, v[10:11]
	v_lshl_add_u64 v[10:11], s[14:15], 0, v[132:133]
	s_lshl_b64 s[40:41], s[40:41], 11
	v_lshl_add_u64 v[10:11], v[10:11], 0, v[6:7]
	v_lshl_add_u64 v[140:141], s[12:13], 0, v[10:11]
	v_lshl_add_u64 v[10:11], s[40:41], 0, v[132:133]
	v_lshl_add_u64 v[6:7], v[10:11], 0, v[6:7]
	v_bfe_u32 v146, v3, 6, 2
	s_waitcnt vmcnt(6)
	v_lshlrev_b32_e32 v149, 6, v5
	v_lshlrev_b32_e32 v5, 13, v5
	v_lshl_add_u64 v[142:143], s[4:5], 0, v[6:7]
	v_lshl_add_u64 v[6:7], s[40:41], 0, v[136:137]
	v_lshlrev_b32_e32 v12, 12, v146
	v_or_b32_e32 v19, 0x800, v5
	v_or_b32_e32 v20, 0x1000, v5
	v_or_b32_e32 v21, 0x1800, v5
	v_lshl_add_u64 v[6:7], v[6:7], 0, v[8:9]
	v_lshl_add_u64 v[144:145], s[4:5], 0, v[6:7]
	s_mov_b32 s14, -2
	s_mov_b64 s[12:13], 0
	v_add_u32_e32 v171, v16, v12
	v_add_u32_e32 v156, v15, v5
	v_add_u32_e32 v155, v14, v19
	v_add_u32_e32 v154, v14, v20
	v_add_u32_e32 v153, v14, v21
	v_add_u32_e32 v168, v17, v12
	v_add_u32_e32 v161, v18, v12
	v_add_u32_e32 v158, v13, v12
	s_mov_b64 s[40:41], 0xc6a0100
	s_mov_b64 s[42:43], 0xc6e0100
	s_mov_b64 s[44:45], 0xc6a0180
	s_mov_b64 s[46:47], 0xc6e0180
	s_barrier
	ds_read_b128 v[174:177], v171
	ds_read_b128 v[178:181], v171 offset:1024
	ds_read_b128 v[182:185], v171 offset:2048
	ds_read_b128 v[186:189], v171 offset:3072
	v_lshl_add_u64 v[222:223], v[140:141], 0, s[12:13]
	v_lshl_add_u64 v[226:227], v[222:223], 0, s[34:35]
	s_or_b32 m0, s100, 0xc000
	v_lshl_add_u64 v[236:237], v[138:139], 0, s[12:13]
	ds_read_b128 v[190:193], v156
	ds_read_b128 v[194:197], v156 offset:1024
	ds_read_b128 v[198:201], v155
	ds_read_b128 v[202:205], v155 offset:1024
	ds_read_b128 v[206:209], v154
	ds_read_b128 v[210:213], v154 offset:1024
	ds_read_b128 v[214:217], v153
	ds_read_b128 v[218:221], v153 offset:1024
	global_load_lds_dwordx4 v[226:227], off
	v_lshl_add_u64 v[226:227], v[236:237], 0, s[34:35]
	s_or_b32 m0, s100, 0xe000
	s_nop 0
	global_load_lds_dwordx4 v[226:227], off
	s_waitcnt lgkmcnt(8)
	s_barrier
	s_waitcnt lgkmcnt(0)
	v_mfma_f32_16x16x32_f16 v[128:131], v[190:193], v[174:177], 0
	v_mfma_f32_16x16x32_f16 v[124:127], v[190:193], v[182:185], 0
	v_mfma_f32_16x16x32_f16 v[120:123], v[198:201], v[174:177], 0
	v_mfma_f32_16x16x32_f16 v[116:119], v[198:201], v[182:185], 0
	v_mfma_f32_16x16x32_f16 v[112:115], v[206:209], v[174:177], 0
	v_mfma_f32_16x16x32_f16 v[108:111], v[206:209], v[182:185], 0
	v_mfma_f32_16x16x32_f16 v[104:107], v[214:217], v[174:177], 0
	v_mfma_f32_16x16x32_f16 v[100:103], v[214:217], v[182:185], 0
	v_mfma_f32_16x16x32_f16 v[128:131], v[194:197], v[178:181], v[128:131]
	v_mfma_f32_16x16x32_f16 v[124:127], v[194:197], v[186:189], v[124:127]
	v_mfma_f32_16x16x32_f16 v[120:123], v[202:205], v[178:181], v[120:123]
	v_mfma_f32_16x16x32_f16 v[116:119], v[202:205], v[186:189], v[116:119]
	v_mfma_f32_16x16x32_f16 v[112:115], v[210:213], v[178:181], v[112:115]
	v_mfma_f32_16x16x32_f16 v[108:111], v[210:213], v[186:189], v[108:111]
	v_mfma_f32_16x16x32_f16 v[104:107], v[218:221], v[178:181], v[104:107]
	v_mfma_f32_16x16x32_f16 v[100:103], v[218:221], v[186:189], v[100:103]
	s_barrier
	v_lshl_add_u64 v[246:247], v[142:143], 0, s[12:13]
	v_lshl_add_u64 v[248:249], v[246:247], 0, s[40:41]
	s_or_b32 m0, s100, 0x10000
	ds_read_b128 v[226:229], v168
	ds_read_b128 v[230:233], v168 offset:1024
	ds_read_b128 v[238:241], v168 offset:2048
	ds_read_b128 v[242:245], v168 offset:3072
	global_load_lds_dwordx4 v[248:249], off
	v_lshl_add_u64 v[248:249], v[144:145], 0, s[12:13]
	v_lshl_add_u64 v[250:251], v[248:249], 0, s[40:41]
	s_or_b32 m0, s100, 0x12000
	s_nop 0
	global_load_lds_dwordx4 v[250:251], off
	s_barrier
; #define LDA8(dst, b, h) _Pragma("unroll") for (int m = 0; m < 4; ++m) _Pragma("unroll") for (int k = 0; k < 2; ++k) \
;     dst[m][k] = *(const bf16x8*)((const char*)SA8(b, h) + lds_byte8(wr * 64 + m * 16 + fr, k * 32 + fq * 8))
; #define LDB8(dst, b, h) _Pragma("unroll") for (int n = 0; n < 2; ++n) _Pragma("unroll") for (int k = 0; k < 2; ++k) \
;     dst[n][k] = *(const bf16x8*)((const char*)SB8(b, h) + lds_byte8(wc * 32 + n * 16 + fr, k * 32 + fq * 8))
; #define WAIT_V8(n) asm volatile("s_waitcnt vmcnt(" #n ")" ::: "memory")
; #define WAIT_L8(n) asm volatile("s_waitcnt lgkmcnt(" #n ")" ::: "memory")
; #define BAR8 __builtin_amdgcn_s_barrier()
; #define SCHED8 __builtin_amdgcn_sched_barrier(0)
;     ...
;     LDB8(B1, 0, 1); STAGE8(SB8(0, 0), Bt, K, bcol, tt + 2);
;     BAR8; WAIT_L8(0); MMA8(0, 1, At, B1); BAR8;
;     LDA8(At, 0, 1); STAGE8(SA8(0, 0), A, lda, brow, tt + 2);
;     BAR8; WAIT_L8(0); MMA8(1, 0, At, B0); BAR8; SCHED8;
;     STAGE8(SB8(0, 1), Bt, K, bcol + 128, tt + 2);
;     WAIT_V8(6); BAR8; MMA8(1, 1, At, B1); BAR8;
;     LDB8(B0, 1, 0); SCHED8; LDA8(At, 1, 0); STAGE8(SA8(0, 1), A, lda, brow + 128, tt + 2);
;     WAIT_L8(8); BAR8; WAIT_L8(0); MMA8(0, 0, At, B0); BAR8; SCHED8;
	s_waitcnt lgkmcnt(0)
	v_mfma_f32_16x16x32_f16 v[96:99], v[190:193], v[226:229], 0
	v_mfma_f32_16x16x32_f16 v[92:95], v[190:193], v[238:241], 0
	v_mfma_f32_16x16x32_f16 v[88:91], v[198:201], v[226:229], 0
	v_mfma_f32_16x16x32_f16 v[84:87], v[198:201], v[238:241], 0
	v_mfma_f32_16x16x32_f16 v[80:83], v[206:209], v[226:229], 0
	v_mfma_f32_16x16x32_f16 v[76:79], v[206:209], v[238:241], 0
	v_mfma_f32_16x16x32_f16 v[72:75], v[214:217], v[226:229], 0
	v_mfma_f32_16x16x32_f16 v[68:71], v[214:217], v[238:241], 0
	v_mfma_f32_16x16x32_f16 v[96:99], v[194:197], v[230:233], v[96:99]
	v_mfma_f32_16x16x32_f16 v[92:95], v[194:197], v[242:245], v[92:95]
	v_mfma_f32_16x16x32_f16 v[88:91], v[202:205], v[230:233], v[88:91]
	v_mfma_f32_16x16x32_f16 v[84:87], v[202:205], v[242:245], v[84:87]
	v_mfma_f32_16x16x32_f16 v[80:83], v[210:213], v[230:233], v[80:83]
	v_mfma_f32_16x16x32_f16 v[76:79], v[210:213], v[242:245], v[76:79]
	v_mfma_f32_16x16x32_f16 v[72:75], v[218:221], v[230:233], v[72:75]
	v_mfma_f32_16x16x32_f16 v[68:71], v[218:221], v[242:245], v[68:71]
	v_lshl_add_u64 v[250:251], v[222:223], 0, s[10:11]
	s_mov_b32 m0, s100
	s_barrier
	ds_read_b128 v[190:193], v156 offset:16384
	ds_read_b128 v[194:197], v156 offset:17408
	ds_read_b128 v[198:201], v155 offset:16384
	ds_read_b128 v[202:205], v155 offset:17408
	ds_read_b128 v[206:209], v154 offset:16384
	ds_read_b128 v[210:213], v154 offset:17408
	ds_read_b128 v[214:217], v153 offset:16384
	ds_read_b128 v[218:221], v153 offset:17408
	global_load_lds_dwordx4 v[250:251], off
	v_lshl_add_u64 v[250:251], v[236:237], 0, s[10:11]
	s_or_b32 m0, s100, 0x2000
	s_nop 0
	global_load_lds_dwordx4 v[250:251], off
	s_barrier
	s_waitcnt lgkmcnt(0)
	v_mfma_f32_16x16x32_f16 v[64:67], v[190:193], v[174:177], 0
	v_mfma_f32_16x16x32_f16 v[60:63], v[190:193], v[182:185], 0
	v_mfma_f32_16x16x32_f16 v[56:59], v[198:201], v[174:177], 0
	v_mfma_f32_16x16x32_f16 v[52:55], v[198:201], v[182:185], 0
	v_mfma_f32_16x16x32_f16 v[48:51], v[206:209], v[174:177], 0
	v_mfma_f32_16x16x32_f16 v[44:47], v[206:209], v[182:185], 0
	v_mfma_f32_16x16x32_f16 v[40:43], v[214:217], v[174:177], 0
	v_mfma_f32_16x16x32_f16 v[36:39], v[214:217], v[182:185], 0
	v_mfma_f32_16x16x32_f16 v[64:67], v[194:197], v[178:181], v[64:67]
	v_mfma_f32_16x16x32_f16 v[60:63], v[194:197], v[186:189], v[60:63]
	v_mfma_f32_16x16x32_f16 v[56:59], v[202:205], v[178:181], v[56:59]
	v_mfma_f32_16x16x32_f16 v[52:55], v[202:205], v[186:189], v[52:55]
	v_mfma_f32_16x16x32_f16 v[48:51], v[210:213], v[178:181], v[48:51]
	v_mfma_f32_16x16x32_f16 v[44:47], v[210:213], v[186:189], v[44:47]
	v_mfma_f32_16x16x32_f16 v[40:43], v[218:221], v[178:181], v[40:43]
	v_mfma_f32_16x16x32_f16 v[36:39], v[218:221], v[186:189], v[36:39]
	s_barrier
	v_lshl_add_u64 v[174:175], v[246:247], 0, s[42:43]
	s_or_b32 m0, s100, 0x14000
	s_nop 0
	global_load_lds_dwordx4 v[174:175], off
	v_lshl_add_u64 v[174:175], v[248:249], 0, s[42:43]
	s_or_b32 m0, s100, 0x16000
	s_nop 0
	global_load_lds_dwordx4 v[174:175], off
	s_waitcnt vmcnt(6)
	s_barrier
	v_mfma_f32_16x16x32_f16 v[32:35], v[190:193], v[226:229], 0
	v_mfma_f32_16x16x32_f16 v[28:31], v[190:193], v[238:241], 0
	v_mfma_f32_16x16x32_f16 v[24:27], v[198:201], v[226:229], 0
	v_mfma_f32_16x16x32_f16 v[20:23], v[198:201], v[238:241], 0
	v_mfma_f32_16x16x32_f16 v[16:19], v[206:209], v[226:229], 0
	v_mfma_f32_16x16x32_f16 v[12:15], v[206:209], v[238:241], 0
	v_mfma_f32_16x16x32_f16 v[8:11], v[214:217], v[226:229], 0
	v_mfma_f32_16x16x32_f16 v[4:7], v[214:217], v[238:241], 0
	v_mfma_f32_16x16x32_f16 v[32:35], v[194:197], v[230:233], v[32:35]
	v_mfma_f32_16x16x32_f16 v[28:31], v[194:197], v[242:245], v[28:31]
	v_mfma_f32_16x16x32_f16 v[24:27], v[202:205], v[230:233], v[24:27]
	v_mfma_f32_16x16x32_f16 v[20:23], v[202:205], v[242:245], v[20:23]
	v_mfma_f32_16x16x32_f16 v[16:19], v[210:213], v[230:233], v[16:19]
	v_mfma_f32_16x16x32_f16 v[12:15], v[210:213], v[242:245], v[12:15]
	v_mfma_f32_16x16x32_f16 v[8:11], v[218:221], v[230:233], v[8:11]
	v_mfma_f32_16x16x32_f16 v[4:7], v[218:221], v[242:245], v[4:7]
	s_barrier
	ds_read_b128 v[174:177], v161
	ds_read_b128 v[178:181], v161 offset:1024
	ds_read_b128 v[182:185], v161 offset:2048
	ds_read_b128 v[186:189], v161 offset:3072
	v_lshl_add_u64 v[226:227], v[222:223], 0, s[18:19]
	s_or_b32 m0, s100, 0x4000
	ds_read_b128 v[190:193], v156 offset:32768
	ds_read_b128 v[194:197], v156 offset:33792
	ds_read_b128 v[198:201], v155 offset:32768
	ds_read_b128 v[202:205], v155 offset:33792
	ds_read_b128 v[206:209], v154 offset:32768
	ds_read_b128 v[210:213], v154 offset:33792
	ds_read_b128 v[214:217], v153 offset:32768
	ds_read_b128 v[218:221], v153 offset:33792
	global_load_lds_dwordx4 v[226:227], off
	v_lshl_add_u64 v[226:227], v[236:237], 0, s[18:19]
	s_or_b32 m0, s100, 0x6000
	s_nop 0
	global_load_lds_dwordx4 v[226:227], off
	s_waitcnt lgkmcnt(8)
	s_barrier
; #define LDA8(dst, b, h) _Pragma("unroll") for (int m = 0; m < 4; ++m) _Pragma("unroll") for (int k = 0; k < 2; ++k) \
;     dst[m][k] = *(const bf16x8*)((const char*)SA8(b, h) + lds_byte8(wr * 64 + m * 16 + fr, k * 32 + fq * 8))
; #define LDB8(dst, b, h) _Pragma("unroll") for (int n = 0; n < 2; ++n) _Pragma("unroll") for (int k = 0; k < 2; ++k) \
;     dst[n][k] = *(const bf16x8*)((const char*)SB8(b, h) + lds_byte8(wc * 32 + n * 16 + fr, k * 32 + fq * 8))
; #define WAIT_V8(n) asm volatile("s_waitcnt vmcnt(" #n ")" ::: "memory")
; #define WAIT_L8(n) asm volatile("s_waitcnt lgkmcnt(" #n ")" ::: "memory")
; #define BAR8 __builtin_amdgcn_s_barrier()
; #define SCHED8 __builtin_amdgcn_sched_barrier(0)
;     ...
;   for (int tt = 0; tt < nt - 2; tt += 2) {
;     ...
;     WAIT_L8(8); BAR8; WAIT_L8(0); MMA8(0, 0, At, B0); BAR8; SCHED8;
;     LDB8(B1, 1, 1); STAGE8(SB8(1, 0), Bt, K, bcol, tt + 3);
;     BAR8; WAIT_L8(0); MMA8(0, 1, At, B1); BAR8;
;     LDA8(At, 1, 1); STAGE8(SA8(1, 0), A, lda, brow, tt + 3);
;     BAR8; WAIT_L8(0); MMA8(1, 0, At, B0); BAR8; SCHED8;
;     STAGE8(SB8(1, 1), Bt, K, bcol + 128, tt + 3);
;     WAIT_V8(6); BAR8; MMA8(1, 1, At, B1); BAR8;
	s_waitcnt lgkmcnt(0)
	v_mfma_f32_16x16x32_f16 v[128:131], v[190:193], v[174:177], v[128:131]
	v_mfma_f32_16x16x32_f16 v[124:127], v[190:193], v[182:185], v[124:127]
	v_mfma_f32_16x16x32_f16 v[120:123], v[198:201], v[174:177], v[120:123]
	v_mfma_f32_16x16x32_f16 v[116:119], v[198:201], v[182:185], v[116:119]
	v_mfma_f32_16x16x32_f16 v[112:115], v[206:209], v[174:177], v[112:115]
	v_mfma_f32_16x16x32_f16 v[108:111], v[206:209], v[182:185], v[108:111]
	v_mfma_f32_16x16x32_f16 v[104:107], v[214:217], v[174:177], v[104:107]
	v_mfma_f32_16x16x32_f16 v[100:103], v[214:217], v[182:185], v[100:103]
	v_mfma_f32_16x16x32_f16 v[128:131], v[194:197], v[178:181], v[128:131]
	v_mfma_f32_16x16x32_f16 v[124:127], v[194:197], v[186:189], v[124:127]
	v_mfma_f32_16x16x32_f16 v[120:123], v[202:205], v[178:181], v[120:123]
	v_mfma_f32_16x16x32_f16 v[116:119], v[202:205], v[186:189], v[116:119]
	v_mfma_f32_16x16x32_f16 v[112:115], v[210:213], v[178:181], v[112:115]
	v_mfma_f32_16x16x32_f16 v[108:111], v[210:213], v[186:189], v[108:111]
	v_mfma_f32_16x16x32_f16 v[104:107], v[218:221], v[178:181], v[104:107]
	v_mfma_f32_16x16x32_f16 v[100:103], v[218:221], v[186:189], v[100:103]
	s_barrier
	v_lshl_add_u64 v[250:251], v[246:247], 0, s[44:45]
	s_or_b32 m0, s100, 0x18000
	ds_read_b128 v[226:229], v158
	ds_read_b128 v[230:233], v158 offset:1024
	ds_read_b128 v[238:241], v158 offset:2048
	ds_read_b128 v[242:245], v158 offset:3072
	global_load_lds_dwordx4 v[250:251], off
	v_lshl_add_u64 v[250:251], v[248:249], 0, s[44:45]
	s_or_b32 m0, s100, 0x1a000
	s_nop 0
	global_load_lds_dwordx4 v[250:251], off
	s_barrier
	s_waitcnt lgkmcnt(0)
	v_mfma_f32_16x16x32_f16 v[96:99], v[190:193], v[226:229], v[96:99]
	v_mfma_f32_16x16x32_f16 v[92:95], v[190:193], v[238:241], v[92:95]
	v_mfma_f32_16x16x32_f16 v[88:91], v[198:201], v[226:229], v[88:91]
	v_mfma_f32_16x16x32_f16 v[84:87], v[198:201], v[238:241], v[84:87]
	v_mfma_f32_16x16x32_f16 v[80:83], v[206:209], v[226:229], v[80:83]
	v_mfma_f32_16x16x32_f16 v[76:79], v[206:209], v[238:241], v[76:79]
	v_mfma_f32_16x16x32_f16 v[72:75], v[214:217], v[226:229], v[72:75]
	v_mfma_f32_16x16x32_f16 v[68:71], v[214:217], v[238:241], v[68:71]
	v_mfma_f32_16x16x32_f16 v[96:99], v[194:197], v[230:233], v[96:99]
	v_mfma_f32_16x16x32_f16 v[92:95], v[194:197], v[242:245], v[92:95]
	v_mfma_f32_16x16x32_f16 v[88:91], v[202:205], v[230:233], v[88:91]
	v_mfma_f32_16x16x32_f16 v[84:87], v[202:205], v[242:245], v[84:87]
	v_mfma_f32_16x16x32_f16 v[80:83], v[210:213], v[230:233], v[80:83]
	v_mfma_f32_16x16x32_f16 v[76:79], v[210:213], v[242:245], v[76:79]
	v_mfma_f32_16x16x32_f16 v[72:75], v[218:221], v[230:233], v[72:75]
	v_mfma_f32_16x16x32_f16 v[68:71], v[218:221], v[242:245], v[68:71]
	v_lshl_add_u64 v[222:223], v[222:223], 0, s[22:23]
	s_or_b32 m0, s100, 0x8000
	s_barrier
	ds_read_b128 v[190:193], v156 offset:49152
	ds_read_b128 v[194:197], v156 offset:50176
	ds_read_b128 v[198:201], v155 offset:49152
	ds_read_b128 v[202:205], v155 offset:50176
	ds_read_b128 v[206:209], v154 offset:49152
	ds_read_b128 v[210:213], v154 offset:50176
	ds_read_b128 v[214:217], v153 offset:49152
	ds_read_b128 v[218:221], v153 offset:50176
	global_load_lds_dwordx4 v[222:223], off
	v_lshl_add_u64 v[222:223], v[236:237], 0, s[22:23]
	s_or_b32 m0, s100, 0xa000
	s_nop 0
	global_load_lds_dwordx4 v[222:223], off
	s_barrier
	s_waitcnt lgkmcnt(0)
	v_mfma_f32_16x16x32_f16 v[64:67], v[190:193], v[174:177], v[64:67]
	v_mfma_f32_16x16x32_f16 v[60:63], v[190:193], v[182:185], v[60:63]
	v_mfma_f32_16x16x32_f16 v[56:59], v[198:201], v[174:177], v[56:59]
	v_mfma_f32_16x16x32_f16 v[52:55], v[198:201], v[182:185], v[52:55]
	v_mfma_f32_16x16x32_f16 v[48:51], v[206:209], v[174:177], v[48:51]
	v_mfma_f32_16x16x32_f16 v[44:47], v[206:209], v[182:185], v[44:47]
	v_mfma_f32_16x16x32_f16 v[40:43], v[214:217], v[174:177], v[40:43]
	v_mfma_f32_16x16x32_f16 v[36:39], v[214:217], v[182:185], v[36:39]
	v_mfma_f32_16x16x32_f16 v[64:67], v[194:197], v[178:181], v[64:67]
	v_mfma_f32_16x16x32_f16 v[60:63], v[194:197], v[186:189], v[60:63]
	v_mfma_f32_16x16x32_f16 v[56:59], v[202:205], v[178:181], v[56:59]
	v_mfma_f32_16x16x32_f16 v[52:55], v[202:205], v[186:189], v[52:55]
	v_mfma_f32_16x16x32_f16 v[48:51], v[210:213], v[178:181], v[48:51]
	v_mfma_f32_16x16x32_f16 v[44:47], v[210:213], v[186:189], v[44:47]
	v_mfma_f32_16x16x32_f16 v[40:43], v[218:221], v[178:181], v[40:43]
	v_mfma_f32_16x16x32_f16 v[36:39], v[218:221], v[186:189], v[36:39]
	s_barrier
	v_lshl_add_u64 v[174:175], v[246:247], 0, s[46:47]
	s_or_b32 m0, s100, 0x1c000
	s_nop 0
	global_load_lds_dwordx4 v[174:175], off
	v_lshl_add_u64 v[174:175], v[248:249], 0, s[46:47]
	s_or_b32 m0, s100, 0x1e000
	s_nop 0
	global_load_lds_dwordx4 v[174:175], off
	s_waitcnt vmcnt(6)
	s_barrier
	v_mfma_f32_16x16x32_f16 v[32:35], v[190:193], v[226:229], v[32:35]
	v_mfma_f32_16x16x32_f16 v[28:31], v[190:193], v[238:241], v[28:31]
	v_mfma_f32_16x16x32_f16 v[24:27], v[198:201], v[226:229], v[24:27]
	v_mfma_f32_16x16x32_f16 v[20:23], v[198:201], v[238:241], v[20:23]
	v_mfma_f32_16x16x32_f16 v[16:19], v[206:209], v[226:229], v[16:19]
	v_mfma_f32_16x16x32_f16 v[12:15], v[206:209], v[238:241], v[12:15]
	v_mfma_f32_16x16x32_f16 v[8:11], v[214:217], v[226:229], v[8:11]
	v_mfma_f32_16x16x32_f16 v[4:7], v[214:217], v[238:241], v[4:7]
	v_mfma_f32_16x16x32_f16 v[32:35], v[194:197], v[230:233], v[32:35]
	v_mfma_f32_16x16x32_f16 v[28:31], v[194:197], v[242:245], v[28:31]
	v_mfma_f32_16x16x32_f16 v[24:27], v[202:205], v[230:233], v[24:27]
	v_mfma_f32_16x16x32_f16 v[20:23], v[202:205], v[242:245], v[20:23]
	v_mfma_f32_16x16x32_f16 v[16:19], v[210:213], v[230:233], v[16:19]
	v_mfma_f32_16x16x32_f16 v[12:15], v[210:213], v[242:245], v[12:15]
	v_mfma_f32_16x16x32_f16 v[8:11], v[218:221], v[230:233], v[8:11]
	v_mfma_f32_16x16x32_f16 v[4:7], v[218:221], v[242:245], v[4:7]
	s_add_i32 s14, s14, 2
	s_add_u32 s12, s12, 0x100
	s_addc_u32 s13, s13, 0
	s_cmp_lt_u32 s14, 12
	s_barrier
	s_cbranch_scc0 .Lpk_exit_4

; #define LDA8(dst, b, h) _Pragma("unroll") for (int m = 0; m < 4; ++m) _Pragma("unroll") for (int k = 0; k < 2; ++k) \
;     dst[m][k] = *(const bf16x8*)((const char*)SA8(b, h) + lds_byte8(wr * 64 + m * 16 + fr, k * 32 + fq * 8))
; #define LDB8(dst, b, h) _Pragma("unroll") for (int n = 0; n < 2; ++n) _Pragma("unroll") for (int k = 0; k < 2; ++k) \
;     dst[n][k] = *(const bf16x8*)((const char*)SB8(b, h) + lds_byte8(wc * 32 + n * 16 + fr, k * 32 + fq * 8))
; #define WAIT_V8(n) asm volatile("s_waitcnt vmcnt(" #n ")" ::: "memory")
; #define WAIT_L8(n) asm volatile("s_waitcnt lgkmcnt(" #n ")" ::: "memory")
; #define BAR8 __builtin_amdgcn_s_barrier()
;     ...
;   { LDB8(B0, 0, 0); LDA8(At, 0, 0); STAGE8(SA8(1, 1), A, lda, brow + 128, nt - 1);
;     BAR8; WAIT_L8(0); MMA8(0, 0, At, B0); BAR8;
;     LDB8(B1, 0, 1); BAR8; WAIT_L8(0); MMA8(0, 1, At, B1); BAR8;
;     LDA8(At, 0, 1); WAIT_V8(4); BAR8; WAIT_L8(0); MMA8(1, 0, At, B0); MMA8(1, 1, At, B1); BAR8; }
.Lpk_exit_4:
	s_add_u32 s8, s8, 0x40780
	s_addc_u32 s9, s9, 0
	v_lshl_add_u64 v[132:133], s[8:9], 0, v[132:133]
	v_lshl_add_u64 v[0:1], v[0:1], 1, v[132:133]
	s_or_b32 m0, s100, 0xc000
	ds_read_b128 v[138:141], v171
	ds_read_b128 v[142:145], v171 offset:1024
	ds_read_b128 v[162:165], v171 offset:2048
	ds_read_b128 v[174:177], v171 offset:3072
	ds_read_b128 v[178:181], v156
	ds_read_b128 v[182:185], v156 offset:1024
	ds_read_b128 v[186:189], v155
	ds_read_b128 v[190:193], v155 offset:1024
	ds_read_b128 v[194:197], v154
	ds_read_b128 v[198:201], v154 offset:1024
	ds_read_b128 v[202:205], v153
	ds_read_b128 v[206:209], v153 offset:1024
	global_load_lds_dwordx4 v[0:1], off
	v_lshl_add_u64 v[0:1], s[8:9], 0, v[136:137]
	v_lshl_add_u64 v[0:1], v[134:135], 1, v[0:1]
	s_or_b32 m0, s100, 0xe000
	s_nop 0
	global_load_lds_dwordx4 v[0:1], off
	s_barrier
	s_waitcnt lgkmcnt(0)
	v_mfma_f32_16x16x32_f16 v[128:131], v[178:181], v[138:141], v[128:131]
	v_mfma_f32_16x16x32_f16 v[124:127], v[178:181], v[162:165], v[124:127]
	v_mfma_f32_16x16x32_f16 v[120:123], v[186:189], v[138:141], v[120:123]
	v_mfma_f32_16x16x32_f16 v[112:115], v[194:197], v[138:141], v[112:115]
	v_mfma_f32_16x16x32_f16 v[128:131], v[182:185], v[142:145], v[128:131]
	v_mfma_f32_16x16x32_f16 v[124:127], v[182:185], v[174:177], v[124:127]
	v_mfma_f32_16x16x32_f16 v[120:123], v[190:193], v[142:145], v[120:123]
	v_mfma_f32_16x16x32_f16 v[116:119], v[186:189], v[162:165], v[116:119]
	v_mfma_f32_16x16x32_f16 v[112:115], v[198:201], v[142:145], v[112:115]
	v_mfma_f32_16x16x32_f16 v[108:111], v[194:197], v[162:165], v[108:111]
	v_mfma_f32_16x16x32_f16 v[104:107], v[202:205], v[138:141], v[104:107]
	v_mfma_f32_16x16x32_f16 v[100:103], v[202:205], v[162:165], v[100:103]
	v_mfma_f32_16x16x32_f16 v[132:135], v[190:193], v[174:177], v[116:119]
	v_mfma_f32_16x16x32_f16 v[170:173], v[198:201], v[174:177], v[108:111]
	v_mfma_f32_16x16x32_f16 v[210:213], v[206:209], v[142:145], v[104:107]
	v_mfma_f32_16x16x32_f16 v[214:217], v[206:209], v[174:177], v[100:103]
	s_barrier
	s_nop 1
	ds_read_b128 v[100:103], v168
	ds_read_b128 v[104:107], v168 offset:1024
	ds_read_b128 v[108:111], v168 offset:2048
	ds_read_b128 v[116:119], v168 offset:3072
	s_barrier
	s_waitcnt lgkmcnt(0)
	v_mfma_f32_16x16x32_f16 v[80:83], v[194:197], v[100:103], v[80:83]
	v_mfma_f32_16x16x32_f16 v[76:79], v[194:197], v[108:111], v[76:79]
	v_mfma_f32_16x16x32_f16 v[72:75], v[202:205], v[100:103], v[72:75]
	v_mfma_f32_16x16x32_f16 v[68:71], v[202:205], v[108:111], v[68:71]
	v_mfma_f32_16x16x32_f16 v[96:99], v[178:181], v[100:103], v[96:99]
	v_mfma_f32_16x16x32_f16 v[92:95], v[178:181], v[108:111], v[92:95]
	v_mfma_f32_16x16x32_f16 v[88:91], v[186:189], v[100:103], v[88:91]
	v_mfma_f32_16x16x32_f16 v[84:87], v[186:189], v[108:111], v[84:87]
	v_mfma_f32_16x16x32_f16 v[80:83], v[198:201], v[104:107], v[80:83]
	v_mfma_f32_16x16x32_f16 v[76:79], v[198:201], v[116:119], v[76:79]
	v_mfma_f32_16x16x32_f16 v[72:75], v[206:209], v[104:107], v[72:75]
	v_mfma_f32_16x16x32_f16 v[68:71], v[206:209], v[116:119], v[68:71]
	v_mfma_f32_16x16x32_f16 v[166:169], v[182:185], v[104:107], v[96:99]
	v_mfma_f32_16x16x32_f16 v[178:181], v[182:185], v[116:119], v[92:95]
	v_mfma_f32_16x16x32_f16 v[182:185], v[190:193], v[104:107], v[88:91]
	v_mfma_f32_16x16x32_f16 v[186:189], v[190:193], v[116:119], v[84:87]
	s_barrier
	s_nop 0
	ds_read_b128 v[84:87], v156 offset:16384
	ds_read_b128 v[88:91], v156 offset:17408
	ds_read_b128 v[92:95], v155 offset:16384
	ds_read_b128 v[96:99], v155 offset:17408
	ds_read_b128 v[190:193], v154 offset:16384
	ds_read_b128 v[194:197], v154 offset:17408
	ds_read_b128 v[198:201], v153 offset:16384
	ds_read_b128 v[202:205], v153 offset:17408
	s_waitcnt vmcnt(4)
	s_barrier
	s_waitcnt lgkmcnt(0)
	v_mfma_f32_16x16x32_f16 v[64:67], v[84:87], v[138:141], v[64:67]
	v_mfma_f32_16x16x32_f16 v[60:63], v[84:87], v[162:165], v[60:63]
	v_mfma_f32_16x16x32_f16 v[56:59], v[92:95], v[138:141], v[56:59]
	v_mfma_f32_16x16x32_f16 v[52:55], v[92:95], v[162:165], v[52:55]
	v_mfma_f32_16x16x32_f16 v[48:51], v[190:193], v[138:141], v[48:51]
	v_mfma_f32_16x16x32_f16 v[44:47], v[190:193], v[162:165], v[44:47]
	v_mfma_f32_16x16x32_f16 v[40:43], v[198:201], v[138:141], v[40:43]
	v_mfma_f32_16x16x32_f16 v[36:39], v[198:201], v[162:165], v[36:39]
	v_mfma_f32_16x16x32_f16 v[64:67], v[88:91], v[142:145], v[64:67]
	v_mfma_f32_16x16x32_f16 v[60:63], v[88:91], v[174:177], v[60:63]
	v_mfma_f32_16x16x32_f16 v[56:59], v[96:99], v[142:145], v[56:59]
	v_mfma_f32_16x16x32_f16 v[52:55], v[96:99], v[174:177], v[52:55]
	v_mfma_f32_16x16x32_f16 v[48:51], v[194:197], v[142:145], v[48:51]
	v_mfma_f32_16x16x32_f16 v[44:47], v[194:197], v[174:177], v[44:47]
	v_mfma_f32_16x16x32_f16 v[40:43], v[202:205], v[142:145], v[40:43]
	v_mfma_f32_16x16x32_f16 v[36:39], v[202:205], v[174:177], v[36:39]
	v_mfma_f32_16x16x32_f16 v[32:35], v[84:87], v[100:103], v[32:35]
	v_mfma_f32_16x16x32_f16 v[28:31], v[84:87], v[108:111], v[28:31]
	v_mfma_f32_16x16x32_f16 v[24:27], v[92:95], v[100:103], v[24:27]
	v_mfma_f32_16x16x32_f16 v[20:23], v[92:95], v[108:111], v[20:23]
	v_mfma_f32_16x16x32_f16 v[16:19], v[190:193], v[100:103], v[16:19]
	v_mfma_f32_16x16x32_f16 v[12:15], v[190:193], v[108:111], v[12:15]
	v_mfma_f32_16x16x32_f16 v[8:11], v[198:201], v[100:103], v[8:11]
	v_mfma_f32_16x16x32_f16 v[4:7], v[198:201], v[108:111], v[4:7]
	v_mfma_f32_16x16x32_f16 v[136:139], v[88:91], v[104:107], v[32:35]
	v_mfma_f32_16x16x32_f16 v[140:143], v[88:91], v[116:119], v[28:31]
	v_mfma_f32_16x16x32_f16 v[162:165], v[96:99], v[104:107], v[24:27]
	v_mfma_f32_16x16x32_f16 v[174:177], v[96:99], v[116:119], v[20:23]
	v_mfma_f32_16x16x32_f16 v[206:209], v[194:197], v[104:107], v[16:19]
	v_mfma_f32_16x16x32_f16 v[190:193], v[194:197], v[116:119], v[12:15]
	v_mfma_f32_16x16x32_f16 v[194:197], v[202:205], v[104:107], v[8:11]
	v_mfma_f32_16x16x32_f16 v[198:201], v[202:205], v[116:119], v[4:7]
	s_barrier
; #define LDA8(dst, b, h) _Pragma("unroll") for (int m = 0; m < 4; ++m) _Pragma("unroll") for (int k = 0; k < 2; ++k) \
;     dst[m][k] = *(const bf16x8*)((const char*)SA8(b, h) + lds_byte8(wr * 64 + m * 16 + fr, k * 32 + fq * 8))
; #define LDB8(dst, b, h) _Pragma("unroll") for (int n = 0; n < 2; ++n) _Pragma("unroll") for (int k = 0; k < 2; ++k) \
;     dst[n][k] = *(const bf16x8*)((const char*)SB8(b, h) + lds_byte8(wc * 32 + n * 16 + fr, k * 32 + fq * 8))
; #define WAIT_V8(n) asm volatile("s_waitcnt vmcnt(" #n ")" ::: "memory")
; #define WAIT_L8(n) asm volatile("s_waitcnt lgkmcnt(" #n ")" ::: "memory")
; #define BAR8 __builtin_amdgcn_s_barrier()
;     ...
;   { LDB8(B0, 1, 0); LDA8(At, 1, 0); WAIT_V8(2); BAR8; WAIT_L8(0); MMA8(0, 0, At, B0); BAR8;
;     LDB8(B1, 1, 1); WAIT_V8(0); BAR8; WAIT_L8(0); MMA8(0, 1, At, B1); BAR8;
;     LDA8(At, 1, 1); BAR8; WAIT_L8(0); MMA8(1, 0, At, B0); MMA8(1, 1, At, B1); BAR8; }
;   if (wr == 0) BAR8;
;   __syncthreads();
;     ...
;   if (t < 256) {
	ds_read_b128 v[202:205], v161
	ds_read_b128 v[218:221], v161 offset:1024
	ds_read_b128 v[226:229], v161 offset:2048
	ds_read_b128 v[230:233], v161 offset:3072
	ds_read_b128 v[8:11], v156 offset:32768
	ds_read_b128 v[12:15], v156 offset:33792
	ds_read_b128 v[16:19], v155 offset:32768
	ds_read_b128 v[24:27], v155 offset:33792
	ds_read_b128 v[28:31], v154 offset:32768
	ds_read_b128 v[32:35], v154 offset:33792
	ds_read_b128 v[238:241], v153 offset:32768
	ds_read_b128 v[242:245], v153 offset:33792
	s_waitcnt vmcnt(2)
	s_barrier
	s_waitcnt lgkmcnt(0)
	v_mfma_f32_16x16x32_f16 v[4:7], v[8:11], v[202:205], v[128:131]
	v_mfma_f32_16x16x32_f16 v[104:107], v[12:15], v[218:221], v[4:7]
	v_mfma_f32_16x16x32_f16 v[4:7], v[8:11], v[226:229], v[124:127]
	v_mfma_f32_16x16x32_f16 v[116:119], v[12:15], v[230:233], v[4:7]
	v_mfma_f32_16x16x32_f16 v[4:7], v[16:19], v[202:205], v[120:123]
	v_mfma_f32_16x16x32_f16 v[100:103], v[24:27], v[218:221], v[4:7]
	v_mfma_f32_16x16x32_f16 v[4:7], v[16:19], v[226:229], v[132:135]
	v_mfma_f32_16x16x32_f16 v[108:111], v[24:27], v[230:233], v[4:7]
	v_mfma_f32_16x16x32_f16 v[4:7], v[28:31], v[202:205], v[112:115]
	v_mfma_f32_16x16x32_f16 v[92:95], v[32:35], v[218:221], v[4:7]
	v_mfma_f32_16x16x32_f16 v[4:7], v[28:31], v[226:229], v[170:173]
	v_mfma_f32_16x16x32_f16 v[96:99], v[32:35], v[230:233], v[4:7]
	v_mfma_f32_16x16x32_f16 v[4:7], v[238:241], v[202:205], v[210:213]
	v_mfma_f32_16x16x32_f16 v[84:87], v[242:245], v[218:221], v[4:7]
	v_mfma_f32_16x16x32_f16 v[4:7], v[238:241], v[226:229], v[214:217]
	v_mfma_f32_16x16x32_f16 v[88:91], v[242:245], v[230:233], v[4:7]
	s_barrier
	ds_read_b128 v[132:135], v158
	ds_read_b128 v[170:173], v158 offset:1024
	ds_read_b128 v[210:213], v158 offset:2048
	ds_read_b128 v[158:161], v158 offset:3072
	s_waitcnt vmcnt(0)
	s_barrier
	s_waitcnt lgkmcnt(0)
	v_mfma_f32_16x16x32_f16 v[4:7], v[8:11], v[132:135], v[166:169]
	v_mfma_f32_16x16x32_f16 v[8:11], v[8:11], v[210:213], v[178:181]
	v_mfma_f32_16x16x32_f16 v[4:7], v[12:15], v[170:173], v[4:7]
	v_mfma_f32_16x16x32_f16 v[20:23], v[12:15], v[158:161], v[8:11]
	v_mfma_f32_16x16x32_f16 v[8:11], v[16:19], v[132:135], v[182:185]
	v_mfma_f32_16x16x32_f16 v[12:15], v[16:19], v[210:213], v[186:189]
	v_mfma_f32_16x16x32_f16 v[8:11], v[24:27], v[170:173], v[8:11]
	v_mfma_f32_16x16x32_f16 v[24:27], v[24:27], v[158:161], v[12:15]
	v_mfma_f32_16x16x32_f16 v[12:15], v[28:31], v[132:135], v[80:83]
	v_mfma_f32_16x16x32_f16 v[16:19], v[28:31], v[210:213], v[76:79]
	v_mfma_f32_16x16x32_f16 v[12:15], v[32:35], v[170:173], v[12:15]
	v_mfma_f32_16x16x32_f16 v[28:31], v[32:35], v[158:161], v[16:19]
	v_mfma_f32_16x16x32_f16 v[16:19], v[238:241], v[132:135], v[72:75]
	v_mfma_f32_16x16x32_f16 v[32:35], v[238:241], v[210:213], v[68:71]
	v_mfma_f32_16x16x32_f16 v[16:19], v[242:245], v[170:173], v[16:19]
	v_mfma_f32_16x16x32_f16 v[32:35], v[242:245], v[158:161], v[32:35]
	s_barrier
	ds_read_b128 v[166:169], v156 offset:49152
	ds_read_b128 v[178:181], v156 offset:50176
	ds_read_b128 v[182:185], v155 offset:49152
	ds_read_b128 v[186:189], v155 offset:50176
	ds_read_b128 v[214:217], v154 offset:49152
	ds_read_b128 v[154:157], v154 offset:50176
	ds_read_b128 v[238:241], v153 offset:49152
	ds_read_b128 v[150:153], v153 offset:50176
	s_barrier
	s_waitcnt lgkmcnt(0)
	v_mfma_f32_16x16x32_f16 v[64:67], v[166:169], v[202:205], v[64:67]
	v_mfma_f32_16x16x32_f16 v[60:63], v[166:169], v[226:229], v[60:63]
	v_mfma_f32_16x16x32_f16 v[56:59], v[182:185], v[202:205], v[56:59]
	v_mfma_f32_16x16x32_f16 v[52:55], v[182:185], v[226:229], v[52:55]
	v_mfma_f32_16x16x32_f16 v[48:51], v[214:217], v[202:205], v[48:51]
	v_mfma_f32_16x16x32_f16 v[44:47], v[214:217], v[226:229], v[44:47]
	v_mfma_f32_16x16x32_f16 v[40:43], v[238:241], v[202:205], v[40:43]
	v_mfma_f32_16x16x32_f16 v[36:39], v[238:241], v[226:229], v[36:39]
	v_mfma_f32_16x16x32_f16 v[128:131], v[178:181], v[218:221], v[64:67]
	v_mfma_f32_16x16x32_f16 v[124:127], v[178:181], v[230:233], v[60:63]
	v_mfma_f32_16x16x32_f16 v[120:123], v[186:189], v[218:221], v[56:59]
	v_mfma_f32_16x16x32_f16 v[112:115], v[186:189], v[230:233], v[52:55]
	v_mfma_f32_16x16x32_f16 v[80:83], v[154:157], v[218:221], v[48:51]
	v_mfma_f32_16x16x32_f16 v[76:79], v[154:157], v[230:233], v[44:47]
	v_mfma_f32_16x16x32_f16 v[72:75], v[150:153], v[218:221], v[40:43]
	v_mfma_f32_16x16x32_f16 v[68:71], v[150:153], v[230:233], v[36:39]
	v_mfma_f32_16x16x32_f16 v[36:39], v[166:169], v[132:135], v[136:139]
	v_mfma_f32_16x16x32_f16 v[64:67], v[178:181], v[170:173], v[36:39]
	v_mfma_f32_16x16x32_f16 v[36:39], v[166:169], v[210:213], v[140:143]
	v_mfma_f32_16x16x32_f16 v[60:63], v[178:181], v[158:161], v[36:39]
	v_mfma_f32_16x16x32_f16 v[36:39], v[182:185], v[132:135], v[162:165]
	v_mfma_f32_16x16x32_f16 v[56:59], v[186:189], v[170:173], v[36:39]
	v_mfma_f32_16x16x32_f16 v[36:39], v[182:185], v[210:213], v[174:177]
	v_mfma_f32_16x16x32_f16 v[52:55], v[186:189], v[158:161], v[36:39]
	v_mfma_f32_16x16x32_f16 v[36:39], v[214:217], v[132:135], v[206:209]
	v_mfma_f32_16x16x32_f16 v[48:51], v[154:157], v[170:173], v[36:39]
	v_mfma_f32_16x16x32_f16 v[36:39], v[214:217], v[210:213], v[190:193]
	v_mfma_f32_16x16x32_f16 v[44:47], v[154:157], v[158:161], v[36:39]
	v_mfma_f32_16x16x32_f16 v[36:39], v[238:241], v[132:135], v[194:197]
	v_mfma_f32_16x16x32_f16 v[40:43], v[150:153], v[170:173], v[36:39]
	v_mfma_f32_16x16x32_f16 v[36:39], v[238:241], v[210:213], v[198:201]
	v_mfma_f32_16x16x32_f16 v[36:39], v[150:153], v[158:161], v[36:39]
	s_movk_i32 s8, 0x100
	v_cmp_gt_u32_e32 vcc, s8, v3
	s_barrier
	s_and_saveexec_b64 s[8:9], vcc
	s_cbranch_execz .LBB0_1018
	s_barrier

; #define LDA8(dst, b, h) _Pragma("unroll") for (int m = 0; m < 4; ++m) _Pragma("unroll") for (int k = 0; k < 2; ++k) \
;     dst[m][k] = *(const bf16x8*)((const char*)SA8(b, h) + lds_byte8(wr * 64 + m * 16 + fr, k * 32 + fq * 8))
; #define LDB8(dst, b, h) _Pragma("unroll") for (int n = 0; n < 2; ++n) _Pragma("unroll") for (int k = 0; k < 2; ++k) \
;     dst[n][k] = *(const bf16x8*)((const char*)SB8(b, h) + lds_byte8(wc * 32 + n * 16 + fr, k * 32 + fq * 8))
; #define WAIT_V8(n) asm volatile("s_waitcnt vmcnt(" #n ")" ::: "memory")
; #define WAIT_L8(n) asm volatile("s_waitcnt lgkmcnt(" #n ")" ::: "memory")
; #define BAR8 __builtin_amdgcn_s_barrier()
; #define SCHED8 __builtin_amdgcn_sched_barrier(0)
;     ...
;   const int brow = m0, bcol = n0;
;   const int wid = t >> 6, lane = t & 63, wr = wid >> 2, wc = wid & 3, fr = lane & 15, fq = lane >> 4;
;   f32x4 acc[2][2][4][2];
;   {
;     float zinit = 0.f;
;     asm volatile("" : "+v"(zinit));
; #pragma unroll
;     for (int a = 0; a < 2; ++a)
; #pragma unroll
;       for (int b = 0; b < 2; ++b)
; #pragma unroll
;         for (int m = 0; m < 4; ++m)
; #pragma unroll
;           for (int n = 0; n < 2; ++n)
; #pragma unroll
;             for (int j = 0; j < 4; ++j) acc[a][b][m][n][j] = zinit;
;   }
;   bf16x8 At[4][2], B0[2][2], B1[2][2];
;   const int nt = K / 64;
;   if (!pre) {
;     STAGE8(SB8(0, 0), Bt, K, bcol, 0); STAGE8(SA8(0, 0), A, lda, brow, 0);
;     STAGE8(SB8(0, 1), Bt, K, bcol + 128, 0); STAGE8(SA8(0, 1), A, lda, brow + 128, 0);
;   }
;   if (wr == 1) BAR8;
;   WAIT_V8(4); BAR8;
;   STAGE8(SB8(1, 0), Bt, K, bcol, 1); STAGE8(SA8(1, 0), A, lda, brow, 1); STAGE8(SB8(1, 1), Bt, K, bcol + 128, 1);
;   WAIT_V8(6); BAR8;
;   for (int tt = 0; tt < nt - 2; tt += 2) {
;     LDB8(B0, 0, 0); SCHED8; LDA8(At, 0, 0); STAGE8(SA8(1, 1), A, lda, brow + 128, tt + 1);
;     WAIT_L8(8); BAR8; WAIT_L8(0); MMA8(0, 0, At, B0); BAR8; SCHED8;
;     LDB8(B1, 0, 1); STAGE8(SB8(0, 0), Bt, K, bcol, tt + 2);
.LBB0_1151:
	s_or_b64 exec, exec, s[12:13]
	s_lshl_b32 s29, s20, 10
	s_and_b32 s36, s29, 0xfc0000
	s_mov_b64 s[38:39], 0x80
	v_lshl_add_u64 v[14:15], v[14:15], 0, s[38:39]
	s_or_b32 m0, s100, 0x18000
	s_waitcnt vmcnt(4)
	s_barrier
	global_load_lds_dwordx4 v[14:15], off
	v_lshl_add_u64 v[14:15], v[18:19], 0, s[38:39]
	s_or_b32 m0, s100, 0x1a000
	global_load_lds_dwordx4 v[14:15], off
	v_lshl_add_u64 v[14:15], v[20:21], 0, s[38:39]
	s_or_b32 m0, s100, 0x8000
	global_load_lds_dwordx4 v[14:15], off
	v_lshl_add_u64 v[14:15], v[22:23], 0, s[38:39]
	s_or_b32 m0, s100, 0xa000
	global_load_lds_dwordx4 v[14:15], off
	v_lshl_add_u64 v[14:15], v[26:27], 0, s[38:39]
	s_or_b32 m0, s100, 0x1c000
	s_nop 0
	global_load_lds_dwordx4 v[14:15], off
	v_lshl_add_u64 v[14:15], v[28:29], 0, s[38:39]
	s_or_b32 m0, s100, 0x1e000
	v_and_b32_e32 v147, 15, v3
	global_load_lds_dwordx4 v[14:15], off
	v_bfe_u32 v148, v3, 4, 2
	v_lshlrev_b32_e32 v14, 4, v148
	v_lshlrev_b32_e32 v15, 6, v147
	v_lshlrev_b32_e32 v18, 2, v3
	v_lshlrev_b64 v[136:137], 9, v[16:17]
	v_or_b32_e32 v17, v14, v15
	v_and_b32_e32 v18, 32, v18
	s_mov_b32 s29, 0x10000
	s_and_b32 s12, s21, 0xffffff00
	v_bitop3_b32 v20, v17, s29, v18 bitop3:0xde
	s_mov_b32 s29, 0x14000
	s_ashr_i32 s13, s12, 31
	v_readlane_b32 s40, v254, 35
	v_bitop3_b32 v19, v14, v18, v15 bitop3:0x36
	v_bitop3_b32 v21, v17, s29, v18 bitop3:0xde
	s_mov_b32 s29, 0x18000
	v_lshlrev_b32_e32 v15, 6, v3
	s_lshl_b64 s[12:13], s[12:13], 10
	s_mov_b32 s37, s40
	v_bitop3_b32 v22, v17, s29, v18 bitop3:0xde
	s_mov_b32 s29, 0x1c000
	v_and_b32_e32 v15, 0x3c0, v15
	v_bitop3_b32 v17, v17, s29, v18 bitop3:0xde
	v_bitop3_b32 v18, v15, v18, v14 bitop3:0x36
	v_lshl_add_u64 v[14:15], s[12:13], 0, v[6:7]
	v_lshl_add_u64 v[6:7], s[36:37], 0, v[6:7]
	v_lshl_add_u64 v[14:15], v[14:15], 0, v[8:9]
	v_lshl_add_u64 v[6:7], v[6:7], 0, v[8:9]
	v_bfe_u32 v146, v3, 6, 2
	s_waitcnt vmcnt(6)
	v_lshlrev_b32_e32 v149, 6, v5
	v_lshlrev_b32_e32 v5, 13, v5
	v_lshl_add_u64 v[138:139], s[4:5], 0, v[14:15]
	v_lshl_add_u64 v[14:15], s[12:13], 0, v[10:11]
	v_lshl_add_u64 v[142:143], s[2:3], 0, v[6:7]
	v_lshl_add_u64 v[6:7], s[36:37], 0, v[10:11]
	v_lshlrev_b64 v[134:135], 9, v[24:25]
	v_readlane_b32 s41, v254, 36
	v_readlane_b32 s42, v254, 37
	v_readlane_b32 s43, v254, 38
	v_lshlrev_b32_e32 v16, 12, v146
	v_or_b32_e32 v23, 0x800, v5
	v_or_b32_e32 v24, 0x1000, v5
	v_or_b32_e32 v25, 0x1800, v5
	v_lshl_add_u64 v[14:15], v[14:15], 0, v[12:13]
	v_lshl_add_u64 v[6:7], v[6:7], 0, v[12:13]
	v_lshl_add_u64 v[140:141], s[4:5], 0, v[14:15]
	v_lshl_add_u64 v[144:145], s[2:3], 0, v[6:7]
	s_mov_b32 s29, -2
	s_mov_b64 s[12:13], 0
	v_add_u32_e32 v171, v20, v16
	v_add_u32_e32 v156, v19, v5
	v_add_u32_e32 v155, v18, v23
	v_add_u32_e32 v154, v18, v24
	v_add_u32_e32 v153, v18, v25
	v_add_u32_e32 v167, v21, v16
	v_add_u32_e32 v160, v22, v16
	v_add_u32_e32 v158, v17, v16
	s_mov_b64 s[36:37], 0x3020080
	s_mov_b64 s[38:39], 0xc9a0100
	s_mov_b64 s[40:41], 0x3000100
	s_mov_b64 s[42:43], 0xc9c0100
	s_mov_b64 s[44:45], 0x3020100
	s_mov_b64 s[46:47], 0xc9a0180
	s_mov_b64 s[48:49], 0x3000180
	s_mov_b64 s[50:51], 0xc9c0180
	s_barrier
	ds_read_b128 v[174:177], v171
	ds_read_b128 v[178:181], v171 offset:1024
	ds_read_b128 v[182:185], v171 offset:2048
	ds_read_b128 v[186:189], v171 offset:3072
	v_lshl_add_u64 v[222:223], v[142:143], 0, s[12:13]
	v_lshl_add_u64 v[226:227], v[222:223], 0, s[36:37]
	s_or_b32 m0, s100, 0xc000
	v_lshl_add_u64 v[236:237], v[144:145], 0, s[12:13]
	ds_read_b128 v[190:193], v156
	ds_read_b128 v[194:197], v156 offset:1024
	ds_read_b128 v[198:201], v155
	ds_read_b128 v[202:205], v155 offset:1024
	ds_read_b128 v[206:209], v154
	ds_read_b128 v[210:213], v154 offset:1024
	ds_read_b128 v[214:217], v153
	ds_read_b128 v[218:221], v153 offset:1024
	global_load_lds_dwordx4 v[226:227], off
	v_lshl_add_u64 v[226:227], v[236:237], 0, s[36:37]
	s_or_b32 m0, s100, 0xe000
	s_nop 0
	global_load_lds_dwordx4 v[226:227], off
	s_waitcnt lgkmcnt(8)
	s_barrier
	s_waitcnt lgkmcnt(0)
	v_mfma_f32_16x16x32_bf16 v[128:131], v[190:193], v[174:177], 0
	v_mfma_f32_16x16x32_bf16 v[124:127], v[190:193], v[182:185], 0
	v_mfma_f32_16x16x32_bf16 v[120:123], v[198:201], v[174:177], 0
	v_mfma_f32_16x16x32_bf16 v[116:119], v[198:201], v[182:185], 0
	v_mfma_f32_16x16x32_bf16 v[112:115], v[206:209], v[174:177], 0
	v_mfma_f32_16x16x32_bf16 v[108:111], v[206:209], v[182:185], 0
	v_mfma_f32_16x16x32_bf16 v[104:107], v[214:217], v[174:177], 0
	v_mfma_f32_16x16x32_bf16 v[100:103], v[214:217], v[182:185], 0
	v_mfma_f32_16x16x32_bf16 v[128:131], v[194:197], v[178:181], v[128:131]
	v_mfma_f32_16x16x32_bf16 v[124:127], v[194:197], v[186:189], v[124:127]
	v_mfma_f32_16x16x32_bf16 v[120:123], v[202:205], v[178:181], v[120:123]
	v_mfma_f32_16x16x32_bf16 v[116:119], v[202:205], v[186:189], v[116:119]
	v_mfma_f32_16x16x32_bf16 v[112:115], v[210:213], v[178:181], v[112:115]
	v_mfma_f32_16x16x32_bf16 v[108:111], v[210:213], v[186:189], v[108:111]
	v_mfma_f32_16x16x32_bf16 v[104:107], v[218:221], v[178:181], v[104:107]
	v_mfma_f32_16x16x32_bf16 v[100:103], v[218:221], v[186:189], v[100:103]
	s_barrier
	v_lshl_add_u64 v[246:247], v[138:139], 0, s[12:13]
	v_lshl_add_u64 v[248:249], v[246:247], 0, s[38:39]
	s_or_b32 m0, s100, 0x10000
	ds_read_b128 v[226:229], v167
	ds_read_b128 v[230:233], v167 offset:1024
	ds_read_b128 v[238:241], v167 offset:2048
	ds_read_b128 v[242:245], v167 offset:3072
	global_load_lds_dwordx4 v[248:249], off
	v_lshl_add_u64 v[248:249], v[140:141], 0, s[12:13]
	v_lshl_add_u64 v[250:251], v[248:249], 0, s[38:39]
	s_or_b32 m0, s100, 0x12000
	s_nop 0
	global_load_lds_dwordx4 v[250:251], off
	s_barrier
; #define LDA8(dst, b, h) _Pragma("unroll") for (int m = 0; m < 4; ++m) _Pragma("unroll") for (int k = 0; k < 2; ++k) \
;     dst[m][k] = *(const bf16x8*)((const char*)SA8(b, h) + lds_byte8(wr * 64 + m * 16 + fr, k * 32 + fq * 8))
; #define LDB8(dst, b, h) _Pragma("unroll") for (int n = 0; n < 2; ++n) _Pragma("unroll") for (int k = 0; k < 2; ++k) \
;     dst[n][k] = *(const bf16x8*)((const char*)SB8(b, h) + lds_byte8(wc * 32 + n * 16 + fr, k * 32 + fq * 8))
; #define WAIT_V8(n) asm volatile("s_waitcnt vmcnt(" #n ")" ::: "memory")
; #define WAIT_L8(n) asm volatile("s_waitcnt lgkmcnt(" #n ")" ::: "memory")
; #define BAR8 __builtin_amdgcn_s_barrier()
; #define SCHED8 __builtin_amdgcn_sched_barrier(0)
;     ...
;     LDB8(B1, 0, 1); STAGE8(SB8(0, 0), Bt, K, bcol, tt + 2);
;     BAR8; WAIT_L8(0); MMA8(0, 1, At, B1); BAR8;
;     LDA8(At, 0, 1); STAGE8(SA8(0, 0), A, lda, brow, tt + 2);
;     BAR8; WAIT_L8(0); MMA8(1, 0, At, B0); BAR8; SCHED8;
;     STAGE8(SB8(0, 1), Bt, K, bcol + 128, tt + 2);
;     WAIT_V8(6); BAR8; MMA8(1, 1, At, B1); BAR8;
;     LDB8(B0, 1, 0); SCHED8; LDA8(At, 1, 0); STAGE8(SA8(0, 1), A, lda, brow + 128, tt + 2);
;     WAIT_L8(8); BAR8; WAIT_L8(0); MMA8(0, 0, At, B0); BAR8; SCHED8;
	s_waitcnt lgkmcnt(0)
	v_mfma_f32_16x16x32_bf16 v[96:99], v[190:193], v[226:229], 0
	v_mfma_f32_16x16x32_bf16 v[92:95], v[190:193], v[238:241], 0
	v_mfma_f32_16x16x32_bf16 v[88:91], v[198:201], v[226:229], 0
	v_mfma_f32_16x16x32_bf16 v[84:87], v[198:201], v[238:241], 0
	v_mfma_f32_16x16x32_bf16 v[80:83], v[206:209], v[226:229], 0
	v_mfma_f32_16x16x32_bf16 v[76:79], v[206:209], v[238:241], 0
	v_mfma_f32_16x16x32_bf16 v[72:75], v[214:217], v[226:229], 0
	v_mfma_f32_16x16x32_bf16 v[68:71], v[214:217], v[238:241], 0
	v_mfma_f32_16x16x32_bf16 v[96:99], v[194:197], v[230:233], v[96:99]
	v_mfma_f32_16x16x32_bf16 v[92:95], v[194:197], v[242:245], v[92:95]
	v_mfma_f32_16x16x32_bf16 v[88:91], v[202:205], v[230:233], v[88:91]
	v_mfma_f32_16x16x32_bf16 v[84:87], v[202:205], v[242:245], v[84:87]
	v_mfma_f32_16x16x32_bf16 v[80:83], v[210:213], v[230:233], v[80:83]
	v_mfma_f32_16x16x32_bf16 v[76:79], v[210:213], v[242:245], v[76:79]
	v_mfma_f32_16x16x32_bf16 v[72:75], v[218:221], v[230:233], v[72:75]
	v_mfma_f32_16x16x32_bf16 v[68:71], v[218:221], v[242:245], v[68:71]
	v_lshl_add_u64 v[250:251], v[222:223], 0, s[40:41]
	s_mov_b32 m0, s100
	s_barrier
	ds_read_b128 v[190:193], v156 offset:16384
	ds_read_b128 v[194:197], v156 offset:17408
	ds_read_b128 v[198:201], v155 offset:16384
	ds_read_b128 v[202:205], v155 offset:17408
	ds_read_b128 v[206:209], v154 offset:16384
	ds_read_b128 v[210:213], v154 offset:17408
	ds_read_b128 v[214:217], v153 offset:16384
	ds_read_b128 v[218:221], v153 offset:17408
	global_load_lds_dwordx4 v[250:251], off
	v_lshl_add_u64 v[250:251], v[236:237], 0, s[40:41]
	s_or_b32 m0, s100, 0x2000
	s_nop 0
	global_load_lds_dwordx4 v[250:251], off
	s_barrier
	s_waitcnt lgkmcnt(0)
	v_mfma_f32_16x16x32_bf16 v[64:67], v[190:193], v[174:177], 0
	v_mfma_f32_16x16x32_bf16 v[60:63], v[190:193], v[182:185], 0
	v_mfma_f32_16x16x32_bf16 v[56:59], v[198:201], v[174:177], 0
	v_mfma_f32_16x16x32_bf16 v[52:55], v[198:201], v[182:185], 0
	v_mfma_f32_16x16x32_bf16 v[48:51], v[206:209], v[174:177], 0
	v_mfma_f32_16x16x32_bf16 v[44:47], v[206:209], v[182:185], 0
	v_mfma_f32_16x16x32_bf16 v[40:43], v[214:217], v[174:177], 0
	v_mfma_f32_16x16x32_bf16 v[36:39], v[214:217], v[182:185], 0
	v_mfma_f32_16x16x32_bf16 v[64:67], v[194:197], v[178:181], v[64:67]
	v_mfma_f32_16x16x32_bf16 v[60:63], v[194:197], v[186:189], v[60:63]
	v_mfma_f32_16x16x32_bf16 v[56:59], v[202:205], v[178:181], v[56:59]
	v_mfma_f32_16x16x32_bf16 v[52:55], v[202:205], v[186:189], v[52:55]
	v_mfma_f32_16x16x32_bf16 v[48:51], v[210:213], v[178:181], v[48:51]
	v_mfma_f32_16x16x32_bf16 v[44:47], v[210:213], v[186:189], v[44:47]
	v_mfma_f32_16x16x32_bf16 v[40:43], v[218:221], v[178:181], v[40:43]
	v_mfma_f32_16x16x32_bf16 v[36:39], v[218:221], v[186:189], v[36:39]
	s_barrier
	v_lshl_add_u64 v[174:175], v[246:247], 0, s[42:43]
	s_or_b32 m0, s100, 0x14000
	s_nop 0
	global_load_lds_dwordx4 v[174:175], off
	v_lshl_add_u64 v[174:175], v[248:249], 0, s[42:43]
	s_or_b32 m0, s100, 0x16000
	s_nop 0
	global_load_lds_dwordx4 v[174:175], off
	s_waitcnt vmcnt(6)
	s_barrier
	v_mfma_f32_16x16x32_bf16 v[32:35], v[190:193], v[226:229], 0
	v_mfma_f32_16x16x32_bf16 v[28:31], v[190:193], v[238:241], 0
	v_mfma_f32_16x16x32_bf16 v[24:27], v[198:201], v[226:229], 0
	v_mfma_f32_16x16x32_bf16 v[20:23], v[198:201], v[238:241], 0
	v_mfma_f32_16x16x32_bf16 v[16:19], v[206:209], v[226:229], 0
	v_mfma_f32_16x16x32_bf16 v[12:15], v[206:209], v[238:241], 0
	v_mfma_f32_16x16x32_bf16 v[8:11], v[214:217], v[226:229], 0
	v_mfma_f32_16x16x32_bf16 v[4:7], v[214:217], v[238:241], 0
	v_mfma_f32_16x16x32_bf16 v[32:35], v[194:197], v[230:233], v[32:35]
	v_mfma_f32_16x16x32_bf16 v[28:31], v[194:197], v[242:245], v[28:31]
	v_mfma_f32_16x16x32_bf16 v[24:27], v[202:205], v[230:233], v[24:27]
	v_mfma_f32_16x16x32_bf16 v[20:23], v[202:205], v[242:245], v[20:23]
	v_mfma_f32_16x16x32_bf16 v[16:19], v[210:213], v[230:233], v[16:19]
	v_mfma_f32_16x16x32_bf16 v[12:15], v[210:213], v[242:245], v[12:15]
	v_mfma_f32_16x16x32_bf16 v[8:11], v[218:221], v[230:233], v[8:11]
	v_mfma_f32_16x16x32_bf16 v[4:7], v[218:221], v[242:245], v[4:7]
	s_barrier
	ds_read_b128 v[174:177], v160
	ds_read_b128 v[178:181], v160 offset:1024
	ds_read_b128 v[182:185], v160 offset:2048
	ds_read_b128 v[186:189], v160 offset:3072
	v_lshl_add_u64 v[226:227], v[222:223], 0, s[44:45]
	s_or_b32 m0, s100, 0x4000
	ds_read_b128 v[190:193], v156 offset:32768
	ds_read_b128 v[194:197], v156 offset:33792
	ds_read_b128 v[198:201], v155 offset:32768
	ds_read_b128 v[202:205], v155 offset:33792
	ds_read_b128 v[206:209], v154 offset:32768
	ds_read_b128 v[210:213], v154 offset:33792
	ds_read_b128 v[214:217], v153 offset:32768
	ds_read_b128 v[218:221], v153 offset:33792
	global_load_lds_dwordx4 v[226:227], off
	v_lshl_add_u64 v[226:227], v[236:237], 0, s[44:45]
	s_or_b32 m0, s100, 0x6000
	s_nop 0
	global_load_lds_dwordx4 v[226:227], off
	s_waitcnt lgkmcnt(8)
	s_barrier
; #define LDA8(dst, b, h) _Pragma("unroll") for (int m = 0; m < 4; ++m) _Pragma("unroll") for (int k = 0; k < 2; ++k) \
;     dst[m][k] = *(const bf16x8*)((const char*)SA8(b, h) + lds_byte8(wr * 64 + m * 16 + fr, k * 32 + fq * 8))
; #define LDB8(dst, b, h) _Pragma("unroll") for (int n = 0; n < 2; ++n) _Pragma("unroll") for (int k = 0; k < 2; ++k) \
;     dst[n][k] = *(const bf16x8*)((const char*)SB8(b, h) + lds_byte8(wc * 32 + n * 16 + fr, k * 32 + fq * 8))
; #define WAIT_V8(n) asm volatile("s_waitcnt vmcnt(" #n ")" ::: "memory")
; #define WAIT_L8(n) asm volatile("s_waitcnt lgkmcnt(" #n ")" ::: "memory")
; #define BAR8 __builtin_amdgcn_s_barrier()
; #define SCHED8 __builtin_amdgcn_sched_barrier(0)
;     ...
;   for (int tt = 0; tt < nt - 2; tt += 2) {
;     ...
;     WAIT_L8(8); BAR8; WAIT_L8(0); MMA8(0, 0, At, B0); BAR8; SCHED8;
;     LDB8(B1, 1, 1); STAGE8(SB8(1, 0), Bt, K, bcol, tt + 3);
;     BAR8; WAIT_L8(0); MMA8(0, 1, At, B1); BAR8;
;     LDA8(At, 1, 1); STAGE8(SA8(1, 0), A, lda, brow, tt + 3);
;     BAR8; WAIT_L8(0); MMA8(1, 0, At, B0); BAR8; SCHED8;
;     STAGE8(SB8(1, 1), Bt, K, bcol + 128, tt + 3);
;     WAIT_V8(6); BAR8; MMA8(1, 1, At, B1); BAR8;
	s_waitcnt lgkmcnt(0)
	v_mfma_f32_16x16x32_bf16 v[128:131], v[190:193], v[174:177], v[128:131]
	v_mfma_f32_16x16x32_bf16 v[124:127], v[190:193], v[182:185], v[124:127]
	v_mfma_f32_16x16x32_bf16 v[120:123], v[198:201], v[174:177], v[120:123]
	v_mfma_f32_16x16x32_bf16 v[116:119], v[198:201], v[182:185], v[116:119]
	v_mfma_f32_16x16x32_bf16 v[112:115], v[206:209], v[174:177], v[112:115]
	v_mfma_f32_16x16x32_bf16 v[108:111], v[206:209], v[182:185], v[108:111]
	v_mfma_f32_16x16x32_bf16 v[104:107], v[214:217], v[174:177], v[104:107]
	v_mfma_f32_16x16x32_bf16 v[100:103], v[214:217], v[182:185], v[100:103]
	v_mfma_f32_16x16x32_bf16 v[128:131], v[194:197], v[178:181], v[128:131]
	v_mfma_f32_16x16x32_bf16 v[124:127], v[194:197], v[186:189], v[124:127]
	v_mfma_f32_16x16x32_bf16 v[120:123], v[202:205], v[178:181], v[120:123]
	v_mfma_f32_16x16x32_bf16 v[116:119], v[202:205], v[186:189], v[116:119]
	v_mfma_f32_16x16x32_bf16 v[112:115], v[210:213], v[178:181], v[112:115]
	v_mfma_f32_16x16x32_bf16 v[108:111], v[210:213], v[186:189], v[108:111]
	v_mfma_f32_16x16x32_bf16 v[104:107], v[218:221], v[178:181], v[104:107]
	v_mfma_f32_16x16x32_bf16 v[100:103], v[218:221], v[186:189], v[100:103]
	s_barrier
	v_lshl_add_u64 v[250:251], v[246:247], 0, s[46:47]
	s_or_b32 m0, s100, 0x18000
	ds_read_b128 v[226:229], v158
	ds_read_b128 v[230:233], v158 offset:1024
	ds_read_b128 v[238:241], v158 offset:2048
	ds_read_b128 v[242:245], v158 offset:3072
	global_load_lds_dwordx4 v[250:251], off
	v_lshl_add_u64 v[250:251], v[248:249], 0, s[46:47]
	s_or_b32 m0, s100, 0x1a000
	s_nop 0
	global_load_lds_dwordx4 v[250:251], off
	s_barrier
	s_waitcnt lgkmcnt(0)
	v_mfma_f32_16x16x32_bf16 v[96:99], v[190:193], v[226:229], v[96:99]
	v_mfma_f32_16x16x32_bf16 v[92:95], v[190:193], v[238:241], v[92:95]
	v_mfma_f32_16x16x32_bf16 v[88:91], v[198:201], v[226:229], v[88:91]
	v_mfma_f32_16x16x32_bf16 v[84:87], v[198:201], v[238:241], v[84:87]
	v_mfma_f32_16x16x32_bf16 v[80:83], v[206:209], v[226:229], v[80:83]
	v_mfma_f32_16x16x32_bf16 v[76:79], v[206:209], v[238:241], v[76:79]
	v_mfma_f32_16x16x32_bf16 v[72:75], v[214:217], v[226:229], v[72:75]
	v_mfma_f32_16x16x32_bf16 v[68:71], v[214:217], v[238:241], v[68:71]
	v_mfma_f32_16x16x32_bf16 v[96:99], v[194:197], v[230:233], v[96:99]
	v_mfma_f32_16x16x32_bf16 v[92:95], v[194:197], v[242:245], v[92:95]
	v_mfma_f32_16x16x32_bf16 v[88:91], v[202:205], v[230:233], v[88:91]
	v_mfma_f32_16x16x32_bf16 v[84:87], v[202:205], v[242:245], v[84:87]
	v_mfma_f32_16x16x32_bf16 v[80:83], v[210:213], v[230:233], v[80:83]
	v_mfma_f32_16x16x32_bf16 v[76:79], v[210:213], v[242:245], v[76:79]
	v_mfma_f32_16x16x32_bf16 v[72:75], v[218:221], v[230:233], v[72:75]
	v_mfma_f32_16x16x32_bf16 v[68:71], v[218:221], v[242:245], v[68:71]
	v_lshl_add_u64 v[222:223], v[222:223], 0, s[48:49]
	s_or_b32 m0, s100, 0x8000
	s_barrier
	ds_read_b128 v[190:193], v156 offset:49152
	ds_read_b128 v[194:197], v156 offset:50176
	ds_read_b128 v[198:201], v155 offset:49152
	ds_read_b128 v[202:205], v155 offset:50176
	ds_read_b128 v[206:209], v154 offset:49152
	ds_read_b128 v[210:213], v154 offset:50176
	ds_read_b128 v[214:217], v153 offset:49152
	ds_read_b128 v[218:221], v153 offset:50176
	global_load_lds_dwordx4 v[222:223], off
	v_lshl_add_u64 v[222:223], v[236:237], 0, s[48:49]
	s_or_b32 m0, s100, 0xa000
	s_nop 0
	global_load_lds_dwordx4 v[222:223], off
	s_barrier
	s_waitcnt lgkmcnt(0)
	v_mfma_f32_16x16x32_bf16 v[64:67], v[190:193], v[174:177], v[64:67]
	v_mfma_f32_16x16x32_bf16 v[60:63], v[190:193], v[182:185], v[60:63]
	v_mfma_f32_16x16x32_bf16 v[56:59], v[198:201], v[174:177], v[56:59]
	v_mfma_f32_16x16x32_bf16 v[52:55], v[198:201], v[182:185], v[52:55]
	v_mfma_f32_16x16x32_bf16 v[48:51], v[206:209], v[174:177], v[48:51]
	v_mfma_f32_16x16x32_bf16 v[44:47], v[206:209], v[182:185], v[44:47]
	v_mfma_f32_16x16x32_bf16 v[40:43], v[214:217], v[174:177], v[40:43]
	v_mfma_f32_16x16x32_bf16 v[36:39], v[214:217], v[182:185], v[36:39]
	v_mfma_f32_16x16x32_bf16 v[64:67], v[194:197], v[178:181], v[64:67]
	v_mfma_f32_16x16x32_bf16 v[60:63], v[194:197], v[186:189], v[60:63]
	v_mfma_f32_16x16x32_bf16 v[56:59], v[202:205], v[178:181], v[56:59]
	v_mfma_f32_16x16x32_bf16 v[52:55], v[202:205], v[186:189], v[52:55]
	v_mfma_f32_16x16x32_bf16 v[48:51], v[210:213], v[178:181], v[48:51]
	v_mfma_f32_16x16x32_bf16 v[44:47], v[210:213], v[186:189], v[44:47]
	v_mfma_f32_16x16x32_bf16 v[40:43], v[218:221], v[178:181], v[40:43]
	v_mfma_f32_16x16x32_bf16 v[36:39], v[218:221], v[186:189], v[36:39]
	s_barrier
	v_lshl_add_u64 v[174:175], v[246:247], 0, s[50:51]
	s_or_b32 m0, s100, 0x1c000
	s_nop 0
	global_load_lds_dwordx4 v[174:175], off
	v_lshl_add_u64 v[174:175], v[248:249], 0, s[50:51]
	s_or_b32 m0, s100, 0x1e000
	s_nop 0
	global_load_lds_dwordx4 v[174:175], off
	s_waitcnt vmcnt(6)
	s_barrier
	v_mfma_f32_16x16x32_bf16 v[32:35], v[190:193], v[226:229], v[32:35]
	v_mfma_f32_16x16x32_bf16 v[28:31], v[190:193], v[238:241], v[28:31]
	v_mfma_f32_16x16x32_bf16 v[24:27], v[198:201], v[226:229], v[24:27]
	v_mfma_f32_16x16x32_bf16 v[20:23], v[198:201], v[238:241], v[20:23]
	v_mfma_f32_16x16x32_bf16 v[16:19], v[206:209], v[226:229], v[16:19]
	v_mfma_f32_16x16x32_bf16 v[12:15], v[206:209], v[238:241], v[12:15]
	v_mfma_f32_16x16x32_bf16 v[8:11], v[214:217], v[226:229], v[8:11]
	v_mfma_f32_16x16x32_bf16 v[4:7], v[214:217], v[238:241], v[4:7]
	v_mfma_f32_16x16x32_bf16 v[32:35], v[194:197], v[230:233], v[32:35]
	v_mfma_f32_16x16x32_bf16 v[28:31], v[194:197], v[242:245], v[28:31]
	v_mfma_f32_16x16x32_bf16 v[24:27], v[202:205], v[230:233], v[24:27]
	v_mfma_f32_16x16x32_bf16 v[20:23], v[202:205], v[242:245], v[20:23]
	v_mfma_f32_16x16x32_bf16 v[16:19], v[210:213], v[230:233], v[16:19]
	v_mfma_f32_16x16x32_bf16 v[12:15], v[210:213], v[242:245], v[12:15]
	v_mfma_f32_16x16x32_bf16 v[8:11], v[218:221], v[230:233], v[8:11]
	v_mfma_f32_16x16x32_bf16 v[4:7], v[218:221], v[242:245], v[4:7]
	s_add_i32 s29, s29, 2
	s_add_u32 s12, s12, 0x100
	s_addc_u32 s13, s13, 0
	s_cmp_lt_u32 s29, 4
	s_barrier
	s_cbranch_scc0 .Lpk_exit_5

; #define LDA8(dst, b, h) _Pragma("unroll") for (int m = 0; m < 4; ++m) _Pragma("unroll") for (int k = 0; k < 2; ++k) \
;     dst[m][k] = *(const bf16x8*)((const char*)SA8(b, h) + lds_byte8(wr * 64 + m * 16 + fr, k * 32 + fq * 8))
; #define LDB8(dst, b, h) _Pragma("unroll") for (int n = 0; n < 2; ++n) _Pragma("unroll") for (int k = 0; k < 2; ++k) \
;     dst[n][k] = *(const bf16x8*)((const char*)SB8(b, h) + lds_byte8(wc * 32 + n * 16 + fr, k * 32 + fq * 8))
; #define WAIT_V8(n) asm volatile("s_waitcnt vmcnt(" #n ")" ::: "memory")
; #define WAIT_L8(n) asm volatile("s_waitcnt lgkmcnt(" #n ")" ::: "memory")
; #define BAR8 __builtin_amdgcn_s_barrier()
;     ...
;   { LDB8(B0, 0, 0); LDA8(At, 0, 0); STAGE8(SA8(1, 1), A, lda, brow + 128, nt - 1);
;     BAR8; WAIT_L8(0); MMA8(0, 0, At, B0); BAR8;
;     LDB8(B1, 0, 1); BAR8; WAIT_L8(0); MMA8(0, 1, At, B1); BAR8;
;     LDA8(At, 0, 1); WAIT_V8(4); BAR8; WAIT_L8(0); MMA8(1, 0, At, B0); MMA8(1, 1, At, B1); BAR8; }
.Lpk_exit_5:
	s_add_u32 s2, s2, s27
	s_addc_u32 s3, s3, 0
	s_add_u32 s2, s2, 0x3000380
	s_addc_u32 s3, s3, 0
	v_lshl_add_u64 v[136:137], v[136:137], 1, s[2:3]
	v_lshl_add_u64 v[0:1], v[0:1], 1, v[136:137]
	s_or_b32 m0, s100, 0xc000
	ds_read_b128 v[138:141], v171
	ds_read_b128 v[142:145], v171 offset:1024
	ds_read_b128 v[162:165], v171 offset:2048
	ds_read_b128 v[168:171], v171 offset:3072
	ds_read_b128 v[174:177], v156
	ds_read_b128 v[178:181], v156 offset:1024
	ds_read_b128 v[182:185], v155
	ds_read_b128 v[186:189], v155 offset:1024
	ds_read_b128 v[190:193], v154
	ds_read_b128 v[194:197], v154 offset:1024
	ds_read_b128 v[198:201], v153
	ds_read_b128 v[202:205], v153 offset:1024
	global_load_lds_dwordx4 v[0:1], off
	v_lshl_add_u64 v[0:1], v[134:135], 1, s[2:3]
	v_lshl_add_u64 v[0:1], v[132:133], 1, v[0:1]
	s_or_b32 m0, s100, 0xe000
	s_nop 0
	global_load_lds_dwordx4 v[0:1], off
	s_barrier
	s_waitcnt lgkmcnt(0)
	v_mfma_f32_16x16x32_bf16 v[128:131], v[174:177], v[138:141], v[128:131]
	v_mfma_f32_16x16x32_bf16 v[124:127], v[174:177], v[162:165], v[124:127]
	v_mfma_f32_16x16x32_bf16 v[120:123], v[182:185], v[138:141], v[120:123]
	v_mfma_f32_16x16x32_bf16 v[112:115], v[190:193], v[138:141], v[112:115]
	v_mfma_f32_16x16x32_bf16 v[128:131], v[178:181], v[142:145], v[128:131]
	v_mfma_f32_16x16x32_bf16 v[124:127], v[178:181], v[168:171], v[124:127]
	v_mfma_f32_16x16x32_bf16 v[120:123], v[186:189], v[142:145], v[120:123]
	v_mfma_f32_16x16x32_bf16 v[116:119], v[182:185], v[162:165], v[116:119]
	v_mfma_f32_16x16x32_bf16 v[112:115], v[194:197], v[142:145], v[112:115]
	v_mfma_f32_16x16x32_bf16 v[108:111], v[190:193], v[162:165], v[108:111]
	v_mfma_f32_16x16x32_bf16 v[104:107], v[198:201], v[138:141], v[104:107]
	v_mfma_f32_16x16x32_bf16 v[100:103], v[198:201], v[162:165], v[100:103]
	v_mfma_f32_16x16x32_bf16 v[132:135], v[186:189], v[168:171], v[116:119]
	v_mfma_f32_16x16x32_bf16 v[206:209], v[194:197], v[168:171], v[108:111]
	v_mfma_f32_16x16x32_bf16 v[210:213], v[202:205], v[142:145], v[104:107]
	v_mfma_f32_16x16x32_bf16 v[214:217], v[202:205], v[168:171], v[100:103]
	s_barrier
	s_nop 1
	ds_read_b128 v[100:103], v167
	ds_read_b128 v[104:107], v167 offset:1024
	ds_read_b128 v[108:111], v167 offset:2048
	ds_read_b128 v[116:119], v167 offset:3072
	s_barrier
	s_waitcnt lgkmcnt(0)
	v_mfma_f32_16x16x32_bf16 v[80:83], v[190:193], v[100:103], v[80:83]
	v_mfma_f32_16x16x32_bf16 v[76:79], v[190:193], v[108:111], v[76:79]
	v_mfma_f32_16x16x32_bf16 v[72:75], v[198:201], v[100:103], v[72:75]
	v_mfma_f32_16x16x32_bf16 v[68:71], v[198:201], v[108:111], v[68:71]
	v_mfma_f32_16x16x32_bf16 v[96:99], v[174:177], v[100:103], v[96:99]
	v_mfma_f32_16x16x32_bf16 v[92:95], v[174:177], v[108:111], v[92:95]
	v_mfma_f32_16x16x32_bf16 v[88:91], v[182:185], v[100:103], v[88:91]
	v_mfma_f32_16x16x32_bf16 v[84:87], v[182:185], v[108:111], v[84:87]
	v_mfma_f32_16x16x32_bf16 v[80:83], v[194:197], v[104:107], v[80:83]
	v_mfma_f32_16x16x32_bf16 v[76:79], v[194:197], v[116:119], v[76:79]
	v_mfma_f32_16x16x32_bf16 v[72:75], v[202:205], v[104:107], v[72:75]
	v_mfma_f32_16x16x32_bf16 v[68:71], v[202:205], v[116:119], v[68:71]
	v_mfma_f32_16x16x32_bf16 v[218:221], v[178:181], v[104:107], v[96:99]
	v_mfma_f32_16x16x32_bf16 v[172:175], v[178:181], v[116:119], v[92:95]
	v_mfma_f32_16x16x32_bf16 v[176:179], v[186:189], v[104:107], v[88:91]
	v_mfma_f32_16x16x32_bf16 v[180:183], v[186:189], v[116:119], v[84:87]
	s_barrier
	s_nop 0
	ds_read_b128 v[84:87], v156 offset:16384
	ds_read_b128 v[88:91], v156 offset:17408
	ds_read_b128 v[92:95], v155 offset:16384
	ds_read_b128 v[96:99], v155 offset:17408
	ds_read_b128 v[184:187], v154 offset:16384
	ds_read_b128 v[188:191], v154 offset:17408
	ds_read_b128 v[192:195], v153 offset:16384
	ds_read_b128 v[196:199], v153 offset:17408
	s_waitcnt vmcnt(4)
	s_barrier
	s_waitcnt lgkmcnt(0)
	v_mfma_f32_16x16x32_bf16 v[64:67], v[84:87], v[138:141], v[64:67]
	v_mfma_f32_16x16x32_bf16 v[60:63], v[84:87], v[162:165], v[60:63]
	v_mfma_f32_16x16x32_bf16 v[56:59], v[92:95], v[138:141], v[56:59]
	v_mfma_f32_16x16x32_bf16 v[52:55], v[92:95], v[162:165], v[52:55]
	v_mfma_f32_16x16x32_bf16 v[48:51], v[184:187], v[138:141], v[48:51]
	v_mfma_f32_16x16x32_bf16 v[44:47], v[184:187], v[162:165], v[44:47]
	v_mfma_f32_16x16x32_bf16 v[40:43], v[192:195], v[138:141], v[40:43]
	v_mfma_f32_16x16x32_bf16 v[36:39], v[192:195], v[162:165], v[36:39]
	v_mfma_f32_16x16x32_bf16 v[64:67], v[88:91], v[142:145], v[64:67]
	v_mfma_f32_16x16x32_bf16 v[60:63], v[88:91], v[168:171], v[60:63]
	v_mfma_f32_16x16x32_bf16 v[56:59], v[96:99], v[142:145], v[56:59]
	v_mfma_f32_16x16x32_bf16 v[52:55], v[96:99], v[168:171], v[52:55]
	v_mfma_f32_16x16x32_bf16 v[48:51], v[188:191], v[142:145], v[48:51]
	v_mfma_f32_16x16x32_bf16 v[44:47], v[188:191], v[168:171], v[44:47]
	v_mfma_f32_16x16x32_bf16 v[40:43], v[196:199], v[142:145], v[40:43]
	v_mfma_f32_16x16x32_bf16 v[36:39], v[196:199], v[168:171], v[36:39]
	v_mfma_f32_16x16x32_bf16 v[32:35], v[84:87], v[100:103], v[32:35]
	v_mfma_f32_16x16x32_bf16 v[28:31], v[84:87], v[108:111], v[28:31]
	v_mfma_f32_16x16x32_bf16 v[24:27], v[92:95], v[100:103], v[24:27]
	v_mfma_f32_16x16x32_bf16 v[20:23], v[92:95], v[108:111], v[20:23]
	v_mfma_f32_16x16x32_bf16 v[16:19], v[184:187], v[100:103], v[16:19]
	v_mfma_f32_16x16x32_bf16 v[12:15], v[184:187], v[108:111], v[12:15]
	v_mfma_f32_16x16x32_bf16 v[8:11], v[192:195], v[100:103], v[8:11]
	v_mfma_f32_16x16x32_bf16 v[4:7], v[192:195], v[108:111], v[4:7]
	v_mfma_f32_16x16x32_bf16 v[136:139], v[88:91], v[104:107], v[32:35]
	v_mfma_f32_16x16x32_bf16 v[140:143], v[88:91], v[116:119], v[28:31]
	v_mfma_f32_16x16x32_bf16 v[162:165], v[96:99], v[104:107], v[24:27]
	v_mfma_f32_16x16x32_bf16 v[166:169], v[96:99], v[116:119], v[20:23]
	v_mfma_f32_16x16x32_bf16 v[200:203], v[188:191], v[104:107], v[16:19]
	v_mfma_f32_16x16x32_bf16 v[184:187], v[188:191], v[116:119], v[12:15]
	v_mfma_f32_16x16x32_bf16 v[188:191], v[196:199], v[104:107], v[8:11]
	v_mfma_f32_16x16x32_bf16 v[192:195], v[196:199], v[116:119], v[4:7]
	s_barrier
; #define LDA8(dst, b, h) _Pragma("unroll") for (int m = 0; m < 4; ++m) _Pragma("unroll") for (int k = 0; k < 2; ++k) \
;     dst[m][k] = *(const bf16x8*)((const char*)SA8(b, h) + lds_byte8(wr * 64 + m * 16 + fr, k * 32 + fq * 8))
; #define LDB8(dst, b, h) _Pragma("unroll") for (int n = 0; n < 2; ++n) _Pragma("unroll") for (int k = 0; k < 2; ++k) \
;     dst[n][k] = *(const bf16x8*)((const char*)SB8(b, h) + lds_byte8(wc * 32 + n * 16 + fr, k * 32 + fq * 8))
; #define WAIT_V8(n) asm volatile("s_waitcnt vmcnt(" #n ")" ::: "memory")
; #define WAIT_L8(n) asm volatile("s_waitcnt lgkmcnt(" #n ")" ::: "memory")
; #define BAR8 __builtin_amdgcn_s_barrier()
;     ...
;   { LDB8(B0, 1, 0); LDA8(At, 1, 0); WAIT_V8(2); BAR8; WAIT_L8(0); MMA8(0, 0, At, B0); BAR8;
;     LDB8(B1, 1, 1); WAIT_V8(0); BAR8; WAIT_L8(0); MMA8(0, 1, At, B1); BAR8;
;     LDA8(At, 1, 1); BAR8; WAIT_L8(0); MMA8(1, 0, At, B0); MMA8(1, 1, At, B1); BAR8; }
;   if (wr == 0) BAR8;
;   __syncthreads();
;     ...
;   if (t < 256) {
	ds_read_b128 v[196:199], v160
	ds_read_b128 v[226:229], v160 offset:1024
	ds_read_b128 v[230:233], v160 offset:2048
	ds_read_b128 v[238:241], v160 offset:3072
	ds_read_b128 v[8:11], v156 offset:32768
	ds_read_b128 v[12:15], v156 offset:33792
	ds_read_b128 v[16:19], v155 offset:32768
	ds_read_b128 v[24:27], v155 offset:33792
	ds_read_b128 v[28:31], v154 offset:32768
	ds_read_b128 v[32:35], v154 offset:33792
	ds_read_b128 v[242:245], v153 offset:32768
	ds_read_b128 v[246:249], v153 offset:33792
	s_waitcnt vmcnt(2)
	s_barrier
	s_waitcnt lgkmcnt(0)
	v_mfma_f32_16x16x32_bf16 v[4:7], v[8:11], v[196:199], v[128:131]
	v_mfma_f32_16x16x32_bf16 v[104:107], v[12:15], v[226:229], v[4:7]
	v_mfma_f32_16x16x32_bf16 v[4:7], v[8:11], v[230:233], v[124:127]
	v_mfma_f32_16x16x32_bf16 v[116:119], v[12:15], v[238:241], v[4:7]
	v_mfma_f32_16x16x32_bf16 v[4:7], v[16:19], v[196:199], v[120:123]
	v_mfma_f32_16x16x32_bf16 v[100:103], v[24:27], v[226:229], v[4:7]
	v_mfma_f32_16x16x32_bf16 v[4:7], v[16:19], v[230:233], v[132:135]
	v_mfma_f32_16x16x32_bf16 v[108:111], v[24:27], v[238:241], v[4:7]
	v_mfma_f32_16x16x32_bf16 v[4:7], v[28:31], v[196:199], v[112:115]
	v_mfma_f32_16x16x32_bf16 v[92:95], v[32:35], v[226:229], v[4:7]
	v_mfma_f32_16x16x32_bf16 v[4:7], v[28:31], v[230:233], v[206:209]
	v_mfma_f32_16x16x32_bf16 v[96:99], v[32:35], v[238:241], v[4:7]
	v_mfma_f32_16x16x32_bf16 v[4:7], v[242:245], v[196:199], v[210:213]
	v_mfma_f32_16x16x32_bf16 v[84:87], v[246:249], v[226:229], v[4:7]
	v_mfma_f32_16x16x32_bf16 v[4:7], v[242:245], v[230:233], v[214:217]
	v_mfma_f32_16x16x32_bf16 v[88:91], v[246:249], v[238:241], v[4:7]
	s_barrier
	ds_read_b128 v[132:135], v158
	ds_read_b128 v[204:207], v158 offset:1024
	ds_read_b128 v[208:211], v158 offset:2048
	ds_read_b128 v[158:161], v158 offset:3072
	s_waitcnt vmcnt(0)
	s_barrier
	s_waitcnt lgkmcnt(0)
	v_mfma_f32_16x16x32_bf16 v[4:7], v[8:11], v[132:135], v[218:221]
	v_mfma_f32_16x16x32_bf16 v[8:11], v[8:11], v[208:211], v[172:175]
	v_mfma_f32_16x16x32_bf16 v[4:7], v[12:15], v[204:207], v[4:7]
	v_mfma_f32_16x16x32_bf16 v[20:23], v[12:15], v[158:161], v[8:11]
	v_mfma_f32_16x16x32_bf16 v[8:11], v[16:19], v[132:135], v[176:179]
	v_mfma_f32_16x16x32_bf16 v[12:15], v[16:19], v[208:211], v[180:183]
	v_mfma_f32_16x16x32_bf16 v[8:11], v[24:27], v[204:207], v[8:11]
	v_mfma_f32_16x16x32_bf16 v[24:27], v[24:27], v[158:161], v[12:15]
	v_mfma_f32_16x16x32_bf16 v[12:15], v[28:31], v[132:135], v[80:83]
	v_mfma_f32_16x16x32_bf16 v[16:19], v[28:31], v[208:211], v[76:79]
	v_mfma_f32_16x16x32_bf16 v[12:15], v[32:35], v[204:207], v[12:15]
	v_mfma_f32_16x16x32_bf16 v[28:31], v[32:35], v[158:161], v[16:19]
	v_mfma_f32_16x16x32_bf16 v[16:19], v[242:245], v[132:135], v[72:75]
	v_mfma_f32_16x16x32_bf16 v[32:35], v[242:245], v[208:211], v[68:71]
	v_mfma_f32_16x16x32_bf16 v[16:19], v[246:249], v[204:207], v[16:19]
	v_mfma_f32_16x16x32_bf16 v[32:35], v[246:249], v[158:161], v[32:35]
	s_barrier
	ds_read_b128 v[170:173], v156 offset:49152
	ds_read_b128 v[174:177], v156 offset:50176
	ds_read_b128 v[178:181], v155 offset:49152
	ds_read_b128 v[212:215], v155 offset:50176
	ds_read_b128 v[216:219], v154 offset:49152
	ds_read_b128 v[154:157], v154 offset:50176
	ds_read_b128 v[220:223], v153 offset:49152
	ds_read_b128 v[150:153], v153 offset:50176
	s_barrier
	s_waitcnt lgkmcnt(0)
	v_mfma_f32_16x16x32_bf16 v[64:67], v[170:173], v[196:199], v[64:67]
	v_mfma_f32_16x16x32_bf16 v[60:63], v[170:173], v[230:233], v[60:63]
	v_mfma_f32_16x16x32_bf16 v[56:59], v[178:181], v[196:199], v[56:59]
	v_mfma_f32_16x16x32_bf16 v[52:55], v[178:181], v[230:233], v[52:55]
	v_mfma_f32_16x16x32_bf16 v[48:51], v[216:219], v[196:199], v[48:51]
	v_mfma_f32_16x16x32_bf16 v[44:47], v[216:219], v[230:233], v[44:47]
	v_mfma_f32_16x16x32_bf16 v[40:43], v[220:223], v[196:199], v[40:43]
	v_mfma_f32_16x16x32_bf16 v[36:39], v[220:223], v[230:233], v[36:39]
	v_mfma_f32_16x16x32_bf16 v[128:131], v[174:177], v[226:229], v[64:67]
	v_mfma_f32_16x16x32_bf16 v[124:127], v[174:177], v[238:241], v[60:63]
	v_mfma_f32_16x16x32_bf16 v[120:123], v[212:215], v[226:229], v[56:59]
	v_mfma_f32_16x16x32_bf16 v[112:115], v[212:215], v[238:241], v[52:55]
	v_mfma_f32_16x16x32_bf16 v[80:83], v[154:157], v[226:229], v[48:51]
	v_mfma_f32_16x16x32_bf16 v[76:79], v[154:157], v[238:241], v[44:47]
	v_mfma_f32_16x16x32_bf16 v[72:75], v[150:153], v[226:229], v[40:43]
	v_mfma_f32_16x16x32_bf16 v[68:71], v[150:153], v[238:241], v[36:39]
	v_mfma_f32_16x16x32_bf16 v[40:43], v[170:173], v[208:211], v[140:143]
	v_mfma_f32_16x16x32_bf16 v[44:47], v[178:181], v[208:211], v[166:169]
	v_mfma_f32_16x16x32_bf16 v[48:51], v[216:219], v[208:211], v[184:187]
	v_mfma_f32_16x16x32_bf16 v[36:39], v[170:173], v[132:135], v[136:139]
	v_mfma_f32_16x16x32_bf16 v[52:55], v[174:177], v[158:161], v[40:43]
	v_mfma_f32_16x16x32_bf16 v[40:43], v[178:181], v[132:135], v[162:165]
	v_mfma_f32_16x16x32_bf16 v[56:59], v[212:215], v[158:161], v[44:47]
	v_mfma_f32_16x16x32_bf16 v[44:47], v[216:219], v[132:135], v[200:203]
	v_mfma_f32_16x16x32_bf16 v[60:63], v[154:157], v[158:161], v[48:51]
	v_mfma_f32_16x16x32_bf16 v[48:51], v[220:223], v[132:135], v[188:191]
	v_mfma_f32_16x16x32_bf16 v[64:67], v[220:223], v[208:211], v[192:195]
	v_mfma_f32_16x16x32_bf16 v[36:39], v[174:177], v[204:207], v[36:39]
	v_mfma_f32_16x16x32_bf16 v[40:43], v[212:215], v[204:207], v[40:43]
	v_mfma_f32_16x16x32_bf16 v[44:47], v[154:157], v[204:207], v[44:47]
	v_mfma_f32_16x16x32_bf16 v[48:51], v[150:153], v[204:207], v[48:51]
	v_mfma_f32_16x16x32_bf16 v[64:67], v[150:153], v[158:161], v[64:67]
	s_movk_i32 s2, 0x100
	v_cmp_gt_u32_e32 vcc, s2, v3
	s_barrier
	s_and_saveexec_b64 s[2:3], vcc
	s_cbranch_execz .LBB0_1155
	s_barrier

; #define WAIT_V8(n) asm volatile("s_waitcnt vmcnt(" #n ")" ::: "memory")
; #define BAR8 __builtin_amdgcn_s_barrier()
;     ...
;   const int brow = m0, bcol = n0;
;   const int wid = t >> 6, lane = t & 63, wr = wid >> 2, wc = wid & 3, fr = lane & 15, fq = lane >> 4;
;   f32x4 acc[2][2][4][2];
;   {
;     float zinit = 0.f;
;     asm volatile("" : "+v"(zinit));
; #pragma unroll
;     for (int a = 0; a < 2; ++a)
; #pragma unroll
;       for (int b = 0; b < 2; ++b)
; #pragma unroll
;         for (int m = 0; m < 4; ++m)
; #pragma unroll
;           for (int n = 0; n < 2; ++n)
; #pragma unroll
;             for (int j = 0; j < 4; ++j) acc[a][b][m][n][j] = zinit;
;   }
;   bf16x8 At[4][2], B0[2][2], B1[2][2];
;   const int nt = K / 64;
;   if (!pre) {
;     STAGE8(SB8(0, 0), Bt, K, bcol, 0); STAGE8(SA8(0, 0), A, lda, brow, 0);
;     STAGE8(SB8(0, 1), Bt, K, bcol + 128, 0); STAGE8(SA8(0, 1), A, lda, brow + 128, 0);
;   }
;   if (wr == 1) BAR8;
;   WAIT_V8(4); BAR8;
;   STAGE8(SB8(1, 0), Bt, K, bcol, 1); STAGE8(SA8(1, 0), A, lda, brow, 1); STAGE8(SB8(1, 1), Bt, K, bcol + 128, 1);
;   WAIT_V8(6); BAR8;
.LBB0_1258:
	s_or_b64 exec, exec, s[8:9]
	v_add_u32_e32 v0, v150, v0
	v_and_b32_e32 v0, 0xfffffc00, v0
	v_sub_u32_e32 v0, v150, v0
	v_lshrrev_b32_e32 v6, 4, v0
	v_add_u32_e32 v1, v3, v1
	v_bitop3_b32 v7, v6, v0, 32 bitop3:0x6c
	v_ashrrev_i32_e32 v0, 31, v0
	v_ashrrev_i32_e32 v1, 6, v1
	v_lshrrev_b32_e32 v0, 26, v0
	v_lshlrev_b32_e32 v6, 3, v1
	v_add_u32_e32 v0, v7, v0
	v_and_b32_e32 v6, -16, v6
	v_ashrrev_i32_e32 v0, 6, v0
	s_and_b32 s1, s12, 63
	s_and_b32 s8, s20, 0xffffff00
	v_add_u32_e32 v6, v0, v6
	v_mul_i32_i24_e32 v0, 64, v0
	s_lshl_b32 s12, s1, 19
	s_ashr_i32 s9, s8, 31
	s_ashr_i32 s1, s0, 31
	v_lshlrev_b32_e32 v1, 5, v1
	v_sub_u32_e32 v0, v7, v0
	v_mov_b32_e32 v13, 1
	s_lshl_b64 s[14:15], s[8:9], 11
	s_lshl_b64 s[8:9], s[0:1], 11
	v_and_b32_e32 v1, 32, v1
	v_ashrrev_i16_sdwa v0, v13, sext(v0) dst_sel:DWORD dst_unused:UNUSED_PAD src0_sel:DWORD src1_sel:BYTE_0
	s_add_u32 s8, s4, s8
	v_add_u32_sdwa v0, v1, sext(v0) dst_sel:DWORD dst_unused:UNUSED_PAD src0_sel:DWORD src1_sel:WORD_0
	v_ashrrev_i32_e32 v7, 31, v6
	v_readlane_b32 s40, v254, 35
	s_addc_u32 s9, s5, s9
	v_lshlrev_b64 v[132:133], 11, v[6:7]
	v_ashrrev_i32_e32 v1, 31, v0
	v_readlane_b32 s41, v254, 36
	v_lshl_add_u64 v[6:7], s[8:9], 0, v[132:133]
	v_lshlrev_b64 v[8:9], 1, v[0:1]
	s_mov_b32 s13, s40
	v_lshl_add_u64 v[6:7], v[6:7], 0, v[8:9]
	s_mov_b64 s[40:41], 0x80
	v_lshl_add_u64 v[6:7], v[6:7], 0, s[40:41]
	s_or_b32 m0, s100, 0x18000
	s_waitcnt vmcnt(4)
	s_barrier
	global_load_lds_dwordx4 v[6:7], off
	v_ashrrev_i32_e32 v6, 31, v152
	v_lshrrev_b32_e32 v6, 22, v6
	v_add_u32_e32 v6, v152, v6
	v_ashrrev_i32_e32 v7, 10, v6
	v_mul_i32_i24_e32 v6, 0x400, v7
	v_sub_u32_e32 v6, v152, v6
	v_lshrrev_b32_e32 v10, 4, v6
	v_bitop3_b32 v10, v10, v6, 32 bitop3:0x6c
	v_ashrrev_i32_e32 v11, 31, v10
	v_lshrrev_b32_e32 v11, 26, v11
	v_add_u32_e32 v11, v10, v11
	v_lshlrev_b32_e32 v6, 3, v7
	v_ashrrev_i32_e32 v12, 6, v11
	v_and_b32_e32 v11, 0xc0, v11
	v_and_b32_e32 v6, -16, v6
	v_lshlrev_b32_e32 v7, 5, v7
	v_sub_u32_e32 v10, v10, v11
	v_add_u32_e32 v6, v12, v6
	v_and_b32_e32 v7, 32, v7
	v_ashrrev_i16_sdwa v10, v13, sext(v10) dst_sel:DWORD dst_unused:UNUSED_PAD src0_sel:DWORD src1_sel:BYTE_0
	v_add_u32_sdwa v134, v7, sext(v10) dst_sel:DWORD dst_unused:UNUSED_PAD src0_sel:DWORD src1_sel:WORD_0
	v_ashrrev_i32_e32 v7, 31, v6
	v_lshlrev_b64 v[136:137], 11, v[6:7]
	v_ashrrev_i32_e32 v135, 31, v134
	v_lshl_add_u64 v[6:7], s[8:9], 0, v[136:137]
	v_lshlrev_b64 v[10:11], 1, v[134:135]
	s_or_b32 m0, s100, 0x1a000
	s_lshl_b32 s1, s27, 11
	v_lshl_add_u64 v[6:7], v[6:7], 0, v[10:11]
	s_waitcnt lgkmcnt(0)
	s_add_u32 s8, s2, s1
	v_lshl_add_u64 v[6:7], v[6:7], 0, s[40:41]
	s_addc_u32 s9, s3, 0
	global_load_lds_dwordx4 v[6:7], off
	v_lshl_add_u64 v[6:7], s[8:9], 0, v[132:133]
	v_lshl_add_u64 v[6:7], v[6:7], 0, v[8:9]
	s_or_b32 s36, s0, 0x80
	v_lshl_add_u64 v[6:7], v[6:7], 0, s[40:41]
	s_or_b32 m0, s100, 0x8000
	s_ashr_i32 s37, s36, 31
	global_load_lds_dwordx4 v[6:7], off
	v_lshl_add_u64 v[6:7], s[8:9], 0, v[136:137]
	s_lshl_b64 s[36:37], s[36:37], 11
	v_lshl_add_u64 v[6:7], v[6:7], 0, v[10:11]
	s_add_u32 s36, s4, s36
	v_lshl_add_u64 v[6:7], v[6:7], 0, s[40:41]
	s_addc_u32 s37, s5, s37
	s_or_b32 m0, s100, 0xa000
	global_load_lds_dwordx4 v[6:7], off
	v_lshl_add_u64 v[6:7], s[36:37], 0, v[132:133]
	v_lshl_add_u64 v[6:7], v[6:7], 0, v[8:9]
	v_lshl_add_u64 v[6:7], v[6:7], 0, s[40:41]
	s_or_b32 m0, s100, 0x1c000
	global_load_lds_dwordx4 v[6:7], off
	v_lshl_add_u64 v[6:7], s[36:37], 0, v[136:137]
	v_lshl_add_u64 v[6:7], v[6:7], 0, v[10:11]
	v_lshl_add_u64 v[6:7], v[6:7], 0, s[40:41]
	s_or_b32 m0, s100, 0x1e000
	v_and_b32_e32 v147, 15, v3
	global_load_lds_dwordx4 v[6:7], off
	v_bfe_u32 v148, v3, 4, 2
	v_lshlrev_b32_e32 v6, 4, v148
	v_lshlrev_b32_e32 v7, 6, v147
	v_lshlrev_b32_e32 v14, 2, v3
	v_or_b32_e32 v13, v6, v7
	v_and_b32_e32 v14, 32, v14
	s_mov_b32 s1, 0x10000
	v_bitop3_b32 v16, v13, s1, v14 bitop3:0xde
	s_mov_b32 s1, 0x14000
	v_bitop3_b32 v15, v6, v14, v7 bitop3:0x36
	v_bitop3_b32 v17, v13, s1, v14 bitop3:0xde
	s_mov_b32 s1, 0x18000
	v_lshlrev_b32_e32 v7, 6, v3
	v_bitop3_b32 v18, v13, s1, v14 bitop3:0xde
	s_mov_b32 s1, 0x1c000
	v_and_b32_e32 v7, 0x3c0, v7
	v_bitop3_b32 v13, v13, s1, v14 bitop3:0xde
	v_bitop3_b32 v14, v7, v14, v6 bitop3:0x36
	v_lshl_add_u64 v[6:7], s[12:13], 0, v[132:133]
	v_lshl_add_u64 v[6:7], v[6:7], 0, v[8:9]
	v_lshl_add_u64 v[138:139], s[2:3], 0, v[6:7]
	v_lshl_add_u64 v[6:7], s[12:13], 0, v[136:137]
	v_lshl_add_u64 v[6:7], v[6:7], 0, v[10:11]
	v_lshl_add_u64 v[140:141], s[2:3], 0, v[6:7]
	v_lshl_add_u64 v[6:7], s[14:15], 0, v[132:133]
	v_lshl_add_u64 v[6:7], v[6:7], 0, v[8:9]
	v_bfe_u32 v146, v3, 6, 2
	s_waitcnt vmcnt(6)
	v_lshlrev_b32_e32 v149, 6, v5
	v_lshlrev_b32_e32 v5, 13, v5
	v_lshl_add_u64 v[142:143], s[6:7], 0, v[6:7]
	v_lshl_add_u64 v[6:7], s[14:15], 0, v[136:137]
	v_readlane_b32 s42, v254, 37
	v_readlane_b32 s43, v254, 38
	v_lshlrev_b32_e32 v12, 12, v146
	v_or_b32_e32 v19, 0x800, v5
	v_or_b32_e32 v20, 0x1000, v5
	v_or_b32_e32 v21, 0x1800, v5
	v_lshl_add_u64 v[6:7], v[6:7], 0, v[10:11]
	v_lshl_add_u64 v[144:145], s[6:7], 0, v[6:7]
	s_mov_b32 s1, -2
	s_mov_b64 s[12:13], 0
	v_add_u32_e32 v171, v16, v12
	v_add_u32_e32 v161, v15, v5
	v_add_u32_e32 v160, v14, v19
	v_add_u32_e32 v159, v14, v20
	v_add_u32_e32 v158, v14, v21
	v_add_u32_e32 v169, v17, v12
	v_add_u32_e32 v163, v18, v12
	v_add_u32_e32 v162, v13, v12
	s_mov_b64 s[36:37], 0xcaa0100
	s_mov_b64 s[40:41], 0xcae0100
	s_mov_b64 s[42:43], 0xcaa0180
	s_mov_b64 s[44:45], 0xcae0180
	s_barrier
; #define LDA8(dst, b, h) _Pragma("unroll") for (int m = 0; m < 4; ++m) _Pragma("unroll") for (int k = 0; k < 2; ++k) \
;     dst[m][k] = *(const bf16x8*)((const char*)SA8(b, h) + lds_byte8(wr * 64 + m * 16 + fr, k * 32 + fq * 8))
; #define LDB8(dst, b, h) _Pragma("unroll") for (int n = 0; n < 2; ++n) _Pragma("unroll") for (int k = 0; k < 2; ++k) \
;     dst[n][k] = *(const bf16x8*)((const char*)SB8(b, h) + lds_byte8(wc * 32 + n * 16 + fr, k * 32 + fq * 8))
; #define WAIT_V8(n) asm volatile("s_waitcnt vmcnt(" #n ")" ::: "memory")
; #define WAIT_L8(n) asm volatile("s_waitcnt lgkmcnt(" #n ")" ::: "memory")
; #define BAR8 __builtin_amdgcn_s_barrier()
; #define SCHED8 __builtin_amdgcn_sched_barrier(0)
;     ...
;     LDB8(B0, 0, 0); SCHED8; LDA8(At, 0, 0); STAGE8(SA8(1, 1), A, lda, brow + 128, tt + 1);
;     WAIT_L8(8); BAR8; WAIT_L8(0); MMA8(0, 0, At, B0); BAR8; SCHED8;
;     LDB8(B1, 0, 1); STAGE8(SB8(0, 0), Bt, K, bcol, tt + 2);
;     BAR8; WAIT_L8(0); MMA8(0, 1, At, B1); BAR8;
;     LDA8(At, 0, 1); STAGE8(SA8(0, 0), A, lda, brow, tt + 2);
;     BAR8; WAIT_L8(0); MMA8(1, 0, At, B0); BAR8; SCHED8;
;     STAGE8(SB8(0, 1), Bt, K, bcol + 128, tt + 2);
;     WAIT_V8(6); BAR8; MMA8(1, 1, At, B1); BAR8;
	ds_read_b128 v[174:177], v171
	ds_read_b128 v[178:181], v171 offset:1024
	ds_read_b128 v[182:185], v171 offset:2048
	ds_read_b128 v[186:189], v171 offset:3072
	v_lshl_add_u64 v[222:223], v[138:139], 0, s[12:13]
	v_lshl_add_u64 v[226:227], v[222:223], 0, s[34:35]
	s_or_b32 m0, s100, 0xc000
	v_lshl_add_u64 v[236:237], v[140:141], 0, s[12:13]
	ds_read_b128 v[190:193], v161
	ds_read_b128 v[194:197], v161 offset:1024
	ds_read_b128 v[198:201], v160
	ds_read_b128 v[202:205], v160 offset:1024
	ds_read_b128 v[206:209], v159
	ds_read_b128 v[210:213], v159 offset:1024
	ds_read_b128 v[214:217], v158
	ds_read_b128 v[218:221], v158 offset:1024
	global_load_lds_dwordx4 v[226:227], off
	v_lshl_add_u64 v[226:227], v[236:237], 0, s[34:35]
	s_or_b32 m0, s100, 0xe000
	s_nop 0
	global_load_lds_dwordx4 v[226:227], off
	s_waitcnt lgkmcnt(8)
	s_barrier
	s_waitcnt lgkmcnt(0)
	v_mfma_f32_16x16x32_f16 v[128:131], v[190:193], v[174:177], 0
	v_mfma_f32_16x16x32_f16 v[124:127], v[190:193], v[182:185], 0
	v_mfma_f32_16x16x32_f16 v[120:123], v[198:201], v[174:177], 0
	v_mfma_f32_16x16x32_f16 v[116:119], v[198:201], v[182:185], 0
	v_mfma_f32_16x16x32_f16 v[112:115], v[206:209], v[174:177], 0
	v_mfma_f32_16x16x32_f16 v[108:111], v[206:209], v[182:185], 0
	v_mfma_f32_16x16x32_f16 v[104:107], v[214:217], v[174:177], 0
	v_mfma_f32_16x16x32_f16 v[100:103], v[214:217], v[182:185], 0
	v_mfma_f32_16x16x32_f16 v[128:131], v[194:197], v[178:181], v[128:131]
	v_mfma_f32_16x16x32_f16 v[124:127], v[194:197], v[186:189], v[124:127]
	v_mfma_f32_16x16x32_f16 v[120:123], v[202:205], v[178:181], v[120:123]
	v_mfma_f32_16x16x32_f16 v[116:119], v[202:205], v[186:189], v[116:119]
	v_mfma_f32_16x16x32_f16 v[112:115], v[210:213], v[178:181], v[112:115]
	v_mfma_f32_16x16x32_f16 v[108:111], v[210:213], v[186:189], v[108:111]
	v_mfma_f32_16x16x32_f16 v[104:107], v[218:221], v[178:181], v[104:107]
	v_mfma_f32_16x16x32_f16 v[100:103], v[218:221], v[186:189], v[100:103]
	s_barrier
	v_lshl_add_u64 v[246:247], v[142:143], 0, s[12:13]
	v_lshl_add_u64 v[248:249], v[246:247], 0, s[36:37]
	s_or_b32 m0, s100, 0x10000
	ds_read_b128 v[226:229], v169
	ds_read_b128 v[230:233], v169 offset:1024
	ds_read_b128 v[238:241], v169 offset:2048
	ds_read_b128 v[242:245], v169 offset:3072
	global_load_lds_dwordx4 v[248:249], off
	v_lshl_add_u64 v[248:249], v[144:145], 0, s[12:13]
	v_lshl_add_u64 v[250:251], v[248:249], 0, s[36:37]
	s_or_b32 m0, s100, 0x12000
	s_nop 0
	global_load_lds_dwordx4 v[250:251], off
	s_barrier
	s_waitcnt lgkmcnt(0)
	v_mfma_f32_16x16x32_f16 v[96:99], v[190:193], v[226:229], 0
	v_mfma_f32_16x16x32_f16 v[92:95], v[190:193], v[238:241], 0
	v_mfma_f32_16x16x32_f16 v[88:91], v[198:201], v[226:229], 0
	v_mfma_f32_16x16x32_f16 v[84:87], v[198:201], v[238:241], 0
	v_mfma_f32_16x16x32_f16 v[80:83], v[206:209], v[226:229], 0
	v_mfma_f32_16x16x32_f16 v[76:79], v[206:209], v[238:241], 0
	v_mfma_f32_16x16x32_f16 v[72:75], v[214:217], v[226:229], 0
	v_mfma_f32_16x16x32_f16 v[68:71], v[214:217], v[238:241], 0
	v_mfma_f32_16x16x32_f16 v[96:99], v[194:197], v[230:233], v[96:99]
	v_mfma_f32_16x16x32_f16 v[92:95], v[194:197], v[242:245], v[92:95]
	v_mfma_f32_16x16x32_f16 v[88:91], v[202:205], v[230:233], v[88:91]
	v_mfma_f32_16x16x32_f16 v[84:87], v[202:205], v[242:245], v[84:87]
	v_mfma_f32_16x16x32_f16 v[80:83], v[210:213], v[230:233], v[80:83]
	v_mfma_f32_16x16x32_f16 v[76:79], v[210:213], v[242:245], v[76:79]
	v_mfma_f32_16x16x32_f16 v[72:75], v[218:221], v[230:233], v[72:75]
	v_mfma_f32_16x16x32_f16 v[68:71], v[218:221], v[242:245], v[68:71]
	v_lshl_add_u64 v[250:251], v[222:223], 0, s[10:11]
	s_mov_b32 m0, s100
	s_barrier
	ds_read_b128 v[190:193], v161 offset:16384
	ds_read_b128 v[194:197], v161 offset:17408
	ds_read_b128 v[198:201], v160 offset:16384
	ds_read_b128 v[202:205], v160 offset:17408
	ds_read_b128 v[206:209], v159 offset:16384
	ds_read_b128 v[210:213], v159 offset:17408
	ds_read_b128 v[214:217], v158 offset:16384
	ds_read_b128 v[218:221], v158 offset:17408
	global_load_lds_dwordx4 v[250:251], off
	v_lshl_add_u64 v[250:251], v[236:237], 0, s[10:11]
	s_or_b32 m0, s100, 0x2000
	s_nop 0
	global_load_lds_dwordx4 v[250:251], off
	s_barrier
	s_waitcnt lgkmcnt(0)
	v_mfma_f32_16x16x32_f16 v[64:67], v[190:193], v[174:177], 0
	v_mfma_f32_16x16x32_f16 v[60:63], v[190:193], v[182:185], 0
	v_mfma_f32_16x16x32_f16 v[56:59], v[198:201], v[174:177], 0
	v_mfma_f32_16x16x32_f16 v[52:55], v[198:201], v[182:185], 0
	v_mfma_f32_16x16x32_f16 v[48:51], v[206:209], v[174:177], 0
	v_mfma_f32_16x16x32_f16 v[44:47], v[206:209], v[182:185], 0
	v_mfma_f32_16x16x32_f16 v[40:43], v[214:217], v[174:177], 0
	v_mfma_f32_16x16x32_f16 v[36:39], v[214:217], v[182:185], 0
	v_mfma_f32_16x16x32_f16 v[64:67], v[194:197], v[178:181], v[64:67]
	v_mfma_f32_16x16x32_f16 v[60:63], v[194:197], v[186:189], v[60:63]
	v_mfma_f32_16x16x32_f16 v[56:59], v[202:205], v[178:181], v[56:59]
	v_mfma_f32_16x16x32_f16 v[52:55], v[202:205], v[186:189], v[52:55]
	v_mfma_f32_16x16x32_f16 v[48:51], v[210:213], v[178:181], v[48:51]
	v_mfma_f32_16x16x32_f16 v[44:47], v[210:213], v[186:189], v[44:47]
	v_mfma_f32_16x16x32_f16 v[40:43], v[218:221], v[178:181], v[40:43]
	v_mfma_f32_16x16x32_f16 v[36:39], v[218:221], v[186:189], v[36:39]
	s_barrier
	v_lshl_add_u64 v[174:175], v[246:247], 0, s[40:41]
	s_or_b32 m0, s100, 0x14000
	s_nop 0
	global_load_lds_dwordx4 v[174:175], off
	v_lshl_add_u64 v[174:175], v[248:249], 0, s[40:41]
	s_or_b32 m0, s100, 0x16000
	s_nop 0
	global_load_lds_dwordx4 v[174:175], off
	s_waitcnt vmcnt(6)
	s_barrier
; #define LDA8(dst, b, h) _Pragma("unroll") for (int m = 0; m < 4; ++m) _Pragma("unroll") for (int k = 0; k < 2; ++k) \
;     dst[m][k] = *(const bf16x8*)((const char*)SA8(b, h) + lds_byte8(wr * 64 + m * 16 + fr, k * 32 + fq * 8))
; #define LDB8(dst, b, h) _Pragma("unroll") for (int n = 0; n < 2; ++n) _Pragma("unroll") for (int k = 0; k < 2; ++k) \
;     dst[n][k] = *(const bf16x8*)((const char*)SB8(b, h) + lds_byte8(wc * 32 + n * 16 + fr, k * 32 + fq * 8))
; #define WAIT_V8(n) asm volatile("s_waitcnt vmcnt(" #n ")" ::: "memory")
; #define WAIT_L8(n) asm volatile("s_waitcnt lgkmcnt(" #n ")" ::: "memory")
; #define BAR8 __builtin_amdgcn_s_barrier()
; #define SCHED8 __builtin_amdgcn_sched_barrier(0)
;     ...
;     WAIT_V8(6); BAR8; MMA8(1, 1, At, B1); BAR8;
;     LDB8(B0, 1, 0); SCHED8; LDA8(At, 1, 0); STAGE8(SA8(0, 1), A, lda, brow + 128, tt + 2);
;     WAIT_L8(8); BAR8; WAIT_L8(0); MMA8(0, 0, At, B0); BAR8; SCHED8;
;     LDB8(B1, 1, 1); STAGE8(SB8(1, 0), Bt, K, bcol, tt + 3);
	v_mfma_f32_16x16x32_f16 v[32:35], v[190:193], v[226:229], 0
	v_mfma_f32_16x16x32_f16 v[28:31], v[190:193], v[238:241], 0
	v_mfma_f32_16x16x32_f16 v[24:27], v[198:201], v[226:229], 0
	v_mfma_f32_16x16x32_f16 v[20:23], v[198:201], v[238:241], 0
	v_mfma_f32_16x16x32_f16 v[16:19], v[206:209], v[226:229], 0
	v_mfma_f32_16x16x32_f16 v[12:15], v[206:209], v[238:241], 0
	v_mfma_f32_16x16x32_f16 v[8:11], v[214:217], v[226:229], 0
	v_mfma_f32_16x16x32_f16 v[4:7], v[214:217], v[238:241], 0
	v_mfma_f32_16x16x32_f16 v[32:35], v[194:197], v[230:233], v[32:35]
	v_mfma_f32_16x16x32_f16 v[28:31], v[194:197], v[242:245], v[28:31]
	v_mfma_f32_16x16x32_f16 v[24:27], v[202:205], v[230:233], v[24:27]
	v_mfma_f32_16x16x32_f16 v[20:23], v[202:205], v[242:245], v[20:23]
	v_mfma_f32_16x16x32_f16 v[16:19], v[210:213], v[230:233], v[16:19]
	v_mfma_f32_16x16x32_f16 v[12:15], v[210:213], v[242:245], v[12:15]
	v_mfma_f32_16x16x32_f16 v[8:11], v[218:221], v[230:233], v[8:11]
	v_mfma_f32_16x16x32_f16 v[4:7], v[218:221], v[242:245], v[4:7]
	s_barrier
	ds_read_b128 v[174:177], v163
	ds_read_b128 v[178:181], v163 offset:1024
	ds_read_b128 v[182:185], v163 offset:2048
	ds_read_b128 v[186:189], v163 offset:3072
	v_lshl_add_u64 v[226:227], v[222:223], 0, s[18:19]
	s_or_b32 m0, s100, 0x4000
	ds_read_b128 v[190:193], v161 offset:32768
	ds_read_b128 v[194:197], v161 offset:33792
	ds_read_b128 v[198:201], v160 offset:32768
	ds_read_b128 v[202:205], v160 offset:33792
	ds_read_b128 v[206:209], v159 offset:32768
	ds_read_b128 v[210:213], v159 offset:33792
	ds_read_b128 v[214:217], v158 offset:32768
	ds_read_b128 v[218:221], v158 offset:33792
	global_load_lds_dwordx4 v[226:227], off
	v_lshl_add_u64 v[226:227], v[236:237], 0, s[18:19]
	s_or_b32 m0, s100, 0x6000
	s_nop 0
	global_load_lds_dwordx4 v[226:227], off
	s_waitcnt lgkmcnt(8)
	s_barrier
	s_waitcnt lgkmcnt(0)
	v_mfma_f32_16x16x32_f16 v[128:131], v[190:193], v[174:177], v[128:131]
	v_mfma_f32_16x16x32_f16 v[124:127], v[190:193], v[182:185], v[124:127]
	v_mfma_f32_16x16x32_f16 v[120:123], v[198:201], v[174:177], v[120:123]
	v_mfma_f32_16x16x32_f16 v[116:119], v[198:201], v[182:185], v[116:119]
	v_mfma_f32_16x16x32_f16 v[112:115], v[206:209], v[174:177], v[112:115]
	v_mfma_f32_16x16x32_f16 v[108:111], v[206:209], v[182:185], v[108:111]
	v_mfma_f32_16x16x32_f16 v[104:107], v[214:217], v[174:177], v[104:107]
	v_mfma_f32_16x16x32_f16 v[100:103], v[214:217], v[182:185], v[100:103]
	v_mfma_f32_16x16x32_f16 v[128:131], v[194:197], v[178:181], v[128:131]
	v_mfma_f32_16x16x32_f16 v[124:127], v[194:197], v[186:189], v[124:127]
	v_mfma_f32_16x16x32_f16 v[120:123], v[202:205], v[178:181], v[120:123]
	v_mfma_f32_16x16x32_f16 v[116:119], v[202:205], v[186:189], v[116:119]
	v_mfma_f32_16x16x32_f16 v[112:115], v[210:213], v[178:181], v[112:115]
	v_mfma_f32_16x16x32_f16 v[108:111], v[210:213], v[186:189], v[108:111]
	v_mfma_f32_16x16x32_f16 v[104:107], v[218:221], v[178:181], v[104:107]
	v_mfma_f32_16x16x32_f16 v[100:103], v[218:221], v[186:189], v[100:103]
	s_barrier
	v_lshl_add_u64 v[250:251], v[246:247], 0, s[42:43]
	s_or_b32 m0, s100, 0x18000
	ds_read_b128 v[226:229], v162
	ds_read_b128 v[230:233], v162 offset:1024
	ds_read_b128 v[238:241], v162 offset:2048
	ds_read_b128 v[242:245], v162 offset:3072
	global_load_lds_dwordx4 v[250:251], off
	v_lshl_add_u64 v[250:251], v[248:249], 0, s[42:43]
	s_or_b32 m0, s100, 0x1a000
	s_nop 0
	global_load_lds_dwordx4 v[250:251], off
	s_barrier
; #define LDA8(dst, b, h) _Pragma("unroll") for (int m = 0; m < 4; ++m) _Pragma("unroll") for (int k = 0; k < 2; ++k) \
;     dst[m][k] = *(const bf16x8*)((const char*)SA8(b, h) + lds_byte8(wr * 64 + m * 16 + fr, k * 32 + fq * 8))
; #define WAIT_V8(n) asm volatile("s_waitcnt vmcnt(" #n ")" ::: "memory")
; #define WAIT_L8(n) asm volatile("s_waitcnt lgkmcnt(" #n ")" ::: "memory")
; #define BAR8 __builtin_amdgcn_s_barrier()
; #define SCHED8 __builtin_amdgcn_sched_barrier(0)
;     ...
;   for (int tt = 0; tt < nt - 2; tt += 2) {
;     ...
;     BAR8; WAIT_L8(0); MMA8(0, 1, At, B1); BAR8;
;     LDA8(At, 1, 1); STAGE8(SA8(1, 0), A, lda, brow, tt + 3);
;     BAR8; WAIT_L8(0); MMA8(1, 0, At, B0); BAR8; SCHED8;
;     STAGE8(SB8(1, 1), Bt, K, bcol + 128, tt + 3);
;     WAIT_V8(6); BAR8; MMA8(1, 1, At, B1); BAR8;
	s_waitcnt lgkmcnt(0)
	v_mfma_f32_16x16x32_f16 v[96:99], v[190:193], v[226:229], v[96:99]
	v_mfma_f32_16x16x32_f16 v[92:95], v[190:193], v[238:241], v[92:95]
	v_mfma_f32_16x16x32_f16 v[88:91], v[198:201], v[226:229], v[88:91]
	v_mfma_f32_16x16x32_f16 v[84:87], v[198:201], v[238:241], v[84:87]
	v_mfma_f32_16x16x32_f16 v[80:83], v[206:209], v[226:229], v[80:83]
	v_mfma_f32_16x16x32_f16 v[76:79], v[206:209], v[238:241], v[76:79]
	v_mfma_f32_16x16x32_f16 v[72:75], v[214:217], v[226:229], v[72:75]
	v_mfma_f32_16x16x32_f16 v[68:71], v[214:217], v[238:241], v[68:71]
	v_mfma_f32_16x16x32_f16 v[96:99], v[194:197], v[230:233], v[96:99]
	v_mfma_f32_16x16x32_f16 v[92:95], v[194:197], v[242:245], v[92:95]
	v_mfma_f32_16x16x32_f16 v[88:91], v[202:205], v[230:233], v[88:91]
	v_mfma_f32_16x16x32_f16 v[84:87], v[202:205], v[242:245], v[84:87]
	v_mfma_f32_16x16x32_f16 v[80:83], v[210:213], v[230:233], v[80:83]
	v_mfma_f32_16x16x32_f16 v[76:79], v[210:213], v[242:245], v[76:79]
	v_mfma_f32_16x16x32_f16 v[72:75], v[218:221], v[230:233], v[72:75]
	v_mfma_f32_16x16x32_f16 v[68:71], v[218:221], v[242:245], v[68:71]
	v_lshl_add_u64 v[222:223], v[222:223], 0, s[22:23]
	s_or_b32 m0, s100, 0x8000
	s_barrier
	ds_read_b128 v[190:193], v161 offset:49152
	ds_read_b128 v[194:197], v161 offset:50176
	ds_read_b128 v[198:201], v160 offset:49152
	ds_read_b128 v[202:205], v160 offset:50176
	ds_read_b128 v[206:209], v159 offset:49152
	ds_read_b128 v[210:213], v159 offset:50176
	ds_read_b128 v[214:217], v158 offset:49152
	ds_read_b128 v[218:221], v158 offset:50176
	global_load_lds_dwordx4 v[222:223], off
	v_lshl_add_u64 v[222:223], v[236:237], 0, s[22:23]
	s_or_b32 m0, s100, 0xa000
	s_nop 0
	global_load_lds_dwordx4 v[222:223], off
	s_barrier
	s_waitcnt lgkmcnt(0)
	v_mfma_f32_16x16x32_f16 v[64:67], v[190:193], v[174:177], v[64:67]
	v_mfma_f32_16x16x32_f16 v[60:63], v[190:193], v[182:185], v[60:63]
	v_mfma_f32_16x16x32_f16 v[56:59], v[198:201], v[174:177], v[56:59]
	v_mfma_f32_16x16x32_f16 v[52:55], v[198:201], v[182:185], v[52:55]
	v_mfma_f32_16x16x32_f16 v[48:51], v[206:209], v[174:177], v[48:51]
	v_mfma_f32_16x16x32_f16 v[44:47], v[206:209], v[182:185], v[44:47]
	v_mfma_f32_16x16x32_f16 v[40:43], v[214:217], v[174:177], v[40:43]
	v_mfma_f32_16x16x32_f16 v[36:39], v[214:217], v[182:185], v[36:39]
	v_mfma_f32_16x16x32_f16 v[64:67], v[194:197], v[178:181], v[64:67]
	v_mfma_f32_16x16x32_f16 v[60:63], v[194:197], v[186:189], v[60:63]
	v_mfma_f32_16x16x32_f16 v[56:59], v[202:205], v[178:181], v[56:59]
	v_mfma_f32_16x16x32_f16 v[52:55], v[202:205], v[186:189], v[52:55]
	v_mfma_f32_16x16x32_f16 v[48:51], v[210:213], v[178:181], v[48:51]
	v_mfma_f32_16x16x32_f16 v[44:47], v[210:213], v[186:189], v[44:47]
	v_mfma_f32_16x16x32_f16 v[40:43], v[218:221], v[178:181], v[40:43]
	v_mfma_f32_16x16x32_f16 v[36:39], v[218:221], v[186:189], v[36:39]
	s_barrier
	v_lshl_add_u64 v[174:175], v[246:247], 0, s[44:45]
	s_or_b32 m0, s100, 0x1c000
	s_nop 0
	global_load_lds_dwordx4 v[174:175], off
	v_lshl_add_u64 v[174:175], v[248:249], 0, s[44:45]
	s_or_b32 m0, s100, 0x1e000
	s_nop 0
	global_load_lds_dwordx4 v[174:175], off
	s_waitcnt vmcnt(6)
	s_barrier
	v_mfma_f32_16x16x32_f16 v[32:35], v[190:193], v[226:229], v[32:35]
	v_mfma_f32_16x16x32_f16 v[28:31], v[190:193], v[238:241], v[28:31]
	v_mfma_f32_16x16x32_f16 v[24:27], v[198:201], v[226:229], v[24:27]
	v_mfma_f32_16x16x32_f16 v[20:23], v[198:201], v[238:241], v[20:23]
	v_mfma_f32_16x16x32_f16 v[16:19], v[206:209], v[226:229], v[16:19]
	v_mfma_f32_16x16x32_f16 v[12:15], v[206:209], v[238:241], v[12:15]
	v_mfma_f32_16x16x32_f16 v[8:11], v[214:217], v[226:229], v[8:11]
	v_mfma_f32_16x16x32_f16 v[4:7], v[214:217], v[238:241], v[4:7]
	v_mfma_f32_16x16x32_f16 v[32:35], v[194:197], v[230:233], v[32:35]
	v_mfma_f32_16x16x32_f16 v[28:31], v[194:197], v[242:245], v[28:31]
	v_mfma_f32_16x16x32_f16 v[24:27], v[202:205], v[230:233], v[24:27]
	v_mfma_f32_16x16x32_f16 v[20:23], v[202:205], v[242:245], v[20:23]
	v_mfma_f32_16x16x32_f16 v[16:19], v[210:213], v[230:233], v[16:19]
	v_mfma_f32_16x16x32_f16 v[12:15], v[210:213], v[242:245], v[12:15]
	v_mfma_f32_16x16x32_f16 v[8:11], v[218:221], v[230:233], v[8:11]
	v_mfma_f32_16x16x32_f16 v[4:7], v[218:221], v[242:245], v[4:7]
	s_add_i32 s1, s1, 2
	s_add_u32 s12, s12, 0x100
	s_addc_u32 s13, s13, 0
	s_cmp_lt_u32 s1, 12
	s_barrier
	s_cbranch_scc0 .Lpk_exit_6

; #define LDA8(dst, b, h) _Pragma("unroll") for (int m = 0; m < 4; ++m) _Pragma("unroll") for (int k = 0; k < 2; ++k) \
;     dst[m][k] = *(const bf16x8*)((const char*)SA8(b, h) + lds_byte8(wr * 64 + m * 16 + fr, k * 32 + fq * 8))
; #define LDB8(dst, b, h) _Pragma("unroll") for (int n = 0; n < 2; ++n) _Pragma("unroll") for (int k = 0; k < 2; ++k) \
;     dst[n][k] = *(const bf16x8*)((const char*)SB8(b, h) + lds_byte8(wc * 32 + n * 16 + fr, k * 32 + fq * 8))
; #define WAIT_V8(n) asm volatile("s_waitcnt vmcnt(" #n ")" ::: "memory")
; #define WAIT_L8(n) asm volatile("s_waitcnt lgkmcnt(" #n ")" ::: "memory")
; #define BAR8 __builtin_amdgcn_s_barrier()
;     ...
;   { LDB8(B0, 0, 0); LDA8(At, 0, 0); STAGE8(SA8(1, 1), A, lda, brow + 128, nt - 1);
;     BAR8; WAIT_L8(0); MMA8(0, 0, At, B0); BAR8;
;     LDB8(B1, 0, 1); BAR8; WAIT_L8(0); MMA8(0, 1, At, B1); BAR8;
;     LDA8(At, 0, 1); WAIT_V8(4); BAR8; WAIT_L8(0); MMA8(1, 0, At, B0); MMA8(1, 1, At, B1); BAR8; }
;   { LDB8(B0, 1, 0); LDA8(At, 1, 0); WAIT_V8(2); BAR8; WAIT_L8(0); MMA8(0, 0, At, B0); BAR8;
;     LDB8(B1, 1, 1); WAIT_V8(0); BAR8; WAIT_L8(0); MMA8(0, 1, At, B1); BAR8;
;     LDA8(At, 1, 1); BAR8; WAIT_L8(0); MMA8(1, 0, At, B0); MMA8(1, 1, At, B1); BAR8; }
.Lpk_exit_6:
	s_add_u32 s8, s8, 0x40780
	s_addc_u32 s9, s9, 0
	v_lshl_add_u64 v[132:133], s[8:9], 0, v[132:133]
	v_lshl_add_u64 v[0:1], v[0:1], 1, v[132:133]
	s_or_b32 m0, s100, 0xc000
	ds_read_b128 v[138:141], v171
	ds_read_b128 v[142:145], v171 offset:1024
	ds_read_b128 v[150:153], v171 offset:2048
	ds_read_b128 v[154:157], v171 offset:3072
	ds_read_b128 v[164:167], v161
	ds_read_b128 v[174:177], v161 offset:1024
	ds_read_b128 v[178:181], v160
	ds_read_b128 v[182:185], v160 offset:1024
	ds_read_b128 v[186:189], v159
	ds_read_b128 v[190:193], v159 offset:1024
	ds_read_b128 v[194:197], v158
	ds_read_b128 v[198:201], v158 offset:1024
	global_load_lds_dwordx4 v[0:1], off
	v_lshl_add_u64 v[0:1], s[8:9], 0, v[136:137]
	v_lshl_add_u64 v[0:1], v[134:135], 1, v[0:1]
	s_or_b32 m0, s100, 0xe000
	s_nop 0
	global_load_lds_dwordx4 v[0:1], off
	s_barrier
	s_waitcnt lgkmcnt(0)
	v_mfma_f32_16x16x32_f16 v[128:131], v[164:167], v[138:141], v[128:131]
	v_mfma_f32_16x16x32_f16 v[124:127], v[164:167], v[150:153], v[124:127]
	v_mfma_f32_16x16x32_f16 v[120:123], v[178:181], v[138:141], v[120:123]
	v_mfma_f32_16x16x32_f16 v[116:119], v[178:181], v[150:153], v[116:119]
	v_mfma_f32_16x16x32_f16 v[104:107], v[194:197], v[138:141], v[104:107]
	v_mfma_f32_16x16x32_f16 v[100:103], v[194:197], v[150:153], v[100:103]
	v_mfma_f32_16x16x32_f16 v[128:131], v[174:177], v[142:145], v[128:131]
	v_mfma_f32_16x16x32_f16 v[124:127], v[174:177], v[154:157], v[124:127]
	v_mfma_f32_16x16x32_f16 v[120:123], v[182:185], v[142:145], v[120:123]
	v_mfma_f32_16x16x32_f16 v[116:119], v[182:185], v[154:157], v[116:119]
	v_mfma_f32_16x16x32_f16 v[112:115], v[186:189], v[138:141], v[112:115]
	v_mfma_f32_16x16x32_f16 v[108:111], v[186:189], v[150:153], v[108:111]
	v_mfma_f32_16x16x32_f16 v[104:107], v[198:201], v[142:145], v[104:107]
	v_mfma_f32_16x16x32_f16 v[100:103], v[198:201], v[154:157], v[100:103]
	v_mfma_f32_16x16x32_f16 v[132:135], v[190:193], v[142:145], v[112:115]
	v_mfma_f32_16x16x32_f16 v[170:173], v[190:193], v[154:157], v[108:111]
	s_barrier
	s_nop 1
	ds_read_b128 v[108:111], v169
	ds_read_b128 v[112:115], v169 offset:1024
	ds_read_b128 v[202:205], v169 offset:2048
	ds_read_b128 v[206:209], v169 offset:3072
	s_barrier
	s_waitcnt lgkmcnt(0)
	v_mfma_f32_16x16x32_f16 v[88:91], v[178:181], v[108:111], v[88:91]
	v_mfma_f32_16x16x32_f16 v[84:87], v[178:181], v[202:205], v[84:87]
	v_mfma_f32_16x16x32_f16 v[72:75], v[194:197], v[108:111], v[72:75]
	v_mfma_f32_16x16x32_f16 v[68:71], v[194:197], v[202:205], v[68:71]
	v_mfma_f32_16x16x32_f16 v[96:99], v[164:167], v[108:111], v[96:99]
	v_mfma_f32_16x16x32_f16 v[92:95], v[164:167], v[202:205], v[92:95]
	v_mfma_f32_16x16x32_f16 v[88:91], v[182:185], v[112:115], v[88:91]
	v_mfma_f32_16x16x32_f16 v[84:87], v[182:185], v[206:209], v[84:87]
	v_mfma_f32_16x16x32_f16 v[80:83], v[186:189], v[108:111], v[80:83]
	v_mfma_f32_16x16x32_f16 v[76:79], v[186:189], v[202:205], v[76:79]
	v_mfma_f32_16x16x32_f16 v[72:75], v[198:201], v[112:115], v[72:75]
	v_mfma_f32_16x16x32_f16 v[68:71], v[198:201], v[206:209], v[68:71]
	v_mfma_f32_16x16x32_f16 v[210:213], v[174:177], v[112:115], v[96:99]
	v_mfma_f32_16x16x32_f16 v[164:167], v[174:177], v[206:209], v[92:95]
	v_mfma_f32_16x16x32_f16 v[174:177], v[190:193], v[112:115], v[80:83]
	v_mfma_f32_16x16x32_f16 v[178:181], v[190:193], v[206:209], v[76:79]
	s_barrier
	s_nop 0
	ds_read_b128 v[76:79], v161 offset:16384
	ds_read_b128 v[80:83], v161 offset:17408
	ds_read_b128 v[92:95], v160 offset:16384
	ds_read_b128 v[96:99], v160 offset:17408
	ds_read_b128 v[182:185], v159 offset:16384
	ds_read_b128 v[186:189], v159 offset:17408
	ds_read_b128 v[190:193], v158 offset:16384
	ds_read_b128 v[194:197], v158 offset:17408
	s_waitcnt vmcnt(4)
	s_barrier
	s_waitcnt lgkmcnt(0)
	v_mfma_f32_16x16x32_f16 v[64:67], v[76:79], v[138:141], v[64:67]
	v_mfma_f32_16x16x32_f16 v[60:63], v[76:79], v[150:153], v[60:63]
	v_mfma_f32_16x16x32_f16 v[56:59], v[92:95], v[138:141], v[56:59]
	v_mfma_f32_16x16x32_f16 v[52:55], v[92:95], v[150:153], v[52:55]
	v_mfma_f32_16x16x32_f16 v[40:43], v[190:193], v[138:141], v[40:43]
	v_mfma_f32_16x16x32_f16 v[36:39], v[190:193], v[150:153], v[36:39]
	v_mfma_f32_16x16x32_f16 v[64:67], v[80:83], v[142:145], v[64:67]
	v_mfma_f32_16x16x32_f16 v[60:63], v[80:83], v[154:157], v[60:63]
	v_mfma_f32_16x16x32_f16 v[56:59], v[96:99], v[142:145], v[56:59]
	v_mfma_f32_16x16x32_f16 v[52:55], v[96:99], v[154:157], v[52:55]
	v_mfma_f32_16x16x32_f16 v[48:51], v[182:185], v[138:141], v[48:51]
	v_mfma_f32_16x16x32_f16 v[44:47], v[182:185], v[150:153], v[44:47]
	v_mfma_f32_16x16x32_f16 v[40:43], v[194:197], v[142:145], v[40:43]
	v_mfma_f32_16x16x32_f16 v[36:39], v[194:197], v[154:157], v[36:39]
	v_mfma_f32_16x16x32_f16 v[198:201], v[186:189], v[142:145], v[48:51]
	v_mfma_f32_16x16x32_f16 v[214:217], v[186:189], v[154:157], v[44:47]
	v_mfma_f32_16x16x32_f16 v[24:27], v[92:95], v[108:111], v[24:27]
	v_mfma_f32_16x16x32_f16 v[20:23], v[92:95], v[202:205], v[20:23]
	v_mfma_f32_16x16x32_f16 v[8:11], v[190:193], v[108:111], v[8:11]
	v_mfma_f32_16x16x32_f16 v[4:7], v[190:193], v[202:205], v[4:7]
	v_mfma_f32_16x16x32_f16 v[32:35], v[76:79], v[108:111], v[32:35]
	v_mfma_f32_16x16x32_f16 v[28:31], v[76:79], v[202:205], v[28:31]
	v_mfma_f32_16x16x32_f16 v[24:27], v[96:99], v[112:115], v[24:27]
	v_mfma_f32_16x16x32_f16 v[20:23], v[96:99], v[206:209], v[20:23]
	v_mfma_f32_16x16x32_f16 v[16:19], v[182:185], v[108:111], v[16:19]
	v_mfma_f32_16x16x32_f16 v[12:15], v[182:185], v[202:205], v[12:15]
	v_mfma_f32_16x16x32_f16 v[8:11], v[194:197], v[112:115], v[8:11]
	v_mfma_f32_16x16x32_f16 v[4:7], v[194:197], v[206:209], v[4:7]
	v_mfma_f32_16x16x32_f16 v[136:139], v[80:83], v[112:115], v[32:35]
	v_mfma_f32_16x16x32_f16 v[140:143], v[80:83], v[206:209], v[28:31]
	v_mfma_f32_16x16x32_f16 v[150:153], v[186:189], v[112:115], v[16:19]
	v_mfma_f32_16x16x32_f16 v[154:157], v[186:189], v[206:209], v[12:15]
	s_barrier
; #define LDA8(dst, b, h) _Pragma("unroll") for (int m = 0; m < 4; ++m) _Pragma("unroll") for (int k = 0; k < 2; ++k) \
;     dst[m][k] = *(const bf16x8*)((const char*)SA8(b, h) + lds_byte8(wr * 64 + m * 16 + fr, k * 32 + fq * 8))
; #define LDB8(dst, b, h) _Pragma("unroll") for (int n = 0; n < 2; ++n) _Pragma("unroll") for (int k = 0; k < 2; ++k) \
;     dst[n][k] = *(const bf16x8*)((const char*)SB8(b, h) + lds_byte8(wc * 32 + n * 16 + fr, k * 32 + fq * 8))
; #define WAIT_V8(n) asm volatile("s_waitcnt vmcnt(" #n ")" ::: "memory")
; #define WAIT_L8(n) asm volatile("s_waitcnt lgkmcnt(" #n ")" ::: "memory")
; #define BAR8 __builtin_amdgcn_s_barrier()
;     ...
;   { LDB8(B0, 1, 0); LDA8(At, 1, 0); WAIT_V8(2); BAR8; WAIT_L8(0); MMA8(0, 0, At, B0); BAR8;
;     LDB8(B1, 1, 1); WAIT_V8(0); BAR8; WAIT_L8(0); MMA8(0, 1, At, B1); BAR8;
;     LDA8(At, 1, 1); BAR8; WAIT_L8(0); MMA8(1, 0, At, B0); MMA8(1, 1, At, B1); BAR8; }
;   if (wr == 0) BAR8;
	s_nop 0
	ds_read_b128 v[12:15], v163
	ds_read_b128 v[16:19], v163 offset:1024
	ds_read_b128 v[182:185], v163 offset:2048
	ds_read_b128 v[186:189], v163 offset:3072
	ds_read_b128 v[28:31], v161 offset:32768
	ds_read_b128 v[32:35], v161 offset:33792
	ds_read_b128 v[44:47], v160 offset:32768
	ds_read_b128 v[48:51], v160 offset:33792
	ds_read_b128 v[190:193], v159 offset:32768
	ds_read_b128 v[194:197], v159 offset:33792
	ds_read_b128 v[202:205], v158 offset:32768
	ds_read_b128 v[206:209], v158 offset:33792
	s_waitcnt vmcnt(2)
	s_barrier
	s_waitcnt lgkmcnt(0)
	v_mfma_f32_16x16x32_f16 v[76:79], v[28:31], v[12:15], v[128:131]
	v_mfma_f32_16x16x32_f16 v[128:131], v[32:35], v[16:19], v[76:79]
	v_mfma_f32_16x16x32_f16 v[76:79], v[28:31], v[182:185], v[124:127]
	v_mfma_f32_16x16x32_f16 v[124:127], v[32:35], v[186:189], v[76:79]
	v_mfma_f32_16x16x32_f16 v[76:79], v[44:47], v[12:15], v[120:123]
	v_mfma_f32_16x16x32_f16 v[112:115], v[48:51], v[16:19], v[76:79]
	v_mfma_f32_16x16x32_f16 v[76:79], v[44:47], v[182:185], v[116:119]
	v_mfma_f32_16x16x32_f16 v[108:111], v[48:51], v[186:189], v[76:79]
	v_mfma_f32_16x16x32_f16 v[76:79], v[190:193], v[12:15], v[132:135]
	v_mfma_f32_16x16x32_f16 v[96:99], v[194:197], v[16:19], v[76:79]
	v_mfma_f32_16x16x32_f16 v[76:79], v[190:193], v[182:185], v[170:173]
	v_mfma_f32_16x16x32_f16 v[92:95], v[194:197], v[186:189], v[76:79]
	v_mfma_f32_16x16x32_f16 v[76:79], v[202:205], v[12:15], v[104:107]
	v_mfma_f32_16x16x32_f16 v[80:83], v[206:209], v[16:19], v[76:79]
	v_mfma_f32_16x16x32_f16 v[76:79], v[202:205], v[182:185], v[100:103]
	v_mfma_f32_16x16x32_f16 v[76:79], v[206:209], v[186:189], v[76:79]
	s_barrier
	ds_read_b128 v[132:135], v162
	ds_read_b128 v[168:171], v162 offset:1024
	ds_read_b128 v[218:221], v162 offset:2048
	ds_read_b128 v[226:229], v162 offset:3072
	s_waitcnt vmcnt(0)
	s_barrier
	s_waitcnt lgkmcnt(0)
	v_mfma_f32_16x16x32_f16 v[100:103], v[28:31], v[132:135], v[210:213]
	v_mfma_f32_16x16x32_f16 v[28:31], v[28:31], v[218:221], v[164:167]
	v_mfma_f32_16x16x32_f16 v[116:119], v[32:35], v[226:229], v[28:31]
	v_mfma_f32_16x16x32_f16 v[28:31], v[44:47], v[132:135], v[88:91]
	v_mfma_f32_16x16x32_f16 v[104:107], v[48:51], v[168:171], v[28:31]
	v_mfma_f32_16x16x32_f16 v[28:31], v[44:47], v[218:221], v[84:87]
	v_mfma_f32_16x16x32_f16 v[120:123], v[32:35], v[168:171], v[100:103]
	v_mfma_f32_16x16x32_f16 v[100:103], v[48:51], v[226:229], v[28:31]
	v_mfma_f32_16x16x32_f16 v[28:31], v[190:193], v[132:135], v[174:177]
	v_mfma_f32_16x16x32_f16 v[88:91], v[194:197], v[168:171], v[28:31]
	v_mfma_f32_16x16x32_f16 v[28:31], v[190:193], v[218:221], v[178:181]
	v_mfma_f32_16x16x32_f16 v[84:87], v[194:197], v[226:229], v[28:31]
	v_mfma_f32_16x16x32_f16 v[28:31], v[202:205], v[132:135], v[72:75]
	v_mfma_f32_16x16x32_f16 v[72:75], v[206:209], v[168:171], v[28:31]
	v_mfma_f32_16x16x32_f16 v[28:31], v[202:205], v[218:221], v[68:71]
	v_mfma_f32_16x16x32_f16 v[68:71], v[206:209], v[226:229], v[28:31]
	s_barrier
	ds_read_b128 v[162:165], v161 offset:49152
	ds_read_b128 v[172:175], v161 offset:50176
	ds_read_b128 v[176:179], v160 offset:49152
	ds_read_b128 v[190:193], v160 offset:50176
	ds_read_b128 v[194:197], v159 offset:49152
	ds_read_b128 v[202:205], v159 offset:50176
	ds_read_b128 v[206:209], v158 offset:49152
	ds_read_b128 v[158:161], v158 offset:50176
	s_barrier
	s_waitcnt lgkmcnt(0)
	v_mfma_f32_16x16x32_f16 v[28:31], v[162:165], v[12:15], v[64:67]
	v_mfma_f32_16x16x32_f16 v[64:67], v[172:175], v[16:19], v[28:31]
	v_mfma_f32_16x16x32_f16 v[28:31], v[162:165], v[182:185], v[60:63]
	v_mfma_f32_16x16x32_f16 v[60:63], v[172:175], v[186:189], v[28:31]
	v_mfma_f32_16x16x32_f16 v[28:31], v[176:179], v[12:15], v[56:59]
	v_mfma_f32_16x16x32_f16 v[48:51], v[190:193], v[16:19], v[28:31]
	v_mfma_f32_16x16x32_f16 v[28:31], v[176:179], v[182:185], v[52:55]
	v_mfma_f32_16x16x32_f16 v[44:47], v[190:193], v[186:189], v[28:31]
	v_mfma_f32_16x16x32_f16 v[28:31], v[194:197], v[12:15], v[198:201]
	v_mfma_f32_16x16x32_f16 v[12:15], v[206:209], v[12:15], v[40:43]
	v_mfma_f32_16x16x32_f16 v[32:35], v[202:205], v[16:19], v[28:31]
	v_mfma_f32_16x16x32_f16 v[28:31], v[194:197], v[182:185], v[214:217]
	v_mfma_f32_16x16x32_f16 v[16:19], v[158:161], v[16:19], v[12:15]
	v_mfma_f32_16x16x32_f16 v[12:15], v[206:209], v[182:185], v[36:39]
	v_mfma_f32_16x16x32_f16 v[28:31], v[202:205], v[186:189], v[28:31]
	v_mfma_f32_16x16x32_f16 v[12:15], v[158:161], v[186:189], v[12:15]
	v_mfma_f32_16x16x32_f16 v[36:39], v[162:165], v[132:135], v[136:139]
	v_mfma_f32_16x16x32_f16 v[56:59], v[172:175], v[168:171], v[36:39]
	v_mfma_f32_16x16x32_f16 v[36:39], v[162:165], v[218:221], v[140:143]
	v_mfma_f32_16x16x32_f16 v[20:23], v[176:179], v[218:221], v[20:23]
	v_mfma_f32_16x16x32_f16 v[52:55], v[172:175], v[226:229], v[36:39]
	v_mfma_f32_16x16x32_f16 v[24:27], v[176:179], v[132:135], v[24:27]
	v_mfma_f32_16x16x32_f16 v[36:39], v[190:193], v[226:229], v[20:23]
	v_mfma_f32_16x16x32_f16 v[20:23], v[194:197], v[132:135], v[150:153]
	v_mfma_f32_16x16x32_f16 v[40:43], v[190:193], v[168:171], v[24:27]
	v_mfma_f32_16x16x32_f16 v[24:27], v[202:205], v[168:171], v[20:23]
	v_mfma_f32_16x16x32_f16 v[20:23], v[194:197], v[218:221], v[154:157]
	v_mfma_f32_16x16x32_f16 v[8:11], v[206:209], v[132:135], v[8:11]
	v_mfma_f32_16x16x32_f16 v[4:7], v[206:209], v[218:221], v[4:7]
	v_mfma_f32_16x16x32_f16 v[20:23], v[202:205], v[226:229], v[20:23]
	v_mfma_f32_16x16x32_f16 v[8:11], v[158:161], v[168:171], v[8:11]
	v_mfma_f32_16x16x32_f16 v[4:7], v[158:161], v[226:229], v[4:7]
	s_movk_i32 s1, 0x100
	v_cmp_gt_u32_e32 vcc, s1, v3
	s_barrier
	s_and_saveexec_b64 s[8:9], vcc
	s_cbranch_execz .LBB0_1262
	s_barrier

; #define LDA8(dst, b, h) _Pragma("unroll") for (int m = 0; m < 4; ++m) _Pragma("unroll") for (int k = 0; k < 2; ++k) \
;     dst[m][k] = *(const bf16x8*)((const char*)SA8(b, h) + lds_byte8(wr * 64 + m * 16 + fr, k * 32 + fq * 8))
; #define LDB8(dst, b, h) _Pragma("unroll") for (int n = 0; n < 2; ++n) _Pragma("unroll") for (int k = 0; k < 2; ++k) \
;     dst[n][k] = *(const bf16x8*)((const char*)SB8(b, h) + lds_byte8(wc * 32 + n * 16 + fr, k * 32 + fq * 8))
; #define WAIT_V8(n) asm volatile("s_waitcnt vmcnt(" #n ")" ::: "memory")
; #define WAIT_L8(n) asm volatile("s_waitcnt lgkmcnt(" #n ")" ::: "memory")
; #define BAR8 __builtin_amdgcn_s_barrier()
; #define SCHED8 __builtin_amdgcn_sched_barrier(0)
;     ...
;   STAGE8(SB8(1, 0), Bt, K, bcol, 1); STAGE8(SA8(1, 0), A, lda, brow, 1); STAGE8(SB8(1, 1), Bt, K, bcol + 128, 1);
;   WAIT_V8(6); BAR8;
;   for (int tt = 0; tt < nt - 2; tt += 2) {
;     LDB8(B0, 0, 0); SCHED8; LDA8(At, 0, 0); STAGE8(SA8(1, 1), A, lda, brow + 128, tt + 1);
;     WAIT_L8(8); BAR8; WAIT_L8(0); MMA8(0, 0, At, B0); BAR8; SCHED8;
;     LDB8(B1, 0, 1); STAGE8(SB8(0, 0), Bt, K, bcol, tt + 2);
;     BAR8; WAIT_L8(0); MMA8(0, 1, At, B1); BAR8;
;     LDA8(At, 0, 1); STAGE8(SA8(0, 0), A, lda, brow, tt + 2);
;     BAR8; WAIT_L8(0); MMA8(1, 0, At, B0); BAR8; SCHED8;
.LBB0_1324:
	s_or_b64 exec, exec, s[12:13]
	s_mov_b64 s[36:37], 0x80
	v_lshl_add_u64 v[10:11], v[10:11], 0, s[36:37]
	s_or_b32 m0, s100, 0x18000
	s_waitcnt vmcnt(4)
	s_barrier
	global_load_lds_dwordx4 v[10:11], off
	v_lshl_add_u64 v[10:11], v[12:13], 0, s[36:37]
	s_or_b32 m0, s100, 0x1a000
	global_load_lds_dwordx4 v[10:11], off
	v_lshl_add_u64 v[10:11], v[14:15], 0, s[36:37]
	s_or_b32 m0, s100, 0x8000
	global_load_lds_dwordx4 v[10:11], off
	v_lshl_add_u64 v[10:11], v[16:17], 0, s[36:37]
	s_or_b32 m0, s100, 0xa000
	global_load_lds_dwordx4 v[10:11], off
	v_lshl_add_u64 v[10:11], v[18:19], 0, s[36:37]
	s_or_b32 m0, s100, 0x1c000
	s_nop 0
	global_load_lds_dwordx4 v[10:11], off
	v_lshl_add_u64 v[10:11], v[20:21], 0, s[36:37]
	s_or_b32 m0, s100, 0x1e000
	v_and_b32_e32 v147, 15, v3
	global_load_lds_dwordx4 v[10:11], off
	v_bfe_u32 v148, v3, 4, 2
	v_lshlrev_b32_e32 v10, 4, v148
	v_lshlrev_b32_e32 v11, 6, v147
	v_lshlrev_b32_e32 v13, 2, v3
	v_or_b32_e32 v12, v10, v11
	v_and_b32_e32 v13, 32, v13
	s_mov_b32 s12, 0x10000
	v_bitop3_b32 v18, v12, s12, v13 bitop3:0xde
	s_mov_b32 s12, 0x14000
	v_bitop3_b32 v17, v10, v13, v11 bitop3:0x36
	v_bitop3_b32 v19, v12, s12, v13 bitop3:0xde
	s_mov_b32 s12, 0x18000
	v_lshlrev_b32_e32 v11, 6, v3
	v_bitop3_b32 v20, v12, s12, v13 bitop3:0xde
	s_mov_b32 s12, 0x1c000
	v_and_b32_e32 v11, 0x3c0, v11
	s_movk_i32 s31, 0x1600
	s_and_b32 s29, s21, 0xffffff00
	v_bitop3_b32 v21, v12, s12, v13 bitop3:0xde
	v_bitop3_b32 v24, v11, v13, v10 bitop3:0x36
	v_mad_i64_i32 v[10:11], s[12:13], v5, s31, 0
	v_mov_b32_e32 v5, 0x1600
	v_mad_i64_i32 v[12:13], s[12:13], s29, v5, v[10:11]
	v_lshl_add_u64 v[12:13], v[12:13], 0, v[6:7]
	v_lshl_add_u64 v[138:139], s[4:5], 0, v[12:13]
	v_mad_i64_i32 v[12:13], s[12:13], v22, s31, 0
	v_mad_i64_i32 v[14:15], s[12:13], s29, v5, v[12:13]
	s_bfe_u32 s29, s20, 0x60008
	v_mov_b32_e32 v5, 0x160000
	v_mad_u64_u32 v[10:11], s[12:13], s29, v5, v[10:11]
	v_lshl_add_u64 v[6:7], v[10:11], 0, v[6:7]
	v_bfe_u32 v146, v3, 6, 2
	s_waitcnt vmcnt(6)
	v_lshlrev_b32_e32 v149, 6, v23
	v_lshlrev_b32_e32 v23, 13, v23
	v_lshl_add_u64 v[142:143], s[2:3], 0, v[6:7]
	v_mad_u64_u32 v[6:7], s[12:13], s29, v5, v[12:13]
	v_lshlrev_b32_e32 v16, 12, v146
	v_or_b32_e32 v25, 0x800, v23
	v_or_b32_e32 v26, 0x1000, v23
	v_or_b32_e32 v27, 0x1800, v23
	v_lshl_add_u64 v[14:15], v[14:15], 0, v[8:9]
	v_lshl_add_u64 v[6:7], v[6:7], 0, v[8:9]
	s_ashr_i32 s9, s8, 31
	v_lshl_add_u64 v[140:141], s[4:5], 0, v[14:15]
	v_lshl_add_u64 v[144:145], s[2:3], 0, v[6:7]
	s_mov_b32 s29, -2
	s_mov_b64 s[12:13], 0
	v_add_u32_e32 v171, v18, v16
	v_add_u32_e32 v156, v17, v23
	v_add_u32_e32 v155, v24, v25
	v_add_u32_e32 v154, v24, v26
	v_add_u32_e32 v153, v24, v27
	v_add_u32_e32 v169, v19, v16
	v_add_u32_e32 v159, v20, v16
	v_add_u32_e32 v158, v21, v16
	s_mov_b64 s[36:37], 0x20b0080
	s_mov_b64 s[38:39], 0xd5a0100
	s_mov_b64 s[40:41], 0x2000100
	s_mov_b64 s[42:43], 0xd650100
	s_mov_b64 s[44:45], 0x20b0100
	s_mov_b64 s[46:47], 0xd5a0180
	s_mov_b64 s[48:49], 0x2000180
	s_mov_b64 s[50:51], 0xd650180
	s_barrier
	ds_read_b128 v[174:177], v171
	ds_read_b128 v[178:181], v171 offset:1024
	ds_read_b128 v[182:185], v171 offset:2048
	ds_read_b128 v[186:189], v171 offset:3072
	v_lshl_add_u64 v[222:223], v[142:143], 0, s[12:13]
	v_lshl_add_u64 v[226:227], v[222:223], 0, s[36:37]
	s_or_b32 m0, s100, 0xc000
	v_lshl_add_u64 v[236:237], v[144:145], 0, s[12:13]
	ds_read_b128 v[190:193], v156
	ds_read_b128 v[194:197], v156 offset:1024
	ds_read_b128 v[198:201], v155
	ds_read_b128 v[202:205], v155 offset:1024
	ds_read_b128 v[206:209], v154
	ds_read_b128 v[210:213], v154 offset:1024
	ds_read_b128 v[214:217], v153
	ds_read_b128 v[218:221], v153 offset:1024
	global_load_lds_dwordx4 v[226:227], off
	v_lshl_add_u64 v[226:227], v[236:237], 0, s[36:37]
	s_or_b32 m0, s100, 0xe000
	s_nop 0
	global_load_lds_dwordx4 v[226:227], off
	s_waitcnt lgkmcnt(8)
	s_barrier
	s_waitcnt lgkmcnt(0)
	v_mfma_f32_16x16x32_bf16 v[128:131], v[190:193], v[174:177], 0
	v_mfma_f32_16x16x32_bf16 v[124:127], v[190:193], v[182:185], 0
	v_mfma_f32_16x16x32_bf16 v[120:123], v[198:201], v[174:177], 0
	v_mfma_f32_16x16x32_bf16 v[116:119], v[198:201], v[182:185], 0
	v_mfma_f32_16x16x32_bf16 v[112:115], v[206:209], v[174:177], 0
	v_mfma_f32_16x16x32_bf16 v[108:111], v[206:209], v[182:185], 0
	v_mfma_f32_16x16x32_bf16 v[104:107], v[214:217], v[174:177], 0
	v_mfma_f32_16x16x32_bf16 v[100:103], v[214:217], v[182:185], 0
	v_mfma_f32_16x16x32_bf16 v[128:131], v[194:197], v[178:181], v[128:131]
	v_mfma_f32_16x16x32_bf16 v[124:127], v[194:197], v[186:189], v[124:127]
	v_mfma_f32_16x16x32_bf16 v[120:123], v[202:205], v[178:181], v[120:123]
	v_mfma_f32_16x16x32_bf16 v[116:119], v[202:205], v[186:189], v[116:119]
	v_mfma_f32_16x16x32_bf16 v[112:115], v[210:213], v[178:181], v[112:115]
	v_mfma_f32_16x16x32_bf16 v[108:111], v[210:213], v[186:189], v[108:111]
	v_mfma_f32_16x16x32_bf16 v[104:107], v[218:221], v[178:181], v[104:107]
	v_mfma_f32_16x16x32_bf16 v[100:103], v[218:221], v[186:189], v[100:103]
	s_barrier
	v_lshl_add_u64 v[246:247], v[138:139], 0, s[12:13]
	v_lshl_add_u64 v[248:249], v[246:247], 0, s[38:39]
	s_or_b32 m0, s100, 0x10000
	ds_read_b128 v[226:229], v169
	ds_read_b128 v[230:233], v169 offset:1024
	ds_read_b128 v[238:241], v169 offset:2048
	ds_read_b128 v[242:245], v169 offset:3072
	global_load_lds_dwordx4 v[248:249], off
	v_lshl_add_u64 v[248:249], v[140:141], 0, s[12:13]
	v_lshl_add_u64 v[250:251], v[248:249], 0, s[38:39]
	s_or_b32 m0, s100, 0x12000
	s_nop 0
	global_load_lds_dwordx4 v[250:251], off
	s_barrier
; #define LDA8(dst, b, h) _Pragma("unroll") for (int m = 0; m < 4; ++m) _Pragma("unroll") for (int k = 0; k < 2; ++k) \
;     dst[m][k] = *(const bf16x8*)((const char*)SA8(b, h) + lds_byte8(wr * 64 + m * 16 + fr, k * 32 + fq * 8))
; #define LDB8(dst, b, h) _Pragma("unroll") for (int n = 0; n < 2; ++n) _Pragma("unroll") for (int k = 0; k < 2; ++k) \
;     dst[n][k] = *(const bf16x8*)((const char*)SB8(b, h) + lds_byte8(wc * 32 + n * 16 + fr, k * 32 + fq * 8))
; #define WAIT_V8(n) asm volatile("s_waitcnt vmcnt(" #n ")" ::: "memory")
; #define WAIT_L8(n) asm volatile("s_waitcnt lgkmcnt(" #n ")" ::: "memory")
; #define BAR8 __builtin_amdgcn_s_barrier()
; #define SCHED8 __builtin_amdgcn_sched_barrier(0)
;     ...
;     BAR8; WAIT_L8(0); MMA8(0, 1, At, B1); BAR8;
;     LDA8(At, 0, 1); STAGE8(SA8(0, 0), A, lda, brow, tt + 2);
;     BAR8; WAIT_L8(0); MMA8(1, 0, At, B0); BAR8; SCHED8;
;     STAGE8(SB8(0, 1), Bt, K, bcol + 128, tt + 2);
;     WAIT_V8(6); BAR8; MMA8(1, 1, At, B1); BAR8;
;     LDB8(B0, 1, 0); SCHED8; LDA8(At, 1, 0); STAGE8(SA8(0, 1), A, lda, brow + 128, tt + 2);
;     WAIT_L8(8); BAR8; WAIT_L8(0); MMA8(0, 0, At, B0); BAR8; SCHED8;
	s_waitcnt lgkmcnt(0)
	v_mfma_f32_16x16x32_bf16 v[96:99], v[190:193], v[226:229], 0
	v_mfma_f32_16x16x32_bf16 v[92:95], v[190:193], v[238:241], 0
	v_mfma_f32_16x16x32_bf16 v[88:91], v[198:201], v[226:229], 0
	v_mfma_f32_16x16x32_bf16 v[84:87], v[198:201], v[238:241], 0
	v_mfma_f32_16x16x32_bf16 v[80:83], v[206:209], v[226:229], 0
	v_mfma_f32_16x16x32_bf16 v[76:79], v[206:209], v[238:241], 0
	v_mfma_f32_16x16x32_bf16 v[72:75], v[214:217], v[226:229], 0
	v_mfma_f32_16x16x32_bf16 v[68:71], v[214:217], v[238:241], 0
	v_mfma_f32_16x16x32_bf16 v[96:99], v[194:197], v[230:233], v[96:99]
	v_mfma_f32_16x16x32_bf16 v[92:95], v[194:197], v[242:245], v[92:95]
	v_mfma_f32_16x16x32_bf16 v[88:91], v[202:205], v[230:233], v[88:91]
	v_mfma_f32_16x16x32_bf16 v[84:87], v[202:205], v[242:245], v[84:87]
	v_mfma_f32_16x16x32_bf16 v[80:83], v[210:213], v[230:233], v[80:83]
	v_mfma_f32_16x16x32_bf16 v[76:79], v[210:213], v[242:245], v[76:79]
	v_mfma_f32_16x16x32_bf16 v[72:75], v[218:221], v[230:233], v[72:75]
	v_mfma_f32_16x16x32_bf16 v[68:71], v[218:221], v[242:245], v[68:71]
	v_lshl_add_u64 v[250:251], v[222:223], 0, s[40:41]
	s_mov_b32 m0, s100
	s_barrier
	ds_read_b128 v[190:193], v156 offset:16384
	ds_read_b128 v[194:197], v156 offset:17408
	ds_read_b128 v[198:201], v155 offset:16384
	ds_read_b128 v[202:205], v155 offset:17408
	ds_read_b128 v[206:209], v154 offset:16384
	ds_read_b128 v[210:213], v154 offset:17408
	ds_read_b128 v[214:217], v153 offset:16384
	ds_read_b128 v[218:221], v153 offset:17408
	global_load_lds_dwordx4 v[250:251], off
	v_lshl_add_u64 v[250:251], v[236:237], 0, s[40:41]
	s_or_b32 m0, s100, 0x2000
	s_nop 0
	global_load_lds_dwordx4 v[250:251], off
	s_barrier
	s_waitcnt lgkmcnt(0)
	v_mfma_f32_16x16x32_bf16 v[64:67], v[190:193], v[174:177], 0
	v_mfma_f32_16x16x32_bf16 v[60:63], v[190:193], v[182:185], 0
	v_mfma_f32_16x16x32_bf16 v[56:59], v[198:201], v[174:177], 0
	v_mfma_f32_16x16x32_bf16 v[52:55], v[198:201], v[182:185], 0
	v_mfma_f32_16x16x32_bf16 v[48:51], v[206:209], v[174:177], 0
	v_mfma_f32_16x16x32_bf16 v[44:47], v[206:209], v[182:185], 0
	v_mfma_f32_16x16x32_bf16 v[40:43], v[214:217], v[174:177], 0
	v_mfma_f32_16x16x32_bf16 v[36:39], v[214:217], v[182:185], 0
	v_mfma_f32_16x16x32_bf16 v[64:67], v[194:197], v[178:181], v[64:67]
	v_mfma_f32_16x16x32_bf16 v[60:63], v[194:197], v[186:189], v[60:63]
	v_mfma_f32_16x16x32_bf16 v[56:59], v[202:205], v[178:181], v[56:59]
	v_mfma_f32_16x16x32_bf16 v[52:55], v[202:205], v[186:189], v[52:55]
	v_mfma_f32_16x16x32_bf16 v[48:51], v[210:213], v[178:181], v[48:51]
	v_mfma_f32_16x16x32_bf16 v[44:47], v[210:213], v[186:189], v[44:47]
	v_mfma_f32_16x16x32_bf16 v[40:43], v[218:221], v[178:181], v[40:43]
	v_mfma_f32_16x16x32_bf16 v[36:39], v[218:221], v[186:189], v[36:39]
	s_barrier
	v_lshl_add_u64 v[174:175], v[246:247], 0, s[42:43]
	s_or_b32 m0, s100, 0x14000
	s_nop 0
	global_load_lds_dwordx4 v[174:175], off
	v_lshl_add_u64 v[174:175], v[248:249], 0, s[42:43]
	s_or_b32 m0, s100, 0x16000
	s_nop 0
	global_load_lds_dwordx4 v[174:175], off
	s_waitcnt vmcnt(6)
	s_barrier
	v_mfma_f32_16x16x32_bf16 v[32:35], v[190:193], v[226:229], 0
	v_mfma_f32_16x16x32_bf16 v[28:31], v[190:193], v[238:241], 0
	v_mfma_f32_16x16x32_bf16 v[24:27], v[198:201], v[226:229], 0
	v_mfma_f32_16x16x32_bf16 v[20:23], v[198:201], v[238:241], 0
	v_mfma_f32_16x16x32_bf16 v[16:19], v[206:209], v[226:229], 0
	v_mfma_f32_16x16x32_bf16 v[12:15], v[206:209], v[238:241], 0
	v_mfma_f32_16x16x32_bf16 v[8:11], v[214:217], v[226:229], 0
	v_mfma_f32_16x16x32_bf16 v[4:7], v[214:217], v[238:241], 0
	v_mfma_f32_16x16x32_bf16 v[32:35], v[194:197], v[230:233], v[32:35]
	v_mfma_f32_16x16x32_bf16 v[28:31], v[194:197], v[242:245], v[28:31]
	v_mfma_f32_16x16x32_bf16 v[24:27], v[202:205], v[230:233], v[24:27]
	v_mfma_f32_16x16x32_bf16 v[20:23], v[202:205], v[242:245], v[20:23]
	v_mfma_f32_16x16x32_bf16 v[16:19], v[210:213], v[230:233], v[16:19]
	v_mfma_f32_16x16x32_bf16 v[12:15], v[210:213], v[242:245], v[12:15]
	v_mfma_f32_16x16x32_bf16 v[8:11], v[218:221], v[230:233], v[8:11]
	v_mfma_f32_16x16x32_bf16 v[4:7], v[218:221], v[242:245], v[4:7]
	s_barrier
	ds_read_b128 v[174:177], v159
	ds_read_b128 v[178:181], v159 offset:1024
	ds_read_b128 v[182:185], v159 offset:2048
	ds_read_b128 v[186:189], v159 offset:3072
	v_lshl_add_u64 v[226:227], v[222:223], 0, s[44:45]
	s_or_b32 m0, s100, 0x4000
	ds_read_b128 v[190:193], v156 offset:32768
	ds_read_b128 v[194:197], v156 offset:33792
	ds_read_b128 v[198:201], v155 offset:32768
	ds_read_b128 v[202:205], v155 offset:33792
	ds_read_b128 v[206:209], v154 offset:32768
	ds_read_b128 v[210:213], v154 offset:33792
	ds_read_b128 v[214:217], v153 offset:32768
	ds_read_b128 v[218:221], v153 offset:33792
	global_load_lds_dwordx4 v[226:227], off
	v_lshl_add_u64 v[226:227], v[236:237], 0, s[44:45]
	s_or_b32 m0, s100, 0x6000
	s_nop 0
	global_load_lds_dwordx4 v[226:227], off
	s_waitcnt lgkmcnt(8)
	s_barrier
; #define LDA8(dst, b, h) _Pragma("unroll") for (int m = 0; m < 4; ++m) _Pragma("unroll") for (int k = 0; k < 2; ++k) \
;     dst[m][k] = *(const bf16x8*)((const char*)SA8(b, h) + lds_byte8(wr * 64 + m * 16 + fr, k * 32 + fq * 8))
; #define LDB8(dst, b, h) _Pragma("unroll") for (int n = 0; n < 2; ++n) _Pragma("unroll") for (int k = 0; k < 2; ++k) \
;     dst[n][k] = *(const bf16x8*)((const char*)SB8(b, h) + lds_byte8(wc * 32 + n * 16 + fr, k * 32 + fq * 8))
; #define WAIT_V8(n) asm volatile("s_waitcnt vmcnt(" #n ")" ::: "memory")
; #define WAIT_L8(n) asm volatile("s_waitcnt lgkmcnt(" #n ")" ::: "memory")
; #define BAR8 __builtin_amdgcn_s_barrier()
; #define SCHED8 __builtin_amdgcn_sched_barrier(0)
;     ...
;     WAIT_L8(8); BAR8; WAIT_L8(0); MMA8(0, 0, At, B0); BAR8; SCHED8;
;     LDB8(B1, 1, 1); STAGE8(SB8(1, 0), Bt, K, bcol, tt + 3);
;     BAR8; WAIT_L8(0); MMA8(0, 1, At, B1); BAR8;
;     LDA8(At, 1, 1); STAGE8(SA8(1, 0), A, lda, brow, tt + 3);
;     BAR8; WAIT_L8(0); MMA8(1, 0, At, B0); BAR8; SCHED8;
;     STAGE8(SB8(1, 1), Bt, K, bcol + 128, tt + 3);
;     WAIT_V8(6); BAR8; MMA8(1, 1, At, B1); BAR8;
;   }
	s_waitcnt lgkmcnt(0)
	v_mfma_f32_16x16x32_bf16 v[128:131], v[190:193], v[174:177], v[128:131]
	v_mfma_f32_16x16x32_bf16 v[124:127], v[190:193], v[182:185], v[124:127]
	v_mfma_f32_16x16x32_bf16 v[120:123], v[198:201], v[174:177], v[120:123]
	v_mfma_f32_16x16x32_bf16 v[116:119], v[198:201], v[182:185], v[116:119]
	v_mfma_f32_16x16x32_bf16 v[112:115], v[206:209], v[174:177], v[112:115]
	v_mfma_f32_16x16x32_bf16 v[108:111], v[206:209], v[182:185], v[108:111]
	v_mfma_f32_16x16x32_bf16 v[104:107], v[214:217], v[174:177], v[104:107]
	v_mfma_f32_16x16x32_bf16 v[100:103], v[214:217], v[182:185], v[100:103]
	v_mfma_f32_16x16x32_bf16 v[128:131], v[194:197], v[178:181], v[128:131]
	v_mfma_f32_16x16x32_bf16 v[124:127], v[194:197], v[186:189], v[124:127]
	v_mfma_f32_16x16x32_bf16 v[120:123], v[202:205], v[178:181], v[120:123]
	v_mfma_f32_16x16x32_bf16 v[116:119], v[202:205], v[186:189], v[116:119]
	v_mfma_f32_16x16x32_bf16 v[112:115], v[210:213], v[178:181], v[112:115]
	v_mfma_f32_16x16x32_bf16 v[108:111], v[210:213], v[186:189], v[108:111]
	v_mfma_f32_16x16x32_bf16 v[104:107], v[218:221], v[178:181], v[104:107]
	v_mfma_f32_16x16x32_bf16 v[100:103], v[218:221], v[186:189], v[100:103]
	s_barrier
	v_lshl_add_u64 v[250:251], v[246:247], 0, s[46:47]
	s_or_b32 m0, s100, 0x18000
	ds_read_b128 v[226:229], v158
	ds_read_b128 v[230:233], v158 offset:1024
	ds_read_b128 v[238:241], v158 offset:2048
	ds_read_b128 v[242:245], v158 offset:3072
	global_load_lds_dwordx4 v[250:251], off
	v_lshl_add_u64 v[250:251], v[248:249], 0, s[46:47]
	s_or_b32 m0, s100, 0x1a000
	s_nop 0
	global_load_lds_dwordx4 v[250:251], off
	s_barrier
	s_waitcnt lgkmcnt(0)
	v_mfma_f32_16x16x32_bf16 v[96:99], v[190:193], v[226:229], v[96:99]
	v_mfma_f32_16x16x32_bf16 v[92:95], v[190:193], v[238:241], v[92:95]
	v_mfma_f32_16x16x32_bf16 v[88:91], v[198:201], v[226:229], v[88:91]
	v_mfma_f32_16x16x32_bf16 v[84:87], v[198:201], v[238:241], v[84:87]
	v_mfma_f32_16x16x32_bf16 v[80:83], v[206:209], v[226:229], v[80:83]
	v_mfma_f32_16x16x32_bf16 v[76:79], v[206:209], v[238:241], v[76:79]
	v_mfma_f32_16x16x32_bf16 v[72:75], v[214:217], v[226:229], v[72:75]
	v_mfma_f32_16x16x32_bf16 v[68:71], v[214:217], v[238:241], v[68:71]
	v_mfma_f32_16x16x32_bf16 v[96:99], v[194:197], v[230:233], v[96:99]
	v_mfma_f32_16x16x32_bf16 v[92:95], v[194:197], v[242:245], v[92:95]
	v_mfma_f32_16x16x32_bf16 v[88:91], v[202:205], v[230:233], v[88:91]
	v_mfma_f32_16x16x32_bf16 v[84:87], v[202:205], v[242:245], v[84:87]
	v_mfma_f32_16x16x32_bf16 v[80:83], v[210:213], v[230:233], v[80:83]
	v_mfma_f32_16x16x32_bf16 v[76:79], v[210:213], v[242:245], v[76:79]
	v_mfma_f32_16x16x32_bf16 v[72:75], v[218:221], v[230:233], v[72:75]
	v_mfma_f32_16x16x32_bf16 v[68:71], v[218:221], v[242:245], v[68:71]
	v_lshl_add_u64 v[222:223], v[222:223], 0, s[48:49]
	s_or_b32 m0, s100, 0x8000
	s_barrier
	ds_read_b128 v[190:193], v156 offset:49152
	ds_read_b128 v[194:197], v156 offset:50176
	ds_read_b128 v[198:201], v155 offset:49152
	ds_read_b128 v[202:205], v155 offset:50176
	ds_read_b128 v[206:209], v154 offset:49152
	ds_read_b128 v[210:213], v154 offset:50176
	ds_read_b128 v[214:217], v153 offset:49152
	ds_read_b128 v[218:221], v153 offset:50176
	global_load_lds_dwordx4 v[222:223], off
	v_lshl_add_u64 v[222:223], v[236:237], 0, s[48:49]
	s_or_b32 m0, s100, 0xa000
	s_nop 0
	global_load_lds_dwordx4 v[222:223], off
	s_barrier
	s_waitcnt lgkmcnt(0)
	v_mfma_f32_16x16x32_bf16 v[64:67], v[190:193], v[174:177], v[64:67]
	v_mfma_f32_16x16x32_bf16 v[60:63], v[190:193], v[182:185], v[60:63]
	v_mfma_f32_16x16x32_bf16 v[56:59], v[198:201], v[174:177], v[56:59]
	v_mfma_f32_16x16x32_bf16 v[52:55], v[198:201], v[182:185], v[52:55]
	v_mfma_f32_16x16x32_bf16 v[48:51], v[206:209], v[174:177], v[48:51]
	v_mfma_f32_16x16x32_bf16 v[44:47], v[206:209], v[182:185], v[44:47]
	v_mfma_f32_16x16x32_bf16 v[40:43], v[214:217], v[174:177], v[40:43]
	v_mfma_f32_16x16x32_bf16 v[36:39], v[214:217], v[182:185], v[36:39]
	v_mfma_f32_16x16x32_bf16 v[64:67], v[194:197], v[178:181], v[64:67]
	v_mfma_f32_16x16x32_bf16 v[60:63], v[194:197], v[186:189], v[60:63]
	v_mfma_f32_16x16x32_bf16 v[56:59], v[202:205], v[178:181], v[56:59]
	v_mfma_f32_16x16x32_bf16 v[52:55], v[202:205], v[186:189], v[52:55]
	v_mfma_f32_16x16x32_bf16 v[48:51], v[210:213], v[178:181], v[48:51]
	v_mfma_f32_16x16x32_bf16 v[44:47], v[210:213], v[186:189], v[44:47]
	v_mfma_f32_16x16x32_bf16 v[40:43], v[218:221], v[178:181], v[40:43]
	v_mfma_f32_16x16x32_bf16 v[36:39], v[218:221], v[186:189], v[36:39]
	s_barrier
	v_lshl_add_u64 v[174:175], v[246:247], 0, s[50:51]
	s_or_b32 m0, s100, 0x1c000
	s_nop 0
	global_load_lds_dwordx4 v[174:175], off
	v_lshl_add_u64 v[174:175], v[248:249], 0, s[50:51]
	s_or_b32 m0, s100, 0x1e000
	s_nop 0
	global_load_lds_dwordx4 v[174:175], off
	s_waitcnt vmcnt(6)
	s_barrier
	v_mfma_f32_16x16x32_bf16 v[32:35], v[190:193], v[226:229], v[32:35]
	v_mfma_f32_16x16x32_bf16 v[28:31], v[190:193], v[238:241], v[28:31]
	v_mfma_f32_16x16x32_bf16 v[24:27], v[198:201], v[226:229], v[24:27]
	v_mfma_f32_16x16x32_bf16 v[20:23], v[198:201], v[238:241], v[20:23]
	v_mfma_f32_16x16x32_bf16 v[16:19], v[206:209], v[226:229], v[16:19]
	v_mfma_f32_16x16x32_bf16 v[12:15], v[206:209], v[238:241], v[12:15]
	v_mfma_f32_16x16x32_bf16 v[8:11], v[214:217], v[226:229], v[8:11]
	v_mfma_f32_16x16x32_bf16 v[4:7], v[214:217], v[238:241], v[4:7]
	v_mfma_f32_16x16x32_bf16 v[32:35], v[194:197], v[230:233], v[32:35]
	v_mfma_f32_16x16x32_bf16 v[28:31], v[194:197], v[242:245], v[28:31]
	v_mfma_f32_16x16x32_bf16 v[24:27], v[202:205], v[230:233], v[24:27]
	v_mfma_f32_16x16x32_bf16 v[20:23], v[202:205], v[242:245], v[20:23]
	v_mfma_f32_16x16x32_bf16 v[16:19], v[210:213], v[230:233], v[16:19]
	v_mfma_f32_16x16x32_bf16 v[12:15], v[210:213], v[242:245], v[12:15]
	v_mfma_f32_16x16x32_bf16 v[8:11], v[218:221], v[230:233], v[8:11]
	v_mfma_f32_16x16x32_bf16 v[4:7], v[218:221], v[242:245], v[4:7]
	s_add_i32 s29, s29, 2
	s_add_u32 s12, s12, 0x100
	s_addc_u32 s13, s13, 0
	s_cmp_lt_u32 s29, 40
	s_barrier
	s_cbranch_scc0 .Lpk_exit_7

; #define LDA8(dst, b, h) _Pragma("unroll") for (int m = 0; m < 4; ++m) _Pragma("unroll") for (int k = 0; k < 2; ++k) \
;     dst[m][k] = *(const bf16x8*)((const char*)SA8(b, h) + lds_byte8(wr * 64 + m * 16 + fr, k * 32 + fq * 8))
; #define LDB8(dst, b, h) _Pragma("unroll") for (int n = 0; n < 2; ++n) _Pragma("unroll") for (int k = 0; k < 2; ++k) \
;     dst[n][k] = *(const bf16x8*)((const char*)SB8(b, h) + lds_byte8(wc * 32 + n * 16 + fr, k * 32 + fq * 8))
; #define WAIT_V8(n) asm volatile("s_waitcnt vmcnt(" #n ")" ::: "memory")
; #define WAIT_L8(n) asm volatile("s_waitcnt lgkmcnt(" #n ")" ::: "memory")
; #define BAR8 __builtin_amdgcn_s_barrier()
;     ...
;   { LDB8(B0, 0, 0); LDA8(At, 0, 0); STAGE8(SA8(1, 1), A, lda, brow + 128, nt - 1);
;     BAR8; WAIT_L8(0); MMA8(0, 0, At, B0); BAR8;
;     LDB8(B1, 0, 1); BAR8; WAIT_L8(0); MMA8(0, 1, At, B1); BAR8;
;     LDA8(At, 0, 1); WAIT_V8(4); BAR8; WAIT_L8(0); MMA8(1, 0, At, B0); MMA8(1, 1, At, B1); BAR8; }
;   { LDB8(B0, 1, 0); LDA8(At, 1, 0); WAIT_V8(2); BAR8; WAIT_L8(0); MMA8(0, 0, At, B0); BAR8;
;     LDB8(B1, 1, 1); WAIT_V8(0); BAR8; WAIT_L8(0); MMA8(0, 1, At, B1); BAR8;
;     LDA8(At, 1, 1); BAR8; WAIT_L8(0); MMA8(1, 0, At, B0); MMA8(1, 1, At, B1); BAR8; }
.Lpk_exit_7:
	s_add_i32 s27, s27, 0xb0000
	s_add_u32 s2, s2, s27
	s_addc_u32 s3, s3, 0
	s_add_u32 s2, s2, 0x2001580
	s_addc_u32 s3, s3, 0
	v_lshl_add_u64 v[132:133], v[132:133], 1, s[2:3]
	v_lshl_add_u64 v[0:1], v[0:1], 1, v[132:133]
	s_or_b32 m0, s100, 0xc000
	ds_read_b128 v[138:141], v171
	ds_read_b128 v[142:145], v171 offset:1024
	ds_read_b128 v[160:163], v171 offset:2048
	ds_read_b128 v[164:167], v171 offset:3072
	ds_read_b128 v[174:177], v156
	ds_read_b128 v[178:181], v156 offset:1024
	ds_read_b128 v[182:185], v155
	ds_read_b128 v[186:189], v155 offset:1024
	ds_read_b128 v[190:193], v154
	ds_read_b128 v[194:197], v154 offset:1024
	ds_read_b128 v[198:201], v153
	ds_read_b128 v[202:205], v153 offset:1024
	global_load_lds_dwordx4 v[0:1], off
	v_lshl_add_u64 v[0:1], v[136:137], 1, s[2:3]
	v_lshl_add_u64 v[0:1], v[134:135], 1, v[0:1]
	s_or_b32 m0, s100, 0xe000
	s_nop 0
	global_load_lds_dwordx4 v[0:1], off
	s_barrier
	s_waitcnt lgkmcnt(0)
	v_mfma_f32_16x16x32_bf16 v[128:131], v[174:177], v[138:141], v[128:131]
	v_mfma_f32_16x16x32_bf16 v[124:127], v[174:177], v[160:163], v[124:127]
	v_mfma_f32_16x16x32_bf16 v[120:123], v[182:185], v[138:141], v[120:123]
	v_mfma_f32_16x16x32_bf16 v[112:115], v[190:193], v[138:141], v[112:115]
	v_mfma_f32_16x16x32_bf16 v[128:131], v[178:181], v[142:145], v[128:131]
	v_mfma_f32_16x16x32_bf16 v[124:127], v[178:181], v[164:167], v[124:127]
	v_mfma_f32_16x16x32_bf16 v[120:123], v[186:189], v[142:145], v[120:123]
	v_mfma_f32_16x16x32_bf16 v[116:119], v[182:185], v[160:163], v[116:119]
	v_mfma_f32_16x16x32_bf16 v[112:115], v[194:197], v[142:145], v[112:115]
	v_mfma_f32_16x16x32_bf16 v[108:111], v[190:193], v[160:163], v[108:111]
	v_mfma_f32_16x16x32_bf16 v[104:107], v[198:201], v[138:141], v[104:107]
	v_mfma_f32_16x16x32_bf16 v[100:103], v[198:201], v[160:163], v[100:103]
	v_mfma_f32_16x16x32_bf16 v[132:135], v[186:189], v[164:167], v[116:119]
	v_mfma_f32_16x16x32_bf16 v[170:173], v[194:197], v[164:167], v[108:111]
	v_mfma_f32_16x16x32_bf16 v[206:209], v[202:205], v[142:145], v[104:107]
	v_mfma_f32_16x16x32_bf16 v[210:213], v[202:205], v[164:167], v[100:103]
	s_barrier
	s_nop 1
	ds_read_b128 v[100:103], v169
	ds_read_b128 v[104:107], v169 offset:1024
	ds_read_b128 v[108:111], v169 offset:2048
	ds_read_b128 v[116:119], v169 offset:3072
	s_barrier
	s_waitcnt lgkmcnt(0)
	v_mfma_f32_16x16x32_bf16 v[80:83], v[190:193], v[100:103], v[80:83]
	v_mfma_f32_16x16x32_bf16 v[76:79], v[190:193], v[108:111], v[76:79]
	v_mfma_f32_16x16x32_bf16 v[72:75], v[198:201], v[100:103], v[72:75]
	v_mfma_f32_16x16x32_bf16 v[68:71], v[198:201], v[108:111], v[68:71]
	v_mfma_f32_16x16x32_bf16 v[96:99], v[174:177], v[100:103], v[96:99]
	v_mfma_f32_16x16x32_bf16 v[92:95], v[174:177], v[108:111], v[92:95]
	v_mfma_f32_16x16x32_bf16 v[88:91], v[182:185], v[100:103], v[88:91]
	v_mfma_f32_16x16x32_bf16 v[84:87], v[182:185], v[108:111], v[84:87]
	v_mfma_f32_16x16x32_bf16 v[80:83], v[194:197], v[104:107], v[80:83]
	v_mfma_f32_16x16x32_bf16 v[76:79], v[194:197], v[116:119], v[76:79]
	v_mfma_f32_16x16x32_bf16 v[72:75], v[202:205], v[104:107], v[72:75]
	v_mfma_f32_16x16x32_bf16 v[68:71], v[202:205], v[116:119], v[68:71]
	v_mfma_f32_16x16x32_bf16 v[214:217], v[178:181], v[104:107], v[96:99]
	v_mfma_f32_16x16x32_bf16 v[174:177], v[178:181], v[116:119], v[92:95]
	v_mfma_f32_16x16x32_bf16 v[178:181], v[186:189], v[104:107], v[88:91]
	v_mfma_f32_16x16x32_bf16 v[182:185], v[186:189], v[116:119], v[84:87]
	s_barrier
	s_nop 0
	ds_read_b128 v[84:87], v156 offset:16384
	ds_read_b128 v[88:91], v156 offset:17408
	ds_read_b128 v[92:95], v155 offset:16384
	ds_read_b128 v[96:99], v155 offset:17408
	ds_read_b128 v[186:189], v154 offset:16384
	ds_read_b128 v[190:193], v154 offset:17408
	ds_read_b128 v[194:197], v153 offset:16384
	ds_read_b128 v[198:201], v153 offset:17408
	s_waitcnt vmcnt(4)
	s_barrier
	s_waitcnt lgkmcnt(0)
	v_mfma_f32_16x16x32_bf16 v[64:67], v[84:87], v[138:141], v[64:67]
	v_mfma_f32_16x16x32_bf16 v[60:63], v[84:87], v[160:163], v[60:63]
	v_mfma_f32_16x16x32_bf16 v[56:59], v[92:95], v[138:141], v[56:59]
	v_mfma_f32_16x16x32_bf16 v[52:55], v[92:95], v[160:163], v[52:55]
	v_mfma_f32_16x16x32_bf16 v[48:51], v[186:189], v[138:141], v[48:51]
	v_mfma_f32_16x16x32_bf16 v[44:47], v[186:189], v[160:163], v[44:47]
	v_mfma_f32_16x16x32_bf16 v[40:43], v[194:197], v[138:141], v[40:43]
	v_mfma_f32_16x16x32_bf16 v[36:39], v[194:197], v[160:163], v[36:39]
	v_mfma_f32_16x16x32_bf16 v[64:67], v[88:91], v[142:145], v[64:67]
	v_mfma_f32_16x16x32_bf16 v[60:63], v[88:91], v[164:167], v[60:63]
	v_mfma_f32_16x16x32_bf16 v[56:59], v[96:99], v[142:145], v[56:59]
	v_mfma_f32_16x16x32_bf16 v[52:55], v[96:99], v[164:167], v[52:55]
	v_mfma_f32_16x16x32_bf16 v[48:51], v[190:193], v[142:145], v[48:51]
	v_mfma_f32_16x16x32_bf16 v[44:47], v[190:193], v[164:167], v[44:47]
	v_mfma_f32_16x16x32_bf16 v[40:43], v[198:201], v[142:145], v[40:43]
	v_mfma_f32_16x16x32_bf16 v[36:39], v[198:201], v[164:167], v[36:39]
	v_mfma_f32_16x16x32_bf16 v[32:35], v[84:87], v[100:103], v[32:35]
	v_mfma_f32_16x16x32_bf16 v[28:31], v[84:87], v[108:111], v[28:31]
	v_mfma_f32_16x16x32_bf16 v[24:27], v[92:95], v[100:103], v[24:27]
	v_mfma_f32_16x16x32_bf16 v[20:23], v[92:95], v[108:111], v[20:23]
	v_mfma_f32_16x16x32_bf16 v[16:19], v[186:189], v[100:103], v[16:19]
	v_mfma_f32_16x16x32_bf16 v[12:15], v[186:189], v[108:111], v[12:15]
	v_mfma_f32_16x16x32_bf16 v[8:11], v[194:197], v[100:103], v[8:11]
	v_mfma_f32_16x16x32_bf16 v[4:7], v[194:197], v[108:111], v[4:7]
	v_mfma_f32_16x16x32_bf16 v[136:139], v[88:91], v[104:107], v[32:35]
	v_mfma_f32_16x16x32_bf16 v[140:143], v[88:91], v[116:119], v[28:31]
	v_mfma_f32_16x16x32_bf16 v[160:163], v[96:99], v[104:107], v[24:27]
	v_mfma_f32_16x16x32_bf16 v[164:167], v[96:99], v[116:119], v[20:23]
	v_mfma_f32_16x16x32_bf16 v[202:205], v[190:193], v[104:107], v[16:19]
	v_mfma_f32_16x16x32_bf16 v[186:189], v[190:193], v[116:119], v[12:15]
	v_mfma_f32_16x16x32_bf16 v[190:193], v[198:201], v[104:107], v[8:11]
	v_mfma_f32_16x16x32_bf16 v[194:197], v[198:201], v[116:119], v[4:7]
	s_barrier
; #define LDA8(dst, b, h) _Pragma("unroll") for (int m = 0; m < 4; ++m) _Pragma("unroll") for (int k = 0; k < 2; ++k) \
;     dst[m][k] = *(const bf16x8*)((const char*)SA8(b, h) + lds_byte8(wr * 64 + m * 16 + fr, k * 32 + fq * 8))
; #define LDB8(dst, b, h) _Pragma("unroll") for (int n = 0; n < 2; ++n) _Pragma("unroll") for (int k = 0; k < 2; ++k) \
;     dst[n][k] = *(const bf16x8*)((const char*)SB8(b, h) + lds_byte8(wc * 32 + n * 16 + fr, k * 32 + fq * 8))
; #define WAIT_V8(n) asm volatile("s_waitcnt vmcnt(" #n ")" ::: "memory")
; #define WAIT_L8(n) asm volatile("s_waitcnt lgkmcnt(" #n ")" ::: "memory")
; #define BAR8 __builtin_amdgcn_s_barrier()
;     ...
;   { LDB8(B0, 1, 0); LDA8(At, 1, 0); WAIT_V8(2); BAR8; WAIT_L8(0); MMA8(0, 0, At, B0); BAR8;
;     LDB8(B1, 1, 1); WAIT_V8(0); BAR8; WAIT_L8(0); MMA8(0, 1, At, B1); BAR8;
;     LDA8(At, 1, 1); BAR8; WAIT_L8(0); MMA8(1, 0, At, B0); MMA8(1, 1, At, B1); BAR8; }
;   if (wr == 0) BAR8;
	ds_read_b128 v[198:201], v159
	ds_read_b128 v[218:221], v159 offset:1024
	ds_read_b128 v[226:229], v159 offset:2048
	ds_read_b128 v[230:233], v159 offset:3072
	ds_read_b128 v[8:11], v156 offset:32768
	ds_read_b128 v[12:15], v156 offset:33792
	ds_read_b128 v[16:19], v155 offset:32768
	ds_read_b128 v[24:27], v155 offset:33792
	ds_read_b128 v[28:31], v154 offset:32768
	ds_read_b128 v[32:35], v154 offset:33792
	ds_read_b128 v[238:241], v153 offset:32768
	ds_read_b128 v[242:245], v153 offset:33792
	s_waitcnt vmcnt(2)
	s_barrier
	s_waitcnt lgkmcnt(0)
	v_mfma_f32_16x16x32_bf16 v[4:7], v[8:11], v[198:201], v[128:131]
	v_mfma_f32_16x16x32_bf16 v[104:107], v[12:15], v[218:221], v[4:7]
	v_mfma_f32_16x16x32_bf16 v[4:7], v[8:11], v[226:229], v[124:127]
	v_mfma_f32_16x16x32_bf16 v[116:119], v[12:15], v[230:233], v[4:7]
	v_mfma_f32_16x16x32_bf16 v[4:7], v[16:19], v[198:201], v[120:123]
	v_mfma_f32_16x16x32_bf16 v[100:103], v[24:27], v[218:221], v[4:7]
	v_mfma_f32_16x16x32_bf16 v[4:7], v[16:19], v[226:229], v[132:135]
	v_mfma_f32_16x16x32_bf16 v[108:111], v[24:27], v[230:233], v[4:7]
	v_mfma_f32_16x16x32_bf16 v[4:7], v[28:31], v[198:201], v[112:115]
	v_mfma_f32_16x16x32_bf16 v[92:95], v[32:35], v[218:221], v[4:7]
	v_mfma_f32_16x16x32_bf16 v[4:7], v[28:31], v[226:229], v[170:173]
	v_mfma_f32_16x16x32_bf16 v[96:99], v[32:35], v[230:233], v[4:7]
	v_mfma_f32_16x16x32_bf16 v[4:7], v[238:241], v[198:201], v[206:209]
	v_mfma_f32_16x16x32_bf16 v[84:87], v[242:245], v[218:221], v[4:7]
	v_mfma_f32_16x16x32_bf16 v[4:7], v[238:241], v[226:229], v[210:213]
	v_mfma_f32_16x16x32_bf16 v[88:91], v[242:245], v[230:233], v[4:7]
	s_barrier
	ds_read_b128 v[132:135], v158
	ds_read_b128 v[168:171], v158 offset:1024
	ds_read_b128 v[206:209], v158 offset:2048
	ds_read_b128 v[210:213], v158 offset:3072
	s_waitcnt vmcnt(0)
	s_barrier
	s_waitcnt lgkmcnt(0)
	v_mfma_f32_16x16x32_bf16 v[4:7], v[8:11], v[132:135], v[214:217]
	v_mfma_f32_16x16x32_bf16 v[8:11], v[8:11], v[206:209], v[174:177]
	v_mfma_f32_16x16x32_bf16 v[4:7], v[12:15], v[168:171], v[4:7]
	v_mfma_f32_16x16x32_bf16 v[20:23], v[12:15], v[210:213], v[8:11]
	v_mfma_f32_16x16x32_bf16 v[8:11], v[16:19], v[132:135], v[178:181]
	v_mfma_f32_16x16x32_bf16 v[12:15], v[16:19], v[206:209], v[182:185]
	v_mfma_f32_16x16x32_bf16 v[8:11], v[24:27], v[168:171], v[8:11]
	v_mfma_f32_16x16x32_bf16 v[24:27], v[24:27], v[210:213], v[12:15]
	v_mfma_f32_16x16x32_bf16 v[12:15], v[28:31], v[132:135], v[80:83]
	v_mfma_f32_16x16x32_bf16 v[16:19], v[28:31], v[206:209], v[76:79]
	v_mfma_f32_16x16x32_bf16 v[12:15], v[32:35], v[168:171], v[12:15]
	v_mfma_f32_16x16x32_bf16 v[28:31], v[32:35], v[210:213], v[16:19]
	v_mfma_f32_16x16x32_bf16 v[16:19], v[238:241], v[132:135], v[72:75]
	v_mfma_f32_16x16x32_bf16 v[32:35], v[238:241], v[206:209], v[68:71]
	v_mfma_f32_16x16x32_bf16 v[16:19], v[242:245], v[168:171], v[16:19]
	v_mfma_f32_16x16x32_bf16 v[32:35], v[242:245], v[210:213], v[32:35]
	s_barrier
	ds_read_b128 v[172:175], v156 offset:49152
	ds_read_b128 v[156:159], v156 offset:50176
	ds_read_b128 v[176:179], v155 offset:49152
	ds_read_b128 v[180:183], v155 offset:50176
	ds_read_b128 v[214:217], v154 offset:49152
	ds_read_b128 v[238:241], v154 offset:50176
	ds_read_b128 v[242:245], v153 offset:49152
	ds_read_b128 v[150:153], v153 offset:50176
	s_barrier
	s_waitcnt lgkmcnt(0)
	v_mfma_f32_16x16x32_bf16 v[64:67], v[172:175], v[198:201], v[64:67]
	v_mfma_f32_16x16x32_bf16 v[60:63], v[172:175], v[226:229], v[60:63]
	v_mfma_f32_16x16x32_bf16 v[56:59], v[176:179], v[198:201], v[56:59]
	v_mfma_f32_16x16x32_bf16 v[52:55], v[176:179], v[226:229], v[52:55]
	v_mfma_f32_16x16x32_bf16 v[48:51], v[214:217], v[198:201], v[48:51]
	v_mfma_f32_16x16x32_bf16 v[44:47], v[214:217], v[226:229], v[44:47]
	v_mfma_f32_16x16x32_bf16 v[40:43], v[242:245], v[198:201], v[40:43]
	v_mfma_f32_16x16x32_bf16 v[36:39], v[242:245], v[226:229], v[36:39]
	v_mfma_f32_16x16x32_bf16 v[128:131], v[156:159], v[218:221], v[64:67]
	v_mfma_f32_16x16x32_bf16 v[124:127], v[156:159], v[230:233], v[60:63]
	v_mfma_f32_16x16x32_bf16 v[120:123], v[180:183], v[218:221], v[56:59]
	v_mfma_f32_16x16x32_bf16 v[112:115], v[180:183], v[230:233], v[52:55]
	v_mfma_f32_16x16x32_bf16 v[80:83], v[238:241], v[218:221], v[48:51]
	v_mfma_f32_16x16x32_bf16 v[76:79], v[238:241], v[230:233], v[44:47]
	v_mfma_f32_16x16x32_bf16 v[72:75], v[150:153], v[218:221], v[40:43]
	v_mfma_f32_16x16x32_bf16 v[68:71], v[150:153], v[230:233], v[36:39]
	v_mfma_f32_16x16x32_bf16 v[40:43], v[172:175], v[206:209], v[140:143]
	v_mfma_f32_16x16x32_bf16 v[44:47], v[176:179], v[206:209], v[164:167]
	v_mfma_f32_16x16x32_bf16 v[48:51], v[214:217], v[206:209], v[186:189]
	v_mfma_f32_16x16x32_bf16 v[36:39], v[172:175], v[132:135], v[136:139]
	v_mfma_f32_16x16x32_bf16 v[52:55], v[156:159], v[210:213], v[40:43]
	v_mfma_f32_16x16x32_bf16 v[40:43], v[176:179], v[132:135], v[160:163]
	v_mfma_f32_16x16x32_bf16 v[56:59], v[180:183], v[210:213], v[44:47]
	v_mfma_f32_16x16x32_bf16 v[44:47], v[214:217], v[132:135], v[202:205]
	v_mfma_f32_16x16x32_bf16 v[60:63], v[238:241], v[210:213], v[48:51]
	v_mfma_f32_16x16x32_bf16 v[48:51], v[242:245], v[132:135], v[190:193]
	v_mfma_f32_16x16x32_bf16 v[64:67], v[242:245], v[206:209], v[194:197]
	v_mfma_f32_16x16x32_bf16 v[36:39], v[156:159], v[168:171], v[36:39]
	v_mfma_f32_16x16x32_bf16 v[40:43], v[180:183], v[168:171], v[40:43]
	v_mfma_f32_16x16x32_bf16 v[44:47], v[238:241], v[168:171], v[44:47]
	v_mfma_f32_16x16x32_bf16 v[48:51], v[150:153], v[168:171], v[48:51]
	v_mfma_f32_16x16x32_bf16 v[64:67], v[150:153], v[210:213], v[64:67]
	s_movk_i32 s2, 0x100
	v_cmp_gt_u32_e32 vcc, s2, v3
	s_barrier
	s_and_saveexec_b64 s[2:3], vcc
	s_cbranch_execz .LBB0_1328
	s_barrier
